# ew phases: first batch's row loads issued before waiting on the gain-pointer scalar load (on top of the epilogue wait move)
# baseline (speedup 1.0000x reference)
; __device__ __forceinline__ float bf_lo(unsigned w) { return __uint_as_float(w << 16); }
; template <bool SRC_F32, int R> __device__ __forceinline__ void ew_load(EwSet<SRC_F32, R>& S, int rb, const float* hsrc32, const bf16* hsrcb, const bf16* f, const float* part, int lane) {
; #pragma unroll
;     for (int i = 0; i < R; ++i) S.p[i] = (lane < 16) ? part[(size_t)(rb + i) * 16 + lane] : 0.f;
; #pragma unroll
;     for (int i = 0; i < R; ++i)
; #pragma unroll
;         for (int j = 0; j < 4; ++j) {
;             S.fw[i][j] = ((const v2u*)(f + (size_t)(rb + i) * D) + lane)[64 * j];
;             if constexpr (SRC_F32) S.h32[i][j] = __builtin_nontemporal_load((const f32x4*)(hsrc32 + (size_t)(rb + i) * D) + lane + 64 * j);
;             else S.hb[i][j] = ((const v2u*)(hsrcb + (size_t)(rb + i) * D) + lane)[64 * j];
;         }
; }
; template <bool SRC_F32, bool FINAL, int R> __device__ __forceinline__ void ew_compute(const EwSet<SRC_F32, R>& S, int rb, const f32x4 (&g)[4], bf16* hb_out, float* out32, float scale, float* rs_out, int lane) {
; #pragma unroll
;     for (int i = 0; i < R; ++i) {
;         float q = S.p[i];
;         q += __shfl_xor(q, 1); q += __shfl_xor(q, 2); q += __shfl_xor(q, 4); q += __shfl_xor(q, 8);
;         const float ss = __shfl(q, 0);
;         const float rs = scale / sqrtf(ss * (1.f / D) + EPS);
;         float s2 = 0.f;
; #pragma unroll
;         for (int j = 0; j < 4; ++j) {
;             f32x4 h;
;             if constexpr (SRC_F32) h = S.h32[i][j];
;             else { const v2u hw = S.hb[i][j]; h.x = bf_lo(hw.x); h.y = bf_hi(hw.x); h.z = bf_lo(hw.y); h.w = bf_hi(hw.y); }
;             const v2u fw = S.fw[i][j];
;             f32x4 v; v.x = h.x + bf_lo(fw.x) * rs * g[j].x; v.y = h.y + bf_hi(fw.x) * rs * g[j].y; v.z = h.z + bf_lo(fw.y) * rs * g[j].z; v.w = h.w + bf_hi(fw.y) * rs * g[j].w;
; template <bool SRC_F32, bool FINAL> __device__ __forceinline__ void ew_phase(const float* hsrc32, const bf16* hsrcb, bf16* hb_out, float* out32, const bf16* f, const float* part, const float* gpost, float scale, float* rs_out, int gw, int NGW, int lane) {
;     ...
;     f32x4 g[4];
; #pragma unroll
;     for (int j = 0; j < 4; ++j) g[j] = ((const f32x4*)gpost + lane)[64 * j];
;     const int step = NGW * R;
;     EwSet<SRC_F32, R> A, B;
;     int rb = gw * R;
;     if (rb < M) ew_load<SRC_F32, R>(A, rb, hsrc32, hsrcb, f, part, lane);
.LBB0_386:
	s_cmp_lt_i32 s30, 4
	s_cselect_b64 s[4:5], -1, 0
	s_and_b64 s[12:13], s[4:5], s[0:1]
	s_andn2_b64 vcc, exec, s[12:13]
	s_cbranch_vccnz .LBB0_432
	s_waitcnt vmcnt(0) lgkmcnt(0)
	s_add_u32 s22, s84, 0xffffff10
	s_addc_u32 s23, s85, -1
	s_load_dwordx2 s[52:53], s[22:23], 0x30
	s_add_u32 s0, s28, 0x5000000
	s_addc_u32 s1, s29, 0
	s_add_u32 s4, s28, 0x15000000
	s_addc_u32 s5, s29, 0
	s_add_u32 s6, s28, 0x3700000
	s_addc_u32 s7, s29, 0
	s_add_u32 s14, s28, 0x3910000
	s_addc_u32 s15, s29, 0
	v_and_b32_e32 v0, 63, v195
	v_lshlrev_b32_e32 v1, 5, v0
	s_and_b32 s26, s2, 7
	s_lshl_b32 s26, s26, 4
	s_bfe_u32 s27, s2, 0x30003
	s_add_u32 s26, s26, s27
	s_lshl_b32 s26, s26, 8
	s_lshr_b32 s27, s2, 6
	s_lshl_b32 s27, s27, 6
	s_add_u32 s26, s26, s27
	v_readfirstlane_b32 s27, v195
	s_lshr_b32 s27, s27, 6
	s_lshl_b32 s27, s27, 3
	s_add_u32 s26, s26, s27
	s_add_u32 s27, s26, 0
	s_lshl_b32 s22, s27, 11
	v_lshl_add_u32 v18, v0, 4, s22
	v_add_u32_e32 v19, 0x1000, v18
	s_lshl_b32 s22, s27, 6
	v_lshl_add_u32 v20, v0, 2, s22
	s_lshl_b32 s22, s27, 2
	v_lshl_add_u32 v21, v0, 2, s22
	global_load_dwordx4 v[32:35], v18, s[0:1]
	global_load_dwordx4 v[36:39], v18, s[0:1] offset:1024
	global_load_dwordx4 v[64:67], v18, s[4:5]
	global_load_dwordx4 v[68:71], v18, s[4:5] offset:1024
	global_load_dwordx4 v[40:43], v18, s[0:1] offset:2048
	global_load_dwordx4 v[44:47], v18, s[0:1] offset:3072
	global_load_dwordx4 v[72:75], v18, s[4:5] offset:2048
	global_load_dwordx4 v[76:79], v18, s[4:5] offset:3072
	global_load_dwordx4 v[48:51], v19, s[0:1]
	global_load_dwordx4 v[52:55], v19, s[0:1] offset:1024
	global_load_dwordx4 v[80:83], v19, s[4:5]
	global_load_dwordx4 v[84:87], v19, s[4:5] offset:1024
	global_load_dwordx4 v[56:59], v19, s[0:1] offset:2048
	global_load_dwordx4 v[60:63], v19, s[0:1] offset:3072
	global_load_dwordx4 v[88:91], v19, s[4:5] offset:2048
	global_load_dwordx4 v[92:95], v19, s[4:5] offset:3072
	global_load_dword v96, v20, s[6:7]
	s_waitcnt lgkmcnt(0)
	global_load_dwordx4 v[2:5], v1, s[52:53]
	global_load_dwordx4 v[6:9], v1, s[52:53] offset:16
	global_load_dwordx4 v[10:13], v1, s[52:53] offset:2048
	global_load_dwordx4 v[14:17], v1, s[52:53] offset:2064
	s_add_u32 s27, s26, 4
	s_lshl_b32 s22, s27, 11
	v_lshl_add_u32 v23, v0, 4, s22
	v_add_u32_e32 v24, 0x1000, v23
	s_lshl_b32 s22, s27, 6
	v_lshl_add_u32 v25, v0, 2, s22
	s_lshl_b32 s22, s27, 2
	v_lshl_add_u32 v26, v0, 2, s22
	global_load_dwordx4 v[100:103], v23, s[0:1]
	global_load_dwordx4 v[104:107], v23, s[0:1] offset:1024
	global_load_dwordx4 v[132:135], v23, s[4:5]
	global_load_dwordx4 v[136:139], v23, s[4:5] offset:1024
	global_load_dwordx4 v[108:111], v23, s[0:1] offset:2048
	global_load_dwordx4 v[112:115], v23, s[0:1] offset:3072
	global_load_dwordx4 v[140:143], v23, s[4:5] offset:2048
	global_load_dwordx4 v[144:147], v23, s[4:5] offset:3072
	global_load_dwordx4 v[116:119], v24, s[0:1]
	global_load_dwordx4 v[120:123], v24, s[0:1] offset:1024
	global_load_dwordx4 v[148:151], v24, s[4:5]
	global_load_dwordx4 v[152:155], v24, s[4:5] offset:1024
	global_load_dwordx4 v[124:127], v24, s[0:1] offset:2048
	global_load_dwordx4 v[128:131], v24, s[0:1] offset:3072
	global_load_dwordx4 v[156:159], v24, s[4:5] offset:2048
	global_load_dwordx4 v[160:163], v24, s[4:5] offset:3072
	global_load_dword v164, v25, s[6:7]
	s_waitcnt vmcnt(17)
	v_add_f32_dpp v96, v96, v96 quad_perm:[1,0,3,2] row_mask:0xf bank_mask:0xf
	s_nop 1
	v_add_f32_dpp v96, v96, v96 quad_perm:[2,3,0,1] row_mask:0xf bank_mask:0xf
	s_nop 1
	v_add_f32_dpp v96, v96, v96 row_half_mirror row_mask:0xf bank_mask:0xf
	s_nop 1
	v_add_f32_dpp v96, v96, v96 row_mirror row_mask:0xf bank_mask:0xf
	s_nop 1
	v_mul_f32_e32 v96, 0x3a800000, v96
	v_add_f32_e32 v96, 0x358637bd, v96
	v_rsq_f32_e32 v96, v96
	s_nop 0
	v_mul_f32_e32 v96, 0x3f000000, v96
	s_nop 0
	v_readlane_b32 s3, v96, 0
	v_readlane_b32 s24, v96, 16
	v_readlane_b32 s98, v96, 32
	v_readlane_b32 s101, v96, 48
	s_nop 1
	v_mov_b32_e32 v184, 0
	v_mov_b32_e32 v185, 0
	v_mov_b32_e32 v186, 0
	v_mov_b32_e32 v187, 0
	v_lshlrev_b32_e32 v168, 16, v32
	v_and_b32_e32 v169, 0xffff0000, v32
	v_lshlrev_b32_e32 v170, 16, v64
	v_and_b32_e32 v171, 0xffff0000, v64
	v_mul_f32_e32 v170, s3, v170
	v_mul_f32_e32 v171, s3, v171
	v_fma_f32 v168, v170, v2, v168
	v_fma_f32 v169, v171, v3, v169
	v_fma_f32 v184, v168, v168, v184
	v_fma_f32 v184, v169, v169, v184
	v_cvt_pk_bf16_f32 v32, v168, v169
	v_lshlrev_b32_e32 v168, 16, v33
	v_and_b32_e32 v169, 0xffff0000, v33
	v_lshlrev_b32_e32 v170, 16, v65
	v_and_b32_e32 v171, 0xffff0000, v65
	v_mul_f32_e32 v170, s3, v170
	v_mul_f32_e32 v171, s3, v171
	v_fma_f32 v168, v170, v4, v168
	v_fma_f32 v169, v171, v5, v169
	v_fma_f32 v184, v168, v168, v184
	v_fma_f32 v184, v169, v169, v184
	v_cvt_pk_bf16_f32 v33, v168, v169
	v_lshlrev_b32_e32 v168, 16, v34
	v_and_b32_e32 v169, 0xffff0000, v34
	v_lshlrev_b32_e32 v170, 16, v66
	v_and_b32_e32 v171, 0xffff0000, v66
	v_mul_f32_e32 v170, s3, v170
	v_mul_f32_e32 v171, s3, v171
	v_fma_f32 v168, v170, v6, v168
	v_fma_f32 v169, v171, v7, v169
	v_fma_f32 v184, v168, v168, v184
	v_fma_f32 v184, v169, v169, v184
	v_cvt_pk_bf16_f32 v34, v168, v169
	v_lshlrev_b32_e32 v168, 16, v35
	v_and_b32_e32 v169, 0xffff0000, v35
	v_lshlrev_b32_e32 v170, 16, v67
	v_and_b32_e32 v171, 0xffff0000, v67
	v_mul_f32_e32 v170, s3, v170
	v_mul_f32_e32 v171, s3, v171
	v_fma_f32 v168, v170, v8, v168
	v_fma_f32 v169, v171, v9, v169
	v_fma_f32 v184, v168, v168, v184
	v_fma_f32 v184, v169, v169, v184
	v_cvt_pk_bf16_f32 v35, v168, v169
	v_lshlrev_b32_e32 v168, 16, v36
	v_and_b32_e32 v169, 0xffff0000, v36
	v_lshlrev_b32_e32 v170, 16, v68
	v_and_b32_e32 v171, 0xffff0000, v68
	v_mul_f32_e32 v170, s3, v170
; __device__ __forceinline__ float bf_lo(unsigned w) { return __uint_as_float(w << 16); }
; __device__ __forceinline__ float bf_hi(unsigned w) { return __uint_as_float(w & 0xffff0000u); }
; __device__ __forceinline__ unsigned pk2(float lo, float hi) { bf16x2_t r = __builtin_convertvector((f32x2_t){lo, hi}, bf16x2_t); return __builtin_bit_cast(unsigned, r); }
; template <bool SRC_F32, bool FINAL, int R> __device__ __forceinline__ void ew_compute(const EwSet<SRC_F32, R>& S, int rb, const f32x4 (&g)[4], bf16* hb_out, float* out32, float scale, float* rs_out, int lane) {
;     ...
; #pragma unroll
;         for (int j = 0; j < 4; ++j) {
;             f32x4 h;
;             if constexpr (SRC_F32) h = S.h32[i][j];
;             else { const v2u hw = S.hb[i][j]; h.x = bf_lo(hw.x); h.y = bf_hi(hw.x); h.z = bf_lo(hw.y); h.w = bf_hi(hw.y); }
;             const v2u fw = S.fw[i][j];
;             f32x4 v; v.x = h.x + bf_lo(fw.x) * rs * g[j].x; v.y = h.y + bf_hi(fw.x) * rs * g[j].y; v.z = h.z + bf_lo(fw.y) * rs * g[j].z; v.w = h.w + bf_hi(fw.y) * rs * g[j].w;
;             if (FINAL) __builtin_nontemporal_store(v, (f32x4*)(out32 + (size_t)(rb + i) * D) + lane + 64 * j);
;             else { v2u o; o.x = pk2(v.x, v.y); o.y = pk2(v.z, v.w); ((v2u*)(hb_out + (size_t)(rb + i) * D) + lane)[64 * j] = o; s2 += (v.x * v.x + v.y * v.y) + (v.z * v.z + v.w * v.w); }
	v_mul_f32_e32 v171, s3, v171
	v_fma_f32 v168, v170, v10, v168
	v_fma_f32 v169, v171, v11, v169
	v_fma_f32 v184, v168, v168, v184
	v_fma_f32 v184, v169, v169, v184
	v_cvt_pk_bf16_f32 v36, v168, v169
	v_lshlrev_b32_e32 v168, 16, v37
	v_and_b32_e32 v169, 0xffff0000, v37
	v_lshlrev_b32_e32 v170, 16, v69
	v_and_b32_e32 v171, 0xffff0000, v69
	v_mul_f32_e32 v170, s3, v170
	v_mul_f32_e32 v171, s3, v171
	v_fma_f32 v168, v170, v12, v168
	v_fma_f32 v169, v171, v13, v169
	v_fma_f32 v184, v168, v168, v184
	v_fma_f32 v184, v169, v169, v184
	v_cvt_pk_bf16_f32 v37, v168, v169
	v_lshlrev_b32_e32 v168, 16, v38
	v_and_b32_e32 v169, 0xffff0000, v38
	v_lshlrev_b32_e32 v170, 16, v70
	v_and_b32_e32 v171, 0xffff0000, v70
	v_mul_f32_e32 v170, s3, v170
	v_mul_f32_e32 v171, s3, v171
	v_fma_f32 v168, v170, v14, v168
	v_fma_f32 v169, v171, v15, v169
	v_fma_f32 v184, v168, v168, v184
	v_fma_f32 v184, v169, v169, v184
	v_cvt_pk_bf16_f32 v38, v168, v169
	v_lshlrev_b32_e32 v168, 16, v39
	v_and_b32_e32 v169, 0xffff0000, v39
	v_lshlrev_b32_e32 v170, 16, v71
	v_and_b32_e32 v171, 0xffff0000, v71
	v_mul_f32_e32 v170, s3, v170
	v_mul_f32_e32 v171, s3, v171
	v_fma_f32 v168, v170, v16, v168
	v_fma_f32 v169, v171, v17, v169
	v_fma_f32 v184, v168, v168, v184
	v_fma_f32 v184, v169, v169, v184
	v_cvt_pk_bf16_f32 v39, v168, v169
	global_store_dwordx4 v18, v[32:35], s[0:1]
	global_store_dwordx4 v18, v[36:39], s[0:1] offset:1024
	v_lshlrev_b32_e32 v168, 16, v40
	v_and_b32_e32 v169, 0xffff0000, v40
	v_lshlrev_b32_e32 v170, 16, v72
	v_and_b32_e32 v171, 0xffff0000, v72
	v_mul_f32_e32 v170, s24, v170
	v_mul_f32_e32 v171, s24, v171
	v_fma_f32 v168, v170, v2, v168
	v_fma_f32 v169, v171, v3, v169
	v_fma_f32 v185, v168, v168, v185
	v_fma_f32 v185, v169, v169, v185
	v_cvt_pk_bf16_f32 v40, v168, v169
	v_lshlrev_b32_e32 v168, 16, v41
	v_and_b32_e32 v169, 0xffff0000, v41
	v_lshlrev_b32_e32 v170, 16, v73
	v_and_b32_e32 v171, 0xffff0000, v73
	v_mul_f32_e32 v170, s24, v170
	v_mul_f32_e32 v171, s24, v171
	v_fma_f32 v168, v170, v4, v168
	v_fma_f32 v169, v171, v5, v169
	v_fma_f32 v185, v168, v168, v185
	v_fma_f32 v185, v169, v169, v185
	v_cvt_pk_bf16_f32 v41, v168, v169
	v_lshlrev_b32_e32 v168, 16, v42
	v_and_b32_e32 v169, 0xffff0000, v42
	v_lshlrev_b32_e32 v170, 16, v74
	v_and_b32_e32 v171, 0xffff0000, v74
	v_mul_f32_e32 v170, s24, v170
	v_mul_f32_e32 v171, s24, v171
	v_fma_f32 v168, v170, v6, v168
	v_fma_f32 v169, v171, v7, v169
	v_fma_f32 v185, v168, v168, v185
	v_fma_f32 v185, v169, v169, v185
	v_cvt_pk_bf16_f32 v42, v168, v169
	v_lshlrev_b32_e32 v168, 16, v43
	v_and_b32_e32 v169, 0xffff0000, v43
	v_lshlrev_b32_e32 v170, 16, v75
	v_and_b32_e32 v171, 0xffff0000, v75
	v_mul_f32_e32 v170, s24, v170
	v_mul_f32_e32 v171, s24, v171
	v_fma_f32 v168, v170, v8, v168
	v_fma_f32 v169, v171, v9, v169
	v_fma_f32 v185, v168, v168, v185
	v_fma_f32 v185, v169, v169, v185
	v_cvt_pk_bf16_f32 v43, v168, v169
	v_lshlrev_b32_e32 v168, 16, v44
	v_and_b32_e32 v169, 0xffff0000, v44
	v_lshlrev_b32_e32 v170, 16, v76
	v_and_b32_e32 v171, 0xffff0000, v76
	v_mul_f32_e32 v170, s24, v170
	v_mul_f32_e32 v171, s24, v171
	v_fma_f32 v168, v170, v10, v168
	v_fma_f32 v169, v171, v11, v169
	v_fma_f32 v185, v168, v168, v185
	v_fma_f32 v185, v169, v169, v185
	v_cvt_pk_bf16_f32 v44, v168, v169
	v_lshlrev_b32_e32 v168, 16, v45
	v_and_b32_e32 v169, 0xffff0000, v45
	v_lshlrev_b32_e32 v170, 16, v77
	v_and_b32_e32 v171, 0xffff0000, v77
	v_mul_f32_e32 v170, s24, v170
	v_mul_f32_e32 v171, s24, v171
	v_fma_f32 v168, v170, v12, v168
	v_fma_f32 v169, v171, v13, v169
	v_fma_f32 v185, v168, v168, v185
	v_fma_f32 v185, v169, v169, v185
	v_cvt_pk_bf16_f32 v45, v168, v169
	v_lshlrev_b32_e32 v168, 16, v46
	v_and_b32_e32 v169, 0xffff0000, v46
	v_lshlrev_b32_e32 v170, 16, v78
	v_and_b32_e32 v171, 0xffff0000, v78
	v_mul_f32_e32 v170, s24, v170
	v_mul_f32_e32 v171, s24, v171
	v_fma_f32 v168, v170, v14, v168
	v_fma_f32 v169, v171, v15, v169
	v_fma_f32 v185, v168, v168, v185
	v_fma_f32 v185, v169, v169, v185
	v_cvt_pk_bf16_f32 v46, v168, v169
	v_lshlrev_b32_e32 v168, 16, v47
	v_and_b32_e32 v169, 0xffff0000, v47
	v_lshlrev_b32_e32 v170, 16, v79
	v_and_b32_e32 v171, 0xffff0000, v79
	v_mul_f32_e32 v170, s24, v170
	v_mul_f32_e32 v171, s24, v171
	v_fma_f32 v168, v170, v16, v168
	v_fma_f32 v169, v171, v17, v169
	v_fma_f32 v185, v168, v168, v185
	v_fma_f32 v185, v169, v169, v185
	v_cvt_pk_bf16_f32 v47, v168, v169
	global_store_dwordx4 v18, v[40:43], s[0:1] offset:2048
	global_store_dwordx4 v18, v[44:47], s[0:1] offset:3072
	v_lshlrev_b32_e32 v168, 16, v48
	v_and_b32_e32 v169, 0xffff0000, v48
	v_lshlrev_b32_e32 v170, 16, v80
	v_and_b32_e32 v171, 0xffff0000, v80
	v_mul_f32_e32 v170, s98, v170
	v_mul_f32_e32 v171, s98, v171
	v_fma_f32 v168, v170, v2, v168
	v_fma_f32 v169, v171, v3, v169
	v_fma_f32 v186, v168, v168, v186
	v_fma_f32 v186, v169, v169, v186
	v_cvt_pk_bf16_f32 v48, v168, v169
	v_lshlrev_b32_e32 v168, 16, v49
	v_and_b32_e32 v169, 0xffff0000, v49
	v_lshlrev_b32_e32 v170, 16, v81
	v_and_b32_e32 v171, 0xffff0000, v81
	v_mul_f32_e32 v170, s98, v170
	v_mul_f32_e32 v171, s98, v171
	v_fma_f32 v168, v170, v4, v168
	v_fma_f32 v169, v171, v5, v169
	v_fma_f32 v186, v168, v168, v186
	v_fma_f32 v186, v169, v169, v186
	v_cvt_pk_bf16_f32 v49, v168, v169
	v_lshlrev_b32_e32 v168, 16, v50
	v_and_b32_e32 v169, 0xffff0000, v50
	v_lshlrev_b32_e32 v170, 16, v82
	v_and_b32_e32 v171, 0xffff0000, v82
	v_mul_f32_e32 v170, s98, v170
	v_mul_f32_e32 v171, s98, v171
	v_fma_f32 v168, v170, v6, v168
	v_fma_f32 v169, v171, v7, v169
	v_fma_f32 v186, v168, v168, v186
	v_fma_f32 v186, v169, v169, v186
	v_cvt_pk_bf16_f32 v50, v168, v169
	v_lshlrev_b32_e32 v168, 16, v51
	v_and_b32_e32 v169, 0xffff0000, v51
; __device__ __forceinline__ float bf_lo(unsigned w) { return __uint_as_float(w << 16); }
; __device__ __forceinline__ float bf_hi(unsigned w) { return __uint_as_float(w & 0xffff0000u); }
; __device__ __forceinline__ unsigned pk2(float lo, float hi) { bf16x2_t r = __builtin_convertvector((f32x2_t){lo, hi}, bf16x2_t); return __builtin_bit_cast(unsigned, r); }
; template <bool SRC_F32, bool FINAL, int R> __device__ __forceinline__ void ew_compute(const EwSet<SRC_F32, R>& S, int rb, const f32x4 (&g)[4], bf16* hb_out, float* out32, float scale, float* rs_out, int lane) {
;     ...
; #pragma unroll
;         for (int j = 0; j < 4; ++j) {
;             f32x4 h;
;             if constexpr (SRC_F32) h = S.h32[i][j];
;             else { const v2u hw = S.hb[i][j]; h.x = bf_lo(hw.x); h.y = bf_hi(hw.x); h.z = bf_lo(hw.y); h.w = bf_hi(hw.y); }
;             const v2u fw = S.fw[i][j];
;             f32x4 v; v.x = h.x + bf_lo(fw.x) * rs * g[j].x; v.y = h.y + bf_hi(fw.x) * rs * g[j].y; v.z = h.z + bf_lo(fw.y) * rs * g[j].z; v.w = h.w + bf_hi(fw.y) * rs * g[j].w;
;             if (FINAL) __builtin_nontemporal_store(v, (f32x4*)(out32 + (size_t)(rb + i) * D) + lane + 64 * j);
;             else { v2u o; o.x = pk2(v.x, v.y); o.y = pk2(v.z, v.w); ((v2u*)(hb_out + (size_t)(rb + i) * D) + lane)[64 * j] = o; s2 += (v.x * v.x + v.y * v.y) + (v.z * v.z + v.w * v.w); }
;         }
;         if (!FINAL) { const float tot = wave_sum(s2); if (lane == 0) rs_out[rb + i] = 1.0f / sqrtf(tot * (1.f / D) + EPS); }
	v_lshlrev_b32_e32 v170, 16, v83
	v_and_b32_e32 v171, 0xffff0000, v83
	v_mul_f32_e32 v170, s98, v170
	v_mul_f32_e32 v171, s98, v171
	v_fma_f32 v168, v170, v8, v168
	v_fma_f32 v169, v171, v9, v169
	v_fma_f32 v186, v168, v168, v186
	v_fma_f32 v186, v169, v169, v186
	v_cvt_pk_bf16_f32 v51, v168, v169
	v_lshlrev_b32_e32 v168, 16, v52
	v_and_b32_e32 v169, 0xffff0000, v52
	v_lshlrev_b32_e32 v170, 16, v84
	v_and_b32_e32 v171, 0xffff0000, v84
	v_mul_f32_e32 v170, s98, v170
	v_mul_f32_e32 v171, s98, v171
	v_fma_f32 v168, v170, v10, v168
	v_fma_f32 v169, v171, v11, v169
	v_fma_f32 v186, v168, v168, v186
	v_fma_f32 v186, v169, v169, v186
	v_cvt_pk_bf16_f32 v52, v168, v169
	v_lshlrev_b32_e32 v168, 16, v53
	v_and_b32_e32 v169, 0xffff0000, v53
	v_lshlrev_b32_e32 v170, 16, v85
	v_and_b32_e32 v171, 0xffff0000, v85
	v_mul_f32_e32 v170, s98, v170
	v_mul_f32_e32 v171, s98, v171
	v_fma_f32 v168, v170, v12, v168
	v_fma_f32 v169, v171, v13, v169
	v_fma_f32 v186, v168, v168, v186
	v_fma_f32 v186, v169, v169, v186
	v_cvt_pk_bf16_f32 v53, v168, v169
	v_lshlrev_b32_e32 v168, 16, v54
	v_and_b32_e32 v169, 0xffff0000, v54
	v_lshlrev_b32_e32 v170, 16, v86
	v_and_b32_e32 v171, 0xffff0000, v86
	v_mul_f32_e32 v170, s98, v170
	v_mul_f32_e32 v171, s98, v171
	v_fma_f32 v168, v170, v14, v168
	v_fma_f32 v169, v171, v15, v169
	v_fma_f32 v186, v168, v168, v186
	v_fma_f32 v186, v169, v169, v186
	v_cvt_pk_bf16_f32 v54, v168, v169
	v_lshlrev_b32_e32 v168, 16, v55
	v_and_b32_e32 v169, 0xffff0000, v55
	v_lshlrev_b32_e32 v170, 16, v87
	v_and_b32_e32 v171, 0xffff0000, v87
	v_mul_f32_e32 v170, s98, v170
	v_mul_f32_e32 v171, s98, v171
	v_fma_f32 v168, v170, v16, v168
	v_fma_f32 v169, v171, v17, v169
	v_fma_f32 v186, v168, v168, v186
	v_fma_f32 v186, v169, v169, v186
	v_cvt_pk_bf16_f32 v55, v168, v169
	global_store_dwordx4 v19, v[48:51], s[0:1]
	global_store_dwordx4 v19, v[52:55], s[0:1] offset:1024
	v_lshlrev_b32_e32 v168, 16, v56
	v_and_b32_e32 v169, 0xffff0000, v56
	v_lshlrev_b32_e32 v170, 16, v88
	v_and_b32_e32 v171, 0xffff0000, v88
	v_mul_f32_e32 v170, s101, v170
	v_mul_f32_e32 v171, s101, v171
	v_fma_f32 v168, v170, v2, v168
	v_fma_f32 v169, v171, v3, v169
	v_fma_f32 v187, v168, v168, v187
	v_fma_f32 v187, v169, v169, v187
	v_cvt_pk_bf16_f32 v56, v168, v169
	v_lshlrev_b32_e32 v168, 16, v57
	v_and_b32_e32 v169, 0xffff0000, v57
	v_lshlrev_b32_e32 v170, 16, v89
	v_and_b32_e32 v171, 0xffff0000, v89
	v_mul_f32_e32 v170, s101, v170
	v_mul_f32_e32 v171, s101, v171
	v_fma_f32 v168, v170, v4, v168
	v_fma_f32 v169, v171, v5, v169
	v_fma_f32 v187, v168, v168, v187
	v_fma_f32 v187, v169, v169, v187
	v_cvt_pk_bf16_f32 v57, v168, v169
	v_lshlrev_b32_e32 v168, 16, v58
	v_and_b32_e32 v169, 0xffff0000, v58
	v_lshlrev_b32_e32 v170, 16, v90
	v_and_b32_e32 v171, 0xffff0000, v90
	v_mul_f32_e32 v170, s101, v170
	v_mul_f32_e32 v171, s101, v171
	v_fma_f32 v168, v170, v6, v168
	v_fma_f32 v169, v171, v7, v169
	v_fma_f32 v187, v168, v168, v187
	v_fma_f32 v187, v169, v169, v187
	v_cvt_pk_bf16_f32 v58, v168, v169
	v_lshlrev_b32_e32 v168, 16, v59
	v_and_b32_e32 v169, 0xffff0000, v59
	v_lshlrev_b32_e32 v170, 16, v91
	v_and_b32_e32 v171, 0xffff0000, v91
	v_mul_f32_e32 v170, s101, v170
	v_mul_f32_e32 v171, s101, v171
	v_fma_f32 v168, v170, v8, v168
	v_fma_f32 v169, v171, v9, v169
	v_fma_f32 v187, v168, v168, v187
	v_fma_f32 v187, v169, v169, v187
	v_cvt_pk_bf16_f32 v59, v168, v169
	v_lshlrev_b32_e32 v168, 16, v60
	v_and_b32_e32 v169, 0xffff0000, v60
	v_lshlrev_b32_e32 v170, 16, v92
	v_and_b32_e32 v171, 0xffff0000, v92
	v_mul_f32_e32 v170, s101, v170
	v_mul_f32_e32 v171, s101, v171
	v_fma_f32 v168, v170, v10, v168
	v_fma_f32 v169, v171, v11, v169
	v_fma_f32 v187, v168, v168, v187
	v_fma_f32 v187, v169, v169, v187
	v_cvt_pk_bf16_f32 v60, v168, v169
	v_lshlrev_b32_e32 v168, 16, v61
	v_and_b32_e32 v169, 0xffff0000, v61
	v_lshlrev_b32_e32 v170, 16, v93
	v_and_b32_e32 v171, 0xffff0000, v93
	v_mul_f32_e32 v170, s101, v170
	v_mul_f32_e32 v171, s101, v171
	v_fma_f32 v168, v170, v12, v168
	v_fma_f32 v169, v171, v13, v169
	v_fma_f32 v187, v168, v168, v187
	v_fma_f32 v187, v169, v169, v187
	v_cvt_pk_bf16_f32 v61, v168, v169
	v_lshlrev_b32_e32 v168, 16, v62
	v_and_b32_e32 v169, 0xffff0000, v62
	v_lshlrev_b32_e32 v170, 16, v94
	v_and_b32_e32 v171, 0xffff0000, v94
	v_mul_f32_e32 v170, s101, v170
	v_mul_f32_e32 v171, s101, v171
	v_fma_f32 v168, v170, v14, v168
	v_fma_f32 v169, v171, v15, v169
	v_fma_f32 v187, v168, v168, v187
	v_fma_f32 v187, v169, v169, v187
	v_cvt_pk_bf16_f32 v62, v168, v169
	v_lshlrev_b32_e32 v168, 16, v63
	v_and_b32_e32 v169, 0xffff0000, v63
	v_lshlrev_b32_e32 v170, 16, v95
	v_and_b32_e32 v171, 0xffff0000, v95
	v_mul_f32_e32 v170, s101, v170
	v_mul_f32_e32 v171, s101, v171
	v_fma_f32 v168, v170, v16, v168
	v_fma_f32 v169, v171, v17, v169
	v_fma_f32 v187, v168, v168, v187
	v_fma_f32 v187, v169, v169, v187
	v_cvt_pk_bf16_f32 v63, v168, v169
	global_store_dwordx4 v19, v[56:59], s[0:1] offset:2048
	global_store_dwordx4 v19, v[60:63], s[0:1] offset:3072
	s_nop 1
	v_add_f32_dpp v184, v184, v184 quad_perm:[1,0,3,2] row_mask:0xf bank_mask:0xf
	v_add_f32_dpp v185, v185, v185 quad_perm:[1,0,3,2] row_mask:0xf bank_mask:0xf
	v_add_f32_dpp v186, v186, v186 quad_perm:[1,0,3,2] row_mask:0xf bank_mask:0xf
	v_add_f32_dpp v187, v187, v187 quad_perm:[1,0,3,2] row_mask:0xf bank_mask:0xf
	v_add_f32_dpp v184, v184, v184 quad_perm:[2,3,0,1] row_mask:0xf bank_mask:0xf
	v_add_f32_dpp v185, v185, v185 quad_perm:[2,3,0,1] row_mask:0xf bank_mask:0xf
	v_add_f32_dpp v186, v186, v186 quad_perm:[2,3,0,1] row_mask:0xf bank_mask:0xf
	v_add_f32_dpp v187, v187, v187 quad_perm:[2,3,0,1] row_mask:0xf bank_mask:0xf
; __device__ __forceinline__ float bf_lo(unsigned w) { return __uint_as_float(w << 16); }
; __device__ __forceinline__ float bf_hi(unsigned w) { return __uint_as_float(w & 0xffff0000u); }
; template <bool SRC_F32, int R> __device__ __forceinline__ void ew_load(EwSet<SRC_F32, R>& S, int rb, const float* hsrc32, const bf16* hsrcb, const bf16* f, const float* part, int lane) {
; #pragma unroll
;     for (int i = 0; i < R; ++i) S.p[i] = (lane < 16) ? part[(size_t)(rb + i) * 16 + lane] : 0.f;
; #pragma unroll
;     for (int i = 0; i < R; ++i)
; #pragma unroll
;         for (int j = 0; j < 4; ++j) {
;             S.fw[i][j] = ((const v2u*)(f + (size_t)(rb + i) * D) + lane)[64 * j];
;             if constexpr (SRC_F32) S.h32[i][j] = __builtin_nontemporal_load((const f32x4*)(hsrc32 + (size_t)(rb + i) * D) + lane + 64 * j);
;             else S.hb[i][j] = ((const v2u*)(hsrcb + (size_t)(rb + i) * D) + lane)[64 * j];
;         }
; }
; template <bool SRC_F32, bool FINAL, int R> __device__ __forceinline__ void ew_compute(const EwSet<SRC_F32, R>& S, int rb, const f32x4 (&g)[4], bf16* hb_out, float* out32, float scale, float* rs_out, int lane) {
; #pragma unroll
;     for (int i = 0; i < R; ++i) {
;         float q = S.p[i];
;         q += __shfl_xor(q, 1); q += __shfl_xor(q, 2); q += __shfl_xor(q, 4); q += __shfl_xor(q, 8);
;         const float ss = __shfl(q, 0);
;         const float rs = scale / sqrtf(ss * (1.f / D) + EPS);
;         float s2 = 0.f;
; #pragma unroll
;         for (int j = 0; j < 4; ++j) {
;             f32x4 h;
;             if constexpr (SRC_F32) h = S.h32[i][j];
;             else { const v2u hw = S.hb[i][j]; h.x = bf_lo(hw.x); h.y = bf_hi(hw.x); h.z = bf_lo(hw.y); h.w = bf_hi(hw.y); }
;             const v2u fw = S.fw[i][j];
;             f32x4 v; v.x = h.x + bf_lo(fw.x) * rs * g[j].x; v.y = h.y + bf_hi(fw.x) * rs * g[j].y; v.z = h.z + bf_lo(fw.y) * rs * g[j].z; v.w = h.w + bf_hi(fw.y) * rs * g[j].w;
;             if (FINAL) __builtin_nontemporal_store(v, (f32x4*)(out32 + (size_t)(rb + i) * D) + lane + 64 * j);
;             else { v2u o; o.x = pk2(v.x, v.y); o.y = pk2(v.z, v.w); ((v2u*)(hb_out + (size_t)(rb + i) * D) + lane)[64 * j] = o; s2 += (v.x * v.x + v.y * v.y) + (v.z * v.z + v.w * v.w); }
;         }
;         if (!FINAL) { const float tot = wave_sum(s2); if (lane == 0) rs_out[rb + i] = 1.0f / sqrtf(tot * (1.f / D) + EPS); }
	v_add_f32_dpp v184, v184, v184 row_half_mirror row_mask:0xf bank_mask:0xf
	v_add_f32_dpp v185, v185, v185 row_half_mirror row_mask:0xf bank_mask:0xf
	v_add_f32_dpp v186, v186, v186 row_half_mirror row_mask:0xf bank_mask:0xf
	v_add_f32_dpp v187, v187, v187 row_half_mirror row_mask:0xf bank_mask:0xf
	v_add_f32_dpp v184, v184, v184 row_mirror row_mask:0xf bank_mask:0xf
	v_add_f32_dpp v185, v185, v185 row_mirror row_mask:0xf bank_mask:0xf
	v_add_f32_dpp v186, v186, v186 row_mirror row_mask:0xf bank_mask:0xf
	v_add_f32_dpp v187, v187, v187 row_mirror row_mask:0xf bank_mask:0xf
	v_add_f32_dpp v184, v184, v184 row_bcast:15 row_mask:0xa bank_mask:0xf
	v_add_f32_dpp v185, v185, v185 row_bcast:15 row_mask:0xa bank_mask:0xf
	v_add_f32_dpp v186, v186, v186 row_bcast:15 row_mask:0xa bank_mask:0xf
	v_add_f32_dpp v187, v187, v187 row_bcast:15 row_mask:0xa bank_mask:0xf
	v_add_f32_dpp v184, v184, v184 row_bcast:31 row_mask:0xc bank_mask:0xf
	v_add_f32_dpp v185, v185, v185 row_bcast:31 row_mask:0xc bank_mask:0xf
	v_add_f32_dpp v186, v186, v186 row_bcast:31 row_mask:0xc bank_mask:0xf
	v_add_f32_dpp v187, v187, v187 row_bcast:31 row_mask:0xc bank_mask:0xf
	s_nop 1
	v_readlane_b32 s3, v184, 63
	v_readlane_b32 s24, v185, 63
	v_readlane_b32 s98, v186, 63
	v_readlane_b32 s101, v187, 63
	s_nop 3
	v_writelane_b32 v188, s3, 0
	v_writelane_b32 v188, s24, 1
	v_writelane_b32 v188, s98, 2
	v_writelane_b32 v188, s101, 3
	s_nop 1
	v_mul_f32_e32 v188, 0x3a800000, v188
	v_add_f32_e32 v188, 0x358637bd, v188
	v_rsq_f32_e32 v188, v188
	s_mov_b64 exec, 15
	global_store_dword v21, v188, s[14:15]
	s_mov_b64 exec, -1
	s_add_u32 s27, s26, 2048
	s_lshl_b32 s22, s27, 11
	v_lshl_add_u32 v18, v0, 4, s22
	v_add_u32_e32 v19, 0x1000, v18
	s_lshl_b32 s22, s27, 6
	v_lshl_add_u32 v20, v0, 2, s22
	s_lshl_b32 s22, s27, 2
	v_lshl_add_u32 v21, v0, 2, s22
	global_load_dwordx4 v[32:35], v18, s[0:1]
	global_load_dwordx4 v[36:39], v18, s[0:1] offset:1024
	global_load_dwordx4 v[64:67], v18, s[4:5]
	global_load_dwordx4 v[68:71], v18, s[4:5] offset:1024
	global_load_dwordx4 v[40:43], v18, s[0:1] offset:2048
	global_load_dwordx4 v[44:47], v18, s[0:1] offset:3072
	global_load_dwordx4 v[72:75], v18, s[4:5] offset:2048
	global_load_dwordx4 v[76:79], v18, s[4:5] offset:3072
	global_load_dwordx4 v[48:51], v19, s[0:1]
	global_load_dwordx4 v[52:55], v19, s[0:1] offset:1024
	global_load_dwordx4 v[80:83], v19, s[4:5]
	global_load_dwordx4 v[84:87], v19, s[4:5] offset:1024
	global_load_dwordx4 v[56:59], v19, s[0:1] offset:2048
	global_load_dwordx4 v[60:63], v19, s[0:1] offset:3072
	global_load_dwordx4 v[88:91], v19, s[4:5] offset:2048
	global_load_dwordx4 v[92:95], v19, s[4:5] offset:3072
	global_load_dword v96, v20, s[6:7]
	s_waitcnt vmcnt(26)
	v_add_f32_dpp v164, v164, v164 quad_perm:[1,0,3,2] row_mask:0xf bank_mask:0xf
	s_nop 1
	v_add_f32_dpp v164, v164, v164 quad_perm:[2,3,0,1] row_mask:0xf bank_mask:0xf
	s_nop 1
	v_add_f32_dpp v164, v164, v164 row_half_mirror row_mask:0xf bank_mask:0xf
	s_nop 1
	v_add_f32_dpp v164, v164, v164 row_mirror row_mask:0xf bank_mask:0xf
	s_nop 1
	v_mul_f32_e32 v164, 0x3a800000, v164
	v_add_f32_e32 v164, 0x358637bd, v164
	v_rsq_f32_e32 v164, v164
	s_nop 0
	v_mul_f32_e32 v164, 0x3f000000, v164
	s_nop 0
	v_readlane_b32 s3, v164, 0
	v_readlane_b32 s24, v164, 16
	v_readlane_b32 s98, v164, 32
	v_readlane_b32 s101, v164, 48
	s_nop 1
	v_mov_b32_e32 v184, 0
	v_mov_b32_e32 v185, 0
	v_mov_b32_e32 v186, 0
	v_mov_b32_e32 v187, 0
	v_lshlrev_b32_e32 v168, 16, v100
	v_and_b32_e32 v169, 0xffff0000, v100
	v_lshlrev_b32_e32 v170, 16, v132
	v_and_b32_e32 v171, 0xffff0000, v132
	v_mul_f32_e32 v170, s3, v170
	v_mul_f32_e32 v171, s3, v171
	v_fma_f32 v168, v170, v2, v168
	v_fma_f32 v169, v171, v3, v169
	v_fma_f32 v184, v168, v168, v184
	v_fma_f32 v184, v169, v169, v184
	v_cvt_pk_bf16_f32 v100, v168, v169
	v_lshlrev_b32_e32 v168, 16, v101
	v_and_b32_e32 v169, 0xffff0000, v101
	v_lshlrev_b32_e32 v170, 16, v133
	v_and_b32_e32 v171, 0xffff0000, v133
	v_mul_f32_e32 v170, s3, v170
	v_mul_f32_e32 v171, s3, v171
	v_fma_f32 v168, v170, v4, v168
	v_fma_f32 v169, v171, v5, v169
	v_fma_f32 v184, v168, v168, v184
	v_fma_f32 v184, v169, v169, v184
	v_cvt_pk_bf16_f32 v101, v168, v169
	v_lshlrev_b32_e32 v168, 16, v102
	v_and_b32_e32 v169, 0xffff0000, v102
	v_lshlrev_b32_e32 v170, 16, v134
	v_and_b32_e32 v171, 0xffff0000, v134
	v_mul_f32_e32 v170, s3, v170
	v_mul_f32_e32 v171, s3, v171
	v_fma_f32 v168, v170, v6, v168
	v_fma_f32 v169, v171, v7, v169
	v_fma_f32 v184, v168, v168, v184
	v_fma_f32 v184, v169, v169, v184
	v_cvt_pk_bf16_f32 v102, v168, v169
	v_lshlrev_b32_e32 v168, 16, v103
	v_and_b32_e32 v169, 0xffff0000, v103
	v_lshlrev_b32_e32 v170, 16, v135
	v_and_b32_e32 v171, 0xffff0000, v135
	v_mul_f32_e32 v170, s3, v170
	v_mul_f32_e32 v171, s3, v171
	v_fma_f32 v168, v170, v8, v168
	v_fma_f32 v169, v171, v9, v169
	v_fma_f32 v184, v168, v168, v184
	v_fma_f32 v184, v169, v169, v184
	v_cvt_pk_bf16_f32 v103, v168, v169
	v_lshlrev_b32_e32 v168, 16, v104
	v_and_b32_e32 v169, 0xffff0000, v104
	v_lshlrev_b32_e32 v170, 16, v136
	v_and_b32_e32 v171, 0xffff0000, v136
	v_mul_f32_e32 v170, s3, v170
	v_mul_f32_e32 v171, s3, v171
	v_fma_f32 v168, v170, v10, v168
	v_fma_f32 v169, v171, v11, v169
	v_fma_f32 v184, v168, v168, v184
	v_fma_f32 v184, v169, v169, v184
	v_cvt_pk_bf16_f32 v104, v168, v169
	v_lshlrev_b32_e32 v168, 16, v105
	v_and_b32_e32 v169, 0xffff0000, v105
	v_lshlrev_b32_e32 v170, 16, v137
	v_and_b32_e32 v171, 0xffff0000, v137
	v_mul_f32_e32 v170, s3, v170
	v_mul_f32_e32 v171, s3, v171
	v_fma_f32 v168, v170, v12, v168
	v_fma_f32 v169, v171, v13, v169
	v_fma_f32 v184, v168, v168, v184
	v_fma_f32 v184, v169, v169, v184
; __device__ __forceinline__ float bf_lo(unsigned w) { return __uint_as_float(w << 16); }
; __device__ __forceinline__ float bf_hi(unsigned w) { return __uint_as_float(w & 0xffff0000u); }
; __device__ __forceinline__ unsigned pk2(float lo, float hi) { bf16x2_t r = __builtin_convertvector((f32x2_t){lo, hi}, bf16x2_t); return __builtin_bit_cast(unsigned, r); }
; template <bool SRC_F32, bool FINAL, int R> __device__ __forceinline__ void ew_compute(const EwSet<SRC_F32, R>& S, int rb, const f32x4 (&g)[4], bf16* hb_out, float* out32, float scale, float* rs_out, int lane) {
;     ...
; #pragma unroll
;         for (int j = 0; j < 4; ++j) {
;             f32x4 h;
;             if constexpr (SRC_F32) h = S.h32[i][j];
;             else { const v2u hw = S.hb[i][j]; h.x = bf_lo(hw.x); h.y = bf_hi(hw.x); h.z = bf_lo(hw.y); h.w = bf_hi(hw.y); }
;             const v2u fw = S.fw[i][j];
;             f32x4 v; v.x = h.x + bf_lo(fw.x) * rs * g[j].x; v.y = h.y + bf_hi(fw.x) * rs * g[j].y; v.z = h.z + bf_lo(fw.y) * rs * g[j].z; v.w = h.w + bf_hi(fw.y) * rs * g[j].w;
;             if (FINAL) __builtin_nontemporal_store(v, (f32x4*)(out32 + (size_t)(rb + i) * D) + lane + 64 * j);
;             else { v2u o; o.x = pk2(v.x, v.y); o.y = pk2(v.z, v.w); ((v2u*)(hb_out + (size_t)(rb + i) * D) + lane)[64 * j] = o; s2 += (v.x * v.x + v.y * v.y) + (v.z * v.z + v.w * v.w); }
	v_cvt_pk_bf16_f32 v105, v168, v169
	v_lshlrev_b32_e32 v168, 16, v106
	v_and_b32_e32 v169, 0xffff0000, v106
	v_lshlrev_b32_e32 v170, 16, v138
	v_and_b32_e32 v171, 0xffff0000, v138
	v_mul_f32_e32 v170, s3, v170
	v_mul_f32_e32 v171, s3, v171
	v_fma_f32 v168, v170, v14, v168
	v_fma_f32 v169, v171, v15, v169
	v_fma_f32 v184, v168, v168, v184
	v_fma_f32 v184, v169, v169, v184
	v_cvt_pk_bf16_f32 v106, v168, v169
	v_lshlrev_b32_e32 v168, 16, v107
	v_and_b32_e32 v169, 0xffff0000, v107
	v_lshlrev_b32_e32 v170, 16, v139
	v_and_b32_e32 v171, 0xffff0000, v139
	v_mul_f32_e32 v170, s3, v170
	v_mul_f32_e32 v171, s3, v171
	v_fma_f32 v168, v170, v16, v168
	v_fma_f32 v169, v171, v17, v169
	v_fma_f32 v184, v168, v168, v184
	v_fma_f32 v184, v169, v169, v184
	v_cvt_pk_bf16_f32 v107, v168, v169
	global_store_dwordx4 v23, v[100:103], s[0:1]
	global_store_dwordx4 v23, v[104:107], s[0:1] offset:1024
	v_lshlrev_b32_e32 v168, 16, v108
	v_and_b32_e32 v169, 0xffff0000, v108
	v_lshlrev_b32_e32 v170, 16, v140
	v_and_b32_e32 v171, 0xffff0000, v140
	v_mul_f32_e32 v170, s24, v170
	v_mul_f32_e32 v171, s24, v171
	v_fma_f32 v168, v170, v2, v168
	v_fma_f32 v169, v171, v3, v169
	v_fma_f32 v185, v168, v168, v185
	v_fma_f32 v185, v169, v169, v185
	v_cvt_pk_bf16_f32 v108, v168, v169
	v_lshlrev_b32_e32 v168, 16, v109
	v_and_b32_e32 v169, 0xffff0000, v109
	v_lshlrev_b32_e32 v170, 16, v141
	v_and_b32_e32 v171, 0xffff0000, v141
	v_mul_f32_e32 v170, s24, v170
	v_mul_f32_e32 v171, s24, v171
	v_fma_f32 v168, v170, v4, v168
	v_fma_f32 v169, v171, v5, v169
	v_fma_f32 v185, v168, v168, v185
	v_fma_f32 v185, v169, v169, v185
	v_cvt_pk_bf16_f32 v109, v168, v169
	v_lshlrev_b32_e32 v168, 16, v110
	v_and_b32_e32 v169, 0xffff0000, v110
	v_lshlrev_b32_e32 v170, 16, v142
	v_and_b32_e32 v171, 0xffff0000, v142
	v_mul_f32_e32 v170, s24, v170
	v_mul_f32_e32 v171, s24, v171
	v_fma_f32 v168, v170, v6, v168
	v_fma_f32 v169, v171, v7, v169
	v_fma_f32 v185, v168, v168, v185
	v_fma_f32 v185, v169, v169, v185
	v_cvt_pk_bf16_f32 v110, v168, v169
	v_lshlrev_b32_e32 v168, 16, v111
	v_and_b32_e32 v169, 0xffff0000, v111
	v_lshlrev_b32_e32 v170, 16, v143
	v_and_b32_e32 v171, 0xffff0000, v143
	v_mul_f32_e32 v170, s24, v170
	v_mul_f32_e32 v171, s24, v171
	v_fma_f32 v168, v170, v8, v168
	v_fma_f32 v169, v171, v9, v169
	v_fma_f32 v185, v168, v168, v185
	v_fma_f32 v185, v169, v169, v185
	v_cvt_pk_bf16_f32 v111, v168, v169
	v_lshlrev_b32_e32 v168, 16, v112
	v_and_b32_e32 v169, 0xffff0000, v112
	v_lshlrev_b32_e32 v170, 16, v144
	v_and_b32_e32 v171, 0xffff0000, v144
	v_mul_f32_e32 v170, s24, v170
	v_mul_f32_e32 v171, s24, v171
	v_fma_f32 v168, v170, v10, v168
	v_fma_f32 v169, v171, v11, v169
	v_fma_f32 v185, v168, v168, v185
	v_fma_f32 v185, v169, v169, v185
	v_cvt_pk_bf16_f32 v112, v168, v169
	v_lshlrev_b32_e32 v168, 16, v113
	v_and_b32_e32 v169, 0xffff0000, v113
	v_lshlrev_b32_e32 v170, 16, v145
	v_and_b32_e32 v171, 0xffff0000, v145
	v_mul_f32_e32 v170, s24, v170
	v_mul_f32_e32 v171, s24, v171
	v_fma_f32 v168, v170, v12, v168
	v_fma_f32 v169, v171, v13, v169
	v_fma_f32 v185, v168, v168, v185
	v_fma_f32 v185, v169, v169, v185
	v_cvt_pk_bf16_f32 v113, v168, v169
	v_lshlrev_b32_e32 v168, 16, v114
	v_and_b32_e32 v169, 0xffff0000, v114
	v_lshlrev_b32_e32 v170, 16, v146
	v_and_b32_e32 v171, 0xffff0000, v146
	v_mul_f32_e32 v170, s24, v170
	v_mul_f32_e32 v171, s24, v171
	v_fma_f32 v168, v170, v14, v168
	v_fma_f32 v169, v171, v15, v169
	v_fma_f32 v185, v168, v168, v185
	v_fma_f32 v185, v169, v169, v185
	v_cvt_pk_bf16_f32 v114, v168, v169
	v_lshlrev_b32_e32 v168, 16, v115
	v_and_b32_e32 v169, 0xffff0000, v115
	v_lshlrev_b32_e32 v170, 16, v147
	v_and_b32_e32 v171, 0xffff0000, v147
	v_mul_f32_e32 v170, s24, v170
	v_mul_f32_e32 v171, s24, v171
	v_fma_f32 v168, v170, v16, v168
	v_fma_f32 v169, v171, v17, v169
	v_fma_f32 v185, v168, v168, v185
	v_fma_f32 v185, v169, v169, v185
	v_cvt_pk_bf16_f32 v115, v168, v169
	global_store_dwordx4 v23, v[108:111], s[0:1] offset:2048
	global_store_dwordx4 v23, v[112:115], s[0:1] offset:3072
	v_lshlrev_b32_e32 v168, 16, v116
	v_and_b32_e32 v169, 0xffff0000, v116
	v_lshlrev_b32_e32 v170, 16, v148
	v_and_b32_e32 v171, 0xffff0000, v148
	v_mul_f32_e32 v170, s98, v170
	v_mul_f32_e32 v171, s98, v171
	v_fma_f32 v168, v170, v2, v168
	v_fma_f32 v169, v171, v3, v169
	v_fma_f32 v186, v168, v168, v186
	v_fma_f32 v186, v169, v169, v186
	v_cvt_pk_bf16_f32 v116, v168, v169
	v_lshlrev_b32_e32 v168, 16, v117
	v_and_b32_e32 v169, 0xffff0000, v117
	v_lshlrev_b32_e32 v170, 16, v149
	v_and_b32_e32 v171, 0xffff0000, v149
	v_mul_f32_e32 v170, s98, v170
	v_mul_f32_e32 v171, s98, v171
	v_fma_f32 v168, v170, v4, v168
	v_fma_f32 v169, v171, v5, v169
	v_fma_f32 v186, v168, v168, v186
	v_fma_f32 v186, v169, v169, v186
	v_cvt_pk_bf16_f32 v117, v168, v169
	v_lshlrev_b32_e32 v168, 16, v118
	v_and_b32_e32 v169, 0xffff0000, v118
	v_lshlrev_b32_e32 v170, 16, v150
	v_and_b32_e32 v171, 0xffff0000, v150
	v_mul_f32_e32 v170, s98, v170
	v_mul_f32_e32 v171, s98, v171
	v_fma_f32 v168, v170, v6, v168
	v_fma_f32 v169, v171, v7, v169
	v_fma_f32 v186, v168, v168, v186
	v_fma_f32 v186, v169, v169, v186
	v_cvt_pk_bf16_f32 v118, v168, v169
	v_lshlrev_b32_e32 v168, 16, v119
	v_and_b32_e32 v169, 0xffff0000, v119
	v_lshlrev_b32_e32 v170, 16, v151
	v_and_b32_e32 v171, 0xffff0000, v151
	v_mul_f32_e32 v170, s98, v170
	v_mul_f32_e32 v171, s98, v171
	v_fma_f32 v168, v170, v8, v168
	v_fma_f32 v169, v171, v9, v169
	v_fma_f32 v186, v168, v168, v186
	v_fma_f32 v186, v169, v169, v186
	v_cvt_pk_bf16_f32 v119, v168, v169
	v_lshlrev_b32_e32 v168, 16, v120
	v_and_b32_e32 v169, 0xffff0000, v120
	v_lshlrev_b32_e32 v170, 16, v152
	v_and_b32_e32 v171, 0xffff0000, v152
; __device__ __forceinline__ float bf_lo(unsigned w) { return __uint_as_float(w << 16); }
; __device__ __forceinline__ float bf_hi(unsigned w) { return __uint_as_float(w & 0xffff0000u); }
; __device__ __forceinline__ unsigned pk2(float lo, float hi) { bf16x2_t r = __builtin_convertvector((f32x2_t){lo, hi}, bf16x2_t); return __builtin_bit_cast(unsigned, r); }
; template <bool SRC_F32, bool FINAL, int R> __device__ __forceinline__ void ew_compute(const EwSet<SRC_F32, R>& S, int rb, const f32x4 (&g)[4], bf16* hb_out, float* out32, float scale, float* rs_out, int lane) {
;     ...
; #pragma unroll
;         for (int j = 0; j < 4; ++j) {
;             f32x4 h;
;             if constexpr (SRC_F32) h = S.h32[i][j];
;             else { const v2u hw = S.hb[i][j]; h.x = bf_lo(hw.x); h.y = bf_hi(hw.x); h.z = bf_lo(hw.y); h.w = bf_hi(hw.y); }
;             const v2u fw = S.fw[i][j];
;             f32x4 v; v.x = h.x + bf_lo(fw.x) * rs * g[j].x; v.y = h.y + bf_hi(fw.x) * rs * g[j].y; v.z = h.z + bf_lo(fw.y) * rs * g[j].z; v.w = h.w + bf_hi(fw.y) * rs * g[j].w;
;             if (FINAL) __builtin_nontemporal_store(v, (f32x4*)(out32 + (size_t)(rb + i) * D) + lane + 64 * j);
;             else { v2u o; o.x = pk2(v.x, v.y); o.y = pk2(v.z, v.w); ((v2u*)(hb_out + (size_t)(rb + i) * D) + lane)[64 * j] = o; s2 += (v.x * v.x + v.y * v.y) + (v.z * v.z + v.w * v.w); }
;         }
;         if (!FINAL) { const float tot = wave_sum(s2); if (lane == 0) rs_out[rb + i] = 1.0f / sqrtf(tot * (1.f / D) + EPS); }
	v_mul_f32_e32 v170, s98, v170
	v_mul_f32_e32 v171, s98, v171
	v_fma_f32 v168, v170, v10, v168
	v_fma_f32 v169, v171, v11, v169
	v_fma_f32 v186, v168, v168, v186
	v_fma_f32 v186, v169, v169, v186
	v_cvt_pk_bf16_f32 v120, v168, v169
	v_lshlrev_b32_e32 v168, 16, v121
	v_and_b32_e32 v169, 0xffff0000, v121
	v_lshlrev_b32_e32 v170, 16, v153
	v_and_b32_e32 v171, 0xffff0000, v153
	v_mul_f32_e32 v170, s98, v170
	v_mul_f32_e32 v171, s98, v171
	v_fma_f32 v168, v170, v12, v168
	v_fma_f32 v169, v171, v13, v169
	v_fma_f32 v186, v168, v168, v186
	v_fma_f32 v186, v169, v169, v186
	v_cvt_pk_bf16_f32 v121, v168, v169
	v_lshlrev_b32_e32 v168, 16, v122
	v_and_b32_e32 v169, 0xffff0000, v122
	v_lshlrev_b32_e32 v170, 16, v154
	v_and_b32_e32 v171, 0xffff0000, v154
	v_mul_f32_e32 v170, s98, v170
	v_mul_f32_e32 v171, s98, v171
	v_fma_f32 v168, v170, v14, v168
	v_fma_f32 v169, v171, v15, v169
	v_fma_f32 v186, v168, v168, v186
	v_fma_f32 v186, v169, v169, v186
	v_cvt_pk_bf16_f32 v122, v168, v169
	v_lshlrev_b32_e32 v168, 16, v123
	v_and_b32_e32 v169, 0xffff0000, v123
	v_lshlrev_b32_e32 v170, 16, v155
	v_and_b32_e32 v171, 0xffff0000, v155
	v_mul_f32_e32 v170, s98, v170
	v_mul_f32_e32 v171, s98, v171
	v_fma_f32 v168, v170, v16, v168
	v_fma_f32 v169, v171, v17, v169
	v_fma_f32 v186, v168, v168, v186
	v_fma_f32 v186, v169, v169, v186
	v_cvt_pk_bf16_f32 v123, v168, v169
	global_store_dwordx4 v24, v[116:119], s[0:1]
	global_store_dwordx4 v24, v[120:123], s[0:1] offset:1024
	v_lshlrev_b32_e32 v168, 16, v124
	v_and_b32_e32 v169, 0xffff0000, v124
	v_lshlrev_b32_e32 v170, 16, v156
	v_and_b32_e32 v171, 0xffff0000, v156
	v_mul_f32_e32 v170, s101, v170
	v_mul_f32_e32 v171, s101, v171
	v_fma_f32 v168, v170, v2, v168
	v_fma_f32 v169, v171, v3, v169
	v_fma_f32 v187, v168, v168, v187
	v_fma_f32 v187, v169, v169, v187
	v_cvt_pk_bf16_f32 v124, v168, v169
	v_lshlrev_b32_e32 v168, 16, v125
	v_and_b32_e32 v169, 0xffff0000, v125
	v_lshlrev_b32_e32 v170, 16, v157
	v_and_b32_e32 v171, 0xffff0000, v157
	v_mul_f32_e32 v170, s101, v170
	v_mul_f32_e32 v171, s101, v171
	v_fma_f32 v168, v170, v4, v168
	v_fma_f32 v169, v171, v5, v169
	v_fma_f32 v187, v168, v168, v187
	v_fma_f32 v187, v169, v169, v187
	v_cvt_pk_bf16_f32 v125, v168, v169
	v_lshlrev_b32_e32 v168, 16, v126
	v_and_b32_e32 v169, 0xffff0000, v126
	v_lshlrev_b32_e32 v170, 16, v158
	v_and_b32_e32 v171, 0xffff0000, v158
	v_mul_f32_e32 v170, s101, v170
	v_mul_f32_e32 v171, s101, v171
	v_fma_f32 v168, v170, v6, v168
	v_fma_f32 v169, v171, v7, v169
	v_fma_f32 v187, v168, v168, v187
	v_fma_f32 v187, v169, v169, v187
	v_cvt_pk_bf16_f32 v126, v168, v169
	v_lshlrev_b32_e32 v168, 16, v127
	v_and_b32_e32 v169, 0xffff0000, v127
	v_lshlrev_b32_e32 v170, 16, v159
	v_and_b32_e32 v171, 0xffff0000, v159
	v_mul_f32_e32 v170, s101, v170
	v_mul_f32_e32 v171, s101, v171
	v_fma_f32 v168, v170, v8, v168
	v_fma_f32 v169, v171, v9, v169
	v_fma_f32 v187, v168, v168, v187
	v_fma_f32 v187, v169, v169, v187
	v_cvt_pk_bf16_f32 v127, v168, v169
	v_lshlrev_b32_e32 v168, 16, v128
	v_and_b32_e32 v169, 0xffff0000, v128
	v_lshlrev_b32_e32 v170, 16, v160
	v_and_b32_e32 v171, 0xffff0000, v160
	v_mul_f32_e32 v170, s101, v170
	v_mul_f32_e32 v171, s101, v171
	v_fma_f32 v168, v170, v10, v168
	v_fma_f32 v169, v171, v11, v169
	v_fma_f32 v187, v168, v168, v187
	v_fma_f32 v187, v169, v169, v187
	v_cvt_pk_bf16_f32 v128, v168, v169
	v_lshlrev_b32_e32 v168, 16, v129
	v_and_b32_e32 v169, 0xffff0000, v129
	v_lshlrev_b32_e32 v170, 16, v161
	v_and_b32_e32 v171, 0xffff0000, v161
	v_mul_f32_e32 v170, s101, v170
	v_mul_f32_e32 v171, s101, v171
	v_fma_f32 v168, v170, v12, v168
	v_fma_f32 v169, v171, v13, v169
	v_fma_f32 v187, v168, v168, v187
	v_fma_f32 v187, v169, v169, v187
	v_cvt_pk_bf16_f32 v129, v168, v169
	v_lshlrev_b32_e32 v168, 16, v130
	v_and_b32_e32 v169, 0xffff0000, v130
	v_lshlrev_b32_e32 v170, 16, v162
	v_and_b32_e32 v171, 0xffff0000, v162
	v_mul_f32_e32 v170, s101, v170
	v_mul_f32_e32 v171, s101, v171
	v_fma_f32 v168, v170, v14, v168
	v_fma_f32 v169, v171, v15, v169
	v_fma_f32 v187, v168, v168, v187
	v_fma_f32 v187, v169, v169, v187
	v_cvt_pk_bf16_f32 v130, v168, v169
	v_lshlrev_b32_e32 v168, 16, v131
	v_and_b32_e32 v169, 0xffff0000, v131
	v_lshlrev_b32_e32 v170, 16, v163
	v_and_b32_e32 v171, 0xffff0000, v163
	v_mul_f32_e32 v170, s101, v170
	v_mul_f32_e32 v171, s101, v171
	v_fma_f32 v168, v170, v16, v168
	v_fma_f32 v169, v171, v17, v169
	v_fma_f32 v187, v168, v168, v187
	v_fma_f32 v187, v169, v169, v187
	v_cvt_pk_bf16_f32 v131, v168, v169
	global_store_dwordx4 v24, v[124:127], s[0:1] offset:2048
	global_store_dwordx4 v24, v[128:131], s[0:1] offset:3072
	s_nop 1
	v_add_f32_dpp v184, v184, v184 quad_perm:[1,0,3,2] row_mask:0xf bank_mask:0xf
	v_add_f32_dpp v185, v185, v185 quad_perm:[1,0,3,2] row_mask:0xf bank_mask:0xf
	v_add_f32_dpp v186, v186, v186 quad_perm:[1,0,3,2] row_mask:0xf bank_mask:0xf
	v_add_f32_dpp v187, v187, v187 quad_perm:[1,0,3,2] row_mask:0xf bank_mask:0xf
	v_add_f32_dpp v184, v184, v184 quad_perm:[2,3,0,1] row_mask:0xf bank_mask:0xf
	v_add_f32_dpp v185, v185, v185 quad_perm:[2,3,0,1] row_mask:0xf bank_mask:0xf
	v_add_f32_dpp v186, v186, v186 quad_perm:[2,3,0,1] row_mask:0xf bank_mask:0xf
	v_add_f32_dpp v187, v187, v187 quad_perm:[2,3,0,1] row_mask:0xf bank_mask:0xf
	v_add_f32_dpp v184, v184, v184 row_half_mirror row_mask:0xf bank_mask:0xf
	v_add_f32_dpp v185, v185, v185 row_half_mirror row_mask:0xf bank_mask:0xf
	v_add_f32_dpp v186, v186, v186 row_half_mirror row_mask:0xf bank_mask:0xf
	v_add_f32_dpp v187, v187, v187 row_half_mirror row_mask:0xf bank_mask:0xf
	v_add_f32_dpp v184, v184, v184 row_mirror row_mask:0xf bank_mask:0xf
; __device__ __forceinline__ float bf_lo(unsigned w) { return __uint_as_float(w << 16); }
; __device__ __forceinline__ float bf_hi(unsigned w) { return __uint_as_float(w & 0xffff0000u); }
; template <bool SRC_F32, int R> __device__ __forceinline__ void ew_load(EwSet<SRC_F32, R>& S, int rb, const float* hsrc32, const bf16* hsrcb, const bf16* f, const float* part, int lane) {
; #pragma unroll
;     for (int i = 0; i < R; ++i) S.p[i] = (lane < 16) ? part[(size_t)(rb + i) * 16 + lane] : 0.f;
; #pragma unroll
;     for (int i = 0; i < R; ++i)
; #pragma unroll
;         for (int j = 0; j < 4; ++j) {
;             S.fw[i][j] = ((const v2u*)(f + (size_t)(rb + i) * D) + lane)[64 * j];
;             if constexpr (SRC_F32) S.h32[i][j] = __builtin_nontemporal_load((const f32x4*)(hsrc32 + (size_t)(rb + i) * D) + lane + 64 * j);
;             else S.hb[i][j] = ((const v2u*)(hsrcb + (size_t)(rb + i) * D) + lane)[64 * j];
;         }
; }
; template <bool SRC_F32, bool FINAL, int R> __device__ __forceinline__ void ew_compute(const EwSet<SRC_F32, R>& S, int rb, const f32x4 (&g)[4], bf16* hb_out, float* out32, float scale, float* rs_out, int lane) {
; #pragma unroll
;     for (int i = 0; i < R; ++i) {
;         float q = S.p[i];
;         q += __shfl_xor(q, 1); q += __shfl_xor(q, 2); q += __shfl_xor(q, 4); q += __shfl_xor(q, 8);
;         const float ss = __shfl(q, 0);
;         const float rs = scale / sqrtf(ss * (1.f / D) + EPS);
;         float s2 = 0.f;
; #pragma unroll
;         for (int j = 0; j < 4; ++j) {
;             f32x4 h;
;             if constexpr (SRC_F32) h = S.h32[i][j];
;             else { const v2u hw = S.hb[i][j]; h.x = bf_lo(hw.x); h.y = bf_hi(hw.x); h.z = bf_lo(hw.y); h.w = bf_hi(hw.y); }
;             const v2u fw = S.fw[i][j];
;             f32x4 v; v.x = h.x + bf_lo(fw.x) * rs * g[j].x; v.y = h.y + bf_hi(fw.x) * rs * g[j].y; v.z = h.z + bf_lo(fw.y) * rs * g[j].z; v.w = h.w + bf_hi(fw.y) * rs * g[j].w;
;             if (FINAL) __builtin_nontemporal_store(v, (f32x4*)(out32 + (size_t)(rb + i) * D) + lane + 64 * j);
;             else { v2u o; o.x = pk2(v.x, v.y); o.y = pk2(v.z, v.w); ((v2u*)(hb_out + (size_t)(rb + i) * D) + lane)[64 * j] = o; s2 += (v.x * v.x + v.y * v.y) + (v.z * v.z + v.w * v.w); }
;         }
;         if (!FINAL) { const float tot = wave_sum(s2); if (lane == 0) rs_out[rb + i] = 1.0f / sqrtf(tot * (1.f / D) + EPS); }
	v_add_f32_dpp v185, v185, v185 row_mirror row_mask:0xf bank_mask:0xf
	v_add_f32_dpp v186, v186, v186 row_mirror row_mask:0xf bank_mask:0xf
	v_add_f32_dpp v187, v187, v187 row_mirror row_mask:0xf bank_mask:0xf
	v_add_f32_dpp v184, v184, v184 row_bcast:15 row_mask:0xa bank_mask:0xf
	v_add_f32_dpp v185, v185, v185 row_bcast:15 row_mask:0xa bank_mask:0xf
	v_add_f32_dpp v186, v186, v186 row_bcast:15 row_mask:0xa bank_mask:0xf
	v_add_f32_dpp v187, v187, v187 row_bcast:15 row_mask:0xa bank_mask:0xf
	v_add_f32_dpp v184, v184, v184 row_bcast:31 row_mask:0xc bank_mask:0xf
	v_add_f32_dpp v185, v185, v185 row_bcast:31 row_mask:0xc bank_mask:0xf
	v_add_f32_dpp v186, v186, v186 row_bcast:31 row_mask:0xc bank_mask:0xf
	v_add_f32_dpp v187, v187, v187 row_bcast:31 row_mask:0xc bank_mask:0xf
	s_nop 1
	v_readlane_b32 s3, v184, 63
	v_readlane_b32 s24, v185, 63
	v_readlane_b32 s98, v186, 63
	v_readlane_b32 s101, v187, 63
	s_nop 3
	v_writelane_b32 v188, s3, 0
	v_writelane_b32 v188, s24, 1
	v_writelane_b32 v188, s98, 2
	v_writelane_b32 v188, s101, 3
	s_nop 1
	v_mul_f32_e32 v188, 0x3a800000, v188
	v_add_f32_e32 v188, 0x358637bd, v188
	v_rsq_f32_e32 v188, v188
	s_mov_b64 exec, 15
	global_store_dword v26, v188, s[14:15]
	s_mov_b64 exec, -1
	s_add_u32 s27, s26, 2052
	s_lshl_b32 s22, s27, 11
	v_lshl_add_u32 v23, v0, 4, s22
	v_add_u32_e32 v24, 0x1000, v23
	s_lshl_b32 s22, s27, 6
	v_lshl_add_u32 v25, v0, 2, s22
	s_lshl_b32 s22, s27, 2
	v_lshl_add_u32 v26, v0, 2, s22
	global_load_dwordx4 v[100:103], v23, s[0:1]
	global_load_dwordx4 v[104:107], v23, s[0:1] offset:1024
	global_load_dwordx4 v[132:135], v23, s[4:5]
	global_load_dwordx4 v[136:139], v23, s[4:5] offset:1024
	global_load_dwordx4 v[108:111], v23, s[0:1] offset:2048
	global_load_dwordx4 v[112:115], v23, s[0:1] offset:3072
	global_load_dwordx4 v[140:143], v23, s[4:5] offset:2048
	global_load_dwordx4 v[144:147], v23, s[4:5] offset:3072
	global_load_dwordx4 v[116:119], v24, s[0:1]
	global_load_dwordx4 v[120:123], v24, s[0:1] offset:1024
	global_load_dwordx4 v[148:151], v24, s[4:5]
	global_load_dwordx4 v[152:155], v24, s[4:5] offset:1024
	global_load_dwordx4 v[124:127], v24, s[0:1] offset:2048
	global_load_dwordx4 v[128:131], v24, s[0:1] offset:3072
	global_load_dwordx4 v[156:159], v24, s[4:5] offset:2048
	global_load_dwordx4 v[160:163], v24, s[4:5] offset:3072
	global_load_dword v164, v25, s[6:7]
	s_waitcnt vmcnt(26)
	v_add_f32_dpp v96, v96, v96 quad_perm:[1,0,3,2] row_mask:0xf bank_mask:0xf
	s_nop 1
	v_add_f32_dpp v96, v96, v96 quad_perm:[2,3,0,1] row_mask:0xf bank_mask:0xf
	s_nop 1
	v_add_f32_dpp v96, v96, v96 row_half_mirror row_mask:0xf bank_mask:0xf
	s_nop 1
	v_add_f32_dpp v96, v96, v96 row_mirror row_mask:0xf bank_mask:0xf
	s_nop 1
	v_mul_f32_e32 v96, 0x3a800000, v96
	v_add_f32_e32 v96, 0x358637bd, v96
	v_rsq_f32_e32 v96, v96
	s_nop 0
	v_mul_f32_e32 v96, 0x3f000000, v96
	s_nop 0
	v_readlane_b32 s3, v96, 0
	v_readlane_b32 s24, v96, 16
	v_readlane_b32 s98, v96, 32
	v_readlane_b32 s101, v96, 48
	s_nop 1
	v_mov_b32_e32 v184, 0
	v_mov_b32_e32 v185, 0
	v_mov_b32_e32 v186, 0
	v_mov_b32_e32 v187, 0
	v_lshlrev_b32_e32 v168, 16, v32
	v_and_b32_e32 v169, 0xffff0000, v32
	v_lshlrev_b32_e32 v170, 16, v64
	v_and_b32_e32 v171, 0xffff0000, v64
	v_mul_f32_e32 v170, s3, v170
	v_mul_f32_e32 v171, s3, v171
	v_fma_f32 v168, v170, v2, v168
	v_fma_f32 v169, v171, v3, v169
	v_fma_f32 v184, v168, v168, v184
	v_fma_f32 v184, v169, v169, v184
	v_cvt_pk_bf16_f32 v32, v168, v169
	v_lshlrev_b32_e32 v168, 16, v33
	v_and_b32_e32 v169, 0xffff0000, v33
	v_lshlrev_b32_e32 v170, 16, v65
	v_and_b32_e32 v171, 0xffff0000, v65
	v_mul_f32_e32 v170, s3, v170
	v_mul_f32_e32 v171, s3, v171
	v_fma_f32 v168, v170, v4, v168
	v_fma_f32 v169, v171, v5, v169
	v_fma_f32 v184, v168, v168, v184
	v_fma_f32 v184, v169, v169, v184
	v_cvt_pk_bf16_f32 v33, v168, v169
	v_lshlrev_b32_e32 v168, 16, v34
	v_and_b32_e32 v169, 0xffff0000, v34
	v_lshlrev_b32_e32 v170, 16, v66
	v_and_b32_e32 v171, 0xffff0000, v66
	v_mul_f32_e32 v170, s3, v170
	v_mul_f32_e32 v171, s3, v171
	v_fma_f32 v168, v170, v6, v168
	v_fma_f32 v169, v171, v7, v169
	v_fma_f32 v184, v168, v168, v184
	v_fma_f32 v184, v169, v169, v184
	v_cvt_pk_bf16_f32 v34, v168, v169
	v_lshlrev_b32_e32 v168, 16, v35
	v_and_b32_e32 v169, 0xffff0000, v35
	v_lshlrev_b32_e32 v170, 16, v67
	v_and_b32_e32 v171, 0xffff0000, v67
	v_mul_f32_e32 v170, s3, v170
	v_mul_f32_e32 v171, s3, v171
	v_fma_f32 v168, v170, v8, v168
	v_fma_f32 v169, v171, v9, v169
	v_fma_f32 v184, v168, v168, v184
	v_fma_f32 v184, v169, v169, v184
	v_cvt_pk_bf16_f32 v35, v168, v169
	v_lshlrev_b32_e32 v168, 16, v36
	v_and_b32_e32 v169, 0xffff0000, v36
	v_lshlrev_b32_e32 v170, 16, v68
	v_and_b32_e32 v171, 0xffff0000, v68
	v_mul_f32_e32 v170, s3, v170
	v_mul_f32_e32 v171, s3, v171
	v_fma_f32 v168, v170, v10, v168
	v_fma_f32 v169, v171, v11, v169
	v_fma_f32 v184, v168, v168, v184
	v_fma_f32 v184, v169, v169, v184
	v_cvt_pk_bf16_f32 v36, v168, v169
	v_lshlrev_b32_e32 v168, 16, v37
	v_and_b32_e32 v169, 0xffff0000, v37
	v_lshlrev_b32_e32 v170, 16, v69
	v_and_b32_e32 v171, 0xffff0000, v69
	v_mul_f32_e32 v170, s3, v170
	v_mul_f32_e32 v171, s3, v171
	v_fma_f32 v168, v170, v12, v168
	v_fma_f32 v169, v171, v13, v169
	v_fma_f32 v184, v168, v168, v184
	v_fma_f32 v184, v169, v169, v184
	v_cvt_pk_bf16_f32 v37, v168, v169
	v_lshlrev_b32_e32 v168, 16, v38
	v_and_b32_e32 v169, 0xffff0000, v38
	v_lshlrev_b32_e32 v170, 16, v70
	v_and_b32_e32 v171, 0xffff0000, v70
	v_mul_f32_e32 v170, s3, v170
	v_mul_f32_e32 v171, s3, v171
	v_fma_f32 v168, v170, v14, v168
	v_fma_f32 v169, v171, v15, v169
	v_fma_f32 v184, v168, v168, v184
	v_fma_f32 v184, v169, v169, v184
	v_cvt_pk_bf16_f32 v38, v168, v169
; __device__ __forceinline__ float bf_lo(unsigned w) { return __uint_as_float(w << 16); }
; __device__ __forceinline__ float bf_hi(unsigned w) { return __uint_as_float(w & 0xffff0000u); }
; __device__ __forceinline__ unsigned pk2(float lo, float hi) { bf16x2_t r = __builtin_convertvector((f32x2_t){lo, hi}, bf16x2_t); return __builtin_bit_cast(unsigned, r); }
; template <bool SRC_F32, bool FINAL, int R> __device__ __forceinline__ void ew_compute(const EwSet<SRC_F32, R>& S, int rb, const f32x4 (&g)[4], bf16* hb_out, float* out32, float scale, float* rs_out, int lane) {
;     ...
; #pragma unroll
;         for (int j = 0; j < 4; ++j) {
;             f32x4 h;
;             if constexpr (SRC_F32) h = S.h32[i][j];
;             else { const v2u hw = S.hb[i][j]; h.x = bf_lo(hw.x); h.y = bf_hi(hw.x); h.z = bf_lo(hw.y); h.w = bf_hi(hw.y); }
;             const v2u fw = S.fw[i][j];
;             f32x4 v; v.x = h.x + bf_lo(fw.x) * rs * g[j].x; v.y = h.y + bf_hi(fw.x) * rs * g[j].y; v.z = h.z + bf_lo(fw.y) * rs * g[j].z; v.w = h.w + bf_hi(fw.y) * rs * g[j].w;
;             if (FINAL) __builtin_nontemporal_store(v, (f32x4*)(out32 + (size_t)(rb + i) * D) + lane + 64 * j);
;             else { v2u o; o.x = pk2(v.x, v.y); o.y = pk2(v.z, v.w); ((v2u*)(hb_out + (size_t)(rb + i) * D) + lane)[64 * j] = o; s2 += (v.x * v.x + v.y * v.y) + (v.z * v.z + v.w * v.w); }
	v_lshlrev_b32_e32 v168, 16, v39
	v_and_b32_e32 v169, 0xffff0000, v39
	v_lshlrev_b32_e32 v170, 16, v71
	v_and_b32_e32 v171, 0xffff0000, v71
	v_mul_f32_e32 v170, s3, v170
	v_mul_f32_e32 v171, s3, v171
	v_fma_f32 v168, v170, v16, v168
	v_fma_f32 v169, v171, v17, v169
	v_fma_f32 v184, v168, v168, v184
	v_fma_f32 v184, v169, v169, v184
	v_cvt_pk_bf16_f32 v39, v168, v169
	global_store_dwordx4 v18, v[32:35], s[0:1]
	global_store_dwordx4 v18, v[36:39], s[0:1] offset:1024
	v_lshlrev_b32_e32 v168, 16, v40
	v_and_b32_e32 v169, 0xffff0000, v40
	v_lshlrev_b32_e32 v170, 16, v72
	v_and_b32_e32 v171, 0xffff0000, v72
	v_mul_f32_e32 v170, s24, v170
	v_mul_f32_e32 v171, s24, v171
	v_fma_f32 v168, v170, v2, v168
	v_fma_f32 v169, v171, v3, v169
	v_fma_f32 v185, v168, v168, v185
	v_fma_f32 v185, v169, v169, v185
	v_cvt_pk_bf16_f32 v40, v168, v169
	v_lshlrev_b32_e32 v168, 16, v41
	v_and_b32_e32 v169, 0xffff0000, v41
	v_lshlrev_b32_e32 v170, 16, v73
	v_and_b32_e32 v171, 0xffff0000, v73
	v_mul_f32_e32 v170, s24, v170
	v_mul_f32_e32 v171, s24, v171
	v_fma_f32 v168, v170, v4, v168
	v_fma_f32 v169, v171, v5, v169
	v_fma_f32 v185, v168, v168, v185
	v_fma_f32 v185, v169, v169, v185
	v_cvt_pk_bf16_f32 v41, v168, v169
	v_lshlrev_b32_e32 v168, 16, v42
	v_and_b32_e32 v169, 0xffff0000, v42
	v_lshlrev_b32_e32 v170, 16, v74
	v_and_b32_e32 v171, 0xffff0000, v74
	v_mul_f32_e32 v170, s24, v170
	v_mul_f32_e32 v171, s24, v171
	v_fma_f32 v168, v170, v6, v168
	v_fma_f32 v169, v171, v7, v169
	v_fma_f32 v185, v168, v168, v185
	v_fma_f32 v185, v169, v169, v185
	v_cvt_pk_bf16_f32 v42, v168, v169
	v_lshlrev_b32_e32 v168, 16, v43
	v_and_b32_e32 v169, 0xffff0000, v43
	v_lshlrev_b32_e32 v170, 16, v75
	v_and_b32_e32 v171, 0xffff0000, v75
	v_mul_f32_e32 v170, s24, v170
	v_mul_f32_e32 v171, s24, v171
	v_fma_f32 v168, v170, v8, v168
	v_fma_f32 v169, v171, v9, v169
	v_fma_f32 v185, v168, v168, v185
	v_fma_f32 v185, v169, v169, v185
	v_cvt_pk_bf16_f32 v43, v168, v169
	v_lshlrev_b32_e32 v168, 16, v44
	v_and_b32_e32 v169, 0xffff0000, v44
	v_lshlrev_b32_e32 v170, 16, v76
	v_and_b32_e32 v171, 0xffff0000, v76
	v_mul_f32_e32 v170, s24, v170
	v_mul_f32_e32 v171, s24, v171
	v_fma_f32 v168, v170, v10, v168
	v_fma_f32 v169, v171, v11, v169
	v_fma_f32 v185, v168, v168, v185
	v_fma_f32 v185, v169, v169, v185
	v_cvt_pk_bf16_f32 v44, v168, v169
	v_lshlrev_b32_e32 v168, 16, v45
	v_and_b32_e32 v169, 0xffff0000, v45
	v_lshlrev_b32_e32 v170, 16, v77
	v_and_b32_e32 v171, 0xffff0000, v77
	v_mul_f32_e32 v170, s24, v170
	v_mul_f32_e32 v171, s24, v171
	v_fma_f32 v168, v170, v12, v168
	v_fma_f32 v169, v171, v13, v169
	v_fma_f32 v185, v168, v168, v185
	v_fma_f32 v185, v169, v169, v185
	v_cvt_pk_bf16_f32 v45, v168, v169
	v_lshlrev_b32_e32 v168, 16, v46
	v_and_b32_e32 v169, 0xffff0000, v46
	v_lshlrev_b32_e32 v170, 16, v78
	v_and_b32_e32 v171, 0xffff0000, v78
	v_mul_f32_e32 v170, s24, v170
	v_mul_f32_e32 v171, s24, v171
	v_fma_f32 v168, v170, v14, v168
	v_fma_f32 v169, v171, v15, v169
	v_fma_f32 v185, v168, v168, v185
	v_fma_f32 v185, v169, v169, v185
	v_cvt_pk_bf16_f32 v46, v168, v169
	v_lshlrev_b32_e32 v168, 16, v47
	v_and_b32_e32 v169, 0xffff0000, v47
	v_lshlrev_b32_e32 v170, 16, v79
	v_and_b32_e32 v171, 0xffff0000, v79
	v_mul_f32_e32 v170, s24, v170
	v_mul_f32_e32 v171, s24, v171
	v_fma_f32 v168, v170, v16, v168
	v_fma_f32 v169, v171, v17, v169
	v_fma_f32 v185, v168, v168, v185
	v_fma_f32 v185, v169, v169, v185
	v_cvt_pk_bf16_f32 v47, v168, v169
	global_store_dwordx4 v18, v[40:43], s[0:1] offset:2048
	global_store_dwordx4 v18, v[44:47], s[0:1] offset:3072
	v_lshlrev_b32_e32 v168, 16, v48
	v_and_b32_e32 v169, 0xffff0000, v48
	v_lshlrev_b32_e32 v170, 16, v80
	v_and_b32_e32 v171, 0xffff0000, v80
	v_mul_f32_e32 v170, s98, v170
	v_mul_f32_e32 v171, s98, v171
	v_fma_f32 v168, v170, v2, v168
	v_fma_f32 v169, v171, v3, v169
	v_fma_f32 v186, v168, v168, v186
	v_fma_f32 v186, v169, v169, v186
	v_cvt_pk_bf16_f32 v48, v168, v169
	v_lshlrev_b32_e32 v168, 16, v49
	v_and_b32_e32 v169, 0xffff0000, v49
	v_lshlrev_b32_e32 v170, 16, v81
	v_and_b32_e32 v171, 0xffff0000, v81
	v_mul_f32_e32 v170, s98, v170
	v_mul_f32_e32 v171, s98, v171
	v_fma_f32 v168, v170, v4, v168
	v_fma_f32 v169, v171, v5, v169
	v_fma_f32 v186, v168, v168, v186
	v_fma_f32 v186, v169, v169, v186
	v_cvt_pk_bf16_f32 v49, v168, v169
	v_lshlrev_b32_e32 v168, 16, v50
	v_and_b32_e32 v169, 0xffff0000, v50
	v_lshlrev_b32_e32 v170, 16, v82
	v_and_b32_e32 v171, 0xffff0000, v82
	v_mul_f32_e32 v170, s98, v170
	v_mul_f32_e32 v171, s98, v171
	v_fma_f32 v168, v170, v6, v168
	v_fma_f32 v169, v171, v7, v169
	v_fma_f32 v186, v168, v168, v186
	v_fma_f32 v186, v169, v169, v186
	v_cvt_pk_bf16_f32 v50, v168, v169
	v_lshlrev_b32_e32 v168, 16, v51
	v_and_b32_e32 v169, 0xffff0000, v51
	v_lshlrev_b32_e32 v170, 16, v83
	v_and_b32_e32 v171, 0xffff0000, v83
	v_mul_f32_e32 v170, s98, v170
	v_mul_f32_e32 v171, s98, v171
	v_fma_f32 v168, v170, v8, v168
	v_fma_f32 v169, v171, v9, v169
	v_fma_f32 v186, v168, v168, v186
	v_fma_f32 v186, v169, v169, v186
	v_cvt_pk_bf16_f32 v51, v168, v169
	v_lshlrev_b32_e32 v168, 16, v52
	v_and_b32_e32 v169, 0xffff0000, v52
	v_lshlrev_b32_e32 v170, 16, v84
	v_and_b32_e32 v171, 0xffff0000, v84
	v_mul_f32_e32 v170, s98, v170
	v_mul_f32_e32 v171, s98, v171
	v_fma_f32 v168, v170, v10, v168
	v_fma_f32 v169, v171, v11, v169
	v_fma_f32 v186, v168, v168, v186
	v_fma_f32 v186, v169, v169, v186
	v_cvt_pk_bf16_f32 v52, v168, v169
	v_lshlrev_b32_e32 v168, 16, v53
	v_and_b32_e32 v169, 0xffff0000, v53
	v_lshlrev_b32_e32 v170, 16, v85
	v_and_b32_e32 v171, 0xffff0000, v85
	v_mul_f32_e32 v170, s98, v170
	v_mul_f32_e32 v171, s98, v171
	v_fma_f32 v168, v170, v12, v168
	v_fma_f32 v169, v171, v13, v169
; __device__ __forceinline__ float bf_lo(unsigned w) { return __uint_as_float(w << 16); }
; __device__ __forceinline__ float bf_hi(unsigned w) { return __uint_as_float(w & 0xffff0000u); }
; __device__ __forceinline__ unsigned pk2(float lo, float hi) { bf16x2_t r = __builtin_convertvector((f32x2_t){lo, hi}, bf16x2_t); return __builtin_bit_cast(unsigned, r); }
; template <bool SRC_F32, bool FINAL, int R> __device__ __forceinline__ void ew_compute(const EwSet<SRC_F32, R>& S, int rb, const f32x4 (&g)[4], bf16* hb_out, float* out32, float scale, float* rs_out, int lane) {
;     ...
; #pragma unroll
;         for (int j = 0; j < 4; ++j) {
;             f32x4 h;
;             if constexpr (SRC_F32) h = S.h32[i][j];
;             else { const v2u hw = S.hb[i][j]; h.x = bf_lo(hw.x); h.y = bf_hi(hw.x); h.z = bf_lo(hw.y); h.w = bf_hi(hw.y); }
;             const v2u fw = S.fw[i][j];
;             f32x4 v; v.x = h.x + bf_lo(fw.x) * rs * g[j].x; v.y = h.y + bf_hi(fw.x) * rs * g[j].y; v.z = h.z + bf_lo(fw.y) * rs * g[j].z; v.w = h.w + bf_hi(fw.y) * rs * g[j].w;
;             if (FINAL) __builtin_nontemporal_store(v, (f32x4*)(out32 + (size_t)(rb + i) * D) + lane + 64 * j);
;             else { v2u o; o.x = pk2(v.x, v.y); o.y = pk2(v.z, v.w); ((v2u*)(hb_out + (size_t)(rb + i) * D) + lane)[64 * j] = o; s2 += (v.x * v.x + v.y * v.y) + (v.z * v.z + v.w * v.w); }
;         }
;         if (!FINAL) { const float tot = wave_sum(s2); if (lane == 0) rs_out[rb + i] = 1.0f / sqrtf(tot * (1.f / D) + EPS); }
	v_fma_f32 v186, v168, v168, v186
	v_fma_f32 v186, v169, v169, v186
	v_cvt_pk_bf16_f32 v53, v168, v169
	v_lshlrev_b32_e32 v168, 16, v54
	v_and_b32_e32 v169, 0xffff0000, v54
	v_lshlrev_b32_e32 v170, 16, v86
	v_and_b32_e32 v171, 0xffff0000, v86
	v_mul_f32_e32 v170, s98, v170
	v_mul_f32_e32 v171, s98, v171
	v_fma_f32 v168, v170, v14, v168
	v_fma_f32 v169, v171, v15, v169
	v_fma_f32 v186, v168, v168, v186
	v_fma_f32 v186, v169, v169, v186
	v_cvt_pk_bf16_f32 v54, v168, v169
	v_lshlrev_b32_e32 v168, 16, v55
	v_and_b32_e32 v169, 0xffff0000, v55
	v_lshlrev_b32_e32 v170, 16, v87
	v_and_b32_e32 v171, 0xffff0000, v87
	v_mul_f32_e32 v170, s98, v170
	v_mul_f32_e32 v171, s98, v171
	v_fma_f32 v168, v170, v16, v168
	v_fma_f32 v169, v171, v17, v169
	v_fma_f32 v186, v168, v168, v186
	v_fma_f32 v186, v169, v169, v186
	v_cvt_pk_bf16_f32 v55, v168, v169
	global_store_dwordx4 v19, v[48:51], s[0:1]
	global_store_dwordx4 v19, v[52:55], s[0:1] offset:1024
	v_lshlrev_b32_e32 v168, 16, v56
	v_and_b32_e32 v169, 0xffff0000, v56
	v_lshlrev_b32_e32 v170, 16, v88
	v_and_b32_e32 v171, 0xffff0000, v88
	v_mul_f32_e32 v170, s101, v170
	v_mul_f32_e32 v171, s101, v171
	v_fma_f32 v168, v170, v2, v168
	v_fma_f32 v169, v171, v3, v169
	v_fma_f32 v187, v168, v168, v187
	v_fma_f32 v187, v169, v169, v187
	v_cvt_pk_bf16_f32 v56, v168, v169
	v_lshlrev_b32_e32 v168, 16, v57
	v_and_b32_e32 v169, 0xffff0000, v57
	v_lshlrev_b32_e32 v170, 16, v89
	v_and_b32_e32 v171, 0xffff0000, v89
	v_mul_f32_e32 v170, s101, v170
	v_mul_f32_e32 v171, s101, v171
	v_fma_f32 v168, v170, v4, v168
	v_fma_f32 v169, v171, v5, v169
	v_fma_f32 v187, v168, v168, v187
	v_fma_f32 v187, v169, v169, v187
	v_cvt_pk_bf16_f32 v57, v168, v169
	v_lshlrev_b32_e32 v168, 16, v58
	v_and_b32_e32 v169, 0xffff0000, v58
	v_lshlrev_b32_e32 v170, 16, v90
	v_and_b32_e32 v171, 0xffff0000, v90
	v_mul_f32_e32 v170, s101, v170
	v_mul_f32_e32 v171, s101, v171
	v_fma_f32 v168, v170, v6, v168
	v_fma_f32 v169, v171, v7, v169
	v_fma_f32 v187, v168, v168, v187
	v_fma_f32 v187, v169, v169, v187
	v_cvt_pk_bf16_f32 v58, v168, v169
	v_lshlrev_b32_e32 v168, 16, v59
	v_and_b32_e32 v169, 0xffff0000, v59
	v_lshlrev_b32_e32 v170, 16, v91
	v_and_b32_e32 v171, 0xffff0000, v91
	v_mul_f32_e32 v170, s101, v170
	v_mul_f32_e32 v171, s101, v171
	v_fma_f32 v168, v170, v8, v168
	v_fma_f32 v169, v171, v9, v169
	v_fma_f32 v187, v168, v168, v187
	v_fma_f32 v187, v169, v169, v187
	v_cvt_pk_bf16_f32 v59, v168, v169
	v_lshlrev_b32_e32 v168, 16, v60
	v_and_b32_e32 v169, 0xffff0000, v60
	v_lshlrev_b32_e32 v170, 16, v92
	v_and_b32_e32 v171, 0xffff0000, v92
	v_mul_f32_e32 v170, s101, v170
	v_mul_f32_e32 v171, s101, v171
	v_fma_f32 v168, v170, v10, v168
	v_fma_f32 v169, v171, v11, v169
	v_fma_f32 v187, v168, v168, v187
	v_fma_f32 v187, v169, v169, v187
	v_cvt_pk_bf16_f32 v60, v168, v169
	v_lshlrev_b32_e32 v168, 16, v61
	v_and_b32_e32 v169, 0xffff0000, v61
	v_lshlrev_b32_e32 v170, 16, v93
	v_and_b32_e32 v171, 0xffff0000, v93
	v_mul_f32_e32 v170, s101, v170
	v_mul_f32_e32 v171, s101, v171
	v_fma_f32 v168, v170, v12, v168
	v_fma_f32 v169, v171, v13, v169
	v_fma_f32 v187, v168, v168, v187
	v_fma_f32 v187, v169, v169, v187
	v_cvt_pk_bf16_f32 v61, v168, v169
	v_lshlrev_b32_e32 v168, 16, v62
	v_and_b32_e32 v169, 0xffff0000, v62
	v_lshlrev_b32_e32 v170, 16, v94
	v_and_b32_e32 v171, 0xffff0000, v94
	v_mul_f32_e32 v170, s101, v170
	v_mul_f32_e32 v171, s101, v171
	v_fma_f32 v168, v170, v14, v168
	v_fma_f32 v169, v171, v15, v169
	v_fma_f32 v187, v168, v168, v187
	v_fma_f32 v187, v169, v169, v187
	v_cvt_pk_bf16_f32 v62, v168, v169
	v_lshlrev_b32_e32 v168, 16, v63
	v_and_b32_e32 v169, 0xffff0000, v63
	v_lshlrev_b32_e32 v170, 16, v95
	v_and_b32_e32 v171, 0xffff0000, v95
	v_mul_f32_e32 v170, s101, v170
	v_mul_f32_e32 v171, s101, v171
	v_fma_f32 v168, v170, v16, v168
	v_fma_f32 v169, v171, v17, v169
	v_fma_f32 v187, v168, v168, v187
	v_fma_f32 v187, v169, v169, v187
	v_cvt_pk_bf16_f32 v63, v168, v169
	global_store_dwordx4 v19, v[56:59], s[0:1] offset:2048
	global_store_dwordx4 v19, v[60:63], s[0:1] offset:3072
	s_nop 1
	v_add_f32_dpp v184, v184, v184 quad_perm:[1,0,3,2] row_mask:0xf bank_mask:0xf
	v_add_f32_dpp v185, v185, v185 quad_perm:[1,0,3,2] row_mask:0xf bank_mask:0xf
	v_add_f32_dpp v186, v186, v186 quad_perm:[1,0,3,2] row_mask:0xf bank_mask:0xf
	v_add_f32_dpp v187, v187, v187 quad_perm:[1,0,3,2] row_mask:0xf bank_mask:0xf
	v_add_f32_dpp v184, v184, v184 quad_perm:[2,3,0,1] row_mask:0xf bank_mask:0xf
	v_add_f32_dpp v185, v185, v185 quad_perm:[2,3,0,1] row_mask:0xf bank_mask:0xf
	v_add_f32_dpp v186, v186, v186 quad_perm:[2,3,0,1] row_mask:0xf bank_mask:0xf
	v_add_f32_dpp v187, v187, v187 quad_perm:[2,3,0,1] row_mask:0xf bank_mask:0xf
	v_add_f32_dpp v184, v184, v184 row_half_mirror row_mask:0xf bank_mask:0xf
	v_add_f32_dpp v185, v185, v185 row_half_mirror row_mask:0xf bank_mask:0xf
	v_add_f32_dpp v186, v186, v186 row_half_mirror row_mask:0xf bank_mask:0xf
	v_add_f32_dpp v187, v187, v187 row_half_mirror row_mask:0xf bank_mask:0xf
	v_add_f32_dpp v184, v184, v184 row_mirror row_mask:0xf bank_mask:0xf
	v_add_f32_dpp v185, v185, v185 row_mirror row_mask:0xf bank_mask:0xf
	v_add_f32_dpp v186, v186, v186 row_mirror row_mask:0xf bank_mask:0xf
	v_add_f32_dpp v187, v187, v187 row_mirror row_mask:0xf bank_mask:0xf
	v_add_f32_dpp v184, v184, v184 row_bcast:15 row_mask:0xa bank_mask:0xf
	v_add_f32_dpp v185, v185, v185 row_bcast:15 row_mask:0xa bank_mask:0xf
	v_add_f32_dpp v186, v186, v186 row_bcast:15 row_mask:0xa bank_mask:0xf
	v_add_f32_dpp v187, v187, v187 row_bcast:15 row_mask:0xa bank_mask:0xf
	v_add_f32_dpp v184, v184, v184 row_bcast:31 row_mask:0xc bank_mask:0xf
	v_add_f32_dpp v185, v185, v185 row_bcast:31 row_mask:0xc bank_mask:0xf
	v_add_f32_dpp v186, v186, v186 row_bcast:31 row_mask:0xc bank_mask:0xf
	v_add_f32_dpp v187, v187, v187 row_bcast:31 row_mask:0xc bank_mask:0xf
	s_nop 1
	v_readlane_b32 s3, v184, 63
	v_readlane_b32 s24, v185, 63
	v_readlane_b32 s98, v186, 63
	v_readlane_b32 s101, v187, 63
	s_nop 3
	v_writelane_b32 v188, s3, 0
	v_writelane_b32 v188, s24, 1
	v_writelane_b32 v188, s98, 2
	v_writelane_b32 v188, s101, 3
	s_nop 1
	v_mul_f32_e32 v188, 0x3a800000, v188
	v_add_f32_e32 v188, 0x358637bd, v188
	v_rsq_f32_e32 v188, v188
	s_mov_b64 exec, 15
	global_store_dword v21, v188, s[14:15]
	s_mov_b64 exec, -1
	s_waitcnt vmcnt(9)
; __device__ __forceinline__ float bf_lo(unsigned w) { return __uint_as_float(w << 16); }
; __device__ __forceinline__ float bf_hi(unsigned w) { return __uint_as_float(w & 0xffff0000u); }
; __device__ __forceinline__ unsigned pk2(float lo, float hi) { bf16x2_t r = __builtin_convertvector((f32x2_t){lo, hi}, bf16x2_t); return __builtin_bit_cast(unsigned, r); }
; template <bool SRC_F32, bool FINAL, int R> __device__ __forceinline__ void ew_compute(const EwSet<SRC_F32, R>& S, int rb, const f32x4 (&g)[4], bf16* hb_out, float* out32, float scale, float* rs_out, int lane) {
; #pragma unroll
;     for (int i = 0; i < R; ++i) {
;         float q = S.p[i];
;         q += __shfl_xor(q, 1); q += __shfl_xor(q, 2); q += __shfl_xor(q, 4); q += __shfl_xor(q, 8);
;         const float ss = __shfl(q, 0);
;         const float rs = scale / sqrtf(ss * (1.f / D) + EPS);
;         float s2 = 0.f;
; #pragma unroll
;         for (int j = 0; j < 4; ++j) {
;             f32x4 h;
;             if constexpr (SRC_F32) h = S.h32[i][j];
;             else { const v2u hw = S.hb[i][j]; h.x = bf_lo(hw.x); h.y = bf_hi(hw.x); h.z = bf_lo(hw.y); h.w = bf_hi(hw.y); }
;             const v2u fw = S.fw[i][j];
;             f32x4 v; v.x = h.x + bf_lo(fw.x) * rs * g[j].x; v.y = h.y + bf_hi(fw.x) * rs * g[j].y; v.z = h.z + bf_lo(fw.y) * rs * g[j].z; v.w = h.w + bf_hi(fw.y) * rs * g[j].w;
;             if (FINAL) __builtin_nontemporal_store(v, (f32x4*)(out32 + (size_t)(rb + i) * D) + lane + 64 * j);
;             else { v2u o; o.x = pk2(v.x, v.y); o.y = pk2(v.z, v.w); ((v2u*)(hb_out + (size_t)(rb + i) * D) + lane)[64 * j] = o; s2 += (v.x * v.x + v.y * v.y) + (v.z * v.z + v.w * v.w); }
	v_add_f32_dpp v164, v164, v164 quad_perm:[1,0,3,2] row_mask:0xf bank_mask:0xf
	s_nop 1
	v_add_f32_dpp v164, v164, v164 quad_perm:[2,3,0,1] row_mask:0xf bank_mask:0xf
	s_nop 1
	v_add_f32_dpp v164, v164, v164 row_half_mirror row_mask:0xf bank_mask:0xf
	s_nop 1
	v_add_f32_dpp v164, v164, v164 row_mirror row_mask:0xf bank_mask:0xf
	s_nop 1
	v_mul_f32_e32 v164, 0x3a800000, v164
	v_add_f32_e32 v164, 0x358637bd, v164
	v_rsq_f32_e32 v164, v164
	s_nop 0
	v_mul_f32_e32 v164, 0x3f000000, v164
	s_nop 0
	v_readlane_b32 s3, v164, 0
	v_readlane_b32 s24, v164, 16
	v_readlane_b32 s98, v164, 32
	v_readlane_b32 s101, v164, 48
	s_nop 1
	v_mov_b32_e32 v184, 0
	v_mov_b32_e32 v185, 0
	v_mov_b32_e32 v186, 0
	v_mov_b32_e32 v187, 0
	v_lshlrev_b32_e32 v168, 16, v100
	v_and_b32_e32 v169, 0xffff0000, v100
	v_lshlrev_b32_e32 v170, 16, v132
	v_and_b32_e32 v171, 0xffff0000, v132
	v_mul_f32_e32 v170, s3, v170
	v_mul_f32_e32 v171, s3, v171
	v_fma_f32 v168, v170, v2, v168
	v_fma_f32 v169, v171, v3, v169
	v_fma_f32 v184, v168, v168, v184
	v_fma_f32 v184, v169, v169, v184
	v_cvt_pk_bf16_f32 v100, v168, v169
	v_lshlrev_b32_e32 v168, 16, v101
	v_and_b32_e32 v169, 0xffff0000, v101
	v_lshlrev_b32_e32 v170, 16, v133
	v_and_b32_e32 v171, 0xffff0000, v133
	v_mul_f32_e32 v170, s3, v170
	v_mul_f32_e32 v171, s3, v171
	v_fma_f32 v168, v170, v4, v168
	v_fma_f32 v169, v171, v5, v169
	v_fma_f32 v184, v168, v168, v184
	v_fma_f32 v184, v169, v169, v184
	v_cvt_pk_bf16_f32 v101, v168, v169
	v_lshlrev_b32_e32 v168, 16, v102
	v_and_b32_e32 v169, 0xffff0000, v102
	v_lshlrev_b32_e32 v170, 16, v134
	v_and_b32_e32 v171, 0xffff0000, v134
	v_mul_f32_e32 v170, s3, v170
	v_mul_f32_e32 v171, s3, v171
	v_fma_f32 v168, v170, v6, v168
	v_fma_f32 v169, v171, v7, v169
	v_fma_f32 v184, v168, v168, v184
	v_fma_f32 v184, v169, v169, v184
	v_cvt_pk_bf16_f32 v102, v168, v169
	v_lshlrev_b32_e32 v168, 16, v103
	v_and_b32_e32 v169, 0xffff0000, v103
	v_lshlrev_b32_e32 v170, 16, v135
	v_and_b32_e32 v171, 0xffff0000, v135
	v_mul_f32_e32 v170, s3, v170
	v_mul_f32_e32 v171, s3, v171
	v_fma_f32 v168, v170, v8, v168
	v_fma_f32 v169, v171, v9, v169
	v_fma_f32 v184, v168, v168, v184
	v_fma_f32 v184, v169, v169, v184
	v_cvt_pk_bf16_f32 v103, v168, v169
	v_lshlrev_b32_e32 v168, 16, v104
	v_and_b32_e32 v169, 0xffff0000, v104
	v_lshlrev_b32_e32 v170, 16, v136
	v_and_b32_e32 v171, 0xffff0000, v136
	v_mul_f32_e32 v170, s3, v170
	v_mul_f32_e32 v171, s3, v171
	v_fma_f32 v168, v170, v10, v168
	v_fma_f32 v169, v171, v11, v169
	v_fma_f32 v184, v168, v168, v184
	v_fma_f32 v184, v169, v169, v184
	v_cvt_pk_bf16_f32 v104, v168, v169
	v_lshlrev_b32_e32 v168, 16, v105
	v_and_b32_e32 v169, 0xffff0000, v105
	v_lshlrev_b32_e32 v170, 16, v137
	v_and_b32_e32 v171, 0xffff0000, v137
	v_mul_f32_e32 v170, s3, v170
	v_mul_f32_e32 v171, s3, v171
	v_fma_f32 v168, v170, v12, v168
	v_fma_f32 v169, v171, v13, v169
	v_fma_f32 v184, v168, v168, v184
	v_fma_f32 v184, v169, v169, v184
	v_cvt_pk_bf16_f32 v105, v168, v169
	v_lshlrev_b32_e32 v168, 16, v106
	v_and_b32_e32 v169, 0xffff0000, v106
	v_lshlrev_b32_e32 v170, 16, v138
	v_and_b32_e32 v171, 0xffff0000, v138
	v_mul_f32_e32 v170, s3, v170
	v_mul_f32_e32 v171, s3, v171
	v_fma_f32 v168, v170, v14, v168
	v_fma_f32 v169, v171, v15, v169
	v_fma_f32 v184, v168, v168, v184
	v_fma_f32 v184, v169, v169, v184
	v_cvt_pk_bf16_f32 v106, v168, v169
	v_lshlrev_b32_e32 v168, 16, v107
	v_and_b32_e32 v169, 0xffff0000, v107
	v_lshlrev_b32_e32 v170, 16, v139
	v_and_b32_e32 v171, 0xffff0000, v139
	v_mul_f32_e32 v170, s3, v170
	v_mul_f32_e32 v171, s3, v171
	v_fma_f32 v168, v170, v16, v168
	v_fma_f32 v169, v171, v17, v169
	v_fma_f32 v184, v168, v168, v184
	v_fma_f32 v184, v169, v169, v184
	v_cvt_pk_bf16_f32 v107, v168, v169
	global_store_dwordx4 v23, v[100:103], s[0:1]
	global_store_dwordx4 v23, v[104:107], s[0:1] offset:1024
	v_lshlrev_b32_e32 v168, 16, v108
	v_and_b32_e32 v169, 0xffff0000, v108
	v_lshlrev_b32_e32 v170, 16, v140
	v_and_b32_e32 v171, 0xffff0000, v140
	v_mul_f32_e32 v170, s24, v170
	v_mul_f32_e32 v171, s24, v171
	v_fma_f32 v168, v170, v2, v168
	v_fma_f32 v169, v171, v3, v169
	v_fma_f32 v185, v168, v168, v185
	v_fma_f32 v185, v169, v169, v185
	v_cvt_pk_bf16_f32 v108, v168, v169
	v_lshlrev_b32_e32 v168, 16, v109
	v_and_b32_e32 v169, 0xffff0000, v109
	v_lshlrev_b32_e32 v170, 16, v141
	v_and_b32_e32 v171, 0xffff0000, v141
	v_mul_f32_e32 v170, s24, v170
	v_mul_f32_e32 v171, s24, v171
	v_fma_f32 v168, v170, v4, v168
	v_fma_f32 v169, v171, v5, v169
	v_fma_f32 v185, v168, v168, v185
	v_fma_f32 v185, v169, v169, v185
	v_cvt_pk_bf16_f32 v109, v168, v169
	v_lshlrev_b32_e32 v168, 16, v110
	v_and_b32_e32 v169, 0xffff0000, v110
	v_lshlrev_b32_e32 v170, 16, v142
	v_and_b32_e32 v171, 0xffff0000, v142
	v_mul_f32_e32 v170, s24, v170
	v_mul_f32_e32 v171, s24, v171
	v_fma_f32 v168, v170, v6, v168
	v_fma_f32 v169, v171, v7, v169
	v_fma_f32 v185, v168, v168, v185
	v_fma_f32 v185, v169, v169, v185
	v_cvt_pk_bf16_f32 v110, v168, v169
	v_lshlrev_b32_e32 v168, 16, v111
	v_and_b32_e32 v169, 0xffff0000, v111
	v_lshlrev_b32_e32 v170, 16, v143
	v_and_b32_e32 v171, 0xffff0000, v143
	v_mul_f32_e32 v170, s24, v170
	v_mul_f32_e32 v171, s24, v171
	v_fma_f32 v168, v170, v8, v168
	v_fma_f32 v169, v171, v9, v169
	v_fma_f32 v185, v168, v168, v185
	v_fma_f32 v185, v169, v169, v185
	v_cvt_pk_bf16_f32 v111, v168, v169
	v_lshlrev_b32_e32 v168, 16, v112
	v_and_b32_e32 v169, 0xffff0000, v112
	v_lshlrev_b32_e32 v170, 16, v144
	v_and_b32_e32 v171, 0xffff0000, v144
	v_mul_f32_e32 v170, s24, v170
	v_mul_f32_e32 v171, s24, v171
	v_fma_f32 v168, v170, v10, v168
	v_fma_f32 v169, v171, v11, v169
	v_fma_f32 v185, v168, v168, v185
	v_fma_f32 v185, v169, v169, v185
; __device__ __forceinline__ float bf_lo(unsigned w) { return __uint_as_float(w << 16); }
; __device__ __forceinline__ float bf_hi(unsigned w) { return __uint_as_float(w & 0xffff0000u); }
; __device__ __forceinline__ unsigned pk2(float lo, float hi) { bf16x2_t r = __builtin_convertvector((f32x2_t){lo, hi}, bf16x2_t); return __builtin_bit_cast(unsigned, r); }
; template <bool SRC_F32, bool FINAL, int R> __device__ __forceinline__ void ew_compute(const EwSet<SRC_F32, R>& S, int rb, const f32x4 (&g)[4], bf16* hb_out, float* out32, float scale, float* rs_out, int lane) {
;     ...
; #pragma unroll
;         for (int j = 0; j < 4; ++j) {
;             f32x4 h;
;             if constexpr (SRC_F32) h = S.h32[i][j];
;             else { const v2u hw = S.hb[i][j]; h.x = bf_lo(hw.x); h.y = bf_hi(hw.x); h.z = bf_lo(hw.y); h.w = bf_hi(hw.y); }
;             const v2u fw = S.fw[i][j];
;             f32x4 v; v.x = h.x + bf_lo(fw.x) * rs * g[j].x; v.y = h.y + bf_hi(fw.x) * rs * g[j].y; v.z = h.z + bf_lo(fw.y) * rs * g[j].z; v.w = h.w + bf_hi(fw.y) * rs * g[j].w;
;             if (FINAL) __builtin_nontemporal_store(v, (f32x4*)(out32 + (size_t)(rb + i) * D) + lane + 64 * j);
;             else { v2u o; o.x = pk2(v.x, v.y); o.y = pk2(v.z, v.w); ((v2u*)(hb_out + (size_t)(rb + i) * D) + lane)[64 * j] = o; s2 += (v.x * v.x + v.y * v.y) + (v.z * v.z + v.w * v.w); }
	v_cvt_pk_bf16_f32 v112, v168, v169
	v_lshlrev_b32_e32 v168, 16, v113
	v_and_b32_e32 v169, 0xffff0000, v113
	v_lshlrev_b32_e32 v170, 16, v145
	v_and_b32_e32 v171, 0xffff0000, v145
	v_mul_f32_e32 v170, s24, v170
	v_mul_f32_e32 v171, s24, v171
	v_fma_f32 v168, v170, v12, v168
	v_fma_f32 v169, v171, v13, v169
	v_fma_f32 v185, v168, v168, v185
	v_fma_f32 v185, v169, v169, v185
	v_cvt_pk_bf16_f32 v113, v168, v169
	v_lshlrev_b32_e32 v168, 16, v114
	v_and_b32_e32 v169, 0xffff0000, v114
	v_lshlrev_b32_e32 v170, 16, v146
	v_and_b32_e32 v171, 0xffff0000, v146
	v_mul_f32_e32 v170, s24, v170
	v_mul_f32_e32 v171, s24, v171
	v_fma_f32 v168, v170, v14, v168
	v_fma_f32 v169, v171, v15, v169
	v_fma_f32 v185, v168, v168, v185
	v_fma_f32 v185, v169, v169, v185
	v_cvt_pk_bf16_f32 v114, v168, v169
	v_lshlrev_b32_e32 v168, 16, v115
	v_and_b32_e32 v169, 0xffff0000, v115
	v_lshlrev_b32_e32 v170, 16, v147
	v_and_b32_e32 v171, 0xffff0000, v147
	v_mul_f32_e32 v170, s24, v170
	v_mul_f32_e32 v171, s24, v171
	v_fma_f32 v168, v170, v16, v168
	v_fma_f32 v169, v171, v17, v169
	v_fma_f32 v185, v168, v168, v185
	v_fma_f32 v185, v169, v169, v185
	v_cvt_pk_bf16_f32 v115, v168, v169
	global_store_dwordx4 v23, v[108:111], s[0:1] offset:2048
	global_store_dwordx4 v23, v[112:115], s[0:1] offset:3072
	v_lshlrev_b32_e32 v168, 16, v116
	v_and_b32_e32 v169, 0xffff0000, v116
	v_lshlrev_b32_e32 v170, 16, v148
	v_and_b32_e32 v171, 0xffff0000, v148
	v_mul_f32_e32 v170, s98, v170
	v_mul_f32_e32 v171, s98, v171
	v_fma_f32 v168, v170, v2, v168
	v_fma_f32 v169, v171, v3, v169
	v_fma_f32 v186, v168, v168, v186
	v_fma_f32 v186, v169, v169, v186
	v_cvt_pk_bf16_f32 v116, v168, v169
	v_lshlrev_b32_e32 v168, 16, v117
	v_and_b32_e32 v169, 0xffff0000, v117
	v_lshlrev_b32_e32 v170, 16, v149
	v_and_b32_e32 v171, 0xffff0000, v149
	v_mul_f32_e32 v170, s98, v170
	v_mul_f32_e32 v171, s98, v171
	v_fma_f32 v168, v170, v4, v168
	v_fma_f32 v169, v171, v5, v169
	v_fma_f32 v186, v168, v168, v186
	v_fma_f32 v186, v169, v169, v186
	v_cvt_pk_bf16_f32 v117, v168, v169
	v_lshlrev_b32_e32 v168, 16, v118
	v_and_b32_e32 v169, 0xffff0000, v118
	v_lshlrev_b32_e32 v170, 16, v150
	v_and_b32_e32 v171, 0xffff0000, v150
	v_mul_f32_e32 v170, s98, v170
	v_mul_f32_e32 v171, s98, v171
	v_fma_f32 v168, v170, v6, v168
	v_fma_f32 v169, v171, v7, v169
	v_fma_f32 v186, v168, v168, v186
	v_fma_f32 v186, v169, v169, v186
	v_cvt_pk_bf16_f32 v118, v168, v169
	v_lshlrev_b32_e32 v168, 16, v119
	v_and_b32_e32 v169, 0xffff0000, v119
	v_lshlrev_b32_e32 v170, 16, v151
	v_and_b32_e32 v171, 0xffff0000, v151
	v_mul_f32_e32 v170, s98, v170
	v_mul_f32_e32 v171, s98, v171
	v_fma_f32 v168, v170, v8, v168
	v_fma_f32 v169, v171, v9, v169
	v_fma_f32 v186, v168, v168, v186
	v_fma_f32 v186, v169, v169, v186
	v_cvt_pk_bf16_f32 v119, v168, v169
	v_lshlrev_b32_e32 v168, 16, v120
	v_and_b32_e32 v169, 0xffff0000, v120
	v_lshlrev_b32_e32 v170, 16, v152
	v_and_b32_e32 v171, 0xffff0000, v152
	v_mul_f32_e32 v170, s98, v170
	v_mul_f32_e32 v171, s98, v171
	v_fma_f32 v168, v170, v10, v168
	v_fma_f32 v169, v171, v11, v169
	v_fma_f32 v186, v168, v168, v186
	v_fma_f32 v186, v169, v169, v186
	v_cvt_pk_bf16_f32 v120, v168, v169
	v_lshlrev_b32_e32 v168, 16, v121
	v_and_b32_e32 v169, 0xffff0000, v121
	v_lshlrev_b32_e32 v170, 16, v153
	v_and_b32_e32 v171, 0xffff0000, v153
	v_mul_f32_e32 v170, s98, v170
	v_mul_f32_e32 v171, s98, v171
	v_fma_f32 v168, v170, v12, v168
	v_fma_f32 v169, v171, v13, v169
	v_fma_f32 v186, v168, v168, v186
	v_fma_f32 v186, v169, v169, v186
	v_cvt_pk_bf16_f32 v121, v168, v169
	v_lshlrev_b32_e32 v168, 16, v122
	v_and_b32_e32 v169, 0xffff0000, v122
	v_lshlrev_b32_e32 v170, 16, v154
	v_and_b32_e32 v171, 0xffff0000, v154
	v_mul_f32_e32 v170, s98, v170
	v_mul_f32_e32 v171, s98, v171
	v_fma_f32 v168, v170, v14, v168
	v_fma_f32 v169, v171, v15, v169
	v_fma_f32 v186, v168, v168, v186
	v_fma_f32 v186, v169, v169, v186
	v_cvt_pk_bf16_f32 v122, v168, v169
	v_lshlrev_b32_e32 v168, 16, v123
	v_and_b32_e32 v169, 0xffff0000, v123
	v_lshlrev_b32_e32 v170, 16, v155
	v_and_b32_e32 v171, 0xffff0000, v155
	v_mul_f32_e32 v170, s98, v170
	v_mul_f32_e32 v171, s98, v171
	v_fma_f32 v168, v170, v16, v168
	v_fma_f32 v169, v171, v17, v169
	v_fma_f32 v186, v168, v168, v186
	v_fma_f32 v186, v169, v169, v186
	v_cvt_pk_bf16_f32 v123, v168, v169
	global_store_dwordx4 v24, v[116:119], s[0:1]
	global_store_dwordx4 v24, v[120:123], s[0:1] offset:1024
	v_lshlrev_b32_e32 v168, 16, v124
	v_and_b32_e32 v169, 0xffff0000, v124
	v_lshlrev_b32_e32 v170, 16, v156
	v_and_b32_e32 v171, 0xffff0000, v156
	v_mul_f32_e32 v170, s101, v170
	v_mul_f32_e32 v171, s101, v171
	v_fma_f32 v168, v170, v2, v168
	v_fma_f32 v169, v171, v3, v169
	v_fma_f32 v187, v168, v168, v187
	v_fma_f32 v187, v169, v169, v187
	v_cvt_pk_bf16_f32 v124, v168, v169
	v_lshlrev_b32_e32 v168, 16, v125
	v_and_b32_e32 v169, 0xffff0000, v125
	v_lshlrev_b32_e32 v170, 16, v157
; __device__ __forceinline__ float bf_lo(unsigned w) { return __uint_as_float(w << 16); }
; __device__ __forceinline__ float bf_hi(unsigned w) { return __uint_as_float(w & 0xffff0000u); }
; __device__ __forceinline__ unsigned pk2(float lo, float hi) { bf16x2_t r = __builtin_convertvector((f32x2_t){lo, hi}, bf16x2_t); return __builtin_bit_cast(unsigned, r); }
; template <bool SRC_F32, bool FINAL, int R> __device__ __forceinline__ void ew_compute(const EwSet<SRC_F32, R>& S, int rb, const f32x4 (&g)[4], bf16* hb_out, float* out32, float scale, float* rs_out, int lane) {
;     ...
; #pragma unroll
;         for (int j = 0; j < 4; ++j) {
;             f32x4 h;
;             if constexpr (SRC_F32) h = S.h32[i][j];
;             else { const v2u hw = S.hb[i][j]; h.x = bf_lo(hw.x); h.y = bf_hi(hw.x); h.z = bf_lo(hw.y); h.w = bf_hi(hw.y); }
;             const v2u fw = S.fw[i][j];
;             f32x4 v; v.x = h.x + bf_lo(fw.x) * rs * g[j].x; v.y = h.y + bf_hi(fw.x) * rs * g[j].y; v.z = h.z + bf_lo(fw.y) * rs * g[j].z; v.w = h.w + bf_hi(fw.y) * rs * g[j].w;
;             if (FINAL) __builtin_nontemporal_store(v, (f32x4*)(out32 + (size_t)(rb + i) * D) + lane + 64 * j);
;             else { v2u o; o.x = pk2(v.x, v.y); o.y = pk2(v.z, v.w); ((v2u*)(hb_out + (size_t)(rb + i) * D) + lane)[64 * j] = o; s2 += (v.x * v.x + v.y * v.y) + (v.z * v.z + v.w * v.w); }
;         }
;         if (!FINAL) { const float tot = wave_sum(s2); if (lane == 0) rs_out[rb + i] = 1.0f / sqrtf(tot * (1.f / D) + EPS); }
	v_and_b32_e32 v171, 0xffff0000, v157
	v_mul_f32_e32 v170, s101, v170
	v_mul_f32_e32 v171, s101, v171
	v_fma_f32 v168, v170, v4, v168
	v_fma_f32 v169, v171, v5, v169
	v_fma_f32 v187, v168, v168, v187
	v_fma_f32 v187, v169, v169, v187
	v_cvt_pk_bf16_f32 v125, v168, v169
	v_lshlrev_b32_e32 v168, 16, v126
	v_and_b32_e32 v169, 0xffff0000, v126
	v_lshlrev_b32_e32 v170, 16, v158
	v_and_b32_e32 v171, 0xffff0000, v158
	v_mul_f32_e32 v170, s101, v170
	v_mul_f32_e32 v171, s101, v171
	v_fma_f32 v168, v170, v6, v168
	v_fma_f32 v169, v171, v7, v169
	v_fma_f32 v187, v168, v168, v187
	v_fma_f32 v187, v169, v169, v187
	v_cvt_pk_bf16_f32 v126, v168, v169
	v_lshlrev_b32_e32 v168, 16, v127
	v_and_b32_e32 v169, 0xffff0000, v127
	v_lshlrev_b32_e32 v170, 16, v159
	v_and_b32_e32 v171, 0xffff0000, v159
	v_mul_f32_e32 v170, s101, v170
	v_mul_f32_e32 v171, s101, v171
	v_fma_f32 v168, v170, v8, v168
	v_fma_f32 v169, v171, v9, v169
	v_fma_f32 v187, v168, v168, v187
	v_fma_f32 v187, v169, v169, v187
	v_cvt_pk_bf16_f32 v127, v168, v169
	v_lshlrev_b32_e32 v168, 16, v128
	v_and_b32_e32 v169, 0xffff0000, v128
	v_lshlrev_b32_e32 v170, 16, v160
	v_and_b32_e32 v171, 0xffff0000, v160
	v_mul_f32_e32 v170, s101, v170
	v_mul_f32_e32 v171, s101, v171
	v_fma_f32 v168, v170, v10, v168
	v_fma_f32 v169, v171, v11, v169
	v_fma_f32 v187, v168, v168, v187
	v_fma_f32 v187, v169, v169, v187
	v_cvt_pk_bf16_f32 v128, v168, v169
	v_lshlrev_b32_e32 v168, 16, v129
	v_and_b32_e32 v169, 0xffff0000, v129
	v_lshlrev_b32_e32 v170, 16, v161
	v_and_b32_e32 v171, 0xffff0000, v161
	v_mul_f32_e32 v170, s101, v170
	v_mul_f32_e32 v171, s101, v171
	v_fma_f32 v168, v170, v12, v168
	v_fma_f32 v169, v171, v13, v169
	v_fma_f32 v187, v168, v168, v187
	v_fma_f32 v187, v169, v169, v187
	v_cvt_pk_bf16_f32 v129, v168, v169
	v_lshlrev_b32_e32 v168, 16, v130
	v_and_b32_e32 v169, 0xffff0000, v130
	v_lshlrev_b32_e32 v170, 16, v162
	v_and_b32_e32 v171, 0xffff0000, v162
	v_mul_f32_e32 v170, s101, v170
	v_mul_f32_e32 v171, s101, v171
	v_fma_f32 v168, v170, v14, v168
	v_fma_f32 v169, v171, v15, v169
	v_fma_f32 v187, v168, v168, v187
	v_fma_f32 v187, v169, v169, v187
	v_cvt_pk_bf16_f32 v130, v168, v169
	v_lshlrev_b32_e32 v168, 16, v131
	v_and_b32_e32 v169, 0xffff0000, v131
	v_lshlrev_b32_e32 v170, 16, v163
	v_and_b32_e32 v171, 0xffff0000, v163
	v_mul_f32_e32 v170, s101, v170
	v_mul_f32_e32 v171, s101, v171
	v_fma_f32 v168, v170, v16, v168
	v_fma_f32 v169, v171, v17, v169
	v_fma_f32 v187, v168, v168, v187
	v_fma_f32 v187, v169, v169, v187
	v_cvt_pk_bf16_f32 v131, v168, v169
	global_store_dwordx4 v24, v[124:127], s[0:1] offset:2048
	global_store_dwordx4 v24, v[128:131], s[0:1] offset:3072
	s_nop 1
	v_add_f32_dpp v184, v184, v184 quad_perm:[1,0,3,2] row_mask:0xf bank_mask:0xf
	v_add_f32_dpp v185, v185, v185 quad_perm:[1,0,3,2] row_mask:0xf bank_mask:0xf
	v_add_f32_dpp v186, v186, v186 quad_perm:[1,0,3,2] row_mask:0xf bank_mask:0xf
	v_add_f32_dpp v187, v187, v187 quad_perm:[1,0,3,2] row_mask:0xf bank_mask:0xf
	v_add_f32_dpp v184, v184, v184 quad_perm:[2,3,0,1] row_mask:0xf bank_mask:0xf
	v_add_f32_dpp v185, v185, v185 quad_perm:[2,3,0,1] row_mask:0xf bank_mask:0xf
	v_add_f32_dpp v186, v186, v186 quad_perm:[2,3,0,1] row_mask:0xf bank_mask:0xf
	v_add_f32_dpp v187, v187, v187 quad_perm:[2,3,0,1] row_mask:0xf bank_mask:0xf
	v_add_f32_dpp v184, v184, v184 row_half_mirror row_mask:0xf bank_mask:0xf
	v_add_f32_dpp v185, v185, v185 row_half_mirror row_mask:0xf bank_mask:0xf
	v_add_f32_dpp v186, v186, v186 row_half_mirror row_mask:0xf bank_mask:0xf
	v_add_f32_dpp v187, v187, v187 row_half_mirror row_mask:0xf bank_mask:0xf
	v_add_f32_dpp v184, v184, v184 row_mirror row_mask:0xf bank_mask:0xf
	v_add_f32_dpp v185, v185, v185 row_mirror row_mask:0xf bank_mask:0xf
	v_add_f32_dpp v186, v186, v186 row_mirror row_mask:0xf bank_mask:0xf
	v_add_f32_dpp v187, v187, v187 row_mirror row_mask:0xf bank_mask:0xf
	v_add_f32_dpp v184, v184, v184 row_bcast:15 row_mask:0xa bank_mask:0xf
	v_add_f32_dpp v185, v185, v185 row_bcast:15 row_mask:0xa bank_mask:0xf
	v_add_f32_dpp v186, v186, v186 row_bcast:15 row_mask:0xa bank_mask:0xf
	v_add_f32_dpp v187, v187, v187 row_bcast:15 row_mask:0xa bank_mask:0xf
	v_add_f32_dpp v184, v184, v184 row_bcast:31 row_mask:0xc bank_mask:0xf
	v_add_f32_dpp v185, v185, v185 row_bcast:31 row_mask:0xc bank_mask:0xf
	v_add_f32_dpp v186, v186, v186 row_bcast:31 row_mask:0xc bank_mask:0xf
	v_add_f32_dpp v187, v187, v187 row_bcast:31 row_mask:0xc bank_mask:0xf
	s_nop 1
	v_readlane_b32 s3, v184, 63
	v_readlane_b32 s24, v185, 63
	v_readlane_b32 s98, v186, 63
	v_readlane_b32 s101, v187, 63
	s_nop 3
	v_writelane_b32 v188, s3, 0
	v_writelane_b32 v188, s24, 1
	v_writelane_b32 v188, s98, 2
	v_writelane_b32 v188, s101, 3
	s_nop 1
	v_mul_f32_e32 v188, 0x3a800000, v188
	v_add_f32_e32 v188, 0x358637bd, v188
	v_rsq_f32_e32 v188, v188
	s_mov_b64 exec, 15
	global_store_dword v26, v188, s[14:15]
	s_mov_b64 exec, -1

; __device__ __forceinline__ float bf_lo(unsigned w) { return __uint_as_float(w << 16); }
; __device__ __forceinline__ float bf_hi(unsigned w) { return __uint_as_float(w & 0xffff0000u); }
; template <bool SRC_F32, bool FINAL, int R> __device__ __forceinline__ void ew_compute(const EwSet<SRC_F32, R>& S, int rb, const f32x4 (&g)[4], bf16* hb_out, float* out32, float scale, float* rs_out, int lane) {
; #pragma unroll
;     for (int i = 0; i < R; ++i) {
;         float q = S.p[i];
;         q += __shfl_xor(q, 1); q += __shfl_xor(q, 2); q += __shfl_xor(q, 4); q += __shfl_xor(q, 8);
;         const float ss = __shfl(q, 0);
;         const float rs = scale / sqrtf(ss * (1.f / D) + EPS);
;         float s2 = 0.f;
; #pragma unroll
;         for (int j = 0; j < 4; ++j) {
;             f32x4 h;
;             if constexpr (SRC_F32) h = S.h32[i][j];
;             else { const v2u hw = S.hb[i][j]; h.x = bf_lo(hw.x); h.y = bf_hi(hw.x); h.z = bf_lo(hw.y); h.w = bf_hi(hw.y); }
;             const v2u fw = S.fw[i][j];
;             f32x4 v; v.x = h.x + bf_lo(fw.x) * rs * g[j].x; v.y = h.y + bf_hi(fw.x) * rs * g[j].y; v.z = h.z + bf_lo(fw.y) * rs * g[j].z; v.w = h.w + bf_hi(fw.y) * rs * g[j].w;
; template <bool SRC_F32, bool FINAL> __device__ __forceinline__ void ew_phase(const float* hsrc32, const bf16* hsrcb, bf16* hb_out, float* out32, const bf16* f, const float* part, const float* gpost, float scale, float* rs_out, int gw, int NGW, int lane) {
;     constexpr int R = SRC_F32 ? 2 : 4;
;     f32x4 g[4];
; #pragma unroll
;     for (int j = 0; j < 4; ++j) g[j] = ((const f32x4*)gpost + lane)[64 * j];
;     const int step = NGW * R;
;     EwSet<SRC_F32, R> A, B;
;     int rb = gw * R;
;     if (rb < M) ew_load<SRC_F32, R>(A, rb, hsrc32, hsrcb, f, part, lane);
; #pragma unroll 1
;     for (; rb < M; rb += 2 * step) {
;         const int nb = rb + step, nb2 = nb + step;
;         if (nb < M) ew_load<SRC_F32, R>(B, nb, hsrc32, hsrcb, f, part, lane);
.LBB0_943:
	s_cmp_lt_i32 s30, 9
	s_cselect_b64 s[4:5], -1, 0
	s_and_b64 s[8:9], s[4:5], s[0:1]
	s_andn2_b64 vcc, exec, s[8:9]
	s_cbranch_vccnz .LBB0_989
	s_waitcnt vmcnt(0) lgkmcnt(0)
	s_add_u32 s22, s84, 0xffffff10
	s_addc_u32 s23, s85, -1
	s_load_dwordx2 s[52:53], s[22:23], 0x88
	s_add_u32 s0, s28, 0x5000000
	s_addc_u32 s1, s29, 0
	s_add_u32 s4, s28, 0x15000000
	s_addc_u32 s5, s29, 0
	s_add_u32 s6, s28, 0x3700000
	s_addc_u32 s7, s29, 0
	s_add_u32 s14, s28, 0x3910000
	s_addc_u32 s15, s29, 0
	v_and_b32_e32 v0, 63, v195
	v_lshlrev_b32_e32 v1, 5, v0
	s_and_b32 s26, s2, 7
	s_lshl_b32 s26, s26, 4
	s_bfe_u32 s27, s2, 0x30003
	s_add_u32 s26, s26, s27
	s_lshl_b32 s26, s26, 8
	s_lshr_b32 s27, s2, 6
	s_lshl_b32 s27, s27, 6
	s_add_u32 s26, s26, s27
	v_readfirstlane_b32 s27, v195
	s_lshr_b32 s27, s27, 6
	s_lshl_b32 s27, s27, 3
	s_add_u32 s26, s26, s27
	s_add_u32 s27, s26, 0
	s_lshl_b32 s22, s27, 11
	v_lshl_add_u32 v18, v0, 4, s22
	v_add_u32_e32 v19, 0x1000, v18
	s_lshl_b32 s22, s27, 6
	v_lshl_add_u32 v20, v0, 2, s22
	s_lshl_b32 s22, s27, 2
	v_lshl_add_u32 v21, v0, 2, s22
	global_load_dwordx4 v[32:35], v18, s[0:1]
	global_load_dwordx4 v[36:39], v18, s[0:1] offset:1024
	global_load_dwordx4 v[64:67], v18, s[4:5]
	global_load_dwordx4 v[68:71], v18, s[4:5] offset:1024
	global_load_dwordx4 v[40:43], v18, s[0:1] offset:2048
	global_load_dwordx4 v[44:47], v18, s[0:1] offset:3072
	global_load_dwordx4 v[72:75], v18, s[4:5] offset:2048
	global_load_dwordx4 v[76:79], v18, s[4:5] offset:3072
	global_load_dwordx4 v[48:51], v19, s[0:1]
	global_load_dwordx4 v[52:55], v19, s[0:1] offset:1024
	global_load_dwordx4 v[80:83], v19, s[4:5]
	global_load_dwordx4 v[84:87], v19, s[4:5] offset:1024
	global_load_dwordx4 v[56:59], v19, s[0:1] offset:2048
	global_load_dwordx4 v[60:63], v19, s[0:1] offset:3072
	global_load_dwordx4 v[88:91], v19, s[4:5] offset:2048
	global_load_dwordx4 v[92:95], v19, s[4:5] offset:3072
	global_load_dword v96, v20, s[6:7]
	s_waitcnt lgkmcnt(0)
	global_load_dwordx4 v[2:5], v1, s[52:53]
	global_load_dwordx4 v[6:9], v1, s[52:53] offset:16
	global_load_dwordx4 v[10:13], v1, s[52:53] offset:2048
	global_load_dwordx4 v[14:17], v1, s[52:53] offset:2064
	s_add_u32 s27, s26, 4
	s_lshl_b32 s22, s27, 11
	v_lshl_add_u32 v23, v0, 4, s22
	v_add_u32_e32 v24, 0x1000, v23
	s_lshl_b32 s22, s27, 6
	v_lshl_add_u32 v25, v0, 2, s22
	s_lshl_b32 s22, s27, 2
	v_lshl_add_u32 v26, v0, 2, s22
	global_load_dwordx4 v[100:103], v23, s[0:1]
	global_load_dwordx4 v[104:107], v23, s[0:1] offset:1024
	global_load_dwordx4 v[132:135], v23, s[4:5]
	global_load_dwordx4 v[136:139], v23, s[4:5] offset:1024
	global_load_dwordx4 v[108:111], v23, s[0:1] offset:2048
	global_load_dwordx4 v[112:115], v23, s[0:1] offset:3072
	global_load_dwordx4 v[140:143], v23, s[4:5] offset:2048
	global_load_dwordx4 v[144:147], v23, s[4:5] offset:3072
	global_load_dwordx4 v[116:119], v24, s[0:1]
	global_load_dwordx4 v[120:123], v24, s[0:1] offset:1024
	global_load_dwordx4 v[148:151], v24, s[4:5]
	global_load_dwordx4 v[152:155], v24, s[4:5] offset:1024
	global_load_dwordx4 v[124:127], v24, s[0:1] offset:2048
	global_load_dwordx4 v[128:131], v24, s[0:1] offset:3072
	global_load_dwordx4 v[156:159], v24, s[4:5] offset:2048
	global_load_dwordx4 v[160:163], v24, s[4:5] offset:3072
	global_load_dword v164, v25, s[6:7]
	s_waitcnt vmcnt(17)
	v_add_f32_dpp v96, v96, v96 quad_perm:[1,0,3,2] row_mask:0xf bank_mask:0xf
	s_nop 1
	v_add_f32_dpp v96, v96, v96 quad_perm:[2,3,0,1] row_mask:0xf bank_mask:0xf
	s_nop 1
	v_add_f32_dpp v96, v96, v96 row_half_mirror row_mask:0xf bank_mask:0xf
	s_nop 1
	v_add_f32_dpp v96, v96, v96 row_mirror row_mask:0xf bank_mask:0xf
	s_nop 1
	v_mul_f32_e32 v96, 0x3a800000, v96
	v_add_f32_e32 v96, 0x358637bd, v96
	v_rsq_f32_e32 v96, v96
	s_nop 0
	v_readlane_b32 s3, v96, 0
	v_readlane_b32 s24, v96, 16
	v_readlane_b32 s98, v96, 32
	v_readlane_b32 s101, v96, 48
	s_nop 1
	v_mov_b32_e32 v184, 0
	v_mov_b32_e32 v185, 0
	v_mov_b32_e32 v186, 0
	v_mov_b32_e32 v187, 0
	v_lshlrev_b32_e32 v168, 16, v32
	v_and_b32_e32 v169, 0xffff0000, v32
	v_lshlrev_b32_e32 v170, 16, v64
	v_and_b32_e32 v171, 0xffff0000, v64
	v_mul_f32_e32 v170, s3, v170
	v_mul_f32_e32 v171, s3, v171
	v_fma_f32 v168, v170, v2, v168
	v_fma_f32 v169, v171, v3, v169
	v_fma_f32 v184, v168, v168, v184
	v_fma_f32 v184, v169, v169, v184
	v_cvt_pk_bf16_f32 v32, v168, v169
	v_lshlrev_b32_e32 v168, 16, v33
	v_and_b32_e32 v169, 0xffff0000, v33
	v_lshlrev_b32_e32 v170, 16, v65
	v_and_b32_e32 v171, 0xffff0000, v65
	v_mul_f32_e32 v170, s3, v170
	v_mul_f32_e32 v171, s3, v171
	v_fma_f32 v168, v170, v4, v168
	v_fma_f32 v169, v171, v5, v169
	v_fma_f32 v184, v168, v168, v184
	v_fma_f32 v184, v169, v169, v184
	v_cvt_pk_bf16_f32 v33, v168, v169
	v_lshlrev_b32_e32 v168, 16, v34
	v_and_b32_e32 v169, 0xffff0000, v34
	v_lshlrev_b32_e32 v170, 16, v66
	v_and_b32_e32 v171, 0xffff0000, v66
	v_mul_f32_e32 v170, s3, v170
	v_mul_f32_e32 v171, s3, v171
	v_fma_f32 v168, v170, v6, v168
	v_fma_f32 v169, v171, v7, v169
	v_fma_f32 v184, v168, v168, v184
	v_fma_f32 v184, v169, v169, v184
	v_cvt_pk_bf16_f32 v34, v168, v169
	v_lshlrev_b32_e32 v168, 16, v35
	v_and_b32_e32 v169, 0xffff0000, v35
	v_lshlrev_b32_e32 v170, 16, v67
	v_and_b32_e32 v171, 0xffff0000, v67
	v_mul_f32_e32 v170, s3, v170
	v_mul_f32_e32 v171, s3, v171
	v_fma_f32 v168, v170, v8, v168
	v_fma_f32 v169, v171, v9, v169
	v_fma_f32 v184, v168, v168, v184
	v_fma_f32 v184, v169, v169, v184
	v_cvt_pk_bf16_f32 v35, v168, v169
	v_lshlrev_b32_e32 v168, 16, v36
	v_and_b32_e32 v169, 0xffff0000, v36
	v_lshlrev_b32_e32 v170, 16, v68
	v_and_b32_e32 v171, 0xffff0000, v68
	v_mul_f32_e32 v170, s3, v170
	v_mul_f32_e32 v171, s3, v171
; __device__ __forceinline__ float bf_lo(unsigned w) { return __uint_as_float(w << 16); }
; __device__ __forceinline__ float bf_hi(unsigned w) { return __uint_as_float(w & 0xffff0000u); }
; __device__ __forceinline__ unsigned pk2(float lo, float hi) { bf16x2_t r = __builtin_convertvector((f32x2_t){lo, hi}, bf16x2_t); return __builtin_bit_cast(unsigned, r); }
; template <bool SRC_F32, bool FINAL, int R> __device__ __forceinline__ void ew_compute(const EwSet<SRC_F32, R>& S, int rb, const f32x4 (&g)[4], bf16* hb_out, float* out32, float scale, float* rs_out, int lane) {
;     ...
; #pragma unroll
;         for (int j = 0; j < 4; ++j) {
;             f32x4 h;
;             if constexpr (SRC_F32) h = S.h32[i][j];
;             else { const v2u hw = S.hb[i][j]; h.x = bf_lo(hw.x); h.y = bf_hi(hw.x); h.z = bf_lo(hw.y); h.w = bf_hi(hw.y); }
;             const v2u fw = S.fw[i][j];
;             f32x4 v; v.x = h.x + bf_lo(fw.x) * rs * g[j].x; v.y = h.y + bf_hi(fw.x) * rs * g[j].y; v.z = h.z + bf_lo(fw.y) * rs * g[j].z; v.w = h.w + bf_hi(fw.y) * rs * g[j].w;
;             if (FINAL) __builtin_nontemporal_store(v, (f32x4*)(out32 + (size_t)(rb + i) * D) + lane + 64 * j);
;             else { v2u o; o.x = pk2(v.x, v.y); o.y = pk2(v.z, v.w); ((v2u*)(hb_out + (size_t)(rb + i) * D) + lane)[64 * j] = o; s2 += (v.x * v.x + v.y * v.y) + (v.z * v.z + v.w * v.w); }
	v_fma_f32 v168, v170, v10, v168
	v_fma_f32 v169, v171, v11, v169
	v_fma_f32 v184, v168, v168, v184
	v_fma_f32 v184, v169, v169, v184
	v_cvt_pk_bf16_f32 v36, v168, v169
	v_lshlrev_b32_e32 v168, 16, v37
	v_and_b32_e32 v169, 0xffff0000, v37
	v_lshlrev_b32_e32 v170, 16, v69
	v_and_b32_e32 v171, 0xffff0000, v69
	v_mul_f32_e32 v170, s3, v170
	v_mul_f32_e32 v171, s3, v171
	v_fma_f32 v168, v170, v12, v168
	v_fma_f32 v169, v171, v13, v169
	v_fma_f32 v184, v168, v168, v184
	v_fma_f32 v184, v169, v169, v184
	v_cvt_pk_bf16_f32 v37, v168, v169
	v_lshlrev_b32_e32 v168, 16, v38
	v_and_b32_e32 v169, 0xffff0000, v38
	v_lshlrev_b32_e32 v170, 16, v70
	v_and_b32_e32 v171, 0xffff0000, v70
	v_mul_f32_e32 v170, s3, v170
	v_mul_f32_e32 v171, s3, v171
	v_fma_f32 v168, v170, v14, v168
	v_fma_f32 v169, v171, v15, v169
	v_fma_f32 v184, v168, v168, v184
	v_fma_f32 v184, v169, v169, v184
	v_cvt_pk_bf16_f32 v38, v168, v169
	v_lshlrev_b32_e32 v168, 16, v39
	v_and_b32_e32 v169, 0xffff0000, v39
	v_lshlrev_b32_e32 v170, 16, v71
	v_and_b32_e32 v171, 0xffff0000, v71
	v_mul_f32_e32 v170, s3, v170
	v_mul_f32_e32 v171, s3, v171
	v_fma_f32 v168, v170, v16, v168
	v_fma_f32 v169, v171, v17, v169
	v_fma_f32 v184, v168, v168, v184
	v_fma_f32 v184, v169, v169, v184
	v_cvt_pk_bf16_f32 v39, v168, v169
	global_store_dwordx4 v18, v[32:35], s[0:1]
	global_store_dwordx4 v18, v[36:39], s[0:1] offset:1024
	v_lshlrev_b32_e32 v168, 16, v40
	v_and_b32_e32 v169, 0xffff0000, v40
	v_lshlrev_b32_e32 v170, 16, v72
	v_and_b32_e32 v171, 0xffff0000, v72
	v_mul_f32_e32 v170, s24, v170
	v_mul_f32_e32 v171, s24, v171
	v_fma_f32 v168, v170, v2, v168
	v_fma_f32 v169, v171, v3, v169
	v_fma_f32 v185, v168, v168, v185
	v_fma_f32 v185, v169, v169, v185
	v_cvt_pk_bf16_f32 v40, v168, v169
	v_lshlrev_b32_e32 v168, 16, v41
	v_and_b32_e32 v169, 0xffff0000, v41
	v_lshlrev_b32_e32 v170, 16, v73
	v_and_b32_e32 v171, 0xffff0000, v73
	v_mul_f32_e32 v170, s24, v170
	v_mul_f32_e32 v171, s24, v171
	v_fma_f32 v168, v170, v4, v168
	v_fma_f32 v169, v171, v5, v169
	v_fma_f32 v185, v168, v168, v185
	v_fma_f32 v185, v169, v169, v185
	v_cvt_pk_bf16_f32 v41, v168, v169
	v_lshlrev_b32_e32 v168, 16, v42
	v_and_b32_e32 v169, 0xffff0000, v42
	v_lshlrev_b32_e32 v170, 16, v74
	v_and_b32_e32 v171, 0xffff0000, v74
	v_mul_f32_e32 v170, s24, v170
	v_mul_f32_e32 v171, s24, v171
	v_fma_f32 v168, v170, v6, v168
	v_fma_f32 v169, v171, v7, v169
	v_fma_f32 v185, v168, v168, v185
	v_fma_f32 v185, v169, v169, v185
	v_cvt_pk_bf16_f32 v42, v168, v169
	v_lshlrev_b32_e32 v168, 16, v43
	v_and_b32_e32 v169, 0xffff0000, v43
	v_lshlrev_b32_e32 v170, 16, v75
	v_and_b32_e32 v171, 0xffff0000, v75
	v_mul_f32_e32 v170, s24, v170
	v_mul_f32_e32 v171, s24, v171
	v_fma_f32 v168, v170, v8, v168
	v_fma_f32 v169, v171, v9, v169
	v_fma_f32 v185, v168, v168, v185
	v_fma_f32 v185, v169, v169, v185
	v_cvt_pk_bf16_f32 v43, v168, v169
	v_lshlrev_b32_e32 v168, 16, v44
	v_and_b32_e32 v169, 0xffff0000, v44
	v_lshlrev_b32_e32 v170, 16, v76
	v_and_b32_e32 v171, 0xffff0000, v76
	v_mul_f32_e32 v170, s24, v170
	v_mul_f32_e32 v171, s24, v171
	v_fma_f32 v168, v170, v10, v168
	v_fma_f32 v169, v171, v11, v169
	v_fma_f32 v185, v168, v168, v185
	v_fma_f32 v185, v169, v169, v185
	v_cvt_pk_bf16_f32 v44, v168, v169
	v_lshlrev_b32_e32 v168, 16, v45
	v_and_b32_e32 v169, 0xffff0000, v45
	v_lshlrev_b32_e32 v170, 16, v77
	v_and_b32_e32 v171, 0xffff0000, v77
	v_mul_f32_e32 v170, s24, v170
	v_mul_f32_e32 v171, s24, v171
	v_fma_f32 v168, v170, v12, v168
	v_fma_f32 v169, v171, v13, v169
	v_fma_f32 v185, v168, v168, v185
	v_fma_f32 v185, v169, v169, v185
	v_cvt_pk_bf16_f32 v45, v168, v169
	v_lshlrev_b32_e32 v168, 16, v46
	v_and_b32_e32 v169, 0xffff0000, v46
	v_lshlrev_b32_e32 v170, 16, v78
	v_and_b32_e32 v171, 0xffff0000, v78
	v_mul_f32_e32 v170, s24, v170
	v_mul_f32_e32 v171, s24, v171
	v_fma_f32 v168, v170, v14, v168
	v_fma_f32 v169, v171, v15, v169
	v_fma_f32 v185, v168, v168, v185
	v_fma_f32 v185, v169, v169, v185
	v_cvt_pk_bf16_f32 v46, v168, v169
	v_lshlrev_b32_e32 v168, 16, v47
	v_and_b32_e32 v169, 0xffff0000, v47
	v_lshlrev_b32_e32 v170, 16, v79
	v_and_b32_e32 v171, 0xffff0000, v79
	v_mul_f32_e32 v170, s24, v170
	v_mul_f32_e32 v171, s24, v171
	v_fma_f32 v168, v170, v16, v168
	v_fma_f32 v169, v171, v17, v169
	v_fma_f32 v185, v168, v168, v185
	v_fma_f32 v185, v169, v169, v185
	v_cvt_pk_bf16_f32 v47, v168, v169
	global_store_dwordx4 v18, v[40:43], s[0:1] offset:2048
	global_store_dwordx4 v18, v[44:47], s[0:1] offset:3072
	v_lshlrev_b32_e32 v168, 16, v48
	v_and_b32_e32 v169, 0xffff0000, v48
	v_lshlrev_b32_e32 v170, 16, v80
	v_and_b32_e32 v171, 0xffff0000, v80
	v_mul_f32_e32 v170, s98, v170
	v_mul_f32_e32 v171, s98, v171
	v_fma_f32 v168, v170, v2, v168
	v_fma_f32 v169, v171, v3, v169
	v_fma_f32 v186, v168, v168, v186
	v_fma_f32 v186, v169, v169, v186
	v_cvt_pk_bf16_f32 v48, v168, v169
	v_lshlrev_b32_e32 v168, 16, v49
	v_and_b32_e32 v169, 0xffff0000, v49
	v_lshlrev_b32_e32 v170, 16, v81
	v_and_b32_e32 v171, 0xffff0000, v81
	v_mul_f32_e32 v170, s98, v170
	v_mul_f32_e32 v171, s98, v171
	v_fma_f32 v168, v170, v4, v168
	v_fma_f32 v169, v171, v5, v169
	v_fma_f32 v186, v168, v168, v186
	v_fma_f32 v186, v169, v169, v186
	v_cvt_pk_bf16_f32 v49, v168, v169
	v_lshlrev_b32_e32 v168, 16, v50
	v_and_b32_e32 v169, 0xffff0000, v50
	v_lshlrev_b32_e32 v170, 16, v82
	v_and_b32_e32 v171, 0xffff0000, v82
	v_mul_f32_e32 v170, s98, v170
	v_mul_f32_e32 v171, s98, v171
	v_fma_f32 v168, v170, v6, v168
	v_fma_f32 v169, v171, v7, v169
	v_fma_f32 v186, v168, v168, v186
	v_fma_f32 v186, v169, v169, v186
	v_cvt_pk_bf16_f32 v50, v168, v169
	v_lshlrev_b32_e32 v168, 16, v51
	v_and_b32_e32 v169, 0xffff0000, v51
; __device__ __forceinline__ float bf_lo(unsigned w) { return __uint_as_float(w << 16); }
; __device__ __forceinline__ float bf_hi(unsigned w) { return __uint_as_float(w & 0xffff0000u); }
; __device__ __forceinline__ unsigned pk2(float lo, float hi) { bf16x2_t r = __builtin_convertvector((f32x2_t){lo, hi}, bf16x2_t); return __builtin_bit_cast(unsigned, r); }
; template <bool SRC_F32, bool FINAL, int R> __device__ __forceinline__ void ew_compute(const EwSet<SRC_F32, R>& S, int rb, const f32x4 (&g)[4], bf16* hb_out, float* out32, float scale, float* rs_out, int lane) {
;     ...
; #pragma unroll
;         for (int j = 0; j < 4; ++j) {
;             f32x4 h;
;             if constexpr (SRC_F32) h = S.h32[i][j];
;             else { const v2u hw = S.hb[i][j]; h.x = bf_lo(hw.x); h.y = bf_hi(hw.x); h.z = bf_lo(hw.y); h.w = bf_hi(hw.y); }
;             const v2u fw = S.fw[i][j];
;             f32x4 v; v.x = h.x + bf_lo(fw.x) * rs * g[j].x; v.y = h.y + bf_hi(fw.x) * rs * g[j].y; v.z = h.z + bf_lo(fw.y) * rs * g[j].z; v.w = h.w + bf_hi(fw.y) * rs * g[j].w;
;             if (FINAL) __builtin_nontemporal_store(v, (f32x4*)(out32 + (size_t)(rb + i) * D) + lane + 64 * j);
;             else { v2u o; o.x = pk2(v.x, v.y); o.y = pk2(v.z, v.w); ((v2u*)(hb_out + (size_t)(rb + i) * D) + lane)[64 * j] = o; s2 += (v.x * v.x + v.y * v.y) + (v.z * v.z + v.w * v.w); }
;         }
;         if (!FINAL) { const float tot = wave_sum(s2); if (lane == 0) rs_out[rb + i] = 1.0f / sqrtf(tot * (1.f / D) + EPS); }
	v_lshlrev_b32_e32 v170, 16, v83
	v_and_b32_e32 v171, 0xffff0000, v83
	v_mul_f32_e32 v170, s98, v170
	v_mul_f32_e32 v171, s98, v171
	v_fma_f32 v168, v170, v8, v168
	v_fma_f32 v169, v171, v9, v169
	v_fma_f32 v186, v168, v168, v186
	v_fma_f32 v186, v169, v169, v186
	v_cvt_pk_bf16_f32 v51, v168, v169
	v_lshlrev_b32_e32 v168, 16, v52
	v_and_b32_e32 v169, 0xffff0000, v52
	v_lshlrev_b32_e32 v170, 16, v84
	v_and_b32_e32 v171, 0xffff0000, v84
	v_mul_f32_e32 v170, s98, v170
	v_mul_f32_e32 v171, s98, v171
	v_fma_f32 v168, v170, v10, v168
	v_fma_f32 v169, v171, v11, v169
	v_fma_f32 v186, v168, v168, v186
	v_fma_f32 v186, v169, v169, v186
	v_cvt_pk_bf16_f32 v52, v168, v169
	v_lshlrev_b32_e32 v168, 16, v53
	v_and_b32_e32 v169, 0xffff0000, v53
	v_lshlrev_b32_e32 v170, 16, v85
	v_and_b32_e32 v171, 0xffff0000, v85
	v_mul_f32_e32 v170, s98, v170
	v_mul_f32_e32 v171, s98, v171
	v_fma_f32 v168, v170, v12, v168
	v_fma_f32 v169, v171, v13, v169
	v_fma_f32 v186, v168, v168, v186
	v_fma_f32 v186, v169, v169, v186
	v_cvt_pk_bf16_f32 v53, v168, v169
	v_lshlrev_b32_e32 v168, 16, v54
	v_and_b32_e32 v169, 0xffff0000, v54
	v_lshlrev_b32_e32 v170, 16, v86
	v_and_b32_e32 v171, 0xffff0000, v86
	v_mul_f32_e32 v170, s98, v170
	v_mul_f32_e32 v171, s98, v171
	v_fma_f32 v168, v170, v14, v168
	v_fma_f32 v169, v171, v15, v169
	v_fma_f32 v186, v168, v168, v186
	v_fma_f32 v186, v169, v169, v186
	v_cvt_pk_bf16_f32 v54, v168, v169
	v_lshlrev_b32_e32 v168, 16, v55
	v_and_b32_e32 v169, 0xffff0000, v55
	v_lshlrev_b32_e32 v170, 16, v87
	v_and_b32_e32 v171, 0xffff0000, v87
	v_mul_f32_e32 v170, s98, v170
	v_mul_f32_e32 v171, s98, v171
	v_fma_f32 v168, v170, v16, v168
	v_fma_f32 v169, v171, v17, v169
	v_fma_f32 v186, v168, v168, v186
	v_fma_f32 v186, v169, v169, v186
	v_cvt_pk_bf16_f32 v55, v168, v169
	global_store_dwordx4 v19, v[48:51], s[0:1]
	global_store_dwordx4 v19, v[52:55], s[0:1] offset:1024
	v_lshlrev_b32_e32 v168, 16, v56
	v_and_b32_e32 v169, 0xffff0000, v56
	v_lshlrev_b32_e32 v170, 16, v88
	v_and_b32_e32 v171, 0xffff0000, v88
	v_mul_f32_e32 v170, s101, v170
	v_mul_f32_e32 v171, s101, v171
	v_fma_f32 v168, v170, v2, v168
	v_fma_f32 v169, v171, v3, v169
	v_fma_f32 v187, v168, v168, v187
	v_fma_f32 v187, v169, v169, v187
	v_cvt_pk_bf16_f32 v56, v168, v169
	v_lshlrev_b32_e32 v168, 16, v57
	v_and_b32_e32 v169, 0xffff0000, v57
	v_lshlrev_b32_e32 v170, 16, v89
	v_and_b32_e32 v171, 0xffff0000, v89
	v_mul_f32_e32 v170, s101, v170
	v_mul_f32_e32 v171, s101, v171
	v_fma_f32 v168, v170, v4, v168
	v_fma_f32 v169, v171, v5, v169
	v_fma_f32 v187, v168, v168, v187
	v_fma_f32 v187, v169, v169, v187
	v_cvt_pk_bf16_f32 v57, v168, v169
	v_lshlrev_b32_e32 v168, 16, v58
	v_and_b32_e32 v169, 0xffff0000, v58
	v_lshlrev_b32_e32 v170, 16, v90
	v_and_b32_e32 v171, 0xffff0000, v90
	v_mul_f32_e32 v170, s101, v170
	v_mul_f32_e32 v171, s101, v171
	v_fma_f32 v168, v170, v6, v168
	v_fma_f32 v169, v171, v7, v169
	v_fma_f32 v187, v168, v168, v187
	v_fma_f32 v187, v169, v169, v187
	v_cvt_pk_bf16_f32 v58, v168, v169
	v_lshlrev_b32_e32 v168, 16, v59
	v_and_b32_e32 v169, 0xffff0000, v59
	v_lshlrev_b32_e32 v170, 16, v91
	v_and_b32_e32 v171, 0xffff0000, v91
	v_mul_f32_e32 v170, s101, v170
	v_mul_f32_e32 v171, s101, v171
	v_fma_f32 v168, v170, v8, v168
	v_fma_f32 v169, v171, v9, v169
	v_fma_f32 v187, v168, v168, v187
	v_fma_f32 v187, v169, v169, v187
	v_cvt_pk_bf16_f32 v59, v168, v169
	v_lshlrev_b32_e32 v168, 16, v60
	v_and_b32_e32 v169, 0xffff0000, v60
	v_lshlrev_b32_e32 v170, 16, v92
	v_and_b32_e32 v171, 0xffff0000, v92
	v_mul_f32_e32 v170, s101, v170
	v_mul_f32_e32 v171, s101, v171
	v_fma_f32 v168, v170, v10, v168
	v_fma_f32 v169, v171, v11, v169
	v_fma_f32 v187, v168, v168, v187
	v_fma_f32 v187, v169, v169, v187
	v_cvt_pk_bf16_f32 v60, v168, v169
	v_lshlrev_b32_e32 v168, 16, v61
	v_and_b32_e32 v169, 0xffff0000, v61
	v_lshlrev_b32_e32 v170, 16, v93
	v_and_b32_e32 v171, 0xffff0000, v93
	v_mul_f32_e32 v170, s101, v170
	v_mul_f32_e32 v171, s101, v171
	v_fma_f32 v168, v170, v12, v168
	v_fma_f32 v169, v171, v13, v169
	v_fma_f32 v187, v168, v168, v187
	v_fma_f32 v187, v169, v169, v187
	v_cvt_pk_bf16_f32 v61, v168, v169
	v_lshlrev_b32_e32 v168, 16, v62
	v_and_b32_e32 v169, 0xffff0000, v62
	v_lshlrev_b32_e32 v170, 16, v94
	v_and_b32_e32 v171, 0xffff0000, v94
	v_mul_f32_e32 v170, s101, v170
	v_mul_f32_e32 v171, s101, v171
	v_fma_f32 v168, v170, v14, v168
	v_fma_f32 v169, v171, v15, v169
	v_fma_f32 v187, v168, v168, v187
	v_fma_f32 v187, v169, v169, v187
	v_cvt_pk_bf16_f32 v62, v168, v169
	v_lshlrev_b32_e32 v168, 16, v63
	v_and_b32_e32 v169, 0xffff0000, v63
	v_lshlrev_b32_e32 v170, 16, v95
	v_and_b32_e32 v171, 0xffff0000, v95
	v_mul_f32_e32 v170, s101, v170
	v_mul_f32_e32 v171, s101, v171
	v_fma_f32 v168, v170, v16, v168
	v_fma_f32 v169, v171, v17, v169
	v_fma_f32 v187, v168, v168, v187
	v_fma_f32 v187, v169, v169, v187
	v_cvt_pk_bf16_f32 v63, v168, v169
	global_store_dwordx4 v19, v[56:59], s[0:1] offset:2048
	global_store_dwordx4 v19, v[60:63], s[0:1] offset:3072
	s_nop 1
	v_add_f32_dpp v184, v184, v184 quad_perm:[1,0,3,2] row_mask:0xf bank_mask:0xf
	v_add_f32_dpp v185, v185, v185 quad_perm:[1,0,3,2] row_mask:0xf bank_mask:0xf
	v_add_f32_dpp v186, v186, v186 quad_perm:[1,0,3,2] row_mask:0xf bank_mask:0xf
	v_add_f32_dpp v187, v187, v187 quad_perm:[1,0,3,2] row_mask:0xf bank_mask:0xf
	v_add_f32_dpp v184, v184, v184 quad_perm:[2,3,0,1] row_mask:0xf bank_mask:0xf
	v_add_f32_dpp v185, v185, v185 quad_perm:[2,3,0,1] row_mask:0xf bank_mask:0xf
	v_add_f32_dpp v186, v186, v186 quad_perm:[2,3,0,1] row_mask:0xf bank_mask:0xf
	v_add_f32_dpp v187, v187, v187 quad_perm:[2,3,0,1] row_mask:0xf bank_mask:0xf
; __device__ __forceinline__ float bf_lo(unsigned w) { return __uint_as_float(w << 16); }
; __device__ __forceinline__ float bf_hi(unsigned w) { return __uint_as_float(w & 0xffff0000u); }
; template <bool SRC_F32, int R> __device__ __forceinline__ void ew_load(EwSet<SRC_F32, R>& S, int rb, const float* hsrc32, const bf16* hsrcb, const bf16* f, const float* part, int lane) {
; #pragma unroll
;     for (int i = 0; i < R; ++i) S.p[i] = (lane < 16) ? part[(size_t)(rb + i) * 16 + lane] : 0.f;
; #pragma unroll
;     for (int i = 0; i < R; ++i)
; #pragma unroll
;         for (int j = 0; j < 4; ++j) {
;             S.fw[i][j] = ((const v2u*)(f + (size_t)(rb + i) * D) + lane)[64 * j];
;             if constexpr (SRC_F32) S.h32[i][j] = __builtin_nontemporal_load((const f32x4*)(hsrc32 + (size_t)(rb + i) * D) + lane + 64 * j);
;             else S.hb[i][j] = ((const v2u*)(hsrcb + (size_t)(rb + i) * D) + lane)[64 * j];
;         }
; }
; template <bool SRC_F32, bool FINAL, int R> __device__ __forceinline__ void ew_compute(const EwSet<SRC_F32, R>& S, int rb, const f32x4 (&g)[4], bf16* hb_out, float* out32, float scale, float* rs_out, int lane) {
; #pragma unroll
;     for (int i = 0; i < R; ++i) {
;         float q = S.p[i];
;         q += __shfl_xor(q, 1); q += __shfl_xor(q, 2); q += __shfl_xor(q, 4); q += __shfl_xor(q, 8);
;         const float ss = __shfl(q, 0);
;         const float rs = scale / sqrtf(ss * (1.f / D) + EPS);
;         float s2 = 0.f;
; #pragma unroll
;         for (int j = 0; j < 4; ++j) {
;             f32x4 h;
;             if constexpr (SRC_F32) h = S.h32[i][j];
;             else { const v2u hw = S.hb[i][j]; h.x = bf_lo(hw.x); h.y = bf_hi(hw.x); h.z = bf_lo(hw.y); h.w = bf_hi(hw.y); }
;             const v2u fw = S.fw[i][j];
;             f32x4 v; v.x = h.x + bf_lo(fw.x) * rs * g[j].x; v.y = h.y + bf_hi(fw.x) * rs * g[j].y; v.z = h.z + bf_lo(fw.y) * rs * g[j].z; v.w = h.w + bf_hi(fw.y) * rs * g[j].w;
;             if (FINAL) __builtin_nontemporal_store(v, (f32x4*)(out32 + (size_t)(rb + i) * D) + lane + 64 * j);
;             else { v2u o; o.x = pk2(v.x, v.y); o.y = pk2(v.z, v.w); ((v2u*)(hb_out + (size_t)(rb + i) * D) + lane)[64 * j] = o; s2 += (v.x * v.x + v.y * v.y) + (v.z * v.z + v.w * v.w); }
;         }
;         if (!FINAL) { const float tot = wave_sum(s2); if (lane == 0) rs_out[rb + i] = 1.0f / sqrtf(tot * (1.f / D) + EPS); }
	v_add_f32_dpp v184, v184, v184 row_half_mirror row_mask:0xf bank_mask:0xf
	v_add_f32_dpp v185, v185, v185 row_half_mirror row_mask:0xf bank_mask:0xf
	v_add_f32_dpp v186, v186, v186 row_half_mirror row_mask:0xf bank_mask:0xf
	v_add_f32_dpp v187, v187, v187 row_half_mirror row_mask:0xf bank_mask:0xf
	v_add_f32_dpp v184, v184, v184 row_mirror row_mask:0xf bank_mask:0xf
	v_add_f32_dpp v185, v185, v185 row_mirror row_mask:0xf bank_mask:0xf
	v_add_f32_dpp v186, v186, v186 row_mirror row_mask:0xf bank_mask:0xf
	v_add_f32_dpp v187, v187, v187 row_mirror row_mask:0xf bank_mask:0xf
	v_add_f32_dpp v184, v184, v184 row_bcast:15 row_mask:0xa bank_mask:0xf
	v_add_f32_dpp v185, v185, v185 row_bcast:15 row_mask:0xa bank_mask:0xf
	v_add_f32_dpp v186, v186, v186 row_bcast:15 row_mask:0xa bank_mask:0xf
	v_add_f32_dpp v187, v187, v187 row_bcast:15 row_mask:0xa bank_mask:0xf
	v_add_f32_dpp v184, v184, v184 row_bcast:31 row_mask:0xc bank_mask:0xf
	v_add_f32_dpp v185, v185, v185 row_bcast:31 row_mask:0xc bank_mask:0xf
	v_add_f32_dpp v186, v186, v186 row_bcast:31 row_mask:0xc bank_mask:0xf
	v_add_f32_dpp v187, v187, v187 row_bcast:31 row_mask:0xc bank_mask:0xf
	s_nop 1
	v_readlane_b32 s3, v184, 63
	v_readlane_b32 s24, v185, 63
	v_readlane_b32 s98, v186, 63
	v_readlane_b32 s101, v187, 63
	s_nop 3
	v_writelane_b32 v188, s3, 0
	v_writelane_b32 v188, s24, 1
	v_writelane_b32 v188, s98, 2
	v_writelane_b32 v188, s101, 3
	s_nop 1
	v_mul_f32_e32 v188, 0x3a800000, v188
	v_add_f32_e32 v188, 0x358637bd, v188
	v_rsq_f32_e32 v188, v188
	s_mov_b64 exec, 15
	global_store_dword v21, v188, s[14:15]
	s_mov_b64 exec, -1
	s_add_u32 s27, s26, 2048
	s_lshl_b32 s22, s27, 11
	v_lshl_add_u32 v18, v0, 4, s22
	v_add_u32_e32 v19, 0x1000, v18
	s_lshl_b32 s22, s27, 6
	v_lshl_add_u32 v20, v0, 2, s22
	s_lshl_b32 s22, s27, 2
	v_lshl_add_u32 v21, v0, 2, s22
	global_load_dwordx4 v[32:35], v18, s[0:1]
	global_load_dwordx4 v[36:39], v18, s[0:1] offset:1024
	global_load_dwordx4 v[64:67], v18, s[4:5]
	global_load_dwordx4 v[68:71], v18, s[4:5] offset:1024
	global_load_dwordx4 v[40:43], v18, s[0:1] offset:2048
	global_load_dwordx4 v[44:47], v18, s[0:1] offset:3072
	global_load_dwordx4 v[72:75], v18, s[4:5] offset:2048
	global_load_dwordx4 v[76:79], v18, s[4:5] offset:3072
	global_load_dwordx4 v[48:51], v19, s[0:1]
	global_load_dwordx4 v[52:55], v19, s[0:1] offset:1024
	global_load_dwordx4 v[80:83], v19, s[4:5]
	global_load_dwordx4 v[84:87], v19, s[4:5] offset:1024
	global_load_dwordx4 v[56:59], v19, s[0:1] offset:2048
	global_load_dwordx4 v[60:63], v19, s[0:1] offset:3072
	global_load_dwordx4 v[88:91], v19, s[4:5] offset:2048
	global_load_dwordx4 v[92:95], v19, s[4:5] offset:3072
	global_load_dword v96, v20, s[6:7]
	s_waitcnt vmcnt(26)
	v_add_f32_dpp v164, v164, v164 quad_perm:[1,0,3,2] row_mask:0xf bank_mask:0xf
	s_nop 1
	v_add_f32_dpp v164, v164, v164 quad_perm:[2,3,0,1] row_mask:0xf bank_mask:0xf
	s_nop 1
	v_add_f32_dpp v164, v164, v164 row_half_mirror row_mask:0xf bank_mask:0xf
	s_nop 1
	v_add_f32_dpp v164, v164, v164 row_mirror row_mask:0xf bank_mask:0xf
	s_nop 1
	v_mul_f32_e32 v164, 0x3a800000, v164
	v_add_f32_e32 v164, 0x358637bd, v164
	v_rsq_f32_e32 v164, v164
	s_nop 0
	v_readlane_b32 s3, v164, 0
	v_readlane_b32 s24, v164, 16
	v_readlane_b32 s98, v164, 32
	v_readlane_b32 s101, v164, 48
	s_nop 1
	v_mov_b32_e32 v184, 0
	v_mov_b32_e32 v185, 0
	v_mov_b32_e32 v186, 0
	v_mov_b32_e32 v187, 0
	v_lshlrev_b32_e32 v168, 16, v100
	v_and_b32_e32 v169, 0xffff0000, v100
	v_lshlrev_b32_e32 v170, 16, v132
	v_and_b32_e32 v171, 0xffff0000, v132
	v_mul_f32_e32 v170, s3, v170
	v_mul_f32_e32 v171, s3, v171
	v_fma_f32 v168, v170, v2, v168
	v_fma_f32 v169, v171, v3, v169
	v_fma_f32 v184, v168, v168, v184
	v_fma_f32 v184, v169, v169, v184
	v_cvt_pk_bf16_f32 v100, v168, v169
	v_lshlrev_b32_e32 v168, 16, v101
	v_and_b32_e32 v169, 0xffff0000, v101
	v_lshlrev_b32_e32 v170, 16, v133
	v_and_b32_e32 v171, 0xffff0000, v133
	v_mul_f32_e32 v170, s3, v170
	v_mul_f32_e32 v171, s3, v171
	v_fma_f32 v168, v170, v4, v168
	v_fma_f32 v169, v171, v5, v169
	v_fma_f32 v184, v168, v168, v184
	v_fma_f32 v184, v169, v169, v184
	v_cvt_pk_bf16_f32 v101, v168, v169
	v_lshlrev_b32_e32 v168, 16, v102
	v_and_b32_e32 v169, 0xffff0000, v102
	v_lshlrev_b32_e32 v170, 16, v134
	v_and_b32_e32 v171, 0xffff0000, v134
	v_mul_f32_e32 v170, s3, v170
	v_mul_f32_e32 v171, s3, v171
	v_fma_f32 v168, v170, v6, v168
	v_fma_f32 v169, v171, v7, v169
	v_fma_f32 v184, v168, v168, v184
	v_fma_f32 v184, v169, v169, v184
	v_cvt_pk_bf16_f32 v102, v168, v169
	v_lshlrev_b32_e32 v168, 16, v103
	v_and_b32_e32 v169, 0xffff0000, v103
	v_lshlrev_b32_e32 v170, 16, v135
	v_and_b32_e32 v171, 0xffff0000, v135
	v_mul_f32_e32 v170, s3, v170
	v_mul_f32_e32 v171, s3, v171
	v_fma_f32 v168, v170, v8, v168
	v_fma_f32 v169, v171, v9, v169
	v_fma_f32 v184, v168, v168, v184
	v_fma_f32 v184, v169, v169, v184
	v_cvt_pk_bf16_f32 v103, v168, v169
	v_lshlrev_b32_e32 v168, 16, v104
	v_and_b32_e32 v169, 0xffff0000, v104
	v_lshlrev_b32_e32 v170, 16, v136
	v_and_b32_e32 v171, 0xffff0000, v136
	v_mul_f32_e32 v170, s3, v170
	v_mul_f32_e32 v171, s3, v171
	v_fma_f32 v168, v170, v10, v168
	v_fma_f32 v169, v171, v11, v169
	v_fma_f32 v184, v168, v168, v184
	v_fma_f32 v184, v169, v169, v184
	v_cvt_pk_bf16_f32 v104, v168, v169
	v_lshlrev_b32_e32 v168, 16, v105
	v_and_b32_e32 v169, 0xffff0000, v105
	v_lshlrev_b32_e32 v170, 16, v137
	v_and_b32_e32 v171, 0xffff0000, v137
	v_mul_f32_e32 v170, s3, v170
	v_mul_f32_e32 v171, s3, v171
	v_fma_f32 v168, v170, v12, v168
	v_fma_f32 v169, v171, v13, v169
	v_fma_f32 v184, v168, v168, v184
	v_fma_f32 v184, v169, v169, v184
	v_cvt_pk_bf16_f32 v105, v168, v169
; __device__ __forceinline__ float bf_lo(unsigned w) { return __uint_as_float(w << 16); }
; __device__ __forceinline__ float bf_hi(unsigned w) { return __uint_as_float(w & 0xffff0000u); }
; __device__ __forceinline__ unsigned pk2(float lo, float hi) { bf16x2_t r = __builtin_convertvector((f32x2_t){lo, hi}, bf16x2_t); return __builtin_bit_cast(unsigned, r); }
; template <bool SRC_F32, bool FINAL, int R> __device__ __forceinline__ void ew_compute(const EwSet<SRC_F32, R>& S, int rb, const f32x4 (&g)[4], bf16* hb_out, float* out32, float scale, float* rs_out, int lane) {
;     ...
; #pragma unroll
;         for (int j = 0; j < 4; ++j) {
;             f32x4 h;
;             if constexpr (SRC_F32) h = S.h32[i][j];
;             else { const v2u hw = S.hb[i][j]; h.x = bf_lo(hw.x); h.y = bf_hi(hw.x); h.z = bf_lo(hw.y); h.w = bf_hi(hw.y); }
;             const v2u fw = S.fw[i][j];
;             f32x4 v; v.x = h.x + bf_lo(fw.x) * rs * g[j].x; v.y = h.y + bf_hi(fw.x) * rs * g[j].y; v.z = h.z + bf_lo(fw.y) * rs * g[j].z; v.w = h.w + bf_hi(fw.y) * rs * g[j].w;
;             if (FINAL) __builtin_nontemporal_store(v, (f32x4*)(out32 + (size_t)(rb + i) * D) + lane + 64 * j);
;             else { v2u o; o.x = pk2(v.x, v.y); o.y = pk2(v.z, v.w); ((v2u*)(hb_out + (size_t)(rb + i) * D) + lane)[64 * j] = o; s2 += (v.x * v.x + v.y * v.y) + (v.z * v.z + v.w * v.w); }
	v_lshlrev_b32_e32 v168, 16, v106
	v_and_b32_e32 v169, 0xffff0000, v106
	v_lshlrev_b32_e32 v170, 16, v138
	v_and_b32_e32 v171, 0xffff0000, v138
	v_mul_f32_e32 v170, s3, v170
	v_mul_f32_e32 v171, s3, v171
	v_fma_f32 v168, v170, v14, v168
	v_fma_f32 v169, v171, v15, v169
	v_fma_f32 v184, v168, v168, v184
	v_fma_f32 v184, v169, v169, v184
	v_cvt_pk_bf16_f32 v106, v168, v169
	v_lshlrev_b32_e32 v168, 16, v107
	v_and_b32_e32 v169, 0xffff0000, v107
	v_lshlrev_b32_e32 v170, 16, v139
	v_and_b32_e32 v171, 0xffff0000, v139
	v_mul_f32_e32 v170, s3, v170
	v_mul_f32_e32 v171, s3, v171
	v_fma_f32 v168, v170, v16, v168
	v_fma_f32 v169, v171, v17, v169
	v_fma_f32 v184, v168, v168, v184
	v_fma_f32 v184, v169, v169, v184
	v_cvt_pk_bf16_f32 v107, v168, v169
	global_store_dwordx4 v23, v[100:103], s[0:1]
	global_store_dwordx4 v23, v[104:107], s[0:1] offset:1024
	v_lshlrev_b32_e32 v168, 16, v108
	v_and_b32_e32 v169, 0xffff0000, v108
	v_lshlrev_b32_e32 v170, 16, v140
	v_and_b32_e32 v171, 0xffff0000, v140
	v_mul_f32_e32 v170, s24, v170
	v_mul_f32_e32 v171, s24, v171
	v_fma_f32 v168, v170, v2, v168
	v_fma_f32 v169, v171, v3, v169
	v_fma_f32 v185, v168, v168, v185
	v_fma_f32 v185, v169, v169, v185
	v_cvt_pk_bf16_f32 v108, v168, v169
	v_lshlrev_b32_e32 v168, 16, v109
	v_and_b32_e32 v169, 0xffff0000, v109
	v_lshlrev_b32_e32 v170, 16, v141
	v_and_b32_e32 v171, 0xffff0000, v141
	v_mul_f32_e32 v170, s24, v170
	v_mul_f32_e32 v171, s24, v171
	v_fma_f32 v168, v170, v4, v168
	v_fma_f32 v169, v171, v5, v169
	v_fma_f32 v185, v168, v168, v185
	v_fma_f32 v185, v169, v169, v185
	v_cvt_pk_bf16_f32 v109, v168, v169
	v_lshlrev_b32_e32 v168, 16, v110
	v_and_b32_e32 v169, 0xffff0000, v110
	v_lshlrev_b32_e32 v170, 16, v142
	v_and_b32_e32 v171, 0xffff0000, v142
	v_mul_f32_e32 v170, s24, v170
	v_mul_f32_e32 v171, s24, v171
	v_fma_f32 v168, v170, v6, v168
	v_fma_f32 v169, v171, v7, v169
	v_fma_f32 v185, v168, v168, v185
	v_fma_f32 v185, v169, v169, v185
	v_cvt_pk_bf16_f32 v110, v168, v169
	v_lshlrev_b32_e32 v168, 16, v111
	v_and_b32_e32 v169, 0xffff0000, v111
	v_lshlrev_b32_e32 v170, 16, v143
	v_and_b32_e32 v171, 0xffff0000, v143
	v_mul_f32_e32 v170, s24, v170
	v_mul_f32_e32 v171, s24, v171
	v_fma_f32 v168, v170, v8, v168
	v_fma_f32 v169, v171, v9, v169
	v_fma_f32 v185, v168, v168, v185
	v_fma_f32 v185, v169, v169, v185
	v_cvt_pk_bf16_f32 v111, v168, v169
	v_lshlrev_b32_e32 v168, 16, v112
	v_and_b32_e32 v169, 0xffff0000, v112
	v_lshlrev_b32_e32 v170, 16, v144
	v_and_b32_e32 v171, 0xffff0000, v144
	v_mul_f32_e32 v170, s24, v170
	v_mul_f32_e32 v171, s24, v171
	v_fma_f32 v168, v170, v10, v168
	v_fma_f32 v169, v171, v11, v169
	v_fma_f32 v185, v168, v168, v185
	v_fma_f32 v185, v169, v169, v185
	v_cvt_pk_bf16_f32 v112, v168, v169
	v_lshlrev_b32_e32 v168, 16, v113
	v_and_b32_e32 v169, 0xffff0000, v113
	v_lshlrev_b32_e32 v170, 16, v145
	v_and_b32_e32 v171, 0xffff0000, v145
	v_mul_f32_e32 v170, s24, v170
	v_mul_f32_e32 v171, s24, v171
	v_fma_f32 v168, v170, v12, v168
	v_fma_f32 v169, v171, v13, v169
	v_fma_f32 v185, v168, v168, v185
	v_fma_f32 v185, v169, v169, v185
	v_cvt_pk_bf16_f32 v113, v168, v169
	v_lshlrev_b32_e32 v168, 16, v114
	v_and_b32_e32 v169, 0xffff0000, v114
	v_lshlrev_b32_e32 v170, 16, v146
	v_and_b32_e32 v171, 0xffff0000, v146
	v_mul_f32_e32 v170, s24, v170
	v_mul_f32_e32 v171, s24, v171
	v_fma_f32 v168, v170, v14, v168
	v_fma_f32 v169, v171, v15, v169
	v_fma_f32 v185, v168, v168, v185
	v_fma_f32 v185, v169, v169, v185
	v_cvt_pk_bf16_f32 v114, v168, v169
	v_lshlrev_b32_e32 v168, 16, v115
	v_and_b32_e32 v169, 0xffff0000, v115
	v_lshlrev_b32_e32 v170, 16, v147
	v_and_b32_e32 v171, 0xffff0000, v147
	v_mul_f32_e32 v170, s24, v170
	v_mul_f32_e32 v171, s24, v171
	v_fma_f32 v168, v170, v16, v168
	v_fma_f32 v169, v171, v17, v169
	v_fma_f32 v185, v168, v168, v185
	v_fma_f32 v185, v169, v169, v185
	v_cvt_pk_bf16_f32 v115, v168, v169
	global_store_dwordx4 v23, v[108:111], s[0:1] offset:2048
	global_store_dwordx4 v23, v[112:115], s[0:1] offset:3072
	v_lshlrev_b32_e32 v168, 16, v116
	v_and_b32_e32 v169, 0xffff0000, v116
	v_lshlrev_b32_e32 v170, 16, v148
	v_and_b32_e32 v171, 0xffff0000, v148
	v_mul_f32_e32 v170, s98, v170
	v_mul_f32_e32 v171, s98, v171
	v_fma_f32 v168, v170, v2, v168
	v_fma_f32 v169, v171, v3, v169
	v_fma_f32 v186, v168, v168, v186
	v_fma_f32 v186, v169, v169, v186
	v_cvt_pk_bf16_f32 v116, v168, v169
	v_lshlrev_b32_e32 v168, 16, v117
	v_and_b32_e32 v169, 0xffff0000, v117
	v_lshlrev_b32_e32 v170, 16, v149
	v_and_b32_e32 v171, 0xffff0000, v149
	v_mul_f32_e32 v170, s98, v170
	v_mul_f32_e32 v171, s98, v171
	v_fma_f32 v168, v170, v4, v168
	v_fma_f32 v169, v171, v5, v169
	v_fma_f32 v186, v168, v168, v186
	v_fma_f32 v186, v169, v169, v186
	v_cvt_pk_bf16_f32 v117, v168, v169
	v_lshlrev_b32_e32 v168, 16, v118
	v_and_b32_e32 v169, 0xffff0000, v118
	v_lshlrev_b32_e32 v170, 16, v150
	v_and_b32_e32 v171, 0xffff0000, v150
	v_mul_f32_e32 v170, s98, v170
	v_mul_f32_e32 v171, s98, v171
	v_fma_f32 v168, v170, v6, v168
	v_fma_f32 v169, v171, v7, v169
	v_fma_f32 v186, v168, v168, v186
	v_fma_f32 v186, v169, v169, v186
	v_cvt_pk_bf16_f32 v118, v168, v169
	v_lshlrev_b32_e32 v168, 16, v119
	v_and_b32_e32 v169, 0xffff0000, v119
	v_lshlrev_b32_e32 v170, 16, v151
	v_and_b32_e32 v171, 0xffff0000, v151
	v_mul_f32_e32 v170, s98, v170
	v_mul_f32_e32 v171, s98, v171
	v_fma_f32 v168, v170, v8, v168
	v_fma_f32 v169, v171, v9, v169
	v_fma_f32 v186, v168, v168, v186
	v_fma_f32 v186, v169, v169, v186
	v_cvt_pk_bf16_f32 v119, v168, v169
	v_lshlrev_b32_e32 v168, 16, v120
	v_and_b32_e32 v169, 0xffff0000, v120
	v_lshlrev_b32_e32 v170, 16, v152
	v_and_b32_e32 v171, 0xffff0000, v152
	v_mul_f32_e32 v170, s98, v170
; __device__ __forceinline__ float bf_lo(unsigned w) { return __uint_as_float(w << 16); }
; __device__ __forceinline__ float bf_hi(unsigned w) { return __uint_as_float(w & 0xffff0000u); }
; __device__ __forceinline__ unsigned pk2(float lo, float hi) { bf16x2_t r = __builtin_convertvector((f32x2_t){lo, hi}, bf16x2_t); return __builtin_bit_cast(unsigned, r); }
; template <bool SRC_F32, bool FINAL, int R> __device__ __forceinline__ void ew_compute(const EwSet<SRC_F32, R>& S, int rb, const f32x4 (&g)[4], bf16* hb_out, float* out32, float scale, float* rs_out, int lane) {
;     ...
; #pragma unroll
;         for (int j = 0; j < 4; ++j) {
;             f32x4 h;
;             if constexpr (SRC_F32) h = S.h32[i][j];
;             else { const v2u hw = S.hb[i][j]; h.x = bf_lo(hw.x); h.y = bf_hi(hw.x); h.z = bf_lo(hw.y); h.w = bf_hi(hw.y); }
;             const v2u fw = S.fw[i][j];
;             f32x4 v; v.x = h.x + bf_lo(fw.x) * rs * g[j].x; v.y = h.y + bf_hi(fw.x) * rs * g[j].y; v.z = h.z + bf_lo(fw.y) * rs * g[j].z; v.w = h.w + bf_hi(fw.y) * rs * g[j].w;
;             if (FINAL) __builtin_nontemporal_store(v, (f32x4*)(out32 + (size_t)(rb + i) * D) + lane + 64 * j);
;             else { v2u o; o.x = pk2(v.x, v.y); o.y = pk2(v.z, v.w); ((v2u*)(hb_out + (size_t)(rb + i) * D) + lane)[64 * j] = o; s2 += (v.x * v.x + v.y * v.y) + (v.z * v.z + v.w * v.w); }
;         }
;         if (!FINAL) { const float tot = wave_sum(s2); if (lane == 0) rs_out[rb + i] = 1.0f / sqrtf(tot * (1.f / D) + EPS); }
	v_mul_f32_e32 v171, s98, v171
	v_fma_f32 v168, v170, v10, v168
	v_fma_f32 v169, v171, v11, v169
	v_fma_f32 v186, v168, v168, v186
	v_fma_f32 v186, v169, v169, v186
	v_cvt_pk_bf16_f32 v120, v168, v169
	v_lshlrev_b32_e32 v168, 16, v121
	v_and_b32_e32 v169, 0xffff0000, v121
	v_lshlrev_b32_e32 v170, 16, v153
	v_and_b32_e32 v171, 0xffff0000, v153
	v_mul_f32_e32 v170, s98, v170
	v_mul_f32_e32 v171, s98, v171
	v_fma_f32 v168, v170, v12, v168
	v_fma_f32 v169, v171, v13, v169
	v_fma_f32 v186, v168, v168, v186
	v_fma_f32 v186, v169, v169, v186
	v_cvt_pk_bf16_f32 v121, v168, v169
	v_lshlrev_b32_e32 v168, 16, v122
	v_and_b32_e32 v169, 0xffff0000, v122
	v_lshlrev_b32_e32 v170, 16, v154
	v_and_b32_e32 v171, 0xffff0000, v154
	v_mul_f32_e32 v170, s98, v170
	v_mul_f32_e32 v171, s98, v171
	v_fma_f32 v168, v170, v14, v168
	v_fma_f32 v169, v171, v15, v169
	v_fma_f32 v186, v168, v168, v186
	v_fma_f32 v186, v169, v169, v186
	v_cvt_pk_bf16_f32 v122, v168, v169
	v_lshlrev_b32_e32 v168, 16, v123
	v_and_b32_e32 v169, 0xffff0000, v123
	v_lshlrev_b32_e32 v170, 16, v155
	v_and_b32_e32 v171, 0xffff0000, v155
	v_mul_f32_e32 v170, s98, v170
	v_mul_f32_e32 v171, s98, v171
	v_fma_f32 v168, v170, v16, v168
	v_fma_f32 v169, v171, v17, v169
	v_fma_f32 v186, v168, v168, v186
	v_fma_f32 v186, v169, v169, v186
	v_cvt_pk_bf16_f32 v123, v168, v169
	global_store_dwordx4 v24, v[116:119], s[0:1]
	global_store_dwordx4 v24, v[120:123], s[0:1] offset:1024
	v_lshlrev_b32_e32 v168, 16, v124
	v_and_b32_e32 v169, 0xffff0000, v124
	v_lshlrev_b32_e32 v170, 16, v156
	v_and_b32_e32 v171, 0xffff0000, v156
	v_mul_f32_e32 v170, s101, v170
	v_mul_f32_e32 v171, s101, v171
	v_fma_f32 v168, v170, v2, v168
	v_fma_f32 v169, v171, v3, v169
	v_fma_f32 v187, v168, v168, v187
	v_fma_f32 v187, v169, v169, v187
	v_cvt_pk_bf16_f32 v124, v168, v169
	v_lshlrev_b32_e32 v168, 16, v125
	v_and_b32_e32 v169, 0xffff0000, v125
	v_lshlrev_b32_e32 v170, 16, v157
	v_and_b32_e32 v171, 0xffff0000, v157
	v_mul_f32_e32 v170, s101, v170
	v_mul_f32_e32 v171, s101, v171
	v_fma_f32 v168, v170, v4, v168
	v_fma_f32 v169, v171, v5, v169
	v_fma_f32 v187, v168, v168, v187
	v_fma_f32 v187, v169, v169, v187
	v_cvt_pk_bf16_f32 v125, v168, v169
	v_lshlrev_b32_e32 v168, 16, v126
	v_and_b32_e32 v169, 0xffff0000, v126
	v_lshlrev_b32_e32 v170, 16, v158
	v_and_b32_e32 v171, 0xffff0000, v158
	v_mul_f32_e32 v170, s101, v170
	v_mul_f32_e32 v171, s101, v171
	v_fma_f32 v168, v170, v6, v168
	v_fma_f32 v169, v171, v7, v169
	v_fma_f32 v187, v168, v168, v187
	v_fma_f32 v187, v169, v169, v187
	v_cvt_pk_bf16_f32 v126, v168, v169
	v_lshlrev_b32_e32 v168, 16, v127
	v_and_b32_e32 v169, 0xffff0000, v127
	v_lshlrev_b32_e32 v170, 16, v159
	v_and_b32_e32 v171, 0xffff0000, v159
	v_mul_f32_e32 v170, s101, v170
	v_mul_f32_e32 v171, s101, v171
	v_fma_f32 v168, v170, v8, v168
	v_fma_f32 v169, v171, v9, v169
	v_fma_f32 v187, v168, v168, v187
	v_fma_f32 v187, v169, v169, v187
	v_cvt_pk_bf16_f32 v127, v168, v169
	v_lshlrev_b32_e32 v168, 16, v128
	v_and_b32_e32 v169, 0xffff0000, v128
	v_lshlrev_b32_e32 v170, 16, v160
	v_and_b32_e32 v171, 0xffff0000, v160
	v_mul_f32_e32 v170, s101, v170
	v_mul_f32_e32 v171, s101, v171
	v_fma_f32 v168, v170, v10, v168
	v_fma_f32 v169, v171, v11, v169
	v_fma_f32 v187, v168, v168, v187
	v_fma_f32 v187, v169, v169, v187
	v_cvt_pk_bf16_f32 v128, v168, v169
	v_lshlrev_b32_e32 v168, 16, v129
	v_and_b32_e32 v169, 0xffff0000, v129
	v_lshlrev_b32_e32 v170, 16, v161
	v_and_b32_e32 v171, 0xffff0000, v161
	v_mul_f32_e32 v170, s101, v170
	v_mul_f32_e32 v171, s101, v171
	v_fma_f32 v168, v170, v12, v168
	v_fma_f32 v169, v171, v13, v169
	v_fma_f32 v187, v168, v168, v187
	v_fma_f32 v187, v169, v169, v187
	v_cvt_pk_bf16_f32 v129, v168, v169
	v_lshlrev_b32_e32 v168, 16, v130
	v_and_b32_e32 v169, 0xffff0000, v130
	v_lshlrev_b32_e32 v170, 16, v162
	v_and_b32_e32 v171, 0xffff0000, v162
	v_mul_f32_e32 v170, s101, v170
	v_mul_f32_e32 v171, s101, v171
	v_fma_f32 v168, v170, v14, v168
	v_fma_f32 v169, v171, v15, v169
	v_fma_f32 v187, v168, v168, v187
	v_fma_f32 v187, v169, v169, v187
	v_cvt_pk_bf16_f32 v130, v168, v169
	v_lshlrev_b32_e32 v168, 16, v131
	v_and_b32_e32 v169, 0xffff0000, v131
	v_lshlrev_b32_e32 v170, 16, v163
	v_and_b32_e32 v171, 0xffff0000, v163
	v_mul_f32_e32 v170, s101, v170
	v_mul_f32_e32 v171, s101, v171
	v_fma_f32 v168, v170, v16, v168
	v_fma_f32 v169, v171, v17, v169
	v_fma_f32 v187, v168, v168, v187
	v_fma_f32 v187, v169, v169, v187
	v_cvt_pk_bf16_f32 v131, v168, v169
	global_store_dwordx4 v24, v[124:127], s[0:1] offset:2048
	global_store_dwordx4 v24, v[128:131], s[0:1] offset:3072
	s_nop 1
	v_add_f32_dpp v184, v184, v184 quad_perm:[1,0,3,2] row_mask:0xf bank_mask:0xf
	v_add_f32_dpp v185, v185, v185 quad_perm:[1,0,3,2] row_mask:0xf bank_mask:0xf
	v_add_f32_dpp v186, v186, v186 quad_perm:[1,0,3,2] row_mask:0xf bank_mask:0xf
	v_add_f32_dpp v187, v187, v187 quad_perm:[1,0,3,2] row_mask:0xf bank_mask:0xf
	v_add_f32_dpp v184, v184, v184 quad_perm:[2,3,0,1] row_mask:0xf bank_mask:0xf
	v_add_f32_dpp v185, v185, v185 quad_perm:[2,3,0,1] row_mask:0xf bank_mask:0xf
	v_add_f32_dpp v186, v186, v186 quad_perm:[2,3,0,1] row_mask:0xf bank_mask:0xf
	v_add_f32_dpp v187, v187, v187 quad_perm:[2,3,0,1] row_mask:0xf bank_mask:0xf
	v_add_f32_dpp v184, v184, v184 row_half_mirror row_mask:0xf bank_mask:0xf
	v_add_f32_dpp v185, v185, v185 row_half_mirror row_mask:0xf bank_mask:0xf
	v_add_f32_dpp v186, v186, v186 row_half_mirror row_mask:0xf bank_mask:0xf
	v_add_f32_dpp v187, v187, v187 row_half_mirror row_mask:0xf bank_mask:0xf
	v_add_f32_dpp v184, v184, v184 row_mirror row_mask:0xf bank_mask:0xf
	v_add_f32_dpp v185, v185, v185 row_mirror row_mask:0xf bank_mask:0xf
; __device__ __forceinline__ float bf_lo(unsigned w) { return __uint_as_float(w << 16); }
; __device__ __forceinline__ float bf_hi(unsigned w) { return __uint_as_float(w & 0xffff0000u); }
; template <bool SRC_F32, int R> __device__ __forceinline__ void ew_load(EwSet<SRC_F32, R>& S, int rb, const float* hsrc32, const bf16* hsrcb, const bf16* f, const float* part, int lane) {
; #pragma unroll
;     for (int i = 0; i < R; ++i) S.p[i] = (lane < 16) ? part[(size_t)(rb + i) * 16 + lane] : 0.f;
; #pragma unroll
;     for (int i = 0; i < R; ++i)
; #pragma unroll
;         for (int j = 0; j < 4; ++j) {
;             S.fw[i][j] = ((const v2u*)(f + (size_t)(rb + i) * D) + lane)[64 * j];
;             if constexpr (SRC_F32) S.h32[i][j] = __builtin_nontemporal_load((const f32x4*)(hsrc32 + (size_t)(rb + i) * D) + lane + 64 * j);
;             else S.hb[i][j] = ((const v2u*)(hsrcb + (size_t)(rb + i) * D) + lane)[64 * j];
;         }
; }
; template <bool SRC_F32, bool FINAL, int R> __device__ __forceinline__ void ew_compute(const EwSet<SRC_F32, R>& S, int rb, const f32x4 (&g)[4], bf16* hb_out, float* out32, float scale, float* rs_out, int lane) {
; #pragma unroll
;     for (int i = 0; i < R; ++i) {
;         float q = S.p[i];
;         q += __shfl_xor(q, 1); q += __shfl_xor(q, 2); q += __shfl_xor(q, 4); q += __shfl_xor(q, 8);
;         const float ss = __shfl(q, 0);
;         const float rs = scale / sqrtf(ss * (1.f / D) + EPS);
;         float s2 = 0.f;
; #pragma unroll
;         for (int j = 0; j < 4; ++j) {
;             f32x4 h;
;             if constexpr (SRC_F32) h = S.h32[i][j];
;             else { const v2u hw = S.hb[i][j]; h.x = bf_lo(hw.x); h.y = bf_hi(hw.x); h.z = bf_lo(hw.y); h.w = bf_hi(hw.y); }
;             const v2u fw = S.fw[i][j];
;             f32x4 v; v.x = h.x + bf_lo(fw.x) * rs * g[j].x; v.y = h.y + bf_hi(fw.x) * rs * g[j].y; v.z = h.z + bf_lo(fw.y) * rs * g[j].z; v.w = h.w + bf_hi(fw.y) * rs * g[j].w;
;             if (FINAL) __builtin_nontemporal_store(v, (f32x4*)(out32 + (size_t)(rb + i) * D) + lane + 64 * j);
;             else { v2u o; o.x = pk2(v.x, v.y); o.y = pk2(v.z, v.w); ((v2u*)(hb_out + (size_t)(rb + i) * D) + lane)[64 * j] = o; s2 += (v.x * v.x + v.y * v.y) + (v.z * v.z + v.w * v.w); }
;         }
;         if (!FINAL) { const float tot = wave_sum(s2); if (lane == 0) rs_out[rb + i] = 1.0f / sqrtf(tot * (1.f / D) + EPS); }
	v_add_f32_dpp v186, v186, v186 row_mirror row_mask:0xf bank_mask:0xf
	v_add_f32_dpp v187, v187, v187 row_mirror row_mask:0xf bank_mask:0xf
	v_add_f32_dpp v184, v184, v184 row_bcast:15 row_mask:0xa bank_mask:0xf
	v_add_f32_dpp v185, v185, v185 row_bcast:15 row_mask:0xa bank_mask:0xf
	v_add_f32_dpp v186, v186, v186 row_bcast:15 row_mask:0xa bank_mask:0xf
	v_add_f32_dpp v187, v187, v187 row_bcast:15 row_mask:0xa bank_mask:0xf
	v_add_f32_dpp v184, v184, v184 row_bcast:31 row_mask:0xc bank_mask:0xf
	v_add_f32_dpp v185, v185, v185 row_bcast:31 row_mask:0xc bank_mask:0xf
	v_add_f32_dpp v186, v186, v186 row_bcast:31 row_mask:0xc bank_mask:0xf
	v_add_f32_dpp v187, v187, v187 row_bcast:31 row_mask:0xc bank_mask:0xf
	s_nop 1
	v_readlane_b32 s3, v184, 63
	v_readlane_b32 s24, v185, 63
	v_readlane_b32 s98, v186, 63
	v_readlane_b32 s101, v187, 63
	s_nop 3
	v_writelane_b32 v188, s3, 0
	v_writelane_b32 v188, s24, 1
	v_writelane_b32 v188, s98, 2
	v_writelane_b32 v188, s101, 3
	s_nop 1
	v_mul_f32_e32 v188, 0x3a800000, v188
	v_add_f32_e32 v188, 0x358637bd, v188
	v_rsq_f32_e32 v188, v188
	s_mov_b64 exec, 15
	global_store_dword v26, v188, s[14:15]
	s_mov_b64 exec, -1
	s_add_u32 s27, s26, 2052
	s_lshl_b32 s22, s27, 11
	v_lshl_add_u32 v23, v0, 4, s22
	v_add_u32_e32 v24, 0x1000, v23
	s_lshl_b32 s22, s27, 6
	v_lshl_add_u32 v25, v0, 2, s22
	s_lshl_b32 s22, s27, 2
	v_lshl_add_u32 v26, v0, 2, s22
	global_load_dwordx4 v[100:103], v23, s[0:1]
	global_load_dwordx4 v[104:107], v23, s[0:1] offset:1024
	global_load_dwordx4 v[132:135], v23, s[4:5]
	global_load_dwordx4 v[136:139], v23, s[4:5] offset:1024
	global_load_dwordx4 v[108:111], v23, s[0:1] offset:2048
	global_load_dwordx4 v[112:115], v23, s[0:1] offset:3072
	global_load_dwordx4 v[140:143], v23, s[4:5] offset:2048
	global_load_dwordx4 v[144:147], v23, s[4:5] offset:3072
	global_load_dwordx4 v[116:119], v24, s[0:1]
	global_load_dwordx4 v[120:123], v24, s[0:1] offset:1024
	global_load_dwordx4 v[148:151], v24, s[4:5]
	global_load_dwordx4 v[152:155], v24, s[4:5] offset:1024
	global_load_dwordx4 v[124:127], v24, s[0:1] offset:2048
	global_load_dwordx4 v[128:131], v24, s[0:1] offset:3072
	global_load_dwordx4 v[156:159], v24, s[4:5] offset:2048
	global_load_dwordx4 v[160:163], v24, s[4:5] offset:3072
	global_load_dword v164, v25, s[6:7]
	s_waitcnt vmcnt(26)
	v_add_f32_dpp v96, v96, v96 quad_perm:[1,0,3,2] row_mask:0xf bank_mask:0xf
	s_nop 1
	v_add_f32_dpp v96, v96, v96 quad_perm:[2,3,0,1] row_mask:0xf bank_mask:0xf
	s_nop 1
	v_add_f32_dpp v96, v96, v96 row_half_mirror row_mask:0xf bank_mask:0xf
	s_nop 1
	v_add_f32_dpp v96, v96, v96 row_mirror row_mask:0xf bank_mask:0xf
	s_nop 1
	v_mul_f32_e32 v96, 0x3a800000, v96
	v_add_f32_e32 v96, 0x358637bd, v96
	v_rsq_f32_e32 v96, v96
	s_nop 0
	v_readlane_b32 s3, v96, 0
	v_readlane_b32 s24, v96, 16
	v_readlane_b32 s98, v96, 32
	v_readlane_b32 s101, v96, 48
	s_nop 1
	v_mov_b32_e32 v184, 0
	v_mov_b32_e32 v185, 0
	v_mov_b32_e32 v186, 0
	v_mov_b32_e32 v187, 0
	v_lshlrev_b32_e32 v168, 16, v32
	v_and_b32_e32 v169, 0xffff0000, v32
	v_lshlrev_b32_e32 v170, 16, v64
	v_and_b32_e32 v171, 0xffff0000, v64
	v_mul_f32_e32 v170, s3, v170
	v_mul_f32_e32 v171, s3, v171
	v_fma_f32 v168, v170, v2, v168
	v_fma_f32 v169, v171, v3, v169
	v_fma_f32 v184, v168, v168, v184
	v_fma_f32 v184, v169, v169, v184
	v_cvt_pk_bf16_f32 v32, v168, v169
	v_lshlrev_b32_e32 v168, 16, v33
	v_and_b32_e32 v169, 0xffff0000, v33
	v_lshlrev_b32_e32 v170, 16, v65
	v_and_b32_e32 v171, 0xffff0000, v65
	v_mul_f32_e32 v170, s3, v170
	v_mul_f32_e32 v171, s3, v171
	v_fma_f32 v168, v170, v4, v168
	v_fma_f32 v169, v171, v5, v169
	v_fma_f32 v184, v168, v168, v184
	v_fma_f32 v184, v169, v169, v184
	v_cvt_pk_bf16_f32 v33, v168, v169
	v_lshlrev_b32_e32 v168, 16, v34
	v_and_b32_e32 v169, 0xffff0000, v34
	v_lshlrev_b32_e32 v170, 16, v66
	v_and_b32_e32 v171, 0xffff0000, v66
	v_mul_f32_e32 v170, s3, v170
	v_mul_f32_e32 v171, s3, v171
	v_fma_f32 v168, v170, v6, v168
	v_fma_f32 v169, v171, v7, v169
	v_fma_f32 v184, v168, v168, v184
	v_fma_f32 v184, v169, v169, v184
	v_cvt_pk_bf16_f32 v34, v168, v169
	v_lshlrev_b32_e32 v168, 16, v35
	v_and_b32_e32 v169, 0xffff0000, v35
	v_lshlrev_b32_e32 v170, 16, v67
	v_and_b32_e32 v171, 0xffff0000, v67
	v_mul_f32_e32 v170, s3, v170
	v_mul_f32_e32 v171, s3, v171
	v_fma_f32 v168, v170, v8, v168
	v_fma_f32 v169, v171, v9, v169
	v_fma_f32 v184, v168, v168, v184
	v_fma_f32 v184, v169, v169, v184
	v_cvt_pk_bf16_f32 v35, v168, v169
	v_lshlrev_b32_e32 v168, 16, v36
	v_and_b32_e32 v169, 0xffff0000, v36
	v_lshlrev_b32_e32 v170, 16, v68
	v_and_b32_e32 v171, 0xffff0000, v68
	v_mul_f32_e32 v170, s3, v170
	v_mul_f32_e32 v171, s3, v171
	v_fma_f32 v168, v170, v10, v168
	v_fma_f32 v169, v171, v11, v169
	v_fma_f32 v184, v168, v168, v184
	v_fma_f32 v184, v169, v169, v184
	v_cvt_pk_bf16_f32 v36, v168, v169
	v_lshlrev_b32_e32 v168, 16, v37
	v_and_b32_e32 v169, 0xffff0000, v37
	v_lshlrev_b32_e32 v170, 16, v69
	v_and_b32_e32 v171, 0xffff0000, v69
	v_mul_f32_e32 v170, s3, v170
	v_mul_f32_e32 v171, s3, v171
	v_fma_f32 v168, v170, v12, v168
	v_fma_f32 v169, v171, v13, v169
	v_fma_f32 v184, v168, v168, v184
	v_fma_f32 v184, v169, v169, v184
	v_cvt_pk_bf16_f32 v37, v168, v169
	v_lshlrev_b32_e32 v168, 16, v38
	v_and_b32_e32 v169, 0xffff0000, v38
	v_lshlrev_b32_e32 v170, 16, v70
	v_and_b32_e32 v171, 0xffff0000, v70
	v_mul_f32_e32 v170, s3, v170
	v_mul_f32_e32 v171, s3, v171
	v_fma_f32 v168, v170, v14, v168
	v_fma_f32 v169, v171, v15, v169
	v_fma_f32 v184, v168, v168, v184
	v_fma_f32 v184, v169, v169, v184
	v_cvt_pk_bf16_f32 v38, v168, v169
	v_lshlrev_b32_e32 v168, 16, v39
	v_and_b32_e32 v169, 0xffff0000, v39
	v_lshlrev_b32_e32 v170, 16, v71
; __device__ __forceinline__ float bf_lo(unsigned w) { return __uint_as_float(w << 16); }
; __device__ __forceinline__ float bf_hi(unsigned w) { return __uint_as_float(w & 0xffff0000u); }
; __device__ __forceinline__ unsigned pk2(float lo, float hi) { bf16x2_t r = __builtin_convertvector((f32x2_t){lo, hi}, bf16x2_t); return __builtin_bit_cast(unsigned, r); }
; template <bool SRC_F32, bool FINAL, int R> __device__ __forceinline__ void ew_compute(const EwSet<SRC_F32, R>& S, int rb, const f32x4 (&g)[4], bf16* hb_out, float* out32, float scale, float* rs_out, int lane) {
;     ...
; #pragma unroll
;         for (int j = 0; j < 4; ++j) {
;             f32x4 h;
;             if constexpr (SRC_F32) h = S.h32[i][j];
;             else { const v2u hw = S.hb[i][j]; h.x = bf_lo(hw.x); h.y = bf_hi(hw.x); h.z = bf_lo(hw.y); h.w = bf_hi(hw.y); }
;             const v2u fw = S.fw[i][j];
;             f32x4 v; v.x = h.x + bf_lo(fw.x) * rs * g[j].x; v.y = h.y + bf_hi(fw.x) * rs * g[j].y; v.z = h.z + bf_lo(fw.y) * rs * g[j].z; v.w = h.w + bf_hi(fw.y) * rs * g[j].w;
;             if (FINAL) __builtin_nontemporal_store(v, (f32x4*)(out32 + (size_t)(rb + i) * D) + lane + 64 * j);
;             else { v2u o; o.x = pk2(v.x, v.y); o.y = pk2(v.z, v.w); ((v2u*)(hb_out + (size_t)(rb + i) * D) + lane)[64 * j] = o; s2 += (v.x * v.x + v.y * v.y) + (v.z * v.z + v.w * v.w); }
	v_and_b32_e32 v171, 0xffff0000, v71
	v_mul_f32_e32 v170, s3, v170
	v_mul_f32_e32 v171, s3, v171
	v_fma_f32 v168, v170, v16, v168
	v_fma_f32 v169, v171, v17, v169
	v_fma_f32 v184, v168, v168, v184
	v_fma_f32 v184, v169, v169, v184
	v_cvt_pk_bf16_f32 v39, v168, v169
	global_store_dwordx4 v18, v[32:35], s[0:1]
	global_store_dwordx4 v18, v[36:39], s[0:1] offset:1024
	v_lshlrev_b32_e32 v168, 16, v40
	v_and_b32_e32 v169, 0xffff0000, v40
	v_lshlrev_b32_e32 v170, 16, v72
	v_and_b32_e32 v171, 0xffff0000, v72
	v_mul_f32_e32 v170, s24, v170
	v_mul_f32_e32 v171, s24, v171
	v_fma_f32 v168, v170, v2, v168
	v_fma_f32 v169, v171, v3, v169
	v_fma_f32 v185, v168, v168, v185
	v_fma_f32 v185, v169, v169, v185
	v_cvt_pk_bf16_f32 v40, v168, v169
	v_lshlrev_b32_e32 v168, 16, v41
	v_and_b32_e32 v169, 0xffff0000, v41
	v_lshlrev_b32_e32 v170, 16, v73
	v_and_b32_e32 v171, 0xffff0000, v73
	v_mul_f32_e32 v170, s24, v170
	v_mul_f32_e32 v171, s24, v171
	v_fma_f32 v168, v170, v4, v168
	v_fma_f32 v169, v171, v5, v169
	v_fma_f32 v185, v168, v168, v185
	v_fma_f32 v185, v169, v169, v185
	v_cvt_pk_bf16_f32 v41, v168, v169
	v_lshlrev_b32_e32 v168, 16, v42
	v_and_b32_e32 v169, 0xffff0000, v42
	v_lshlrev_b32_e32 v170, 16, v74
	v_and_b32_e32 v171, 0xffff0000, v74
	v_mul_f32_e32 v170, s24, v170
	v_mul_f32_e32 v171, s24, v171
	v_fma_f32 v168, v170, v6, v168
	v_fma_f32 v169, v171, v7, v169
	v_fma_f32 v185, v168, v168, v185
	v_fma_f32 v185, v169, v169, v185
	v_cvt_pk_bf16_f32 v42, v168, v169
	v_lshlrev_b32_e32 v168, 16, v43
	v_and_b32_e32 v169, 0xffff0000, v43
	v_lshlrev_b32_e32 v170, 16, v75
	v_and_b32_e32 v171, 0xffff0000, v75
	v_mul_f32_e32 v170, s24, v170
	v_mul_f32_e32 v171, s24, v171
	v_fma_f32 v168, v170, v8, v168
	v_fma_f32 v169, v171, v9, v169
	v_fma_f32 v185, v168, v168, v185
	v_fma_f32 v185, v169, v169, v185
	v_cvt_pk_bf16_f32 v43, v168, v169
	v_lshlrev_b32_e32 v168, 16, v44
	v_and_b32_e32 v169, 0xffff0000, v44
	v_lshlrev_b32_e32 v170, 16, v76
	v_and_b32_e32 v171, 0xffff0000, v76
	v_mul_f32_e32 v170, s24, v170
	v_mul_f32_e32 v171, s24, v171
	v_fma_f32 v168, v170, v10, v168
	v_fma_f32 v169, v171, v11, v169
	v_fma_f32 v185, v168, v168, v185
	v_fma_f32 v185, v169, v169, v185
	v_cvt_pk_bf16_f32 v44, v168, v169
	v_lshlrev_b32_e32 v168, 16, v45
	v_and_b32_e32 v169, 0xffff0000, v45
	v_lshlrev_b32_e32 v170, 16, v77
	v_and_b32_e32 v171, 0xffff0000, v77
	v_mul_f32_e32 v170, s24, v170
	v_mul_f32_e32 v171, s24, v171
	v_fma_f32 v168, v170, v12, v168
	v_fma_f32 v169, v171, v13, v169
	v_fma_f32 v185, v168, v168, v185
	v_fma_f32 v185, v169, v169, v185
	v_cvt_pk_bf16_f32 v45, v168, v169
	v_lshlrev_b32_e32 v168, 16, v46
	v_and_b32_e32 v169, 0xffff0000, v46
	v_lshlrev_b32_e32 v170, 16, v78
	v_and_b32_e32 v171, 0xffff0000, v78
	v_mul_f32_e32 v170, s24, v170
	v_mul_f32_e32 v171, s24, v171
	v_fma_f32 v168, v170, v14, v168
	v_fma_f32 v169, v171, v15, v169
	v_fma_f32 v185, v168, v168, v185
	v_fma_f32 v185, v169, v169, v185
	v_cvt_pk_bf16_f32 v46, v168, v169
	v_lshlrev_b32_e32 v168, 16, v47
	v_and_b32_e32 v169, 0xffff0000, v47
	v_lshlrev_b32_e32 v170, 16, v79
	v_and_b32_e32 v171, 0xffff0000, v79
	v_mul_f32_e32 v170, s24, v170
	v_mul_f32_e32 v171, s24, v171
	v_fma_f32 v168, v170, v16, v168
	v_fma_f32 v169, v171, v17, v169
	v_fma_f32 v185, v168, v168, v185
	v_fma_f32 v185, v169, v169, v185
	v_cvt_pk_bf16_f32 v47, v168, v169
	global_store_dwordx4 v18, v[40:43], s[0:1] offset:2048
	global_store_dwordx4 v18, v[44:47], s[0:1] offset:3072
	v_lshlrev_b32_e32 v168, 16, v48
	v_and_b32_e32 v169, 0xffff0000, v48
	v_lshlrev_b32_e32 v170, 16, v80
	v_and_b32_e32 v171, 0xffff0000, v80
	v_mul_f32_e32 v170, s98, v170
	v_mul_f32_e32 v171, s98, v171
	v_fma_f32 v168, v170, v2, v168
	v_fma_f32 v169, v171, v3, v169
	v_fma_f32 v186, v168, v168, v186
	v_fma_f32 v186, v169, v169, v186
	v_cvt_pk_bf16_f32 v48, v168, v169
	v_lshlrev_b32_e32 v168, 16, v49
	v_and_b32_e32 v169, 0xffff0000, v49
	v_lshlrev_b32_e32 v170, 16, v81
	v_and_b32_e32 v171, 0xffff0000, v81
	v_mul_f32_e32 v170, s98, v170
	v_mul_f32_e32 v171, s98, v171
	v_fma_f32 v168, v170, v4, v168
	v_fma_f32 v169, v171, v5, v169
	v_fma_f32 v186, v168, v168, v186
	v_fma_f32 v186, v169, v169, v186
	v_cvt_pk_bf16_f32 v49, v168, v169
	v_lshlrev_b32_e32 v168, 16, v50
	v_and_b32_e32 v169, 0xffff0000, v50
	v_lshlrev_b32_e32 v170, 16, v82
	v_and_b32_e32 v171, 0xffff0000, v82
	v_mul_f32_e32 v170, s98, v170
	v_mul_f32_e32 v171, s98, v171
	v_fma_f32 v168, v170, v6, v168
	v_fma_f32 v169, v171, v7, v169
	v_fma_f32 v186, v168, v168, v186
	v_fma_f32 v186, v169, v169, v186
	v_cvt_pk_bf16_f32 v50, v168, v169
	v_lshlrev_b32_e32 v168, 16, v51
	v_and_b32_e32 v169, 0xffff0000, v51
	v_lshlrev_b32_e32 v170, 16, v83
	v_and_b32_e32 v171, 0xffff0000, v83
	v_mul_f32_e32 v170, s98, v170
	v_mul_f32_e32 v171, s98, v171
	v_fma_f32 v168, v170, v8, v168
	v_fma_f32 v169, v171, v9, v169
	v_fma_f32 v186, v168, v168, v186
	v_fma_f32 v186, v169, v169, v186
	v_cvt_pk_bf16_f32 v51, v168, v169
	v_lshlrev_b32_e32 v168, 16, v52
	v_and_b32_e32 v169, 0xffff0000, v52
	v_lshlrev_b32_e32 v170, 16, v84
	v_and_b32_e32 v171, 0xffff0000, v84
	v_mul_f32_e32 v170, s98, v170
	v_mul_f32_e32 v171, s98, v171
	v_fma_f32 v168, v170, v10, v168
	v_fma_f32 v169, v171, v11, v169
	v_fma_f32 v186, v168, v168, v186
	v_fma_f32 v186, v169, v169, v186
	v_cvt_pk_bf16_f32 v52, v168, v169
	v_lshlrev_b32_e32 v168, 16, v53
	v_and_b32_e32 v169, 0xffff0000, v53
	v_lshlrev_b32_e32 v170, 16, v85
	v_and_b32_e32 v171, 0xffff0000, v85
	v_mul_f32_e32 v170, s98, v170
	v_mul_f32_e32 v171, s98, v171
	v_fma_f32 v168, v170, v12, v168
	v_fma_f32 v169, v171, v13, v169
	v_fma_f32 v186, v168, v168, v186
	v_fma_f32 v186, v169, v169, v186
	v_cvt_pk_bf16_f32 v53, v168, v169
; __device__ __forceinline__ float bf_lo(unsigned w) { return __uint_as_float(w << 16); }
; __device__ __forceinline__ float bf_hi(unsigned w) { return __uint_as_float(w & 0xffff0000u); }
; __device__ __forceinline__ unsigned pk2(float lo, float hi) { bf16x2_t r = __builtin_convertvector((f32x2_t){lo, hi}, bf16x2_t); return __builtin_bit_cast(unsigned, r); }
; template <bool SRC_F32, bool FINAL, int R> __device__ __forceinline__ void ew_compute(const EwSet<SRC_F32, R>& S, int rb, const f32x4 (&g)[4], bf16* hb_out, float* out32, float scale, float* rs_out, int lane) {
;     ...
; #pragma unroll
;         for (int j = 0; j < 4; ++j) {
;             f32x4 h;
;             if constexpr (SRC_F32) h = S.h32[i][j];
;             else { const v2u hw = S.hb[i][j]; h.x = bf_lo(hw.x); h.y = bf_hi(hw.x); h.z = bf_lo(hw.y); h.w = bf_hi(hw.y); }
;             const v2u fw = S.fw[i][j];
;             f32x4 v; v.x = h.x + bf_lo(fw.x) * rs * g[j].x; v.y = h.y + bf_hi(fw.x) * rs * g[j].y; v.z = h.z + bf_lo(fw.y) * rs * g[j].z; v.w = h.w + bf_hi(fw.y) * rs * g[j].w;
;             if (FINAL) __builtin_nontemporal_store(v, (f32x4*)(out32 + (size_t)(rb + i) * D) + lane + 64 * j);
;             else { v2u o; o.x = pk2(v.x, v.y); o.y = pk2(v.z, v.w); ((v2u*)(hb_out + (size_t)(rb + i) * D) + lane)[64 * j] = o; s2 += (v.x * v.x + v.y * v.y) + (v.z * v.z + v.w * v.w); }
;         }
;         if (!FINAL) { const float tot = wave_sum(s2); if (lane == 0) rs_out[rb + i] = 1.0f / sqrtf(tot * (1.f / D) + EPS); }
	v_lshlrev_b32_e32 v168, 16, v54
	v_and_b32_e32 v169, 0xffff0000, v54
	v_lshlrev_b32_e32 v170, 16, v86
	v_and_b32_e32 v171, 0xffff0000, v86
	v_mul_f32_e32 v170, s98, v170
	v_mul_f32_e32 v171, s98, v171
	v_fma_f32 v168, v170, v14, v168
	v_fma_f32 v169, v171, v15, v169
	v_fma_f32 v186, v168, v168, v186
	v_fma_f32 v186, v169, v169, v186
	v_cvt_pk_bf16_f32 v54, v168, v169
	v_lshlrev_b32_e32 v168, 16, v55
	v_and_b32_e32 v169, 0xffff0000, v55
	v_lshlrev_b32_e32 v170, 16, v87
	v_and_b32_e32 v171, 0xffff0000, v87
	v_mul_f32_e32 v170, s98, v170
	v_mul_f32_e32 v171, s98, v171
	v_fma_f32 v168, v170, v16, v168
	v_fma_f32 v169, v171, v17, v169
	v_fma_f32 v186, v168, v168, v186
	v_fma_f32 v186, v169, v169, v186
	v_cvt_pk_bf16_f32 v55, v168, v169
	global_store_dwordx4 v19, v[48:51], s[0:1]
	global_store_dwordx4 v19, v[52:55], s[0:1] offset:1024
	v_lshlrev_b32_e32 v168, 16, v56
	v_and_b32_e32 v169, 0xffff0000, v56
	v_lshlrev_b32_e32 v170, 16, v88
	v_and_b32_e32 v171, 0xffff0000, v88
	v_mul_f32_e32 v170, s101, v170
	v_mul_f32_e32 v171, s101, v171
	v_fma_f32 v168, v170, v2, v168
	v_fma_f32 v169, v171, v3, v169
	v_fma_f32 v187, v168, v168, v187
	v_fma_f32 v187, v169, v169, v187
	v_cvt_pk_bf16_f32 v56, v168, v169
	v_lshlrev_b32_e32 v168, 16, v57
	v_and_b32_e32 v169, 0xffff0000, v57
	v_lshlrev_b32_e32 v170, 16, v89
	v_and_b32_e32 v171, 0xffff0000, v89
	v_mul_f32_e32 v170, s101, v170
	v_mul_f32_e32 v171, s101, v171
	v_fma_f32 v168, v170, v4, v168
	v_fma_f32 v169, v171, v5, v169
	v_fma_f32 v187, v168, v168, v187
	v_fma_f32 v187, v169, v169, v187
	v_cvt_pk_bf16_f32 v57, v168, v169
	v_lshlrev_b32_e32 v168, 16, v58
	v_and_b32_e32 v169, 0xffff0000, v58
	v_lshlrev_b32_e32 v170, 16, v90
	v_and_b32_e32 v171, 0xffff0000, v90
	v_mul_f32_e32 v170, s101, v170
	v_mul_f32_e32 v171, s101, v171
	v_fma_f32 v168, v170, v6, v168
	v_fma_f32 v169, v171, v7, v169
	v_fma_f32 v187, v168, v168, v187
	v_fma_f32 v187, v169, v169, v187
	v_cvt_pk_bf16_f32 v58, v168, v169
	v_lshlrev_b32_e32 v168, 16, v59
	v_and_b32_e32 v169, 0xffff0000, v59
	v_lshlrev_b32_e32 v170, 16, v91
	v_and_b32_e32 v171, 0xffff0000, v91
	v_mul_f32_e32 v170, s101, v170
	v_mul_f32_e32 v171, s101, v171
	v_fma_f32 v168, v170, v8, v168
	v_fma_f32 v169, v171, v9, v169
	v_fma_f32 v187, v168, v168, v187
	v_fma_f32 v187, v169, v169, v187
	v_cvt_pk_bf16_f32 v59, v168, v169
	v_lshlrev_b32_e32 v168, 16, v60
	v_and_b32_e32 v169, 0xffff0000, v60
	v_lshlrev_b32_e32 v170, 16, v92
	v_and_b32_e32 v171, 0xffff0000, v92
	v_mul_f32_e32 v170, s101, v170
	v_mul_f32_e32 v171, s101, v171
	v_fma_f32 v168, v170, v10, v168
	v_fma_f32 v169, v171, v11, v169
	v_fma_f32 v187, v168, v168, v187
	v_fma_f32 v187, v169, v169, v187
	v_cvt_pk_bf16_f32 v60, v168, v169
	v_lshlrev_b32_e32 v168, 16, v61
	v_and_b32_e32 v169, 0xffff0000, v61
	v_lshlrev_b32_e32 v170, 16, v93
	v_and_b32_e32 v171, 0xffff0000, v93
	v_mul_f32_e32 v170, s101, v170
	v_mul_f32_e32 v171, s101, v171
	v_fma_f32 v168, v170, v12, v168
	v_fma_f32 v169, v171, v13, v169
	v_fma_f32 v187, v168, v168, v187
	v_fma_f32 v187, v169, v169, v187
	v_cvt_pk_bf16_f32 v61, v168, v169
	v_lshlrev_b32_e32 v168, 16, v62
	v_and_b32_e32 v169, 0xffff0000, v62
	v_lshlrev_b32_e32 v170, 16, v94
	v_and_b32_e32 v171, 0xffff0000, v94
	v_mul_f32_e32 v170, s101, v170
	v_mul_f32_e32 v171, s101, v171
	v_fma_f32 v168, v170, v14, v168
	v_fma_f32 v169, v171, v15, v169
	v_fma_f32 v187, v168, v168, v187
	v_fma_f32 v187, v169, v169, v187
	v_cvt_pk_bf16_f32 v62, v168, v169
	v_lshlrev_b32_e32 v168, 16, v63
	v_and_b32_e32 v169, 0xffff0000, v63
	v_lshlrev_b32_e32 v170, 16, v95
	v_and_b32_e32 v171, 0xffff0000, v95
	v_mul_f32_e32 v170, s101, v170
	v_mul_f32_e32 v171, s101, v171
	v_fma_f32 v168, v170, v16, v168
	v_fma_f32 v169, v171, v17, v169
	v_fma_f32 v187, v168, v168, v187
	v_fma_f32 v187, v169, v169, v187
	v_cvt_pk_bf16_f32 v63, v168, v169
	global_store_dwordx4 v19, v[56:59], s[0:1] offset:2048
	global_store_dwordx4 v19, v[60:63], s[0:1] offset:3072
	s_nop 1
	v_add_f32_dpp v184, v184, v184 quad_perm:[1,0,3,2] row_mask:0xf bank_mask:0xf
	v_add_f32_dpp v185, v185, v185 quad_perm:[1,0,3,2] row_mask:0xf bank_mask:0xf
	v_add_f32_dpp v186, v186, v186 quad_perm:[1,0,3,2] row_mask:0xf bank_mask:0xf
	v_add_f32_dpp v187, v187, v187 quad_perm:[1,0,3,2] row_mask:0xf bank_mask:0xf
	v_add_f32_dpp v184, v184, v184 quad_perm:[2,3,0,1] row_mask:0xf bank_mask:0xf
	v_add_f32_dpp v185, v185, v185 quad_perm:[2,3,0,1] row_mask:0xf bank_mask:0xf
	v_add_f32_dpp v186, v186, v186 quad_perm:[2,3,0,1] row_mask:0xf bank_mask:0xf
	v_add_f32_dpp v187, v187, v187 quad_perm:[2,3,0,1] row_mask:0xf bank_mask:0xf
	v_add_f32_dpp v184, v184, v184 row_half_mirror row_mask:0xf bank_mask:0xf
	v_add_f32_dpp v185, v185, v185 row_half_mirror row_mask:0xf bank_mask:0xf
	v_add_f32_dpp v186, v186, v186 row_half_mirror row_mask:0xf bank_mask:0xf
	v_add_f32_dpp v187, v187, v187 row_half_mirror row_mask:0xf bank_mask:0xf
	v_add_f32_dpp v184, v184, v184 row_mirror row_mask:0xf bank_mask:0xf
	v_add_f32_dpp v185, v185, v185 row_mirror row_mask:0xf bank_mask:0xf
	v_add_f32_dpp v186, v186, v186 row_mirror row_mask:0xf bank_mask:0xf
	v_add_f32_dpp v187, v187, v187 row_mirror row_mask:0xf bank_mask:0xf
	v_add_f32_dpp v184, v184, v184 row_bcast:15 row_mask:0xa bank_mask:0xf
	v_add_f32_dpp v185, v185, v185 row_bcast:15 row_mask:0xa bank_mask:0xf
	v_add_f32_dpp v186, v186, v186 row_bcast:15 row_mask:0xa bank_mask:0xf
	v_add_f32_dpp v187, v187, v187 row_bcast:15 row_mask:0xa bank_mask:0xf
	v_add_f32_dpp v184, v184, v184 row_bcast:31 row_mask:0xc bank_mask:0xf
	v_add_f32_dpp v185, v185, v185 row_bcast:31 row_mask:0xc bank_mask:0xf
	v_add_f32_dpp v186, v186, v186 row_bcast:31 row_mask:0xc bank_mask:0xf
	v_add_f32_dpp v187, v187, v187 row_bcast:31 row_mask:0xc bank_mask:0xf
	s_nop 1
	v_readlane_b32 s3, v184, 63
	v_readlane_b32 s24, v185, 63
	v_readlane_b32 s98, v186, 63
	v_readlane_b32 s101, v187, 63
	s_nop 3
	v_writelane_b32 v188, s3, 0
	v_writelane_b32 v188, s24, 1
	v_writelane_b32 v188, s98, 2
	v_writelane_b32 v188, s101, 3
	s_nop 1
	v_mul_f32_e32 v188, 0x3a800000, v188
	v_add_f32_e32 v188, 0x358637bd, v188
	v_rsq_f32_e32 v188, v188
	s_mov_b64 exec, 15
	global_store_dword v21, v188, s[14:15]
	s_mov_b64 exec, -1
	s_waitcnt vmcnt(9)
; __device__ __forceinline__ float bf_lo(unsigned w) { return __uint_as_float(w << 16); }
; __device__ __forceinline__ float bf_hi(unsigned w) { return __uint_as_float(w & 0xffff0000u); }
; __device__ __forceinline__ unsigned pk2(float lo, float hi) { bf16x2_t r = __builtin_convertvector((f32x2_t){lo, hi}, bf16x2_t); return __builtin_bit_cast(unsigned, r); }
; template <bool SRC_F32, bool FINAL, int R> __device__ __forceinline__ void ew_compute(const EwSet<SRC_F32, R>& S, int rb, const f32x4 (&g)[4], bf16* hb_out, float* out32, float scale, float* rs_out, int lane) {
; #pragma unroll
;     for (int i = 0; i < R; ++i) {
;         float q = S.p[i];
;         q += __shfl_xor(q, 1); q += __shfl_xor(q, 2); q += __shfl_xor(q, 4); q += __shfl_xor(q, 8);
;         const float ss = __shfl(q, 0);
;         const float rs = scale / sqrtf(ss * (1.f / D) + EPS);
;         float s2 = 0.f;
; #pragma unroll
;         for (int j = 0; j < 4; ++j) {
;             f32x4 h;
;             if constexpr (SRC_F32) h = S.h32[i][j];
;             else { const v2u hw = S.hb[i][j]; h.x = bf_lo(hw.x); h.y = bf_hi(hw.x); h.z = bf_lo(hw.y); h.w = bf_hi(hw.y); }
;             const v2u fw = S.fw[i][j];
;             f32x4 v; v.x = h.x + bf_lo(fw.x) * rs * g[j].x; v.y = h.y + bf_hi(fw.x) * rs * g[j].y; v.z = h.z + bf_lo(fw.y) * rs * g[j].z; v.w = h.w + bf_hi(fw.y) * rs * g[j].w;
;             if (FINAL) __builtin_nontemporal_store(v, (f32x4*)(out32 + (size_t)(rb + i) * D) + lane + 64 * j);
;             else { v2u o; o.x = pk2(v.x, v.y); o.y = pk2(v.z, v.w); ((v2u*)(hb_out + (size_t)(rb + i) * D) + lane)[64 * j] = o; s2 += (v.x * v.x + v.y * v.y) + (v.z * v.z + v.w * v.w); }
	v_add_f32_dpp v164, v164, v164 quad_perm:[1,0,3,2] row_mask:0xf bank_mask:0xf
	s_nop 1
	v_add_f32_dpp v164, v164, v164 quad_perm:[2,3,0,1] row_mask:0xf bank_mask:0xf
	s_nop 1
	v_add_f32_dpp v164, v164, v164 row_half_mirror row_mask:0xf bank_mask:0xf
	s_nop 1
	v_add_f32_dpp v164, v164, v164 row_mirror row_mask:0xf bank_mask:0xf
	s_nop 1
	v_mul_f32_e32 v164, 0x3a800000, v164
	v_add_f32_e32 v164, 0x358637bd, v164
	v_rsq_f32_e32 v164, v164
	s_nop 0
	v_readlane_b32 s3, v164, 0
	v_readlane_b32 s24, v164, 16
	v_readlane_b32 s98, v164, 32
	v_readlane_b32 s101, v164, 48
	s_nop 1
	v_mov_b32_e32 v184, 0
	v_mov_b32_e32 v185, 0
	v_mov_b32_e32 v186, 0
	v_mov_b32_e32 v187, 0
	v_lshlrev_b32_e32 v168, 16, v100
	v_and_b32_e32 v169, 0xffff0000, v100
	v_lshlrev_b32_e32 v170, 16, v132
	v_and_b32_e32 v171, 0xffff0000, v132
	v_mul_f32_e32 v170, s3, v170
	v_mul_f32_e32 v171, s3, v171
	v_fma_f32 v168, v170, v2, v168
	v_fma_f32 v169, v171, v3, v169
	v_fma_f32 v184, v168, v168, v184
	v_fma_f32 v184, v169, v169, v184
	v_cvt_pk_bf16_f32 v100, v168, v169
	v_lshlrev_b32_e32 v168, 16, v101
	v_and_b32_e32 v169, 0xffff0000, v101
	v_lshlrev_b32_e32 v170, 16, v133
	v_and_b32_e32 v171, 0xffff0000, v133
	v_mul_f32_e32 v170, s3, v170
	v_mul_f32_e32 v171, s3, v171
	v_fma_f32 v168, v170, v4, v168
	v_fma_f32 v169, v171, v5, v169
	v_fma_f32 v184, v168, v168, v184
	v_fma_f32 v184, v169, v169, v184
	v_cvt_pk_bf16_f32 v101, v168, v169
	v_lshlrev_b32_e32 v168, 16, v102
	v_and_b32_e32 v169, 0xffff0000, v102
	v_lshlrev_b32_e32 v170, 16, v134
	v_and_b32_e32 v171, 0xffff0000, v134
	v_mul_f32_e32 v170, s3, v170
	v_mul_f32_e32 v171, s3, v171
	v_fma_f32 v168, v170, v6, v168
	v_fma_f32 v169, v171, v7, v169
	v_fma_f32 v184, v168, v168, v184
	v_fma_f32 v184, v169, v169, v184
	v_cvt_pk_bf16_f32 v102, v168, v169
	v_lshlrev_b32_e32 v168, 16, v103
	v_and_b32_e32 v169, 0xffff0000, v103
	v_lshlrev_b32_e32 v170, 16, v135
	v_and_b32_e32 v171, 0xffff0000, v135
	v_mul_f32_e32 v170, s3, v170
	v_mul_f32_e32 v171, s3, v171
	v_fma_f32 v168, v170, v8, v168
	v_fma_f32 v169, v171, v9, v169
	v_fma_f32 v184, v168, v168, v184
	v_fma_f32 v184, v169, v169, v184
	v_cvt_pk_bf16_f32 v103, v168, v169
	v_lshlrev_b32_e32 v168, 16, v104
	v_and_b32_e32 v169, 0xffff0000, v104
	v_lshlrev_b32_e32 v170, 16, v136
	v_and_b32_e32 v171, 0xffff0000, v136
	v_mul_f32_e32 v170, s3, v170
	v_mul_f32_e32 v171, s3, v171
	v_fma_f32 v168, v170, v10, v168
	v_fma_f32 v169, v171, v11, v169
	v_fma_f32 v184, v168, v168, v184
	v_fma_f32 v184, v169, v169, v184
	v_cvt_pk_bf16_f32 v104, v168, v169
	v_lshlrev_b32_e32 v168, 16, v105
	v_and_b32_e32 v169, 0xffff0000, v105
	v_lshlrev_b32_e32 v170, 16, v137
	v_and_b32_e32 v171, 0xffff0000, v137
	v_mul_f32_e32 v170, s3, v170
	v_mul_f32_e32 v171, s3, v171
	v_fma_f32 v168, v170, v12, v168
	v_fma_f32 v169, v171, v13, v169
	v_fma_f32 v184, v168, v168, v184
	v_fma_f32 v184, v169, v169, v184
	v_cvt_pk_bf16_f32 v105, v168, v169
	v_lshlrev_b32_e32 v168, 16, v106
	v_and_b32_e32 v169, 0xffff0000, v106
	v_lshlrev_b32_e32 v170, 16, v138
	v_and_b32_e32 v171, 0xffff0000, v138
	v_mul_f32_e32 v170, s3, v170
	v_mul_f32_e32 v171, s3, v171
	v_fma_f32 v168, v170, v14, v168
	v_fma_f32 v169, v171, v15, v169
	v_fma_f32 v184, v168, v168, v184
	v_fma_f32 v184, v169, v169, v184
	v_cvt_pk_bf16_f32 v106, v168, v169
	v_lshlrev_b32_e32 v168, 16, v107
	v_and_b32_e32 v169, 0xffff0000, v107
	v_lshlrev_b32_e32 v170, 16, v139
	v_and_b32_e32 v171, 0xffff0000, v139
	v_mul_f32_e32 v170, s3, v170
	v_mul_f32_e32 v171, s3, v171
	v_fma_f32 v168, v170, v16, v168
	v_fma_f32 v169, v171, v17, v169
	v_fma_f32 v184, v168, v168, v184
	v_fma_f32 v184, v169, v169, v184
	v_cvt_pk_bf16_f32 v107, v168, v169
	global_store_dwordx4 v23, v[100:103], s[0:1]
	global_store_dwordx4 v23, v[104:107], s[0:1] offset:1024
	v_lshlrev_b32_e32 v168, 16, v108
	v_and_b32_e32 v169, 0xffff0000, v108
	v_lshlrev_b32_e32 v170, 16, v140
	v_and_b32_e32 v171, 0xffff0000, v140
	v_mul_f32_e32 v170, s24, v170
	v_mul_f32_e32 v171, s24, v171
	v_fma_f32 v168, v170, v2, v168
	v_fma_f32 v169, v171, v3, v169
	v_fma_f32 v185, v168, v168, v185
	v_fma_f32 v185, v169, v169, v185
	v_cvt_pk_bf16_f32 v108, v168, v169
	v_lshlrev_b32_e32 v168, 16, v109
	v_and_b32_e32 v169, 0xffff0000, v109
	v_lshlrev_b32_e32 v170, 16, v141
	v_and_b32_e32 v171, 0xffff0000, v141
	v_mul_f32_e32 v170, s24, v170
	v_mul_f32_e32 v171, s24, v171
	v_fma_f32 v168, v170, v4, v168
	v_fma_f32 v169, v171, v5, v169
	v_fma_f32 v185, v168, v168, v185
	v_fma_f32 v185, v169, v169, v185
	v_cvt_pk_bf16_f32 v109, v168, v169
	v_lshlrev_b32_e32 v168, 16, v110
	v_and_b32_e32 v169, 0xffff0000, v110
	v_lshlrev_b32_e32 v170, 16, v142
	v_and_b32_e32 v171, 0xffff0000, v142
	v_mul_f32_e32 v170, s24, v170
	v_mul_f32_e32 v171, s24, v171
	v_fma_f32 v168, v170, v6, v168
	v_fma_f32 v169, v171, v7, v169
	v_fma_f32 v185, v168, v168, v185
	v_fma_f32 v185, v169, v169, v185
	v_cvt_pk_bf16_f32 v110, v168, v169
	v_lshlrev_b32_e32 v168, 16, v111
	v_and_b32_e32 v169, 0xffff0000, v111
	v_lshlrev_b32_e32 v170, 16, v143
	v_and_b32_e32 v171, 0xffff0000, v143
	v_mul_f32_e32 v170, s24, v170
	v_mul_f32_e32 v171, s24, v171
	v_fma_f32 v168, v170, v8, v168
	v_fma_f32 v169, v171, v9, v169
	v_fma_f32 v185, v168, v168, v185
	v_fma_f32 v185, v169, v169, v185
	v_cvt_pk_bf16_f32 v111, v168, v169
	v_lshlrev_b32_e32 v168, 16, v112
	v_and_b32_e32 v169, 0xffff0000, v112
	v_lshlrev_b32_e32 v170, 16, v144
	v_and_b32_e32 v171, 0xffff0000, v144
	v_mul_f32_e32 v170, s24, v170
	v_mul_f32_e32 v171, s24, v171
	v_fma_f32 v168, v170, v10, v168
	v_fma_f32 v169, v171, v11, v169
	v_fma_f32 v185, v168, v168, v185
	v_fma_f32 v185, v169, v169, v185
	v_cvt_pk_bf16_f32 v112, v168, v169
; __device__ __forceinline__ float bf_lo(unsigned w) { return __uint_as_float(w << 16); }
; __device__ __forceinline__ float bf_hi(unsigned w) { return __uint_as_float(w & 0xffff0000u); }
; __device__ __forceinline__ unsigned pk2(float lo, float hi) { bf16x2_t r = __builtin_convertvector((f32x2_t){lo, hi}, bf16x2_t); return __builtin_bit_cast(unsigned, r); }
; template <bool SRC_F32, bool FINAL, int R> __device__ __forceinline__ void ew_compute(const EwSet<SRC_F32, R>& S, int rb, const f32x4 (&g)[4], bf16* hb_out, float* out32, float scale, float* rs_out, int lane) {
;     ...
; #pragma unroll
;         for (int j = 0; j < 4; ++j) {
;             f32x4 h;
;             if constexpr (SRC_F32) h = S.h32[i][j];
;             else { const v2u hw = S.hb[i][j]; h.x = bf_lo(hw.x); h.y = bf_hi(hw.x); h.z = bf_lo(hw.y); h.w = bf_hi(hw.y); }
;             const v2u fw = S.fw[i][j];
;             f32x4 v; v.x = h.x + bf_lo(fw.x) * rs * g[j].x; v.y = h.y + bf_hi(fw.x) * rs * g[j].y; v.z = h.z + bf_lo(fw.y) * rs * g[j].z; v.w = h.w + bf_hi(fw.y) * rs * g[j].w;
;             if (FINAL) __builtin_nontemporal_store(v, (f32x4*)(out32 + (size_t)(rb + i) * D) + lane + 64 * j);
;             else { v2u o; o.x = pk2(v.x, v.y); o.y = pk2(v.z, v.w); ((v2u*)(hb_out + (size_t)(rb + i) * D) + lane)[64 * j] = o; s2 += (v.x * v.x + v.y * v.y) + (v.z * v.z + v.w * v.w); }
	v_lshlrev_b32_e32 v168, 16, v113
	v_and_b32_e32 v169, 0xffff0000, v113
	v_lshlrev_b32_e32 v170, 16, v145
	v_and_b32_e32 v171, 0xffff0000, v145
	v_mul_f32_e32 v170, s24, v170
	v_mul_f32_e32 v171, s24, v171
	v_fma_f32 v168, v170, v12, v168
	v_fma_f32 v169, v171, v13, v169
	v_fma_f32 v185, v168, v168, v185
	v_fma_f32 v185, v169, v169, v185
	v_cvt_pk_bf16_f32 v113, v168, v169
	v_lshlrev_b32_e32 v168, 16, v114
	v_and_b32_e32 v169, 0xffff0000, v114
	v_lshlrev_b32_e32 v170, 16, v146
	v_and_b32_e32 v171, 0xffff0000, v146
	v_mul_f32_e32 v170, s24, v170
	v_mul_f32_e32 v171, s24, v171
	v_fma_f32 v168, v170, v14, v168
	v_fma_f32 v169, v171, v15, v169
	v_fma_f32 v185, v168, v168, v185
	v_fma_f32 v185, v169, v169, v185
	v_cvt_pk_bf16_f32 v114, v168, v169
	v_lshlrev_b32_e32 v168, 16, v115
	v_and_b32_e32 v169, 0xffff0000, v115
	v_lshlrev_b32_e32 v170, 16, v147
	v_and_b32_e32 v171, 0xffff0000, v147
	v_mul_f32_e32 v170, s24, v170
	v_mul_f32_e32 v171, s24, v171
	v_fma_f32 v168, v170, v16, v168
	v_fma_f32 v169, v171, v17, v169
	v_fma_f32 v185, v168, v168, v185
	v_fma_f32 v185, v169, v169, v185
	v_cvt_pk_bf16_f32 v115, v168, v169
	global_store_dwordx4 v23, v[108:111], s[0:1] offset:2048
	global_store_dwordx4 v23, v[112:115], s[0:1] offset:3072
	v_lshlrev_b32_e32 v168, 16, v116
	v_and_b32_e32 v169, 0xffff0000, v116
	v_lshlrev_b32_e32 v170, 16, v148
	v_and_b32_e32 v171, 0xffff0000, v148
	v_mul_f32_e32 v170, s98, v170
	v_mul_f32_e32 v171, s98, v171
	v_fma_f32 v168, v170, v2, v168
	v_fma_f32 v169, v171, v3, v169
	v_fma_f32 v186, v168, v168, v186
	v_fma_f32 v186, v169, v169, v186
	v_cvt_pk_bf16_f32 v116, v168, v169
	v_lshlrev_b32_e32 v168, 16, v117
	v_and_b32_e32 v169, 0xffff0000, v117
	v_lshlrev_b32_e32 v170, 16, v149
	v_and_b32_e32 v171, 0xffff0000, v149
	v_mul_f32_e32 v170, s98, v170
	v_mul_f32_e32 v171, s98, v171
	v_fma_f32 v168, v170, v4, v168
	v_fma_f32 v169, v171, v5, v169
	v_fma_f32 v186, v168, v168, v186
	v_fma_f32 v186, v169, v169, v186
	v_cvt_pk_bf16_f32 v117, v168, v169
	v_lshlrev_b32_e32 v168, 16, v118
	v_and_b32_e32 v169, 0xffff0000, v118
	v_lshlrev_b32_e32 v170, 16, v150
	v_and_b32_e32 v171, 0xffff0000, v150
	v_mul_f32_e32 v170, s98, v170
	v_mul_f32_e32 v171, s98, v171
	v_fma_f32 v168, v170, v6, v168
	v_fma_f32 v169, v171, v7, v169
	v_fma_f32 v186, v168, v168, v186
	v_fma_f32 v186, v169, v169, v186
	v_cvt_pk_bf16_f32 v118, v168, v169
	v_lshlrev_b32_e32 v168, 16, v119
	v_and_b32_e32 v169, 0xffff0000, v119
	v_lshlrev_b32_e32 v170, 16, v151
	v_and_b32_e32 v171, 0xffff0000, v151
	v_mul_f32_e32 v170, s98, v170
	v_mul_f32_e32 v171, s98, v171
	v_fma_f32 v168, v170, v8, v168
	v_fma_f32 v169, v171, v9, v169
	v_fma_f32 v186, v168, v168, v186
	v_fma_f32 v186, v169, v169, v186
	v_cvt_pk_bf16_f32 v119, v168, v169
	v_lshlrev_b32_e32 v168, 16, v120
	v_and_b32_e32 v169, 0xffff0000, v120
	v_lshlrev_b32_e32 v170, 16, v152
	v_and_b32_e32 v171, 0xffff0000, v152
	v_mul_f32_e32 v170, s98, v170
	v_mul_f32_e32 v171, s98, v171
	v_fma_f32 v168, v170, v10, v168
	v_fma_f32 v169, v171, v11, v169
	v_fma_f32 v186, v168, v168, v186
	v_fma_f32 v186, v169, v169, v186
	v_cvt_pk_bf16_f32 v120, v168, v169
	v_lshlrev_b32_e32 v168, 16, v121
	v_and_b32_e32 v169, 0xffff0000, v121
	v_lshlrev_b32_e32 v170, 16, v153
	v_and_b32_e32 v171, 0xffff0000, v153
	v_mul_f32_e32 v170, s98, v170
	v_mul_f32_e32 v171, s98, v171
	v_fma_f32 v168, v170, v12, v168
	v_fma_f32 v169, v171, v13, v169
	v_fma_f32 v186, v168, v168, v186
	v_fma_f32 v186, v169, v169, v186
	v_cvt_pk_bf16_f32 v121, v168, v169
	v_lshlrev_b32_e32 v168, 16, v122
	v_and_b32_e32 v169, 0xffff0000, v122
	v_lshlrev_b32_e32 v170, 16, v154
	v_and_b32_e32 v171, 0xffff0000, v154
	v_mul_f32_e32 v170, s98, v170
	v_mul_f32_e32 v171, s98, v171
	v_fma_f32 v168, v170, v14, v168
	v_fma_f32 v169, v171, v15, v169
	v_fma_f32 v186, v168, v168, v186
	v_fma_f32 v186, v169, v169, v186
	v_cvt_pk_bf16_f32 v122, v168, v169
	v_lshlrev_b32_e32 v168, 16, v123
	v_and_b32_e32 v169, 0xffff0000, v123
	v_lshlrev_b32_e32 v170, 16, v155
	v_and_b32_e32 v171, 0xffff0000, v155
	v_mul_f32_e32 v170, s98, v170
	v_mul_f32_e32 v171, s98, v171
	v_fma_f32 v168, v170, v16, v168
	v_fma_f32 v169, v171, v17, v169
	v_fma_f32 v186, v168, v168, v186
	v_fma_f32 v186, v169, v169, v186
	v_cvt_pk_bf16_f32 v123, v168, v169
	global_store_dwordx4 v24, v[116:119], s[0:1]
	global_store_dwordx4 v24, v[120:123], s[0:1] offset:1024
	v_lshlrev_b32_e32 v168, 16, v124
	v_and_b32_e32 v169, 0xffff0000, v124
	v_lshlrev_b32_e32 v170, 16, v156
	v_and_b32_e32 v171, 0xffff0000, v156
	v_mul_f32_e32 v170, s101, v170
	v_mul_f32_e32 v171, s101, v171
	v_fma_f32 v168, v170, v2, v168
	v_fma_f32 v169, v171, v3, v169
	v_fma_f32 v187, v168, v168, v187
	v_fma_f32 v187, v169, v169, v187
	v_cvt_pk_bf16_f32 v124, v168, v169
	v_lshlrev_b32_e32 v168, 16, v125
	v_and_b32_e32 v169, 0xffff0000, v125
	v_lshlrev_b32_e32 v170, 16, v157
	v_and_b32_e32 v171, 0xffff0000, v157
; __device__ __forceinline__ float bf_lo(unsigned w) { return __uint_as_float(w << 16); }
; __device__ __forceinline__ float bf_hi(unsigned w) { return __uint_as_float(w & 0xffff0000u); }
; __device__ __forceinline__ unsigned pk2(float lo, float hi) { bf16x2_t r = __builtin_convertvector((f32x2_t){lo, hi}, bf16x2_t); return __builtin_bit_cast(unsigned, r); }
; template <bool SRC_F32, bool FINAL, int R> __device__ __forceinline__ void ew_compute(const EwSet<SRC_F32, R>& S, int rb, const f32x4 (&g)[4], bf16* hb_out, float* out32, float scale, float* rs_out, int lane) {
;     ...
; #pragma unroll
;         for (int j = 0; j < 4; ++j) {
;             f32x4 h;
;             if constexpr (SRC_F32) h = S.h32[i][j];
;             else { const v2u hw = S.hb[i][j]; h.x = bf_lo(hw.x); h.y = bf_hi(hw.x); h.z = bf_lo(hw.y); h.w = bf_hi(hw.y); }
;             const v2u fw = S.fw[i][j];
;             f32x4 v; v.x = h.x + bf_lo(fw.x) * rs * g[j].x; v.y = h.y + bf_hi(fw.x) * rs * g[j].y; v.z = h.z + bf_lo(fw.y) * rs * g[j].z; v.w = h.w + bf_hi(fw.y) * rs * g[j].w;
;             if (FINAL) __builtin_nontemporal_store(v, (f32x4*)(out32 + (size_t)(rb + i) * D) + lane + 64 * j);
;             else { v2u o; o.x = pk2(v.x, v.y); o.y = pk2(v.z, v.w); ((v2u*)(hb_out + (size_t)(rb + i) * D) + lane)[64 * j] = o; s2 += (v.x * v.x + v.y * v.y) + (v.z * v.z + v.w * v.w); }
;         }
;         if (!FINAL) { const float tot = wave_sum(s2); if (lane == 0) rs_out[rb + i] = 1.0f / sqrtf(tot * (1.f / D) + EPS); }
	v_mul_f32_e32 v170, s101, v170
	v_mul_f32_e32 v171, s101, v171
	v_fma_f32 v168, v170, v4, v168
	v_fma_f32 v169, v171, v5, v169
	v_fma_f32 v187, v168, v168, v187
	v_fma_f32 v187, v169, v169, v187
	v_cvt_pk_bf16_f32 v125, v168, v169
	v_lshlrev_b32_e32 v168, 16, v126
	v_and_b32_e32 v169, 0xffff0000, v126
	v_lshlrev_b32_e32 v170, 16, v158
	v_and_b32_e32 v171, 0xffff0000, v158
	v_mul_f32_e32 v170, s101, v170
	v_mul_f32_e32 v171, s101, v171
	v_fma_f32 v168, v170, v6, v168
	v_fma_f32 v169, v171, v7, v169
	v_fma_f32 v187, v168, v168, v187
	v_fma_f32 v187, v169, v169, v187
	v_cvt_pk_bf16_f32 v126, v168, v169
	v_lshlrev_b32_e32 v168, 16, v127
	v_and_b32_e32 v169, 0xffff0000, v127
	v_lshlrev_b32_e32 v170, 16, v159
	v_and_b32_e32 v171, 0xffff0000, v159
	v_mul_f32_e32 v170, s101, v170
	v_mul_f32_e32 v171, s101, v171
	v_fma_f32 v168, v170, v8, v168
	v_fma_f32 v169, v171, v9, v169
	v_fma_f32 v187, v168, v168, v187
	v_fma_f32 v187, v169, v169, v187
	v_cvt_pk_bf16_f32 v127, v168, v169
	v_lshlrev_b32_e32 v168, 16, v128
	v_and_b32_e32 v169, 0xffff0000, v128
	v_lshlrev_b32_e32 v170, 16, v160
	v_and_b32_e32 v171, 0xffff0000, v160
	v_mul_f32_e32 v170, s101, v170
	v_mul_f32_e32 v171, s101, v171
	v_fma_f32 v168, v170, v10, v168
	v_fma_f32 v169, v171, v11, v169
	v_fma_f32 v187, v168, v168, v187
	v_fma_f32 v187, v169, v169, v187
	v_cvt_pk_bf16_f32 v128, v168, v169
	v_lshlrev_b32_e32 v168, 16, v129
	v_and_b32_e32 v169, 0xffff0000, v129
	v_lshlrev_b32_e32 v170, 16, v161
	v_and_b32_e32 v171, 0xffff0000, v161
	v_mul_f32_e32 v170, s101, v170
	v_mul_f32_e32 v171, s101, v171
	v_fma_f32 v168, v170, v12, v168
	v_fma_f32 v169, v171, v13, v169
	v_fma_f32 v187, v168, v168, v187
	v_fma_f32 v187, v169, v169, v187
	v_cvt_pk_bf16_f32 v129, v168, v169
	v_lshlrev_b32_e32 v168, 16, v130
	v_and_b32_e32 v169, 0xffff0000, v130
	v_lshlrev_b32_e32 v170, 16, v162
	v_and_b32_e32 v171, 0xffff0000, v162
	v_mul_f32_e32 v170, s101, v170
	v_mul_f32_e32 v171, s101, v171
	v_fma_f32 v168, v170, v14, v168
	v_fma_f32 v169, v171, v15, v169
	v_fma_f32 v187, v168, v168, v187
	v_fma_f32 v187, v169, v169, v187
	v_cvt_pk_bf16_f32 v130, v168, v169
	v_lshlrev_b32_e32 v168, 16, v131
	v_and_b32_e32 v169, 0xffff0000, v131
	v_lshlrev_b32_e32 v170, 16, v163
	v_and_b32_e32 v171, 0xffff0000, v163
	v_mul_f32_e32 v170, s101, v170
	v_mul_f32_e32 v171, s101, v171
	v_fma_f32 v168, v170, v16, v168
	v_fma_f32 v169, v171, v17, v169
	v_fma_f32 v187, v168, v168, v187
	v_fma_f32 v187, v169, v169, v187
	v_cvt_pk_bf16_f32 v131, v168, v169
	global_store_dwordx4 v24, v[124:127], s[0:1] offset:2048
	global_store_dwordx4 v24, v[128:131], s[0:1] offset:3072
	s_nop 1
	v_add_f32_dpp v184, v184, v184 quad_perm:[1,0,3,2] row_mask:0xf bank_mask:0xf
	v_add_f32_dpp v185, v185, v185 quad_perm:[1,0,3,2] row_mask:0xf bank_mask:0xf
	v_add_f32_dpp v186, v186, v186 quad_perm:[1,0,3,2] row_mask:0xf bank_mask:0xf
	v_add_f32_dpp v187, v187, v187 quad_perm:[1,0,3,2] row_mask:0xf bank_mask:0xf
	v_add_f32_dpp v184, v184, v184 quad_perm:[2,3,0,1] row_mask:0xf bank_mask:0xf
	v_add_f32_dpp v185, v185, v185 quad_perm:[2,3,0,1] row_mask:0xf bank_mask:0xf
	v_add_f32_dpp v186, v186, v186 quad_perm:[2,3,0,1] row_mask:0xf bank_mask:0xf
	v_add_f32_dpp v187, v187, v187 quad_perm:[2,3,0,1] row_mask:0xf bank_mask:0xf
	v_add_f32_dpp v184, v184, v184 row_half_mirror row_mask:0xf bank_mask:0xf
	v_add_f32_dpp v185, v185, v185 row_half_mirror row_mask:0xf bank_mask:0xf
	v_add_f32_dpp v186, v186, v186 row_half_mirror row_mask:0xf bank_mask:0xf
	v_add_f32_dpp v187, v187, v187 row_half_mirror row_mask:0xf bank_mask:0xf
	v_add_f32_dpp v184, v184, v184 row_mirror row_mask:0xf bank_mask:0xf
	v_add_f32_dpp v185, v185, v185 row_mirror row_mask:0xf bank_mask:0xf
	v_add_f32_dpp v186, v186, v186 row_mirror row_mask:0xf bank_mask:0xf
	v_add_f32_dpp v187, v187, v187 row_mirror row_mask:0xf bank_mask:0xf
	v_add_f32_dpp v184, v184, v184 row_bcast:15 row_mask:0xa bank_mask:0xf
	v_add_f32_dpp v185, v185, v185 row_bcast:15 row_mask:0xa bank_mask:0xf
	v_add_f32_dpp v186, v186, v186 row_bcast:15 row_mask:0xa bank_mask:0xf
	v_add_f32_dpp v187, v187, v187 row_bcast:15 row_mask:0xa bank_mask:0xf
	v_add_f32_dpp v184, v184, v184 row_bcast:31 row_mask:0xc bank_mask:0xf
	v_add_f32_dpp v185, v185, v185 row_bcast:31 row_mask:0xc bank_mask:0xf
	v_add_f32_dpp v186, v186, v186 row_bcast:31 row_mask:0xc bank_mask:0xf
	v_add_f32_dpp v187, v187, v187 row_bcast:31 row_mask:0xc bank_mask:0xf
	s_nop 1
	v_readlane_b32 s3, v184, 63
	v_readlane_b32 s24, v185, 63
	v_readlane_b32 s98, v186, 63
	v_readlane_b32 s101, v187, 63
	s_nop 3
	v_writelane_b32 v188, s3, 0
	v_writelane_b32 v188, s24, 1
	v_writelane_b32 v188, s98, 2
	v_writelane_b32 v188, s101, 3
	s_nop 1
	v_mul_f32_e32 v188, 0x3a800000, v188
	v_add_f32_e32 v188, 0x358637bd, v188
	v_rsq_f32_e32 v188, v188
	s_mov_b64 exec, 15
	global_store_dword v26, v188, s[14:15]
	s_mov_b64 exec, -1

; __device__ __forceinline__ float bf_lo(unsigned w) { return __uint_as_float(w << 16); }
; __device__ __forceinline__ float bf_hi(unsigned w) { return __uint_as_float(w & 0xffff0000u); }
; template <bool SRC_F32, int R> __device__ __forceinline__ void ew_load(EwSet<SRC_F32, R>& S, int rb, const float* hsrc32, const bf16* hsrcb, const bf16* f, const float* part, int lane) {
; #pragma unroll
;     for (int i = 0; i < R; ++i) S.p[i] = (lane < 16) ? part[(size_t)(rb + i) * 16 + lane] : 0.f;
; #pragma unroll
;     for (int i = 0; i < R; ++i)
; #pragma unroll
;         for (int j = 0; j < 4; ++j) {
;             S.fw[i][j] = ((const v2u*)(f + (size_t)(rb + i) * D) + lane)[64 * j];
;             if constexpr (SRC_F32) S.h32[i][j] = __builtin_nontemporal_load((const f32x4*)(hsrc32 + (size_t)(rb + i) * D) + lane + 64 * j);
;             else S.hb[i][j] = ((const v2u*)(hsrcb + (size_t)(rb + i) * D) + lane)[64 * j];
;         }
; }
; template <bool SRC_F32, bool FINAL, int R> __device__ __forceinline__ void ew_compute(const EwSet<SRC_F32, R>& S, int rb, const f32x4 (&g)[4], bf16* hb_out, float* out32, float scale, float* rs_out, int lane) {
; #pragma unroll
;     for (int i = 0; i < R; ++i) {
;         float q = S.p[i];
;         q += __shfl_xor(q, 1); q += __shfl_xor(q, 2); q += __shfl_xor(q, 4); q += __shfl_xor(q, 8);
;         const float ss = __shfl(q, 0);
;         const float rs = scale / sqrtf(ss * (1.f / D) + EPS);
;         float s2 = 0.f;
; #pragma unroll
;         for (int j = 0; j < 4; ++j) {
;             f32x4 h;
;             if constexpr (SRC_F32) h = S.h32[i][j];
;             else { const v2u hw = S.hb[i][j]; h.x = bf_lo(hw.x); h.y = bf_hi(hw.x); h.z = bf_lo(hw.y); h.w = bf_hi(hw.y); }
;             const v2u fw = S.fw[i][j];
;             f32x4 v; v.x = h.x + bf_lo(fw.x) * rs * g[j].x; v.y = h.y + bf_hi(fw.x) * rs * g[j].y; v.z = h.z + bf_lo(fw.y) * rs * g[j].z; v.w = h.w + bf_hi(fw.y) * rs * g[j].w;
;             if (FINAL) __builtin_nontemporal_store(v, (f32x4*)(out32 + (size_t)(rb + i) * D) + lane + 64 * j);
;             else { v2u o; o.x = pk2(v.x, v.y); o.y = pk2(v.z, v.w); ((v2u*)(hb_out + (size_t)(rb + i) * D) + lane)[64 * j] = o; s2 += (v.x * v.x + v.y * v.y) + (v.z * v.z + v.w * v.w); }
;         }
;         if (!FINAL) { const float tot = wave_sum(s2); if (lane == 0) rs_out[rb + i] = 1.0f / sqrtf(tot * (1.f / D) + EPS); }
;     }
; }
.LBB0_1213:
	s_cmp_lt_i32 s30, 12
	s_cselect_b64 s[4:5], -1, 0
	s_and_b64 s[8:9], s[4:5], s[0:1]
	s_andn2_b64 vcc, exec, s[8:9]
	s_cbranch_vccnz .LBB0_1259
	s_waitcnt vmcnt(0) lgkmcnt(0)
	s_add_u32 s22, s84, 0xffffff10
	s_addc_u32 s23, s85, -1
	s_load_dwordx2 s[52:53], s[22:23], 0xb0
	s_add_u32 s0, s28, 0x5000000
	s_addc_u32 s1, s29, 0
	s_add_u32 s4, s28, 0x15000000
	s_addc_u32 s5, s29, 0
	s_add_u32 s6, s28, 0x3700000
	s_addc_u32 s7, s29, 0
	s_add_u32 s14, s28, 0x3910000
	s_addc_u32 s15, s29, 0
	v_and_b32_e32 v0, 63, v195
	v_lshlrev_b32_e32 v1, 5, v0
	s_and_b32 s26, s2, 7
	s_lshl_b32 s26, s26, 4
	s_bfe_u32 s27, s2, 0x30003
	s_add_u32 s26, s26, s27
	s_lshl_b32 s26, s26, 8
	s_lshr_b32 s27, s2, 6
	s_lshl_b32 s27, s27, 6
	s_add_u32 s26, s26, s27
	v_readfirstlane_b32 s27, v195
	s_lshr_b32 s27, s27, 6
	s_lshl_b32 s27, s27, 3
	s_add_u32 s26, s26, s27
	s_add_u32 s27, s26, 0
	s_lshl_b32 s22, s27, 11
	v_lshl_add_u32 v18, v0, 4, s22
	v_add_u32_e32 v19, 0x1000, v18
	s_lshl_b32 s22, s27, 6
	v_lshl_add_u32 v20, v0, 2, s22
	s_lshl_b32 s22, s27, 2
	v_lshl_add_u32 v21, v0, 2, s22
	global_load_dwordx4 v[32:35], v18, s[0:1]
	global_load_dwordx4 v[36:39], v18, s[0:1] offset:1024
	global_load_dwordx4 v[64:67], v18, s[4:5]
	global_load_dwordx4 v[68:71], v18, s[4:5] offset:1024
	global_load_dwordx4 v[40:43], v18, s[0:1] offset:2048
	global_load_dwordx4 v[44:47], v18, s[0:1] offset:3072
	global_load_dwordx4 v[72:75], v18, s[4:5] offset:2048
	global_load_dwordx4 v[76:79], v18, s[4:5] offset:3072
	global_load_dwordx4 v[48:51], v19, s[0:1]
	global_load_dwordx4 v[52:55], v19, s[0:1] offset:1024
	global_load_dwordx4 v[80:83], v19, s[4:5]
	global_load_dwordx4 v[84:87], v19, s[4:5] offset:1024
	global_load_dwordx4 v[56:59], v19, s[0:1] offset:2048
	global_load_dwordx4 v[60:63], v19, s[0:1] offset:3072
	global_load_dwordx4 v[88:91], v19, s[4:5] offset:2048
	global_load_dwordx4 v[92:95], v19, s[4:5] offset:3072
	global_load_dword v96, v20, s[6:7]
	s_waitcnt lgkmcnt(0)
	global_load_dwordx4 v[2:5], v1, s[52:53]
	global_load_dwordx4 v[6:9], v1, s[52:53] offset:16
	global_load_dwordx4 v[10:13], v1, s[52:53] offset:2048
	global_load_dwordx4 v[14:17], v1, s[52:53] offset:2064
	s_add_u32 s27, s26, 4
	s_lshl_b32 s22, s27, 11
	v_lshl_add_u32 v23, v0, 4, s22
	v_add_u32_e32 v24, 0x1000, v23
	s_lshl_b32 s22, s27, 6
	v_lshl_add_u32 v25, v0, 2, s22
	s_lshl_b32 s22, s27, 2
	v_lshl_add_u32 v26, v0, 2, s22
	global_load_dwordx4 v[100:103], v23, s[0:1]
	global_load_dwordx4 v[104:107], v23, s[0:1] offset:1024
	global_load_dwordx4 v[132:135], v23, s[4:5]
	global_load_dwordx4 v[136:139], v23, s[4:5] offset:1024
	global_load_dwordx4 v[108:111], v23, s[0:1] offset:2048
	global_load_dwordx4 v[112:115], v23, s[0:1] offset:3072
	global_load_dwordx4 v[140:143], v23, s[4:5] offset:2048
	global_load_dwordx4 v[144:147], v23, s[4:5] offset:3072
	global_load_dwordx4 v[116:119], v24, s[0:1]
	global_load_dwordx4 v[120:123], v24, s[0:1] offset:1024
	global_load_dwordx4 v[148:151], v24, s[4:5]
	global_load_dwordx4 v[152:155], v24, s[4:5] offset:1024
	global_load_dwordx4 v[124:127], v24, s[0:1] offset:2048
	global_load_dwordx4 v[128:131], v24, s[0:1] offset:3072
	global_load_dwordx4 v[156:159], v24, s[4:5] offset:2048
	global_load_dwordx4 v[160:163], v24, s[4:5] offset:3072
	global_load_dword v164, v25, s[6:7]
	s_waitcnt vmcnt(17)
	v_add_f32_dpp v96, v96, v96 quad_perm:[1,0,3,2] row_mask:0xf bank_mask:0xf
	s_nop 1
	v_add_f32_dpp v96, v96, v96 quad_perm:[2,3,0,1] row_mask:0xf bank_mask:0xf
	s_nop 1
	v_add_f32_dpp v96, v96, v96 row_half_mirror row_mask:0xf bank_mask:0xf
	s_nop 1
	v_add_f32_dpp v96, v96, v96 row_mirror row_mask:0xf bank_mask:0xf
	s_nop 1
	v_mul_f32_e32 v96, 0x3a800000, v96
	v_add_f32_e32 v96, 0x358637bd, v96
	v_rsq_f32_e32 v96, v96
	s_nop 0
	v_mul_f32_e32 v96, 0x3f000000, v96
	s_nop 0
	v_readlane_b32 s3, v96, 0
	v_readlane_b32 s24, v96, 16
	v_readlane_b32 s98, v96, 32
	v_readlane_b32 s101, v96, 48
	s_nop 1
	v_mov_b32_e32 v184, 0
	v_mov_b32_e32 v185, 0
	v_mov_b32_e32 v186, 0
	v_mov_b32_e32 v187, 0
	v_lshlrev_b32_e32 v168, 16, v32
	v_and_b32_e32 v169, 0xffff0000, v32
	v_lshlrev_b32_e32 v170, 16, v64
	v_and_b32_e32 v171, 0xffff0000, v64
	v_mul_f32_e32 v170, s3, v170
	v_mul_f32_e32 v171, s3, v171
	v_fma_f32 v168, v170, v2, v168
	v_fma_f32 v169, v171, v3, v169
	v_fma_f32 v184, v168, v168, v184
	v_fma_f32 v184, v169, v169, v184
	v_cvt_pk_bf16_f32 v32, v168, v169
	v_lshlrev_b32_e32 v168, 16, v33
	v_and_b32_e32 v169, 0xffff0000, v33
	v_lshlrev_b32_e32 v170, 16, v65
	v_and_b32_e32 v171, 0xffff0000, v65
	v_mul_f32_e32 v170, s3, v170
	v_mul_f32_e32 v171, s3, v171
	v_fma_f32 v168, v170, v4, v168
	v_fma_f32 v169, v171, v5, v169
	v_fma_f32 v184, v168, v168, v184
	v_fma_f32 v184, v169, v169, v184
	v_cvt_pk_bf16_f32 v33, v168, v169
	v_lshlrev_b32_e32 v168, 16, v34
	v_and_b32_e32 v169, 0xffff0000, v34
	v_lshlrev_b32_e32 v170, 16, v66
	v_and_b32_e32 v171, 0xffff0000, v66
	v_mul_f32_e32 v170, s3, v170
	v_mul_f32_e32 v171, s3, v171
	v_fma_f32 v168, v170, v6, v168
	v_fma_f32 v169, v171, v7, v169
	v_fma_f32 v184, v168, v168, v184
	v_fma_f32 v184, v169, v169, v184
	v_cvt_pk_bf16_f32 v34, v168, v169
	v_lshlrev_b32_e32 v168, 16, v35
	v_and_b32_e32 v169, 0xffff0000, v35
	v_lshlrev_b32_e32 v170, 16, v67
	v_and_b32_e32 v171, 0xffff0000, v67
	v_mul_f32_e32 v170, s3, v170
	v_mul_f32_e32 v171, s3, v171
	v_fma_f32 v168, v170, v8, v168
	v_fma_f32 v169, v171, v9, v169
	v_fma_f32 v184, v168, v168, v184
	v_fma_f32 v184, v169, v169, v184
	v_cvt_pk_bf16_f32 v35, v168, v169
	v_lshlrev_b32_e32 v168, 16, v36
	v_and_b32_e32 v169, 0xffff0000, v36
	v_lshlrev_b32_e32 v170, 16, v68
	v_and_b32_e32 v171, 0xffff0000, v68
	v_mul_f32_e32 v170, s3, v170
; __device__ __forceinline__ float bf_lo(unsigned w) { return __uint_as_float(w << 16); }
; __device__ __forceinline__ float bf_hi(unsigned w) { return __uint_as_float(w & 0xffff0000u); }
; __device__ __forceinline__ unsigned pk2(float lo, float hi) { bf16x2_t r = __builtin_convertvector((f32x2_t){lo, hi}, bf16x2_t); return __builtin_bit_cast(unsigned, r); }
; template <bool SRC_F32, bool FINAL, int R> __device__ __forceinline__ void ew_compute(const EwSet<SRC_F32, R>& S, int rb, const f32x4 (&g)[4], bf16* hb_out, float* out32, float scale, float* rs_out, int lane) {
;     ...
; #pragma unroll
;         for (int j = 0; j < 4; ++j) {
;             f32x4 h;
;             if constexpr (SRC_F32) h = S.h32[i][j];
;             else { const v2u hw = S.hb[i][j]; h.x = bf_lo(hw.x); h.y = bf_hi(hw.x); h.z = bf_lo(hw.y); h.w = bf_hi(hw.y); }
;             const v2u fw = S.fw[i][j];
;             f32x4 v; v.x = h.x + bf_lo(fw.x) * rs * g[j].x; v.y = h.y + bf_hi(fw.x) * rs * g[j].y; v.z = h.z + bf_lo(fw.y) * rs * g[j].z; v.w = h.w + bf_hi(fw.y) * rs * g[j].w;
;             if (FINAL) __builtin_nontemporal_store(v, (f32x4*)(out32 + (size_t)(rb + i) * D) + lane + 64 * j);
;             else { v2u o; o.x = pk2(v.x, v.y); o.y = pk2(v.z, v.w); ((v2u*)(hb_out + (size_t)(rb + i) * D) + lane)[64 * j] = o; s2 += (v.x * v.x + v.y * v.y) + (v.z * v.z + v.w * v.w); }
	v_mul_f32_e32 v171, s3, v171
	v_fma_f32 v168, v170, v10, v168
	v_fma_f32 v169, v171, v11, v169
	v_fma_f32 v184, v168, v168, v184
	v_fma_f32 v184, v169, v169, v184
	v_cvt_pk_bf16_f32 v36, v168, v169
	v_lshlrev_b32_e32 v168, 16, v37
	v_and_b32_e32 v169, 0xffff0000, v37
	v_lshlrev_b32_e32 v170, 16, v69
	v_and_b32_e32 v171, 0xffff0000, v69
	v_mul_f32_e32 v170, s3, v170
	v_mul_f32_e32 v171, s3, v171
	v_fma_f32 v168, v170, v12, v168
	v_fma_f32 v169, v171, v13, v169
	v_fma_f32 v184, v168, v168, v184
	v_fma_f32 v184, v169, v169, v184
	v_cvt_pk_bf16_f32 v37, v168, v169
	v_lshlrev_b32_e32 v168, 16, v38
	v_and_b32_e32 v169, 0xffff0000, v38
	v_lshlrev_b32_e32 v170, 16, v70
	v_and_b32_e32 v171, 0xffff0000, v70
	v_mul_f32_e32 v170, s3, v170
	v_mul_f32_e32 v171, s3, v171
	v_fma_f32 v168, v170, v14, v168
	v_fma_f32 v169, v171, v15, v169
	v_fma_f32 v184, v168, v168, v184
	v_fma_f32 v184, v169, v169, v184
	v_cvt_pk_bf16_f32 v38, v168, v169
	v_lshlrev_b32_e32 v168, 16, v39
	v_and_b32_e32 v169, 0xffff0000, v39
	v_lshlrev_b32_e32 v170, 16, v71
	v_and_b32_e32 v171, 0xffff0000, v71
	v_mul_f32_e32 v170, s3, v170
	v_mul_f32_e32 v171, s3, v171
	v_fma_f32 v168, v170, v16, v168
	v_fma_f32 v169, v171, v17, v169
	v_fma_f32 v184, v168, v168, v184
	v_fma_f32 v184, v169, v169, v184
	v_cvt_pk_bf16_f32 v39, v168, v169
	global_store_dwordx4 v18, v[32:35], s[0:1]
	global_store_dwordx4 v18, v[36:39], s[0:1] offset:1024
	v_lshlrev_b32_e32 v168, 16, v40
	v_and_b32_e32 v169, 0xffff0000, v40
	v_lshlrev_b32_e32 v170, 16, v72
	v_and_b32_e32 v171, 0xffff0000, v72
	v_mul_f32_e32 v170, s24, v170
	v_mul_f32_e32 v171, s24, v171
	v_fma_f32 v168, v170, v2, v168
	v_fma_f32 v169, v171, v3, v169
	v_fma_f32 v185, v168, v168, v185
	v_fma_f32 v185, v169, v169, v185
	v_cvt_pk_bf16_f32 v40, v168, v169
	v_lshlrev_b32_e32 v168, 16, v41
	v_and_b32_e32 v169, 0xffff0000, v41
	v_lshlrev_b32_e32 v170, 16, v73
	v_and_b32_e32 v171, 0xffff0000, v73
	v_mul_f32_e32 v170, s24, v170
	v_mul_f32_e32 v171, s24, v171
	v_fma_f32 v168, v170, v4, v168
	v_fma_f32 v169, v171, v5, v169
	v_fma_f32 v185, v168, v168, v185
	v_fma_f32 v185, v169, v169, v185
	v_cvt_pk_bf16_f32 v41, v168, v169
	v_lshlrev_b32_e32 v168, 16, v42
	v_and_b32_e32 v169, 0xffff0000, v42
	v_lshlrev_b32_e32 v170, 16, v74
	v_and_b32_e32 v171, 0xffff0000, v74
	v_mul_f32_e32 v170, s24, v170
	v_mul_f32_e32 v171, s24, v171
	v_fma_f32 v168, v170, v6, v168
	v_fma_f32 v169, v171, v7, v169
	v_fma_f32 v185, v168, v168, v185
	v_fma_f32 v185, v169, v169, v185
	v_cvt_pk_bf16_f32 v42, v168, v169
	v_lshlrev_b32_e32 v168, 16, v43
	v_and_b32_e32 v169, 0xffff0000, v43
	v_lshlrev_b32_e32 v170, 16, v75
	v_and_b32_e32 v171, 0xffff0000, v75
	v_mul_f32_e32 v170, s24, v170
	v_mul_f32_e32 v171, s24, v171
	v_fma_f32 v168, v170, v8, v168
	v_fma_f32 v169, v171, v9, v169
	v_fma_f32 v185, v168, v168, v185
	v_fma_f32 v185, v169, v169, v185
	v_cvt_pk_bf16_f32 v43, v168, v169
	v_lshlrev_b32_e32 v168, 16, v44
	v_and_b32_e32 v169, 0xffff0000, v44
	v_lshlrev_b32_e32 v170, 16, v76
	v_and_b32_e32 v171, 0xffff0000, v76
	v_mul_f32_e32 v170, s24, v170
	v_mul_f32_e32 v171, s24, v171
	v_fma_f32 v168, v170, v10, v168
	v_fma_f32 v169, v171, v11, v169
	v_fma_f32 v185, v168, v168, v185
	v_fma_f32 v185, v169, v169, v185
	v_cvt_pk_bf16_f32 v44, v168, v169
	v_lshlrev_b32_e32 v168, 16, v45
	v_and_b32_e32 v169, 0xffff0000, v45
	v_lshlrev_b32_e32 v170, 16, v77
	v_and_b32_e32 v171, 0xffff0000, v77
	v_mul_f32_e32 v170, s24, v170
	v_mul_f32_e32 v171, s24, v171
	v_fma_f32 v168, v170, v12, v168
	v_fma_f32 v169, v171, v13, v169
	v_fma_f32 v185, v168, v168, v185
	v_fma_f32 v185, v169, v169, v185
	v_cvt_pk_bf16_f32 v45, v168, v169
	v_lshlrev_b32_e32 v168, 16, v46
	v_and_b32_e32 v169, 0xffff0000, v46
	v_lshlrev_b32_e32 v170, 16, v78
	v_and_b32_e32 v171, 0xffff0000, v78
	v_mul_f32_e32 v170, s24, v170
	v_mul_f32_e32 v171, s24, v171
	v_fma_f32 v168, v170, v14, v168
	v_fma_f32 v169, v171, v15, v169
	v_fma_f32 v185, v168, v168, v185
	v_fma_f32 v185, v169, v169, v185
	v_cvt_pk_bf16_f32 v46, v168, v169
	v_lshlrev_b32_e32 v168, 16, v47
	v_and_b32_e32 v169, 0xffff0000, v47
	v_lshlrev_b32_e32 v170, 16, v79
	v_and_b32_e32 v171, 0xffff0000, v79
	v_mul_f32_e32 v170, s24, v170
	v_mul_f32_e32 v171, s24, v171
	v_fma_f32 v168, v170, v16, v168
	v_fma_f32 v169, v171, v17, v169
	v_fma_f32 v185, v168, v168, v185
	v_fma_f32 v185, v169, v169, v185
	v_cvt_pk_bf16_f32 v47, v168, v169
	global_store_dwordx4 v18, v[40:43], s[0:1] offset:2048
	global_store_dwordx4 v18, v[44:47], s[0:1] offset:3072
	v_lshlrev_b32_e32 v168, 16, v48
	v_and_b32_e32 v169, 0xffff0000, v48
	v_lshlrev_b32_e32 v170, 16, v80
	v_and_b32_e32 v171, 0xffff0000, v80
	v_mul_f32_e32 v170, s98, v170
	v_mul_f32_e32 v171, s98, v171
	v_fma_f32 v168, v170, v2, v168
	v_fma_f32 v169, v171, v3, v169
	v_fma_f32 v186, v168, v168, v186
	v_fma_f32 v186, v169, v169, v186
	v_cvt_pk_bf16_f32 v48, v168, v169
	v_lshlrev_b32_e32 v168, 16, v49
	v_and_b32_e32 v169, 0xffff0000, v49
	v_lshlrev_b32_e32 v170, 16, v81
	v_and_b32_e32 v171, 0xffff0000, v81
	v_mul_f32_e32 v170, s98, v170
	v_mul_f32_e32 v171, s98, v171
	v_fma_f32 v168, v170, v4, v168
	v_fma_f32 v169, v171, v5, v169
	v_fma_f32 v186, v168, v168, v186
	v_fma_f32 v186, v169, v169, v186
	v_cvt_pk_bf16_f32 v49, v168, v169
	v_lshlrev_b32_e32 v168, 16, v50
	v_and_b32_e32 v169, 0xffff0000, v50
	v_lshlrev_b32_e32 v170, 16, v82
	v_and_b32_e32 v171, 0xffff0000, v82
	v_mul_f32_e32 v170, s98, v170
	v_mul_f32_e32 v171, s98, v171
	v_fma_f32 v168, v170, v6, v168
	v_fma_f32 v169, v171, v7, v169
	v_fma_f32 v186, v168, v168, v186
	v_fma_f32 v186, v169, v169, v186
	v_cvt_pk_bf16_f32 v50, v168, v169
	v_lshlrev_b32_e32 v168, 16, v51
	v_and_b32_e32 v169, 0xffff0000, v51
; __device__ __forceinline__ float bf_lo(unsigned w) { return __uint_as_float(w << 16); }
; __device__ __forceinline__ float bf_hi(unsigned w) { return __uint_as_float(w & 0xffff0000u); }
; __device__ __forceinline__ unsigned pk2(float lo, float hi) { bf16x2_t r = __builtin_convertvector((f32x2_t){lo, hi}, bf16x2_t); return __builtin_bit_cast(unsigned, r); }
; template <bool SRC_F32, bool FINAL, int R> __device__ __forceinline__ void ew_compute(const EwSet<SRC_F32, R>& S, int rb, const f32x4 (&g)[4], bf16* hb_out, float* out32, float scale, float* rs_out, int lane) {
;     ...
; #pragma unroll
;         for (int j = 0; j < 4; ++j) {
;             f32x4 h;
;             if constexpr (SRC_F32) h = S.h32[i][j];
;             else { const v2u hw = S.hb[i][j]; h.x = bf_lo(hw.x); h.y = bf_hi(hw.x); h.z = bf_lo(hw.y); h.w = bf_hi(hw.y); }
;             const v2u fw = S.fw[i][j];
;             f32x4 v; v.x = h.x + bf_lo(fw.x) * rs * g[j].x; v.y = h.y + bf_hi(fw.x) * rs * g[j].y; v.z = h.z + bf_lo(fw.y) * rs * g[j].z; v.w = h.w + bf_hi(fw.y) * rs * g[j].w;
;             if (FINAL) __builtin_nontemporal_store(v, (f32x4*)(out32 + (size_t)(rb + i) * D) + lane + 64 * j);
;             else { v2u o; o.x = pk2(v.x, v.y); o.y = pk2(v.z, v.w); ((v2u*)(hb_out + (size_t)(rb + i) * D) + lane)[64 * j] = o; s2 += (v.x * v.x + v.y * v.y) + (v.z * v.z + v.w * v.w); }
;         }
;         if (!FINAL) { const float tot = wave_sum(s2); if (lane == 0) rs_out[rb + i] = 1.0f / sqrtf(tot * (1.f / D) + EPS); }
	v_lshlrev_b32_e32 v170, 16, v83
	v_and_b32_e32 v171, 0xffff0000, v83
	v_mul_f32_e32 v170, s98, v170
	v_mul_f32_e32 v171, s98, v171
	v_fma_f32 v168, v170, v8, v168
	v_fma_f32 v169, v171, v9, v169
	v_fma_f32 v186, v168, v168, v186
	v_fma_f32 v186, v169, v169, v186
	v_cvt_pk_bf16_f32 v51, v168, v169
	v_lshlrev_b32_e32 v168, 16, v52
	v_and_b32_e32 v169, 0xffff0000, v52
	v_lshlrev_b32_e32 v170, 16, v84
	v_and_b32_e32 v171, 0xffff0000, v84
	v_mul_f32_e32 v170, s98, v170
	v_mul_f32_e32 v171, s98, v171
	v_fma_f32 v168, v170, v10, v168
	v_fma_f32 v169, v171, v11, v169
	v_fma_f32 v186, v168, v168, v186
	v_fma_f32 v186, v169, v169, v186
	v_cvt_pk_bf16_f32 v52, v168, v169
	v_lshlrev_b32_e32 v168, 16, v53
	v_and_b32_e32 v169, 0xffff0000, v53
	v_lshlrev_b32_e32 v170, 16, v85
	v_and_b32_e32 v171, 0xffff0000, v85
	v_mul_f32_e32 v170, s98, v170
	v_mul_f32_e32 v171, s98, v171
	v_fma_f32 v168, v170, v12, v168
	v_fma_f32 v169, v171, v13, v169
	v_fma_f32 v186, v168, v168, v186
	v_fma_f32 v186, v169, v169, v186
	v_cvt_pk_bf16_f32 v53, v168, v169
	v_lshlrev_b32_e32 v168, 16, v54
	v_and_b32_e32 v169, 0xffff0000, v54
	v_lshlrev_b32_e32 v170, 16, v86
	v_and_b32_e32 v171, 0xffff0000, v86
	v_mul_f32_e32 v170, s98, v170
	v_mul_f32_e32 v171, s98, v171
	v_fma_f32 v168, v170, v14, v168
	v_fma_f32 v169, v171, v15, v169
	v_fma_f32 v186, v168, v168, v186
	v_fma_f32 v186, v169, v169, v186
	v_cvt_pk_bf16_f32 v54, v168, v169
	v_lshlrev_b32_e32 v168, 16, v55
	v_and_b32_e32 v169, 0xffff0000, v55
	v_lshlrev_b32_e32 v170, 16, v87
	v_and_b32_e32 v171, 0xffff0000, v87
	v_mul_f32_e32 v170, s98, v170
	v_mul_f32_e32 v171, s98, v171
	v_fma_f32 v168, v170, v16, v168
	v_fma_f32 v169, v171, v17, v169
	v_fma_f32 v186, v168, v168, v186
	v_fma_f32 v186, v169, v169, v186
	v_cvt_pk_bf16_f32 v55, v168, v169
	global_store_dwordx4 v19, v[48:51], s[0:1]
	global_store_dwordx4 v19, v[52:55], s[0:1] offset:1024
	v_lshlrev_b32_e32 v168, 16, v56
	v_and_b32_e32 v169, 0xffff0000, v56
	v_lshlrev_b32_e32 v170, 16, v88
	v_and_b32_e32 v171, 0xffff0000, v88
	v_mul_f32_e32 v170, s101, v170
	v_mul_f32_e32 v171, s101, v171
	v_fma_f32 v168, v170, v2, v168
	v_fma_f32 v169, v171, v3, v169
	v_fma_f32 v187, v168, v168, v187
	v_fma_f32 v187, v169, v169, v187
	v_cvt_pk_bf16_f32 v56, v168, v169
	v_lshlrev_b32_e32 v168, 16, v57
	v_and_b32_e32 v169, 0xffff0000, v57
	v_lshlrev_b32_e32 v170, 16, v89
	v_and_b32_e32 v171, 0xffff0000, v89
	v_mul_f32_e32 v170, s101, v170
	v_mul_f32_e32 v171, s101, v171
	v_fma_f32 v168, v170, v4, v168
	v_fma_f32 v169, v171, v5, v169
	v_fma_f32 v187, v168, v168, v187
	v_fma_f32 v187, v169, v169, v187
	v_cvt_pk_bf16_f32 v57, v168, v169
	v_lshlrev_b32_e32 v168, 16, v58
	v_and_b32_e32 v169, 0xffff0000, v58
	v_lshlrev_b32_e32 v170, 16, v90
	v_and_b32_e32 v171, 0xffff0000, v90
	v_mul_f32_e32 v170, s101, v170
	v_mul_f32_e32 v171, s101, v171
	v_fma_f32 v168, v170, v6, v168
	v_fma_f32 v169, v171, v7, v169
	v_fma_f32 v187, v168, v168, v187
	v_fma_f32 v187, v169, v169, v187
	v_cvt_pk_bf16_f32 v58, v168, v169
	v_lshlrev_b32_e32 v168, 16, v59
	v_and_b32_e32 v169, 0xffff0000, v59
	v_lshlrev_b32_e32 v170, 16, v91
	v_and_b32_e32 v171, 0xffff0000, v91
	v_mul_f32_e32 v170, s101, v170
	v_mul_f32_e32 v171, s101, v171
	v_fma_f32 v168, v170, v8, v168
	v_fma_f32 v169, v171, v9, v169
	v_fma_f32 v187, v168, v168, v187
	v_fma_f32 v187, v169, v169, v187
	v_cvt_pk_bf16_f32 v59, v168, v169
	v_lshlrev_b32_e32 v168, 16, v60
	v_and_b32_e32 v169, 0xffff0000, v60
	v_lshlrev_b32_e32 v170, 16, v92
	v_and_b32_e32 v171, 0xffff0000, v92
	v_mul_f32_e32 v170, s101, v170
	v_mul_f32_e32 v171, s101, v171
	v_fma_f32 v168, v170, v10, v168
	v_fma_f32 v169, v171, v11, v169
	v_fma_f32 v187, v168, v168, v187
	v_fma_f32 v187, v169, v169, v187
	v_cvt_pk_bf16_f32 v60, v168, v169
	v_lshlrev_b32_e32 v168, 16, v61
	v_and_b32_e32 v169, 0xffff0000, v61
	v_lshlrev_b32_e32 v170, 16, v93
	v_and_b32_e32 v171, 0xffff0000, v93
	v_mul_f32_e32 v170, s101, v170
	v_mul_f32_e32 v171, s101, v171
	v_fma_f32 v168, v170, v12, v168
	v_fma_f32 v169, v171, v13, v169
	v_fma_f32 v187, v168, v168, v187
	v_fma_f32 v187, v169, v169, v187
	v_cvt_pk_bf16_f32 v61, v168, v169
	v_lshlrev_b32_e32 v168, 16, v62
	v_and_b32_e32 v169, 0xffff0000, v62
	v_lshlrev_b32_e32 v170, 16, v94
	v_and_b32_e32 v171, 0xffff0000, v94
	v_mul_f32_e32 v170, s101, v170
	v_mul_f32_e32 v171, s101, v171
	v_fma_f32 v168, v170, v14, v168
	v_fma_f32 v169, v171, v15, v169
	v_fma_f32 v187, v168, v168, v187
	v_fma_f32 v187, v169, v169, v187
	v_cvt_pk_bf16_f32 v62, v168, v169
	v_lshlrev_b32_e32 v168, 16, v63
	v_and_b32_e32 v169, 0xffff0000, v63
	v_lshlrev_b32_e32 v170, 16, v95
	v_and_b32_e32 v171, 0xffff0000, v95
	v_mul_f32_e32 v170, s101, v170
	v_mul_f32_e32 v171, s101, v171
	v_fma_f32 v168, v170, v16, v168
	v_fma_f32 v169, v171, v17, v169
	v_fma_f32 v187, v168, v168, v187
	v_fma_f32 v187, v169, v169, v187
	v_cvt_pk_bf16_f32 v63, v168, v169
	global_store_dwordx4 v19, v[56:59], s[0:1] offset:2048
	global_store_dwordx4 v19, v[60:63], s[0:1] offset:3072
	s_nop 1
	v_add_f32_dpp v184, v184, v184 quad_perm:[1,0,3,2] row_mask:0xf bank_mask:0xf
	v_add_f32_dpp v185, v185, v185 quad_perm:[1,0,3,2] row_mask:0xf bank_mask:0xf
	v_add_f32_dpp v186, v186, v186 quad_perm:[1,0,3,2] row_mask:0xf bank_mask:0xf
	v_add_f32_dpp v187, v187, v187 quad_perm:[1,0,3,2] row_mask:0xf bank_mask:0xf
	v_add_f32_dpp v184, v184, v184 quad_perm:[2,3,0,1] row_mask:0xf bank_mask:0xf
	v_add_f32_dpp v185, v185, v185 quad_perm:[2,3,0,1] row_mask:0xf bank_mask:0xf
	v_add_f32_dpp v186, v186, v186 quad_perm:[2,3,0,1] row_mask:0xf bank_mask:0xf
	v_add_f32_dpp v187, v187, v187 quad_perm:[2,3,0,1] row_mask:0xf bank_mask:0xf
; __device__ __forceinline__ float bf_lo(unsigned w) { return __uint_as_float(w << 16); }
; __device__ __forceinline__ float bf_hi(unsigned w) { return __uint_as_float(w & 0xffff0000u); }
; template <bool SRC_F32, int R> __device__ __forceinline__ void ew_load(EwSet<SRC_F32, R>& S, int rb, const float* hsrc32, const bf16* hsrcb, const bf16* f, const float* part, int lane) {
; #pragma unroll
;     for (int i = 0; i < R; ++i) S.p[i] = (lane < 16) ? part[(size_t)(rb + i) * 16 + lane] : 0.f;
; #pragma unroll
;     for (int i = 0; i < R; ++i)
; #pragma unroll
;         for (int j = 0; j < 4; ++j) {
;             S.fw[i][j] = ((const v2u*)(f + (size_t)(rb + i) * D) + lane)[64 * j];
;             if constexpr (SRC_F32) S.h32[i][j] = __builtin_nontemporal_load((const f32x4*)(hsrc32 + (size_t)(rb + i) * D) + lane + 64 * j);
;             else S.hb[i][j] = ((const v2u*)(hsrcb + (size_t)(rb + i) * D) + lane)[64 * j];
;         }
; }
; template <bool SRC_F32, bool FINAL, int R> __device__ __forceinline__ void ew_compute(const EwSet<SRC_F32, R>& S, int rb, const f32x4 (&g)[4], bf16* hb_out, float* out32, float scale, float* rs_out, int lane) {
; #pragma unroll
;     for (int i = 0; i < R; ++i) {
;         float q = S.p[i];
;         q += __shfl_xor(q, 1); q += __shfl_xor(q, 2); q += __shfl_xor(q, 4); q += __shfl_xor(q, 8);
;         const float ss = __shfl(q, 0);
;         const float rs = scale / sqrtf(ss * (1.f / D) + EPS);
;         float s2 = 0.f;
; #pragma unroll
;         for (int j = 0; j < 4; ++j) {
;             f32x4 h;
;             if constexpr (SRC_F32) h = S.h32[i][j];
;             else { const v2u hw = S.hb[i][j]; h.x = bf_lo(hw.x); h.y = bf_hi(hw.x); h.z = bf_lo(hw.y); h.w = bf_hi(hw.y); }
;             const v2u fw = S.fw[i][j];
;             f32x4 v; v.x = h.x + bf_lo(fw.x) * rs * g[j].x; v.y = h.y + bf_hi(fw.x) * rs * g[j].y; v.z = h.z + bf_lo(fw.y) * rs * g[j].z; v.w = h.w + bf_hi(fw.y) * rs * g[j].w;
;             if (FINAL) __builtin_nontemporal_store(v, (f32x4*)(out32 + (size_t)(rb + i) * D) + lane + 64 * j);
;             else { v2u o; o.x = pk2(v.x, v.y); o.y = pk2(v.z, v.w); ((v2u*)(hb_out + (size_t)(rb + i) * D) + lane)[64 * j] = o; s2 += (v.x * v.x + v.y * v.y) + (v.z * v.z + v.w * v.w); }
;         }
;         if (!FINAL) { const float tot = wave_sum(s2); if (lane == 0) rs_out[rb + i] = 1.0f / sqrtf(tot * (1.f / D) + EPS); }
	v_add_f32_dpp v184, v184, v184 row_half_mirror row_mask:0xf bank_mask:0xf
	v_add_f32_dpp v185, v185, v185 row_half_mirror row_mask:0xf bank_mask:0xf
	v_add_f32_dpp v186, v186, v186 row_half_mirror row_mask:0xf bank_mask:0xf
	v_add_f32_dpp v187, v187, v187 row_half_mirror row_mask:0xf bank_mask:0xf
	v_add_f32_dpp v184, v184, v184 row_mirror row_mask:0xf bank_mask:0xf
	v_add_f32_dpp v185, v185, v185 row_mirror row_mask:0xf bank_mask:0xf
	v_add_f32_dpp v186, v186, v186 row_mirror row_mask:0xf bank_mask:0xf
	v_add_f32_dpp v187, v187, v187 row_mirror row_mask:0xf bank_mask:0xf
	v_add_f32_dpp v184, v184, v184 row_bcast:15 row_mask:0xa bank_mask:0xf
	v_add_f32_dpp v185, v185, v185 row_bcast:15 row_mask:0xa bank_mask:0xf
	v_add_f32_dpp v186, v186, v186 row_bcast:15 row_mask:0xa bank_mask:0xf
	v_add_f32_dpp v187, v187, v187 row_bcast:15 row_mask:0xa bank_mask:0xf
	v_add_f32_dpp v184, v184, v184 row_bcast:31 row_mask:0xc bank_mask:0xf
	v_add_f32_dpp v185, v185, v185 row_bcast:31 row_mask:0xc bank_mask:0xf
	v_add_f32_dpp v186, v186, v186 row_bcast:31 row_mask:0xc bank_mask:0xf
	v_add_f32_dpp v187, v187, v187 row_bcast:31 row_mask:0xc bank_mask:0xf
	s_nop 1
	v_readlane_b32 s3, v184, 63
	v_readlane_b32 s24, v185, 63
	v_readlane_b32 s98, v186, 63
	v_readlane_b32 s101, v187, 63
	s_nop 3
	v_writelane_b32 v188, s3, 0
	v_writelane_b32 v188, s24, 1
	v_writelane_b32 v188, s98, 2
	v_writelane_b32 v188, s101, 3
	s_nop 1
	v_mul_f32_e32 v188, 0x3a800000, v188
	v_add_f32_e32 v188, 0x358637bd, v188
	v_rsq_f32_e32 v188, v188
	s_mov_b64 exec, 15
	global_store_dword v21, v188, s[14:15]
	s_mov_b64 exec, -1
	s_add_u32 s27, s26, 2048
	s_lshl_b32 s22, s27, 11
	v_lshl_add_u32 v18, v0, 4, s22
	v_add_u32_e32 v19, 0x1000, v18
	s_lshl_b32 s22, s27, 6
	v_lshl_add_u32 v20, v0, 2, s22
	s_lshl_b32 s22, s27, 2
	v_lshl_add_u32 v21, v0, 2, s22
	global_load_dwordx4 v[32:35], v18, s[0:1]
	global_load_dwordx4 v[36:39], v18, s[0:1] offset:1024
	global_load_dwordx4 v[64:67], v18, s[4:5]
	global_load_dwordx4 v[68:71], v18, s[4:5] offset:1024
	global_load_dwordx4 v[40:43], v18, s[0:1] offset:2048
	global_load_dwordx4 v[44:47], v18, s[0:1] offset:3072
	global_load_dwordx4 v[72:75], v18, s[4:5] offset:2048
	global_load_dwordx4 v[76:79], v18, s[4:5] offset:3072
	global_load_dwordx4 v[48:51], v19, s[0:1]
	global_load_dwordx4 v[52:55], v19, s[0:1] offset:1024
	global_load_dwordx4 v[80:83], v19, s[4:5]
	global_load_dwordx4 v[84:87], v19, s[4:5] offset:1024
	global_load_dwordx4 v[56:59], v19, s[0:1] offset:2048
	global_load_dwordx4 v[60:63], v19, s[0:1] offset:3072
	global_load_dwordx4 v[88:91], v19, s[4:5] offset:2048
	global_load_dwordx4 v[92:95], v19, s[4:5] offset:3072
	global_load_dword v96, v20, s[6:7]
	s_waitcnt vmcnt(26)
	v_add_f32_dpp v164, v164, v164 quad_perm:[1,0,3,2] row_mask:0xf bank_mask:0xf
	s_nop 1
	v_add_f32_dpp v164, v164, v164 quad_perm:[2,3,0,1] row_mask:0xf bank_mask:0xf
	s_nop 1
	v_add_f32_dpp v164, v164, v164 row_half_mirror row_mask:0xf bank_mask:0xf
	s_nop 1
	v_add_f32_dpp v164, v164, v164 row_mirror row_mask:0xf bank_mask:0xf
	s_nop 1
	v_mul_f32_e32 v164, 0x3a800000, v164
	v_add_f32_e32 v164, 0x358637bd, v164
	v_rsq_f32_e32 v164, v164
	s_nop 0
	v_mul_f32_e32 v164, 0x3f000000, v164
	s_nop 0
	v_readlane_b32 s3, v164, 0
	v_readlane_b32 s24, v164, 16
	v_readlane_b32 s98, v164, 32
	v_readlane_b32 s101, v164, 48
	s_nop 1
	v_mov_b32_e32 v184, 0
	v_mov_b32_e32 v185, 0
	v_mov_b32_e32 v186, 0
	v_mov_b32_e32 v187, 0
	v_lshlrev_b32_e32 v168, 16, v100
	v_and_b32_e32 v169, 0xffff0000, v100
	v_lshlrev_b32_e32 v170, 16, v132
	v_and_b32_e32 v171, 0xffff0000, v132
	v_mul_f32_e32 v170, s3, v170
	v_mul_f32_e32 v171, s3, v171
	v_fma_f32 v168, v170, v2, v168
	v_fma_f32 v169, v171, v3, v169
	v_fma_f32 v184, v168, v168, v184
	v_fma_f32 v184, v169, v169, v184
	v_cvt_pk_bf16_f32 v100, v168, v169
	v_lshlrev_b32_e32 v168, 16, v101
	v_and_b32_e32 v169, 0xffff0000, v101
	v_lshlrev_b32_e32 v170, 16, v133
	v_and_b32_e32 v171, 0xffff0000, v133
	v_mul_f32_e32 v170, s3, v170
	v_mul_f32_e32 v171, s3, v171
	v_fma_f32 v168, v170, v4, v168
	v_fma_f32 v169, v171, v5, v169
	v_fma_f32 v184, v168, v168, v184
	v_fma_f32 v184, v169, v169, v184
	v_cvt_pk_bf16_f32 v101, v168, v169
	v_lshlrev_b32_e32 v168, 16, v102
	v_and_b32_e32 v169, 0xffff0000, v102
	v_lshlrev_b32_e32 v170, 16, v134
	v_and_b32_e32 v171, 0xffff0000, v134
	v_mul_f32_e32 v170, s3, v170
	v_mul_f32_e32 v171, s3, v171
	v_fma_f32 v168, v170, v6, v168
	v_fma_f32 v169, v171, v7, v169
	v_fma_f32 v184, v168, v168, v184
	v_fma_f32 v184, v169, v169, v184
	v_cvt_pk_bf16_f32 v102, v168, v169
	v_lshlrev_b32_e32 v168, 16, v103
	v_and_b32_e32 v169, 0xffff0000, v103
	v_lshlrev_b32_e32 v170, 16, v135
	v_and_b32_e32 v171, 0xffff0000, v135
	v_mul_f32_e32 v170, s3, v170
	v_mul_f32_e32 v171, s3, v171
	v_fma_f32 v168, v170, v8, v168
	v_fma_f32 v169, v171, v9, v169
	v_fma_f32 v184, v168, v168, v184
	v_fma_f32 v184, v169, v169, v184
	v_cvt_pk_bf16_f32 v103, v168, v169
	v_lshlrev_b32_e32 v168, 16, v104
	v_and_b32_e32 v169, 0xffff0000, v104
	v_lshlrev_b32_e32 v170, 16, v136
	v_and_b32_e32 v171, 0xffff0000, v136
	v_mul_f32_e32 v170, s3, v170
	v_mul_f32_e32 v171, s3, v171
	v_fma_f32 v168, v170, v10, v168
	v_fma_f32 v169, v171, v11, v169
	v_fma_f32 v184, v168, v168, v184
	v_fma_f32 v184, v169, v169, v184
	v_cvt_pk_bf16_f32 v104, v168, v169
	v_lshlrev_b32_e32 v168, 16, v105
	v_and_b32_e32 v169, 0xffff0000, v105
	v_lshlrev_b32_e32 v170, 16, v137
	v_and_b32_e32 v171, 0xffff0000, v137
	v_mul_f32_e32 v170, s3, v170
	v_mul_f32_e32 v171, s3, v171
	v_fma_f32 v168, v170, v12, v168
	v_fma_f32 v169, v171, v13, v169
	v_fma_f32 v184, v168, v168, v184
	v_fma_f32 v184, v169, v169, v184
; __device__ __forceinline__ float bf_lo(unsigned w) { return __uint_as_float(w << 16); }
; __device__ __forceinline__ float bf_hi(unsigned w) { return __uint_as_float(w & 0xffff0000u); }
; __device__ __forceinline__ unsigned pk2(float lo, float hi) { bf16x2_t r = __builtin_convertvector((f32x2_t){lo, hi}, bf16x2_t); return __builtin_bit_cast(unsigned, r); }
; template <bool SRC_F32, bool FINAL, int R> __device__ __forceinline__ void ew_compute(const EwSet<SRC_F32, R>& S, int rb, const f32x4 (&g)[4], bf16* hb_out, float* out32, float scale, float* rs_out, int lane) {
;     ...
; #pragma unroll
;         for (int j = 0; j < 4; ++j) {
;             f32x4 h;
;             if constexpr (SRC_F32) h = S.h32[i][j];
;             else { const v2u hw = S.hb[i][j]; h.x = bf_lo(hw.x); h.y = bf_hi(hw.x); h.z = bf_lo(hw.y); h.w = bf_hi(hw.y); }
;             const v2u fw = S.fw[i][j];
;             f32x4 v; v.x = h.x + bf_lo(fw.x) * rs * g[j].x; v.y = h.y + bf_hi(fw.x) * rs * g[j].y; v.z = h.z + bf_lo(fw.y) * rs * g[j].z; v.w = h.w + bf_hi(fw.y) * rs * g[j].w;
;             if (FINAL) __builtin_nontemporal_store(v, (f32x4*)(out32 + (size_t)(rb + i) * D) + lane + 64 * j);
;             else { v2u o; o.x = pk2(v.x, v.y); o.y = pk2(v.z, v.w); ((v2u*)(hb_out + (size_t)(rb + i) * D) + lane)[64 * j] = o; s2 += (v.x * v.x + v.y * v.y) + (v.z * v.z + v.w * v.w); }
	v_cvt_pk_bf16_f32 v105, v168, v169
	v_lshlrev_b32_e32 v168, 16, v106
	v_and_b32_e32 v169, 0xffff0000, v106
	v_lshlrev_b32_e32 v170, 16, v138
	v_and_b32_e32 v171, 0xffff0000, v138
	v_mul_f32_e32 v170, s3, v170
	v_mul_f32_e32 v171, s3, v171
	v_fma_f32 v168, v170, v14, v168
	v_fma_f32 v169, v171, v15, v169
	v_fma_f32 v184, v168, v168, v184
	v_fma_f32 v184, v169, v169, v184
	v_cvt_pk_bf16_f32 v106, v168, v169
	v_lshlrev_b32_e32 v168, 16, v107
	v_and_b32_e32 v169, 0xffff0000, v107
	v_lshlrev_b32_e32 v170, 16, v139
	v_and_b32_e32 v171, 0xffff0000, v139
	v_mul_f32_e32 v170, s3, v170
	v_mul_f32_e32 v171, s3, v171
	v_fma_f32 v168, v170, v16, v168
	v_fma_f32 v169, v171, v17, v169
	v_fma_f32 v184, v168, v168, v184
	v_fma_f32 v184, v169, v169, v184
	v_cvt_pk_bf16_f32 v107, v168, v169
	global_store_dwordx4 v23, v[100:103], s[0:1]
	global_store_dwordx4 v23, v[104:107], s[0:1] offset:1024
	v_lshlrev_b32_e32 v168, 16, v108
	v_and_b32_e32 v169, 0xffff0000, v108
	v_lshlrev_b32_e32 v170, 16, v140
	v_and_b32_e32 v171, 0xffff0000, v140
	v_mul_f32_e32 v170, s24, v170
	v_mul_f32_e32 v171, s24, v171
	v_fma_f32 v168, v170, v2, v168
	v_fma_f32 v169, v171, v3, v169
	v_fma_f32 v185, v168, v168, v185
	v_fma_f32 v185, v169, v169, v185
	v_cvt_pk_bf16_f32 v108, v168, v169
	v_lshlrev_b32_e32 v168, 16, v109
	v_and_b32_e32 v169, 0xffff0000, v109
	v_lshlrev_b32_e32 v170, 16, v141
	v_and_b32_e32 v171, 0xffff0000, v141
	v_mul_f32_e32 v170, s24, v170
	v_mul_f32_e32 v171, s24, v171
	v_fma_f32 v168, v170, v4, v168
	v_fma_f32 v169, v171, v5, v169
	v_fma_f32 v185, v168, v168, v185
	v_fma_f32 v185, v169, v169, v185
	v_cvt_pk_bf16_f32 v109, v168, v169
	v_lshlrev_b32_e32 v168, 16, v110
	v_and_b32_e32 v169, 0xffff0000, v110
	v_lshlrev_b32_e32 v170, 16, v142
	v_and_b32_e32 v171, 0xffff0000, v142
	v_mul_f32_e32 v170, s24, v170
	v_mul_f32_e32 v171, s24, v171
	v_fma_f32 v168, v170, v6, v168
	v_fma_f32 v169, v171, v7, v169
	v_fma_f32 v185, v168, v168, v185
	v_fma_f32 v185, v169, v169, v185
	v_cvt_pk_bf16_f32 v110, v168, v169
	v_lshlrev_b32_e32 v168, 16, v111
	v_and_b32_e32 v169, 0xffff0000, v111
	v_lshlrev_b32_e32 v170, 16, v143
	v_and_b32_e32 v171, 0xffff0000, v143
	v_mul_f32_e32 v170, s24, v170
	v_mul_f32_e32 v171, s24, v171
	v_fma_f32 v168, v170, v8, v168
	v_fma_f32 v169, v171, v9, v169
	v_fma_f32 v185, v168, v168, v185
	v_fma_f32 v185, v169, v169, v185
	v_cvt_pk_bf16_f32 v111, v168, v169
	v_lshlrev_b32_e32 v168, 16, v112
	v_and_b32_e32 v169, 0xffff0000, v112
	v_lshlrev_b32_e32 v170, 16, v144
	v_and_b32_e32 v171, 0xffff0000, v144
	v_mul_f32_e32 v170, s24, v170
	v_mul_f32_e32 v171, s24, v171
	v_fma_f32 v168, v170, v10, v168
	v_fma_f32 v169, v171, v11, v169
	v_fma_f32 v185, v168, v168, v185
	v_fma_f32 v185, v169, v169, v185
	v_cvt_pk_bf16_f32 v112, v168, v169
	v_lshlrev_b32_e32 v168, 16, v113
	v_and_b32_e32 v169, 0xffff0000, v113
	v_lshlrev_b32_e32 v170, 16, v145
	v_and_b32_e32 v171, 0xffff0000, v145
	v_mul_f32_e32 v170, s24, v170
	v_mul_f32_e32 v171, s24, v171
	v_fma_f32 v168, v170, v12, v168
	v_fma_f32 v169, v171, v13, v169
	v_fma_f32 v185, v168, v168, v185
	v_fma_f32 v185, v169, v169, v185
	v_cvt_pk_bf16_f32 v113, v168, v169
	v_lshlrev_b32_e32 v168, 16, v114
	v_and_b32_e32 v169, 0xffff0000, v114
	v_lshlrev_b32_e32 v170, 16, v146
	v_and_b32_e32 v171, 0xffff0000, v146
	v_mul_f32_e32 v170, s24, v170
	v_mul_f32_e32 v171, s24, v171
	v_fma_f32 v168, v170, v14, v168
	v_fma_f32 v169, v171, v15, v169
	v_fma_f32 v185, v168, v168, v185
	v_fma_f32 v185, v169, v169, v185
	v_cvt_pk_bf16_f32 v114, v168, v169
	v_lshlrev_b32_e32 v168, 16, v115
	v_and_b32_e32 v169, 0xffff0000, v115
	v_lshlrev_b32_e32 v170, 16, v147
	v_and_b32_e32 v171, 0xffff0000, v147
	v_mul_f32_e32 v170, s24, v170
	v_mul_f32_e32 v171, s24, v171
	v_fma_f32 v168, v170, v16, v168
	v_fma_f32 v169, v171, v17, v169
	v_fma_f32 v185, v168, v168, v185
	v_fma_f32 v185, v169, v169, v185
	v_cvt_pk_bf16_f32 v115, v168, v169
	global_store_dwordx4 v23, v[108:111], s[0:1] offset:2048
	global_store_dwordx4 v23, v[112:115], s[0:1] offset:3072
	v_lshlrev_b32_e32 v168, 16, v116
	v_and_b32_e32 v169, 0xffff0000, v116
	v_lshlrev_b32_e32 v170, 16, v148
	v_and_b32_e32 v171, 0xffff0000, v148
	v_mul_f32_e32 v170, s98, v170
	v_mul_f32_e32 v171, s98, v171
	v_fma_f32 v168, v170, v2, v168
	v_fma_f32 v169, v171, v3, v169
	v_fma_f32 v186, v168, v168, v186
	v_fma_f32 v186, v169, v169, v186
	v_cvt_pk_bf16_f32 v116, v168, v169
	v_lshlrev_b32_e32 v168, 16, v117
	v_and_b32_e32 v169, 0xffff0000, v117
	v_lshlrev_b32_e32 v170, 16, v149
	v_and_b32_e32 v171, 0xffff0000, v149
	v_mul_f32_e32 v170, s98, v170
	v_mul_f32_e32 v171, s98, v171
	v_fma_f32 v168, v170, v4, v168
	v_fma_f32 v169, v171, v5, v169
	v_fma_f32 v186, v168, v168, v186
	v_fma_f32 v186, v169, v169, v186
	v_cvt_pk_bf16_f32 v117, v168, v169
	v_lshlrev_b32_e32 v168, 16, v118
	v_and_b32_e32 v169, 0xffff0000, v118
	v_lshlrev_b32_e32 v170, 16, v150
	v_and_b32_e32 v171, 0xffff0000, v150
	v_mul_f32_e32 v170, s98, v170
	v_mul_f32_e32 v171, s98, v171
	v_fma_f32 v168, v170, v6, v168
	v_fma_f32 v169, v171, v7, v169
	v_fma_f32 v186, v168, v168, v186
	v_fma_f32 v186, v169, v169, v186
	v_cvt_pk_bf16_f32 v118, v168, v169
	v_lshlrev_b32_e32 v168, 16, v119
	v_and_b32_e32 v169, 0xffff0000, v119
	v_lshlrev_b32_e32 v170, 16, v151
	v_and_b32_e32 v171, 0xffff0000, v151
	v_mul_f32_e32 v170, s98, v170
	v_mul_f32_e32 v171, s98, v171
	v_fma_f32 v168, v170, v8, v168
	v_fma_f32 v169, v171, v9, v169
	v_fma_f32 v186, v168, v168, v186
	v_fma_f32 v186, v169, v169, v186
	v_cvt_pk_bf16_f32 v119, v168, v169
	v_lshlrev_b32_e32 v168, 16, v120
	v_and_b32_e32 v169, 0xffff0000, v120
	v_lshlrev_b32_e32 v170, 16, v152
	v_and_b32_e32 v171, 0xffff0000, v152
; __device__ __forceinline__ float bf_lo(unsigned w) { return __uint_as_float(w << 16); }
; __device__ __forceinline__ float bf_hi(unsigned w) { return __uint_as_float(w & 0xffff0000u); }
; __device__ __forceinline__ unsigned pk2(float lo, float hi) { bf16x2_t r = __builtin_convertvector((f32x2_t){lo, hi}, bf16x2_t); return __builtin_bit_cast(unsigned, r); }
; template <bool SRC_F32, bool FINAL, int R> __device__ __forceinline__ void ew_compute(const EwSet<SRC_F32, R>& S, int rb, const f32x4 (&g)[4], bf16* hb_out, float* out32, float scale, float* rs_out, int lane) {
;     ...
; #pragma unroll
;         for (int j = 0; j < 4; ++j) {
;             f32x4 h;
;             if constexpr (SRC_F32) h = S.h32[i][j];
;             else { const v2u hw = S.hb[i][j]; h.x = bf_lo(hw.x); h.y = bf_hi(hw.x); h.z = bf_lo(hw.y); h.w = bf_hi(hw.y); }
;             const v2u fw = S.fw[i][j];
;             f32x4 v; v.x = h.x + bf_lo(fw.x) * rs * g[j].x; v.y = h.y + bf_hi(fw.x) * rs * g[j].y; v.z = h.z + bf_lo(fw.y) * rs * g[j].z; v.w = h.w + bf_hi(fw.y) * rs * g[j].w;
;             if (FINAL) __builtin_nontemporal_store(v, (f32x4*)(out32 + (size_t)(rb + i) * D) + lane + 64 * j);
;             else { v2u o; o.x = pk2(v.x, v.y); o.y = pk2(v.z, v.w); ((v2u*)(hb_out + (size_t)(rb + i) * D) + lane)[64 * j] = o; s2 += (v.x * v.x + v.y * v.y) + (v.z * v.z + v.w * v.w); }
;         }
;         if (!FINAL) { const float tot = wave_sum(s2); if (lane == 0) rs_out[rb + i] = 1.0f / sqrtf(tot * (1.f / D) + EPS); }
	v_mul_f32_e32 v170, s98, v170
	v_mul_f32_e32 v171, s98, v171
	v_fma_f32 v168, v170, v10, v168
	v_fma_f32 v169, v171, v11, v169
	v_fma_f32 v186, v168, v168, v186
	v_fma_f32 v186, v169, v169, v186
	v_cvt_pk_bf16_f32 v120, v168, v169
	v_lshlrev_b32_e32 v168, 16, v121
	v_and_b32_e32 v169, 0xffff0000, v121
	v_lshlrev_b32_e32 v170, 16, v153
	v_and_b32_e32 v171, 0xffff0000, v153
	v_mul_f32_e32 v170, s98, v170
	v_mul_f32_e32 v171, s98, v171
	v_fma_f32 v168, v170, v12, v168
	v_fma_f32 v169, v171, v13, v169
	v_fma_f32 v186, v168, v168, v186
	v_fma_f32 v186, v169, v169, v186
	v_cvt_pk_bf16_f32 v121, v168, v169
	v_lshlrev_b32_e32 v168, 16, v122
	v_and_b32_e32 v169, 0xffff0000, v122
	v_lshlrev_b32_e32 v170, 16, v154
	v_and_b32_e32 v171, 0xffff0000, v154
	v_mul_f32_e32 v170, s98, v170
	v_mul_f32_e32 v171, s98, v171
	v_fma_f32 v168, v170, v14, v168
	v_fma_f32 v169, v171, v15, v169
	v_fma_f32 v186, v168, v168, v186
	v_fma_f32 v186, v169, v169, v186
	v_cvt_pk_bf16_f32 v122, v168, v169
	v_lshlrev_b32_e32 v168, 16, v123
	v_and_b32_e32 v169, 0xffff0000, v123
	v_lshlrev_b32_e32 v170, 16, v155
	v_and_b32_e32 v171, 0xffff0000, v155
	v_mul_f32_e32 v170, s98, v170
	v_mul_f32_e32 v171, s98, v171
	v_fma_f32 v168, v170, v16, v168
	v_fma_f32 v169, v171, v17, v169
	v_fma_f32 v186, v168, v168, v186
	v_fma_f32 v186, v169, v169, v186
	v_cvt_pk_bf16_f32 v123, v168, v169
	global_store_dwordx4 v24, v[116:119], s[0:1]
	global_store_dwordx4 v24, v[120:123], s[0:1] offset:1024
	v_lshlrev_b32_e32 v168, 16, v124
	v_and_b32_e32 v169, 0xffff0000, v124
	v_lshlrev_b32_e32 v170, 16, v156
	v_and_b32_e32 v171, 0xffff0000, v156
	v_mul_f32_e32 v170, s101, v170
	v_mul_f32_e32 v171, s101, v171
	v_fma_f32 v168, v170, v2, v168
	v_fma_f32 v169, v171, v3, v169
	v_fma_f32 v187, v168, v168, v187
	v_fma_f32 v187, v169, v169, v187
	v_cvt_pk_bf16_f32 v124, v168, v169
	v_lshlrev_b32_e32 v168, 16, v125
	v_and_b32_e32 v169, 0xffff0000, v125
	v_lshlrev_b32_e32 v170, 16, v157
	v_and_b32_e32 v171, 0xffff0000, v157
	v_mul_f32_e32 v170, s101, v170
	v_mul_f32_e32 v171, s101, v171
	v_fma_f32 v168, v170, v4, v168
	v_fma_f32 v169, v171, v5, v169
	v_fma_f32 v187, v168, v168, v187
	v_fma_f32 v187, v169, v169, v187
	v_cvt_pk_bf16_f32 v125, v168, v169
	v_lshlrev_b32_e32 v168, 16, v126
	v_and_b32_e32 v169, 0xffff0000, v126
	v_lshlrev_b32_e32 v170, 16, v158
	v_and_b32_e32 v171, 0xffff0000, v158
	v_mul_f32_e32 v170, s101, v170
	v_mul_f32_e32 v171, s101, v171
	v_fma_f32 v168, v170, v6, v168
	v_fma_f32 v169, v171, v7, v169
	v_fma_f32 v187, v168, v168, v187
	v_fma_f32 v187, v169, v169, v187
	v_cvt_pk_bf16_f32 v126, v168, v169
	v_lshlrev_b32_e32 v168, 16, v127
	v_and_b32_e32 v169, 0xffff0000, v127
	v_lshlrev_b32_e32 v170, 16, v159
	v_and_b32_e32 v171, 0xffff0000, v159
	v_mul_f32_e32 v170, s101, v170
	v_mul_f32_e32 v171, s101, v171
	v_fma_f32 v168, v170, v8, v168
	v_fma_f32 v169, v171, v9, v169
	v_fma_f32 v187, v168, v168, v187
	v_fma_f32 v187, v169, v169, v187
	v_cvt_pk_bf16_f32 v127, v168, v169
	v_lshlrev_b32_e32 v168, 16, v128
	v_and_b32_e32 v169, 0xffff0000, v128
	v_lshlrev_b32_e32 v170, 16, v160
	v_and_b32_e32 v171, 0xffff0000, v160
	v_mul_f32_e32 v170, s101, v170
	v_mul_f32_e32 v171, s101, v171
	v_fma_f32 v168, v170, v10, v168
	v_fma_f32 v169, v171, v11, v169
	v_fma_f32 v187, v168, v168, v187
	v_fma_f32 v187, v169, v169, v187
	v_cvt_pk_bf16_f32 v128, v168, v169
	v_lshlrev_b32_e32 v168, 16, v129
	v_and_b32_e32 v169, 0xffff0000, v129
	v_lshlrev_b32_e32 v170, 16, v161
	v_and_b32_e32 v171, 0xffff0000, v161
	v_mul_f32_e32 v170, s101, v170
	v_mul_f32_e32 v171, s101, v171
	v_fma_f32 v168, v170, v12, v168
	v_fma_f32 v169, v171, v13, v169
	v_fma_f32 v187, v168, v168, v187
	v_fma_f32 v187, v169, v169, v187
	v_cvt_pk_bf16_f32 v129, v168, v169
	v_lshlrev_b32_e32 v168, 16, v130
	v_and_b32_e32 v169, 0xffff0000, v130
	v_lshlrev_b32_e32 v170, 16, v162
	v_and_b32_e32 v171, 0xffff0000, v162
	v_mul_f32_e32 v170, s101, v170
	v_mul_f32_e32 v171, s101, v171
	v_fma_f32 v168, v170, v14, v168
	v_fma_f32 v169, v171, v15, v169
	v_fma_f32 v187, v168, v168, v187
	v_fma_f32 v187, v169, v169, v187
	v_cvt_pk_bf16_f32 v130, v168, v169
	v_lshlrev_b32_e32 v168, 16, v131
	v_and_b32_e32 v169, 0xffff0000, v131
	v_lshlrev_b32_e32 v170, 16, v163
	v_and_b32_e32 v171, 0xffff0000, v163
	v_mul_f32_e32 v170, s101, v170
	v_mul_f32_e32 v171, s101, v171
	v_fma_f32 v168, v170, v16, v168
	v_fma_f32 v169, v171, v17, v169
	v_fma_f32 v187, v168, v168, v187
	v_fma_f32 v187, v169, v169, v187
	v_cvt_pk_bf16_f32 v131, v168, v169
	global_store_dwordx4 v24, v[124:127], s[0:1] offset:2048
	global_store_dwordx4 v24, v[128:131], s[0:1] offset:3072
	s_nop 1
	v_add_f32_dpp v184, v184, v184 quad_perm:[1,0,3,2] row_mask:0xf bank_mask:0xf
	v_add_f32_dpp v185, v185, v185 quad_perm:[1,0,3,2] row_mask:0xf bank_mask:0xf
	v_add_f32_dpp v186, v186, v186 quad_perm:[1,0,3,2] row_mask:0xf bank_mask:0xf
	v_add_f32_dpp v187, v187, v187 quad_perm:[1,0,3,2] row_mask:0xf bank_mask:0xf
	v_add_f32_dpp v184, v184, v184 quad_perm:[2,3,0,1] row_mask:0xf bank_mask:0xf
	v_add_f32_dpp v185, v185, v185 quad_perm:[2,3,0,1] row_mask:0xf bank_mask:0xf
	v_add_f32_dpp v186, v186, v186 quad_perm:[2,3,0,1] row_mask:0xf bank_mask:0xf
	v_add_f32_dpp v187, v187, v187 quad_perm:[2,3,0,1] row_mask:0xf bank_mask:0xf
	v_add_f32_dpp v184, v184, v184 row_half_mirror row_mask:0xf bank_mask:0xf
	v_add_f32_dpp v185, v185, v185 row_half_mirror row_mask:0xf bank_mask:0xf
	v_add_f32_dpp v186, v186, v186 row_half_mirror row_mask:0xf bank_mask:0xf
	v_add_f32_dpp v187, v187, v187 row_half_mirror row_mask:0xf bank_mask:0xf
	v_add_f32_dpp v184, v184, v184 row_mirror row_mask:0xf bank_mask:0xf
; __device__ __forceinline__ float bf_lo(unsigned w) { return __uint_as_float(w << 16); }
; __device__ __forceinline__ float bf_hi(unsigned w) { return __uint_as_float(w & 0xffff0000u); }
; template <bool SRC_F32, int R> __device__ __forceinline__ void ew_load(EwSet<SRC_F32, R>& S, int rb, const float* hsrc32, const bf16* hsrcb, const bf16* f, const float* part, int lane) {
; #pragma unroll
;     for (int i = 0; i < R; ++i) S.p[i] = (lane < 16) ? part[(size_t)(rb + i) * 16 + lane] : 0.f;
; #pragma unroll
;     for (int i = 0; i < R; ++i)
; #pragma unroll
;         for (int j = 0; j < 4; ++j) {
;             S.fw[i][j] = ((const v2u*)(f + (size_t)(rb + i) * D) + lane)[64 * j];
;             if constexpr (SRC_F32) S.h32[i][j] = __builtin_nontemporal_load((const f32x4*)(hsrc32 + (size_t)(rb + i) * D) + lane + 64 * j);
;             else S.hb[i][j] = ((const v2u*)(hsrcb + (size_t)(rb + i) * D) + lane)[64 * j];
;         }
; }
; template <bool SRC_F32, bool FINAL, int R> __device__ __forceinline__ void ew_compute(const EwSet<SRC_F32, R>& S, int rb, const f32x4 (&g)[4], bf16* hb_out, float* out32, float scale, float* rs_out, int lane) {
; #pragma unroll
;     for (int i = 0; i < R; ++i) {
;         float q = S.p[i];
;         q += __shfl_xor(q, 1); q += __shfl_xor(q, 2); q += __shfl_xor(q, 4); q += __shfl_xor(q, 8);
;         const float ss = __shfl(q, 0);
;         const float rs = scale / sqrtf(ss * (1.f / D) + EPS);
;         float s2 = 0.f;
; #pragma unroll
;         for (int j = 0; j < 4; ++j) {
;             f32x4 h;
;             if constexpr (SRC_F32) h = S.h32[i][j];
;             else { const v2u hw = S.hb[i][j]; h.x = bf_lo(hw.x); h.y = bf_hi(hw.x); h.z = bf_lo(hw.y); h.w = bf_hi(hw.y); }
;             const v2u fw = S.fw[i][j];
;             f32x4 v; v.x = h.x + bf_lo(fw.x) * rs * g[j].x; v.y = h.y + bf_hi(fw.x) * rs * g[j].y; v.z = h.z + bf_lo(fw.y) * rs * g[j].z; v.w = h.w + bf_hi(fw.y) * rs * g[j].w;
;             if (FINAL) __builtin_nontemporal_store(v, (f32x4*)(out32 + (size_t)(rb + i) * D) + lane + 64 * j);
;             else { v2u o; o.x = pk2(v.x, v.y); o.y = pk2(v.z, v.w); ((v2u*)(hb_out + (size_t)(rb + i) * D) + lane)[64 * j] = o; s2 += (v.x * v.x + v.y * v.y) + (v.z * v.z + v.w * v.w); }
;         }
;         if (!FINAL) { const float tot = wave_sum(s2); if (lane == 0) rs_out[rb + i] = 1.0f / sqrtf(tot * (1.f / D) + EPS); }
	v_add_f32_dpp v185, v185, v185 row_mirror row_mask:0xf bank_mask:0xf
	v_add_f32_dpp v186, v186, v186 row_mirror row_mask:0xf bank_mask:0xf
	v_add_f32_dpp v187, v187, v187 row_mirror row_mask:0xf bank_mask:0xf
	v_add_f32_dpp v184, v184, v184 row_bcast:15 row_mask:0xa bank_mask:0xf
	v_add_f32_dpp v185, v185, v185 row_bcast:15 row_mask:0xa bank_mask:0xf
	v_add_f32_dpp v186, v186, v186 row_bcast:15 row_mask:0xa bank_mask:0xf
	v_add_f32_dpp v187, v187, v187 row_bcast:15 row_mask:0xa bank_mask:0xf
	v_add_f32_dpp v184, v184, v184 row_bcast:31 row_mask:0xc bank_mask:0xf
	v_add_f32_dpp v185, v185, v185 row_bcast:31 row_mask:0xc bank_mask:0xf
	v_add_f32_dpp v186, v186, v186 row_bcast:31 row_mask:0xc bank_mask:0xf
	v_add_f32_dpp v187, v187, v187 row_bcast:31 row_mask:0xc bank_mask:0xf
	s_nop 1
	v_readlane_b32 s3, v184, 63
	v_readlane_b32 s24, v185, 63
	v_readlane_b32 s98, v186, 63
	v_readlane_b32 s101, v187, 63
	s_nop 3
	v_writelane_b32 v188, s3, 0
	v_writelane_b32 v188, s24, 1
	v_writelane_b32 v188, s98, 2
	v_writelane_b32 v188, s101, 3
	s_nop 1
	v_mul_f32_e32 v188, 0x3a800000, v188
	v_add_f32_e32 v188, 0x358637bd, v188
	v_rsq_f32_e32 v188, v188
	s_mov_b64 exec, 15
	global_store_dword v26, v188, s[14:15]
	s_mov_b64 exec, -1
	s_add_u32 s27, s26, 2052
	s_lshl_b32 s22, s27, 11
	v_lshl_add_u32 v23, v0, 4, s22
	v_add_u32_e32 v24, 0x1000, v23
	s_lshl_b32 s22, s27, 6
	v_lshl_add_u32 v25, v0, 2, s22
	s_lshl_b32 s22, s27, 2
	v_lshl_add_u32 v26, v0, 2, s22
	global_load_dwordx4 v[100:103], v23, s[0:1]
	global_load_dwordx4 v[104:107], v23, s[0:1] offset:1024
	global_load_dwordx4 v[132:135], v23, s[4:5]
	global_load_dwordx4 v[136:139], v23, s[4:5] offset:1024
	global_load_dwordx4 v[108:111], v23, s[0:1] offset:2048
	global_load_dwordx4 v[112:115], v23, s[0:1] offset:3072
	global_load_dwordx4 v[140:143], v23, s[4:5] offset:2048
	global_load_dwordx4 v[144:147], v23, s[4:5] offset:3072
	global_load_dwordx4 v[116:119], v24, s[0:1]
	global_load_dwordx4 v[120:123], v24, s[0:1] offset:1024
	global_load_dwordx4 v[148:151], v24, s[4:5]
	global_load_dwordx4 v[152:155], v24, s[4:5] offset:1024
	global_load_dwordx4 v[124:127], v24, s[0:1] offset:2048
	global_load_dwordx4 v[128:131], v24, s[0:1] offset:3072
	global_load_dwordx4 v[156:159], v24, s[4:5] offset:2048
	global_load_dwordx4 v[160:163], v24, s[4:5] offset:3072
	global_load_dword v164, v25, s[6:7]
	s_waitcnt vmcnt(26)
	v_add_f32_dpp v96, v96, v96 quad_perm:[1,0,3,2] row_mask:0xf bank_mask:0xf
	s_nop 1
	v_add_f32_dpp v96, v96, v96 quad_perm:[2,3,0,1] row_mask:0xf bank_mask:0xf
	s_nop 1
	v_add_f32_dpp v96, v96, v96 row_half_mirror row_mask:0xf bank_mask:0xf
	s_nop 1
	v_add_f32_dpp v96, v96, v96 row_mirror row_mask:0xf bank_mask:0xf
	s_nop 1
	v_mul_f32_e32 v96, 0x3a800000, v96
	v_add_f32_e32 v96, 0x358637bd, v96
	v_rsq_f32_e32 v96, v96
	s_nop 0
	v_mul_f32_e32 v96, 0x3f000000, v96
	s_nop 0
	v_readlane_b32 s3, v96, 0
	v_readlane_b32 s24, v96, 16
	v_readlane_b32 s98, v96, 32
	v_readlane_b32 s101, v96, 48
	s_nop 1
	v_mov_b32_e32 v184, 0
	v_mov_b32_e32 v185, 0
	v_mov_b32_e32 v186, 0
	v_mov_b32_e32 v187, 0
	v_lshlrev_b32_e32 v168, 16, v32
	v_and_b32_e32 v169, 0xffff0000, v32
	v_lshlrev_b32_e32 v170, 16, v64
	v_and_b32_e32 v171, 0xffff0000, v64
	v_mul_f32_e32 v170, s3, v170
	v_mul_f32_e32 v171, s3, v171
	v_fma_f32 v168, v170, v2, v168
	v_fma_f32 v169, v171, v3, v169
	v_fma_f32 v184, v168, v168, v184
	v_fma_f32 v184, v169, v169, v184
	v_cvt_pk_bf16_f32 v32, v168, v169
	v_lshlrev_b32_e32 v168, 16, v33
	v_and_b32_e32 v169, 0xffff0000, v33
	v_lshlrev_b32_e32 v170, 16, v65
	v_and_b32_e32 v171, 0xffff0000, v65
	v_mul_f32_e32 v170, s3, v170
	v_mul_f32_e32 v171, s3, v171
	v_fma_f32 v168, v170, v4, v168
	v_fma_f32 v169, v171, v5, v169
	v_fma_f32 v184, v168, v168, v184
	v_fma_f32 v184, v169, v169, v184
	v_cvt_pk_bf16_f32 v33, v168, v169
	v_lshlrev_b32_e32 v168, 16, v34
	v_and_b32_e32 v169, 0xffff0000, v34
	v_lshlrev_b32_e32 v170, 16, v66
	v_and_b32_e32 v171, 0xffff0000, v66
	v_mul_f32_e32 v170, s3, v170
	v_mul_f32_e32 v171, s3, v171
	v_fma_f32 v168, v170, v6, v168
	v_fma_f32 v169, v171, v7, v169
	v_fma_f32 v184, v168, v168, v184
	v_fma_f32 v184, v169, v169, v184
	v_cvt_pk_bf16_f32 v34, v168, v169
	v_lshlrev_b32_e32 v168, 16, v35
	v_and_b32_e32 v169, 0xffff0000, v35
	v_lshlrev_b32_e32 v170, 16, v67
	v_and_b32_e32 v171, 0xffff0000, v67
	v_mul_f32_e32 v170, s3, v170
	v_mul_f32_e32 v171, s3, v171
	v_fma_f32 v168, v170, v8, v168
	v_fma_f32 v169, v171, v9, v169
	v_fma_f32 v184, v168, v168, v184
	v_fma_f32 v184, v169, v169, v184
	v_cvt_pk_bf16_f32 v35, v168, v169
	v_lshlrev_b32_e32 v168, 16, v36
	v_and_b32_e32 v169, 0xffff0000, v36
	v_lshlrev_b32_e32 v170, 16, v68
	v_and_b32_e32 v171, 0xffff0000, v68
	v_mul_f32_e32 v170, s3, v170
	v_mul_f32_e32 v171, s3, v171
	v_fma_f32 v168, v170, v10, v168
	v_fma_f32 v169, v171, v11, v169
	v_fma_f32 v184, v168, v168, v184
	v_fma_f32 v184, v169, v169, v184
	v_cvt_pk_bf16_f32 v36, v168, v169
	v_lshlrev_b32_e32 v168, 16, v37
	v_and_b32_e32 v169, 0xffff0000, v37
	v_lshlrev_b32_e32 v170, 16, v69
	v_and_b32_e32 v171, 0xffff0000, v69
	v_mul_f32_e32 v170, s3, v170
	v_mul_f32_e32 v171, s3, v171
	v_fma_f32 v168, v170, v12, v168
	v_fma_f32 v169, v171, v13, v169
	v_fma_f32 v184, v168, v168, v184
	v_fma_f32 v184, v169, v169, v184
	v_cvt_pk_bf16_f32 v37, v168, v169
	v_lshlrev_b32_e32 v168, 16, v38
	v_and_b32_e32 v169, 0xffff0000, v38
	v_lshlrev_b32_e32 v170, 16, v70
	v_and_b32_e32 v171, 0xffff0000, v70
	v_mul_f32_e32 v170, s3, v170
	v_mul_f32_e32 v171, s3, v171
	v_fma_f32 v168, v170, v14, v168
	v_fma_f32 v169, v171, v15, v169
	v_fma_f32 v184, v168, v168, v184
	v_fma_f32 v184, v169, v169, v184
	v_cvt_pk_bf16_f32 v38, v168, v169
; __device__ __forceinline__ float bf_lo(unsigned w) { return __uint_as_float(w << 16); }
; __device__ __forceinline__ float bf_hi(unsigned w) { return __uint_as_float(w & 0xffff0000u); }
; __device__ __forceinline__ unsigned pk2(float lo, float hi) { bf16x2_t r = __builtin_convertvector((f32x2_t){lo, hi}, bf16x2_t); return __builtin_bit_cast(unsigned, r); }
; template <bool SRC_F32, bool FINAL, int R> __device__ __forceinline__ void ew_compute(const EwSet<SRC_F32, R>& S, int rb, const f32x4 (&g)[4], bf16* hb_out, float* out32, float scale, float* rs_out, int lane) {
;     ...
; #pragma unroll
;         for (int j = 0; j < 4; ++j) {
;             f32x4 h;
;             if constexpr (SRC_F32) h = S.h32[i][j];
;             else { const v2u hw = S.hb[i][j]; h.x = bf_lo(hw.x); h.y = bf_hi(hw.x); h.z = bf_lo(hw.y); h.w = bf_hi(hw.y); }
;             const v2u fw = S.fw[i][j];
;             f32x4 v; v.x = h.x + bf_lo(fw.x) * rs * g[j].x; v.y = h.y + bf_hi(fw.x) * rs * g[j].y; v.z = h.z + bf_lo(fw.y) * rs * g[j].z; v.w = h.w + bf_hi(fw.y) * rs * g[j].w;
;             if (FINAL) __builtin_nontemporal_store(v, (f32x4*)(out32 + (size_t)(rb + i) * D) + lane + 64 * j);
;             else { v2u o; o.x = pk2(v.x, v.y); o.y = pk2(v.z, v.w); ((v2u*)(hb_out + (size_t)(rb + i) * D) + lane)[64 * j] = o; s2 += (v.x * v.x + v.y * v.y) + (v.z * v.z + v.w * v.w); }
	v_lshlrev_b32_e32 v168, 16, v39
	v_and_b32_e32 v169, 0xffff0000, v39
	v_lshlrev_b32_e32 v170, 16, v71
	v_and_b32_e32 v171, 0xffff0000, v71
	v_mul_f32_e32 v170, s3, v170
	v_mul_f32_e32 v171, s3, v171
	v_fma_f32 v168, v170, v16, v168
	v_fma_f32 v169, v171, v17, v169
	v_fma_f32 v184, v168, v168, v184
	v_fma_f32 v184, v169, v169, v184
	v_cvt_pk_bf16_f32 v39, v168, v169
	global_store_dwordx4 v18, v[32:35], s[0:1]
	global_store_dwordx4 v18, v[36:39], s[0:1] offset:1024
	v_lshlrev_b32_e32 v168, 16, v40
	v_and_b32_e32 v169, 0xffff0000, v40
	v_lshlrev_b32_e32 v170, 16, v72
	v_and_b32_e32 v171, 0xffff0000, v72
	v_mul_f32_e32 v170, s24, v170
	v_mul_f32_e32 v171, s24, v171
	v_fma_f32 v168, v170, v2, v168
	v_fma_f32 v169, v171, v3, v169
	v_fma_f32 v185, v168, v168, v185
	v_fma_f32 v185, v169, v169, v185
	v_cvt_pk_bf16_f32 v40, v168, v169
	v_lshlrev_b32_e32 v168, 16, v41
	v_and_b32_e32 v169, 0xffff0000, v41
	v_lshlrev_b32_e32 v170, 16, v73
	v_and_b32_e32 v171, 0xffff0000, v73
	v_mul_f32_e32 v170, s24, v170
	v_mul_f32_e32 v171, s24, v171
	v_fma_f32 v168, v170, v4, v168
	v_fma_f32 v169, v171, v5, v169
	v_fma_f32 v185, v168, v168, v185
	v_fma_f32 v185, v169, v169, v185
	v_cvt_pk_bf16_f32 v41, v168, v169
	v_lshlrev_b32_e32 v168, 16, v42
	v_and_b32_e32 v169, 0xffff0000, v42
	v_lshlrev_b32_e32 v170, 16, v74
	v_and_b32_e32 v171, 0xffff0000, v74
	v_mul_f32_e32 v170, s24, v170
	v_mul_f32_e32 v171, s24, v171
	v_fma_f32 v168, v170, v6, v168
	v_fma_f32 v169, v171, v7, v169
	v_fma_f32 v185, v168, v168, v185
	v_fma_f32 v185, v169, v169, v185
	v_cvt_pk_bf16_f32 v42, v168, v169
	v_lshlrev_b32_e32 v168, 16, v43
	v_and_b32_e32 v169, 0xffff0000, v43
	v_lshlrev_b32_e32 v170, 16, v75
	v_and_b32_e32 v171, 0xffff0000, v75
	v_mul_f32_e32 v170, s24, v170
	v_mul_f32_e32 v171, s24, v171
	v_fma_f32 v168, v170, v8, v168
	v_fma_f32 v169, v171, v9, v169
	v_fma_f32 v185, v168, v168, v185
	v_fma_f32 v185, v169, v169, v185
	v_cvt_pk_bf16_f32 v43, v168, v169
	v_lshlrev_b32_e32 v168, 16, v44
	v_and_b32_e32 v169, 0xffff0000, v44
	v_lshlrev_b32_e32 v170, 16, v76
	v_and_b32_e32 v171, 0xffff0000, v76
	v_mul_f32_e32 v170, s24, v170
	v_mul_f32_e32 v171, s24, v171
	v_fma_f32 v168, v170, v10, v168
	v_fma_f32 v169, v171, v11, v169
	v_fma_f32 v185, v168, v168, v185
	v_fma_f32 v185, v169, v169, v185
	v_cvt_pk_bf16_f32 v44, v168, v169
	v_lshlrev_b32_e32 v168, 16, v45
	v_and_b32_e32 v169, 0xffff0000, v45
	v_lshlrev_b32_e32 v170, 16, v77
	v_and_b32_e32 v171, 0xffff0000, v77
	v_mul_f32_e32 v170, s24, v170
	v_mul_f32_e32 v171, s24, v171
	v_fma_f32 v168, v170, v12, v168
	v_fma_f32 v169, v171, v13, v169
	v_fma_f32 v185, v168, v168, v185
	v_fma_f32 v185, v169, v169, v185
	v_cvt_pk_bf16_f32 v45, v168, v169
	v_lshlrev_b32_e32 v168, 16, v46
	v_and_b32_e32 v169, 0xffff0000, v46
	v_lshlrev_b32_e32 v170, 16, v78
	v_and_b32_e32 v171, 0xffff0000, v78
	v_mul_f32_e32 v170, s24, v170
	v_mul_f32_e32 v171, s24, v171
	v_fma_f32 v168, v170, v14, v168
	v_fma_f32 v169, v171, v15, v169
	v_fma_f32 v185, v168, v168, v185
	v_fma_f32 v185, v169, v169, v185
	v_cvt_pk_bf16_f32 v46, v168, v169
	v_lshlrev_b32_e32 v168, 16, v47
	v_and_b32_e32 v169, 0xffff0000, v47
	v_lshlrev_b32_e32 v170, 16, v79
	v_and_b32_e32 v171, 0xffff0000, v79
	v_mul_f32_e32 v170, s24, v170
	v_mul_f32_e32 v171, s24, v171
	v_fma_f32 v168, v170, v16, v168
	v_fma_f32 v169, v171, v17, v169
	v_fma_f32 v185, v168, v168, v185
	v_fma_f32 v185, v169, v169, v185
	v_cvt_pk_bf16_f32 v47, v168, v169
	global_store_dwordx4 v18, v[40:43], s[0:1] offset:2048
	global_store_dwordx4 v18, v[44:47], s[0:1] offset:3072
	v_lshlrev_b32_e32 v168, 16, v48
	v_and_b32_e32 v169, 0xffff0000, v48
	v_lshlrev_b32_e32 v170, 16, v80
	v_and_b32_e32 v171, 0xffff0000, v80
	v_mul_f32_e32 v170, s98, v170
	v_mul_f32_e32 v171, s98, v171
	v_fma_f32 v168, v170, v2, v168
	v_fma_f32 v169, v171, v3, v169
	v_fma_f32 v186, v168, v168, v186
	v_fma_f32 v186, v169, v169, v186
	v_cvt_pk_bf16_f32 v48, v168, v169
	v_lshlrev_b32_e32 v168, 16, v49
	v_and_b32_e32 v169, 0xffff0000, v49
	v_lshlrev_b32_e32 v170, 16, v81
	v_and_b32_e32 v171, 0xffff0000, v81
	v_mul_f32_e32 v170, s98, v170
	v_mul_f32_e32 v171, s98, v171
	v_fma_f32 v168, v170, v4, v168
	v_fma_f32 v169, v171, v5, v169
	v_fma_f32 v186, v168, v168, v186
	v_fma_f32 v186, v169, v169, v186
	v_cvt_pk_bf16_f32 v49, v168, v169
	v_lshlrev_b32_e32 v168, 16, v50
	v_and_b32_e32 v169, 0xffff0000, v50
	v_lshlrev_b32_e32 v170, 16, v82
	v_and_b32_e32 v171, 0xffff0000, v82
	v_mul_f32_e32 v170, s98, v170
	v_mul_f32_e32 v171, s98, v171
	v_fma_f32 v168, v170, v6, v168
	v_fma_f32 v169, v171, v7, v169
	v_fma_f32 v186, v168, v168, v186
	v_fma_f32 v186, v169, v169, v186
	v_cvt_pk_bf16_f32 v50, v168, v169
	v_lshlrev_b32_e32 v168, 16, v51
	v_and_b32_e32 v169, 0xffff0000, v51
	v_lshlrev_b32_e32 v170, 16, v83
	v_and_b32_e32 v171, 0xffff0000, v83
	v_mul_f32_e32 v170, s98, v170
	v_mul_f32_e32 v171, s98, v171
	v_fma_f32 v168, v170, v8, v168
	v_fma_f32 v169, v171, v9, v169
	v_fma_f32 v186, v168, v168, v186
	v_fma_f32 v186, v169, v169, v186
	v_cvt_pk_bf16_f32 v51, v168, v169
	v_lshlrev_b32_e32 v168, 16, v52
	v_and_b32_e32 v169, 0xffff0000, v52
	v_lshlrev_b32_e32 v170, 16, v84
	v_and_b32_e32 v171, 0xffff0000, v84
	v_mul_f32_e32 v170, s98, v170
	v_mul_f32_e32 v171, s98, v171
	v_fma_f32 v168, v170, v10, v168
	v_fma_f32 v169, v171, v11, v169
	v_fma_f32 v186, v168, v168, v186
	v_fma_f32 v186, v169, v169, v186
	v_cvt_pk_bf16_f32 v52, v168, v169
	v_lshlrev_b32_e32 v168, 16, v53
	v_and_b32_e32 v169, 0xffff0000, v53
	v_lshlrev_b32_e32 v170, 16, v85
	v_and_b32_e32 v171, 0xffff0000, v85
	v_mul_f32_e32 v170, s98, v170
	v_mul_f32_e32 v171, s98, v171
	v_fma_f32 v168, v170, v12, v168
	v_fma_f32 v169, v171, v13, v169
; __device__ __forceinline__ float bf_lo(unsigned w) { return __uint_as_float(w << 16); }
; __device__ __forceinline__ float bf_hi(unsigned w) { return __uint_as_float(w & 0xffff0000u); }
; __device__ __forceinline__ unsigned pk2(float lo, float hi) { bf16x2_t r = __builtin_convertvector((f32x2_t){lo, hi}, bf16x2_t); return __builtin_bit_cast(unsigned, r); }
; template <bool SRC_F32, bool FINAL, int R> __device__ __forceinline__ void ew_compute(const EwSet<SRC_F32, R>& S, int rb, const f32x4 (&g)[4], bf16* hb_out, float* out32, float scale, float* rs_out, int lane) {
;     ...
; #pragma unroll
;         for (int j = 0; j < 4; ++j) {
;             f32x4 h;
;             if constexpr (SRC_F32) h = S.h32[i][j];
;             else { const v2u hw = S.hb[i][j]; h.x = bf_lo(hw.x); h.y = bf_hi(hw.x); h.z = bf_lo(hw.y); h.w = bf_hi(hw.y); }
;             const v2u fw = S.fw[i][j];
;             f32x4 v; v.x = h.x + bf_lo(fw.x) * rs * g[j].x; v.y = h.y + bf_hi(fw.x) * rs * g[j].y; v.z = h.z + bf_lo(fw.y) * rs * g[j].z; v.w = h.w + bf_hi(fw.y) * rs * g[j].w;
;             if (FINAL) __builtin_nontemporal_store(v, (f32x4*)(out32 + (size_t)(rb + i) * D) + lane + 64 * j);
;             else { v2u o; o.x = pk2(v.x, v.y); o.y = pk2(v.z, v.w); ((v2u*)(hb_out + (size_t)(rb + i) * D) + lane)[64 * j] = o; s2 += (v.x * v.x + v.y * v.y) + (v.z * v.z + v.w * v.w); }
;         }
;         if (!FINAL) { const float tot = wave_sum(s2); if (lane == 0) rs_out[rb + i] = 1.0f / sqrtf(tot * (1.f / D) + EPS); }
	v_fma_f32 v186, v168, v168, v186
	v_fma_f32 v186, v169, v169, v186
	v_cvt_pk_bf16_f32 v53, v168, v169
	v_lshlrev_b32_e32 v168, 16, v54
	v_and_b32_e32 v169, 0xffff0000, v54
	v_lshlrev_b32_e32 v170, 16, v86
	v_and_b32_e32 v171, 0xffff0000, v86
	v_mul_f32_e32 v170, s98, v170
	v_mul_f32_e32 v171, s98, v171
	v_fma_f32 v168, v170, v14, v168
	v_fma_f32 v169, v171, v15, v169
	v_fma_f32 v186, v168, v168, v186
	v_fma_f32 v186, v169, v169, v186
	v_cvt_pk_bf16_f32 v54, v168, v169
	v_lshlrev_b32_e32 v168, 16, v55
	v_and_b32_e32 v169, 0xffff0000, v55
	v_lshlrev_b32_e32 v170, 16, v87
	v_and_b32_e32 v171, 0xffff0000, v87
	v_mul_f32_e32 v170, s98, v170
	v_mul_f32_e32 v171, s98, v171
	v_fma_f32 v168, v170, v16, v168
	v_fma_f32 v169, v171, v17, v169
	v_fma_f32 v186, v168, v168, v186
	v_fma_f32 v186, v169, v169, v186
	v_cvt_pk_bf16_f32 v55, v168, v169
	global_store_dwordx4 v19, v[48:51], s[0:1]
	global_store_dwordx4 v19, v[52:55], s[0:1] offset:1024
	v_lshlrev_b32_e32 v168, 16, v56
	v_and_b32_e32 v169, 0xffff0000, v56
	v_lshlrev_b32_e32 v170, 16, v88
	v_and_b32_e32 v171, 0xffff0000, v88
	v_mul_f32_e32 v170, s101, v170
	v_mul_f32_e32 v171, s101, v171
	v_fma_f32 v168, v170, v2, v168
	v_fma_f32 v169, v171, v3, v169
	v_fma_f32 v187, v168, v168, v187
	v_fma_f32 v187, v169, v169, v187
	v_cvt_pk_bf16_f32 v56, v168, v169
	v_lshlrev_b32_e32 v168, 16, v57
	v_and_b32_e32 v169, 0xffff0000, v57
	v_lshlrev_b32_e32 v170, 16, v89
	v_and_b32_e32 v171, 0xffff0000, v89
	v_mul_f32_e32 v170, s101, v170
	v_mul_f32_e32 v171, s101, v171
	v_fma_f32 v168, v170, v4, v168
	v_fma_f32 v169, v171, v5, v169
	v_fma_f32 v187, v168, v168, v187
	v_fma_f32 v187, v169, v169, v187
	v_cvt_pk_bf16_f32 v57, v168, v169
	v_lshlrev_b32_e32 v168, 16, v58
	v_and_b32_e32 v169, 0xffff0000, v58
	v_lshlrev_b32_e32 v170, 16, v90
	v_and_b32_e32 v171, 0xffff0000, v90
	v_mul_f32_e32 v170, s101, v170
	v_mul_f32_e32 v171, s101, v171
	v_fma_f32 v168, v170, v6, v168
	v_fma_f32 v169, v171, v7, v169
	v_fma_f32 v187, v168, v168, v187
	v_fma_f32 v187, v169, v169, v187
	v_cvt_pk_bf16_f32 v58, v168, v169
	v_lshlrev_b32_e32 v168, 16, v59
	v_and_b32_e32 v169, 0xffff0000, v59
	v_lshlrev_b32_e32 v170, 16, v91
	v_and_b32_e32 v171, 0xffff0000, v91
	v_mul_f32_e32 v170, s101, v170
	v_mul_f32_e32 v171, s101, v171
	v_fma_f32 v168, v170, v8, v168
	v_fma_f32 v169, v171, v9, v169
	v_fma_f32 v187, v168, v168, v187
	v_fma_f32 v187, v169, v169, v187
	v_cvt_pk_bf16_f32 v59, v168, v169
	v_lshlrev_b32_e32 v168, 16, v60
	v_and_b32_e32 v169, 0xffff0000, v60
	v_lshlrev_b32_e32 v170, 16, v92
	v_and_b32_e32 v171, 0xffff0000, v92
	v_mul_f32_e32 v170, s101, v170
	v_mul_f32_e32 v171, s101, v171
	v_fma_f32 v168, v170, v10, v168
	v_fma_f32 v169, v171, v11, v169
	v_fma_f32 v187, v168, v168, v187
	v_fma_f32 v187, v169, v169, v187
	v_cvt_pk_bf16_f32 v60, v168, v169
	v_lshlrev_b32_e32 v168, 16, v61
	v_and_b32_e32 v169, 0xffff0000, v61
	v_lshlrev_b32_e32 v170, 16, v93
	v_and_b32_e32 v171, 0xffff0000, v93
	v_mul_f32_e32 v170, s101, v170
	v_mul_f32_e32 v171, s101, v171
	v_fma_f32 v168, v170, v12, v168
	v_fma_f32 v169, v171, v13, v169
	v_fma_f32 v187, v168, v168, v187
	v_fma_f32 v187, v169, v169, v187
	v_cvt_pk_bf16_f32 v61, v168, v169
	v_lshlrev_b32_e32 v168, 16, v62
	v_and_b32_e32 v169, 0xffff0000, v62
	v_lshlrev_b32_e32 v170, 16, v94
	v_and_b32_e32 v171, 0xffff0000, v94
	v_mul_f32_e32 v170, s101, v170
	v_mul_f32_e32 v171, s101, v171
	v_fma_f32 v168, v170, v14, v168
	v_fma_f32 v169, v171, v15, v169
	v_fma_f32 v187, v168, v168, v187
	v_fma_f32 v187, v169, v169, v187
	v_cvt_pk_bf16_f32 v62, v168, v169
	v_lshlrev_b32_e32 v168, 16, v63
	v_and_b32_e32 v169, 0xffff0000, v63
	v_lshlrev_b32_e32 v170, 16, v95
	v_and_b32_e32 v171, 0xffff0000, v95
	v_mul_f32_e32 v170, s101, v170
	v_mul_f32_e32 v171, s101, v171
	v_fma_f32 v168, v170, v16, v168
	v_fma_f32 v169, v171, v17, v169
	v_fma_f32 v187, v168, v168, v187
	v_fma_f32 v187, v169, v169, v187
	v_cvt_pk_bf16_f32 v63, v168, v169
	global_store_dwordx4 v19, v[56:59], s[0:1] offset:2048
	global_store_dwordx4 v19, v[60:63], s[0:1] offset:3072
	s_nop 1
	v_add_f32_dpp v184, v184, v184 quad_perm:[1,0,3,2] row_mask:0xf bank_mask:0xf
	v_add_f32_dpp v185, v185, v185 quad_perm:[1,0,3,2] row_mask:0xf bank_mask:0xf
	v_add_f32_dpp v186, v186, v186 quad_perm:[1,0,3,2] row_mask:0xf bank_mask:0xf
	v_add_f32_dpp v187, v187, v187 quad_perm:[1,0,3,2] row_mask:0xf bank_mask:0xf
	v_add_f32_dpp v184, v184, v184 quad_perm:[2,3,0,1] row_mask:0xf bank_mask:0xf
	v_add_f32_dpp v185, v185, v185 quad_perm:[2,3,0,1] row_mask:0xf bank_mask:0xf
	v_add_f32_dpp v186, v186, v186 quad_perm:[2,3,0,1] row_mask:0xf bank_mask:0xf
	v_add_f32_dpp v187, v187, v187 quad_perm:[2,3,0,1] row_mask:0xf bank_mask:0xf
	v_add_f32_dpp v184, v184, v184 row_half_mirror row_mask:0xf bank_mask:0xf
	v_add_f32_dpp v185, v185, v185 row_half_mirror row_mask:0xf bank_mask:0xf
	v_add_f32_dpp v186, v186, v186 row_half_mirror row_mask:0xf bank_mask:0xf
	v_add_f32_dpp v187, v187, v187 row_half_mirror row_mask:0xf bank_mask:0xf
	v_add_f32_dpp v184, v184, v184 row_mirror row_mask:0xf bank_mask:0xf
	v_add_f32_dpp v185, v185, v185 row_mirror row_mask:0xf bank_mask:0xf
	v_add_f32_dpp v186, v186, v186 row_mirror row_mask:0xf bank_mask:0xf
	v_add_f32_dpp v187, v187, v187 row_mirror row_mask:0xf bank_mask:0xf
	v_add_f32_dpp v184, v184, v184 row_bcast:15 row_mask:0xa bank_mask:0xf
	v_add_f32_dpp v185, v185, v185 row_bcast:15 row_mask:0xa bank_mask:0xf
	v_add_f32_dpp v186, v186, v186 row_bcast:15 row_mask:0xa bank_mask:0xf
	v_add_f32_dpp v187, v187, v187 row_bcast:15 row_mask:0xa bank_mask:0xf
	v_add_f32_dpp v184, v184, v184 row_bcast:31 row_mask:0xc bank_mask:0xf
	v_add_f32_dpp v185, v185, v185 row_bcast:31 row_mask:0xc bank_mask:0xf
	v_add_f32_dpp v186, v186, v186 row_bcast:31 row_mask:0xc bank_mask:0xf
	v_add_f32_dpp v187, v187, v187 row_bcast:31 row_mask:0xc bank_mask:0xf
	s_nop 1
	v_readlane_b32 s3, v184, 63
	v_readlane_b32 s24, v185, 63
	v_readlane_b32 s98, v186, 63
	v_readlane_b32 s101, v187, 63
	s_nop 3
	v_writelane_b32 v188, s3, 0
	v_writelane_b32 v188, s24, 1
	v_writelane_b32 v188, s98, 2
	v_writelane_b32 v188, s101, 3
	s_nop 1
	v_mul_f32_e32 v188, 0x3a800000, v188
	v_add_f32_e32 v188, 0x358637bd, v188
	v_rsq_f32_e32 v188, v188
	s_mov_b64 exec, 15
	global_store_dword v21, v188, s[14:15]
	s_mov_b64 exec, -1
	s_waitcnt vmcnt(9)
; __device__ __forceinline__ float bf_lo(unsigned w) { return __uint_as_float(w << 16); }
; __device__ __forceinline__ float bf_hi(unsigned w) { return __uint_as_float(w & 0xffff0000u); }
; __device__ __forceinline__ unsigned pk2(float lo, float hi) { bf16x2_t r = __builtin_convertvector((f32x2_t){lo, hi}, bf16x2_t); return __builtin_bit_cast(unsigned, r); }
; template <bool SRC_F32, bool FINAL, int R> __device__ __forceinline__ void ew_compute(const EwSet<SRC_F32, R>& S, int rb, const f32x4 (&g)[4], bf16* hb_out, float* out32, float scale, float* rs_out, int lane) {
;     ...
;         q += __shfl_xor(q, 1); q += __shfl_xor(q, 2); q += __shfl_xor(q, 4); q += __shfl_xor(q, 8);
;         const float ss = __shfl(q, 0);
;         const float rs = scale / sqrtf(ss * (1.f / D) + EPS);
;         float s2 = 0.f;
; #pragma unroll
;         for (int j = 0; j < 4; ++j) {
;             f32x4 h;
;             if constexpr (SRC_F32) h = S.h32[i][j];
;             else { const v2u hw = S.hb[i][j]; h.x = bf_lo(hw.x); h.y = bf_hi(hw.x); h.z = bf_lo(hw.y); h.w = bf_hi(hw.y); }
;             const v2u fw = S.fw[i][j];
;             f32x4 v; v.x = h.x + bf_lo(fw.x) * rs * g[j].x; v.y = h.y + bf_hi(fw.x) * rs * g[j].y; v.z = h.z + bf_lo(fw.y) * rs * g[j].z; v.w = h.w + bf_hi(fw.y) * rs * g[j].w;
;             if (FINAL) __builtin_nontemporal_store(v, (f32x4*)(out32 + (size_t)(rb + i) * D) + lane + 64 * j);
;             else { v2u o; o.x = pk2(v.x, v.y); o.y = pk2(v.z, v.w); ((v2u*)(hb_out + (size_t)(rb + i) * D) + lane)[64 * j] = o; s2 += (v.x * v.x + v.y * v.y) + (v.z * v.z + v.w * v.w); }
	v_add_f32_dpp v164, v164, v164 quad_perm:[1,0,3,2] row_mask:0xf bank_mask:0xf
	s_nop 1
	v_add_f32_dpp v164, v164, v164 quad_perm:[2,3,0,1] row_mask:0xf bank_mask:0xf
	s_nop 1
	v_add_f32_dpp v164, v164, v164 row_half_mirror row_mask:0xf bank_mask:0xf
	s_nop 1
	v_add_f32_dpp v164, v164, v164 row_mirror row_mask:0xf bank_mask:0xf
	s_nop 1
	v_mul_f32_e32 v164, 0x3a800000, v164
	v_add_f32_e32 v164, 0x358637bd, v164
	v_rsq_f32_e32 v164, v164
	s_nop 0
	v_mul_f32_e32 v164, 0x3f000000, v164
	s_nop 0
	v_readlane_b32 s3, v164, 0
	v_readlane_b32 s24, v164, 16
	v_readlane_b32 s98, v164, 32
	v_readlane_b32 s101, v164, 48
	s_nop 1
	v_mov_b32_e32 v184, 0
	v_mov_b32_e32 v185, 0
	v_mov_b32_e32 v186, 0
	v_mov_b32_e32 v187, 0
	v_lshlrev_b32_e32 v168, 16, v100
	v_and_b32_e32 v169, 0xffff0000, v100
	v_lshlrev_b32_e32 v170, 16, v132
	v_and_b32_e32 v171, 0xffff0000, v132
	v_mul_f32_e32 v170, s3, v170
	v_mul_f32_e32 v171, s3, v171
	v_fma_f32 v168, v170, v2, v168
	v_fma_f32 v169, v171, v3, v169
	v_fma_f32 v184, v168, v168, v184
	v_fma_f32 v184, v169, v169, v184
	v_cvt_pk_bf16_f32 v100, v168, v169
	v_lshlrev_b32_e32 v168, 16, v101
	v_and_b32_e32 v169, 0xffff0000, v101
	v_lshlrev_b32_e32 v170, 16, v133
	v_and_b32_e32 v171, 0xffff0000, v133
	v_mul_f32_e32 v170, s3, v170
	v_mul_f32_e32 v171, s3, v171
	v_fma_f32 v168, v170, v4, v168
	v_fma_f32 v169, v171, v5, v169
	v_fma_f32 v184, v168, v168, v184
	v_fma_f32 v184, v169, v169, v184
	v_cvt_pk_bf16_f32 v101, v168, v169
	v_lshlrev_b32_e32 v168, 16, v102
	v_and_b32_e32 v169, 0xffff0000, v102
	v_lshlrev_b32_e32 v170, 16, v134
	v_and_b32_e32 v171, 0xffff0000, v134
	v_mul_f32_e32 v170, s3, v170
	v_mul_f32_e32 v171, s3, v171
	v_fma_f32 v168, v170, v6, v168
	v_fma_f32 v169, v171, v7, v169
	v_fma_f32 v184, v168, v168, v184
	v_fma_f32 v184, v169, v169, v184
	v_cvt_pk_bf16_f32 v102, v168, v169
	v_lshlrev_b32_e32 v168, 16, v103
	v_and_b32_e32 v169, 0xffff0000, v103
	v_lshlrev_b32_e32 v170, 16, v135
	v_and_b32_e32 v171, 0xffff0000, v135
	v_mul_f32_e32 v170, s3, v170
	v_mul_f32_e32 v171, s3, v171
	v_fma_f32 v168, v170, v8, v168
	v_fma_f32 v169, v171, v9, v169
	v_fma_f32 v184, v168, v168, v184
	v_fma_f32 v184, v169, v169, v184
	v_cvt_pk_bf16_f32 v103, v168, v169
	v_lshlrev_b32_e32 v168, 16, v104
	v_and_b32_e32 v169, 0xffff0000, v104
	v_lshlrev_b32_e32 v170, 16, v136
	v_and_b32_e32 v171, 0xffff0000, v136
	v_mul_f32_e32 v170, s3, v170
	v_mul_f32_e32 v171, s3, v171
	v_fma_f32 v168, v170, v10, v168
	v_fma_f32 v169, v171, v11, v169
	v_fma_f32 v184, v168, v168, v184
	v_fma_f32 v184, v169, v169, v184
	v_cvt_pk_bf16_f32 v104, v168, v169
	v_lshlrev_b32_e32 v168, 16, v105
	v_and_b32_e32 v169, 0xffff0000, v105
	v_lshlrev_b32_e32 v170, 16, v137
	v_and_b32_e32 v171, 0xffff0000, v137
	v_mul_f32_e32 v170, s3, v170
	v_mul_f32_e32 v171, s3, v171
	v_fma_f32 v168, v170, v12, v168
	v_fma_f32 v169, v171, v13, v169
	v_fma_f32 v184, v168, v168, v184
	v_fma_f32 v184, v169, v169, v184
	v_cvt_pk_bf16_f32 v105, v168, v169
	v_lshlrev_b32_e32 v168, 16, v106
	v_and_b32_e32 v169, 0xffff0000, v106
	v_lshlrev_b32_e32 v170, 16, v138
	v_and_b32_e32 v171, 0xffff0000, v138
	v_mul_f32_e32 v170, s3, v170
	v_mul_f32_e32 v171, s3, v171
	v_fma_f32 v168, v170, v14, v168
	v_fma_f32 v169, v171, v15, v169
	v_fma_f32 v184, v168, v168, v184
	v_fma_f32 v184, v169, v169, v184
	v_cvt_pk_bf16_f32 v106, v168, v169
	v_lshlrev_b32_e32 v168, 16, v107
	v_and_b32_e32 v169, 0xffff0000, v107
	v_lshlrev_b32_e32 v170, 16, v139
	v_and_b32_e32 v171, 0xffff0000, v139
	v_mul_f32_e32 v170, s3, v170
	v_mul_f32_e32 v171, s3, v171
	v_fma_f32 v168, v170, v16, v168
	v_fma_f32 v169, v171, v17, v169
	v_fma_f32 v184, v168, v168, v184
	v_fma_f32 v184, v169, v169, v184
	v_cvt_pk_bf16_f32 v107, v168, v169
	global_store_dwordx4 v23, v[100:103], s[0:1]
	global_store_dwordx4 v23, v[104:107], s[0:1] offset:1024
	v_lshlrev_b32_e32 v168, 16, v108
	v_and_b32_e32 v169, 0xffff0000, v108
	v_lshlrev_b32_e32 v170, 16, v140
	v_and_b32_e32 v171, 0xffff0000, v140
	v_mul_f32_e32 v170, s24, v170
	v_mul_f32_e32 v171, s24, v171
	v_fma_f32 v168, v170, v2, v168
	v_fma_f32 v169, v171, v3, v169
	v_fma_f32 v185, v168, v168, v185
	v_fma_f32 v185, v169, v169, v185
	v_cvt_pk_bf16_f32 v108, v168, v169
	v_lshlrev_b32_e32 v168, 16, v109
	v_and_b32_e32 v169, 0xffff0000, v109
	v_lshlrev_b32_e32 v170, 16, v141
	v_and_b32_e32 v171, 0xffff0000, v141
	v_mul_f32_e32 v170, s24, v170
	v_mul_f32_e32 v171, s24, v171
	v_fma_f32 v168, v170, v4, v168
	v_fma_f32 v169, v171, v5, v169
	v_fma_f32 v185, v168, v168, v185
	v_fma_f32 v185, v169, v169, v185
	v_cvt_pk_bf16_f32 v109, v168, v169
	v_lshlrev_b32_e32 v168, 16, v110
	v_and_b32_e32 v169, 0xffff0000, v110
	v_lshlrev_b32_e32 v170, 16, v142
	v_and_b32_e32 v171, 0xffff0000, v142
	v_mul_f32_e32 v170, s24, v170
	v_mul_f32_e32 v171, s24, v171
	v_fma_f32 v168, v170, v6, v168
	v_fma_f32 v169, v171, v7, v169
	v_fma_f32 v185, v168, v168, v185
	v_fma_f32 v185, v169, v169, v185
	v_cvt_pk_bf16_f32 v110, v168, v169
	v_lshlrev_b32_e32 v168, 16, v111
	v_and_b32_e32 v169, 0xffff0000, v111
	v_lshlrev_b32_e32 v170, 16, v143
	v_and_b32_e32 v171, 0xffff0000, v143
	v_mul_f32_e32 v170, s24, v170
	v_mul_f32_e32 v171, s24, v171
	v_fma_f32 v168, v170, v8, v168
	v_fma_f32 v169, v171, v9, v169
	v_fma_f32 v185, v168, v168, v185
	v_fma_f32 v185, v169, v169, v185
	v_cvt_pk_bf16_f32 v111, v168, v169
	v_lshlrev_b32_e32 v168, 16, v112
	v_and_b32_e32 v169, 0xffff0000, v112
	v_lshlrev_b32_e32 v170, 16, v144
	v_and_b32_e32 v171, 0xffff0000, v144
	v_mul_f32_e32 v170, s24, v170
	v_mul_f32_e32 v171, s24, v171
	v_fma_f32 v168, v170, v10, v168
	v_fma_f32 v169, v171, v11, v169
	v_fma_f32 v185, v168, v168, v185
	v_fma_f32 v185, v169, v169, v185
; __device__ __forceinline__ float bf_lo(unsigned w) { return __uint_as_float(w << 16); }
; __device__ __forceinline__ float bf_hi(unsigned w) { return __uint_as_float(w & 0xffff0000u); }
; __device__ __forceinline__ unsigned pk2(float lo, float hi) { bf16x2_t r = __builtin_convertvector((f32x2_t){lo, hi}, bf16x2_t); return __builtin_bit_cast(unsigned, r); }
; template <bool SRC_F32, bool FINAL, int R> __device__ __forceinline__ void ew_compute(const EwSet<SRC_F32, R>& S, int rb, const f32x4 (&g)[4], bf16* hb_out, float* out32, float scale, float* rs_out, int lane) {
;     ...
; #pragma unroll
;         for (int j = 0; j < 4; ++j) {
;             f32x4 h;
;             if constexpr (SRC_F32) h = S.h32[i][j];
;             else { const v2u hw = S.hb[i][j]; h.x = bf_lo(hw.x); h.y = bf_hi(hw.x); h.z = bf_lo(hw.y); h.w = bf_hi(hw.y); }
;             const v2u fw = S.fw[i][j];
;             f32x4 v; v.x = h.x + bf_lo(fw.x) * rs * g[j].x; v.y = h.y + bf_hi(fw.x) * rs * g[j].y; v.z = h.z + bf_lo(fw.y) * rs * g[j].z; v.w = h.w + bf_hi(fw.y) * rs * g[j].w;
;             if (FINAL) __builtin_nontemporal_store(v, (f32x4*)(out32 + (size_t)(rb + i) * D) + lane + 64 * j);
;             else { v2u o; o.x = pk2(v.x, v.y); o.y = pk2(v.z, v.w); ((v2u*)(hb_out + (size_t)(rb + i) * D) + lane)[64 * j] = o; s2 += (v.x * v.x + v.y * v.y) + (v.z * v.z + v.w * v.w); }
	v_cvt_pk_bf16_f32 v112, v168, v169
	v_lshlrev_b32_e32 v168, 16, v113
	v_and_b32_e32 v169, 0xffff0000, v113
	v_lshlrev_b32_e32 v170, 16, v145
	v_and_b32_e32 v171, 0xffff0000, v145
	v_mul_f32_e32 v170, s24, v170
	v_mul_f32_e32 v171, s24, v171
	v_fma_f32 v168, v170, v12, v168
	v_fma_f32 v169, v171, v13, v169
	v_fma_f32 v185, v168, v168, v185
	v_fma_f32 v185, v169, v169, v185
	v_cvt_pk_bf16_f32 v113, v168, v169
	v_lshlrev_b32_e32 v168, 16, v114
	v_and_b32_e32 v169, 0xffff0000, v114
	v_lshlrev_b32_e32 v170, 16, v146
	v_and_b32_e32 v171, 0xffff0000, v146
	v_mul_f32_e32 v170, s24, v170
	v_mul_f32_e32 v171, s24, v171
	v_fma_f32 v168, v170, v14, v168
	v_fma_f32 v169, v171, v15, v169
	v_fma_f32 v185, v168, v168, v185
	v_fma_f32 v185, v169, v169, v185
	v_cvt_pk_bf16_f32 v114, v168, v169
	v_lshlrev_b32_e32 v168, 16, v115
	v_and_b32_e32 v169, 0xffff0000, v115
	v_lshlrev_b32_e32 v170, 16, v147
	v_and_b32_e32 v171, 0xffff0000, v147
	v_mul_f32_e32 v170, s24, v170
	v_mul_f32_e32 v171, s24, v171
	v_fma_f32 v168, v170, v16, v168
	v_fma_f32 v169, v171, v17, v169
	v_fma_f32 v185, v168, v168, v185
	v_fma_f32 v185, v169, v169, v185
	v_cvt_pk_bf16_f32 v115, v168, v169
	global_store_dwordx4 v23, v[108:111], s[0:1] offset:2048
	global_store_dwordx4 v23, v[112:115], s[0:1] offset:3072
	v_lshlrev_b32_e32 v168, 16, v116
	v_and_b32_e32 v169, 0xffff0000, v116
	v_lshlrev_b32_e32 v170, 16, v148
	v_and_b32_e32 v171, 0xffff0000, v148
	v_mul_f32_e32 v170, s98, v170
	v_mul_f32_e32 v171, s98, v171
	v_fma_f32 v168, v170, v2, v168
	v_fma_f32 v169, v171, v3, v169
	v_fma_f32 v186, v168, v168, v186
	v_fma_f32 v186, v169, v169, v186
	v_cvt_pk_bf16_f32 v116, v168, v169
	v_lshlrev_b32_e32 v168, 16, v117
	v_and_b32_e32 v169, 0xffff0000, v117
	v_lshlrev_b32_e32 v170, 16, v149
	v_and_b32_e32 v171, 0xffff0000, v149
	v_mul_f32_e32 v170, s98, v170
	v_mul_f32_e32 v171, s98, v171
	v_fma_f32 v168, v170, v4, v168
	v_fma_f32 v169, v171, v5, v169
	v_fma_f32 v186, v168, v168, v186
	v_fma_f32 v186, v169, v169, v186
	v_cvt_pk_bf16_f32 v117, v168, v169
	v_lshlrev_b32_e32 v168, 16, v118
	v_and_b32_e32 v169, 0xffff0000, v118
	v_lshlrev_b32_e32 v170, 16, v150
	v_and_b32_e32 v171, 0xffff0000, v150
	v_mul_f32_e32 v170, s98, v170
	v_mul_f32_e32 v171, s98, v171
	v_fma_f32 v168, v170, v6, v168
	v_fma_f32 v169, v171, v7, v169
	v_fma_f32 v186, v168, v168, v186
	v_fma_f32 v186, v169, v169, v186
	v_cvt_pk_bf16_f32 v118, v168, v169
	v_lshlrev_b32_e32 v168, 16, v119
	v_and_b32_e32 v169, 0xffff0000, v119
	v_lshlrev_b32_e32 v170, 16, v151
	v_and_b32_e32 v171, 0xffff0000, v151
	v_mul_f32_e32 v170, s98, v170
	v_mul_f32_e32 v171, s98, v171
	v_fma_f32 v168, v170, v8, v168
	v_fma_f32 v169, v171, v9, v169
	v_fma_f32 v186, v168, v168, v186
	v_fma_f32 v186, v169, v169, v186
	v_cvt_pk_bf16_f32 v119, v168, v169
	v_lshlrev_b32_e32 v168, 16, v120
	v_and_b32_e32 v169, 0xffff0000, v120
	v_lshlrev_b32_e32 v170, 16, v152
	v_and_b32_e32 v171, 0xffff0000, v152
	v_mul_f32_e32 v170, s98, v170
	v_mul_f32_e32 v171, s98, v171
	v_fma_f32 v168, v170, v10, v168
	v_fma_f32 v169, v171, v11, v169
	v_fma_f32 v186, v168, v168, v186
	v_fma_f32 v186, v169, v169, v186
	v_cvt_pk_bf16_f32 v120, v168, v169
	v_lshlrev_b32_e32 v168, 16, v121
	v_and_b32_e32 v169, 0xffff0000, v121
	v_lshlrev_b32_e32 v170, 16, v153
	v_and_b32_e32 v171, 0xffff0000, v153
	v_mul_f32_e32 v170, s98, v170
	v_mul_f32_e32 v171, s98, v171
	v_fma_f32 v168, v170, v12, v168
	v_fma_f32 v169, v171, v13, v169
	v_fma_f32 v186, v168, v168, v186
	v_fma_f32 v186, v169, v169, v186
	v_cvt_pk_bf16_f32 v121, v168, v169
	v_lshlrev_b32_e32 v168, 16, v122
	v_and_b32_e32 v169, 0xffff0000, v122
	v_lshlrev_b32_e32 v170, 16, v154
	v_and_b32_e32 v171, 0xffff0000, v154
	v_mul_f32_e32 v170, s98, v170
	v_mul_f32_e32 v171, s98, v171
	v_fma_f32 v168, v170, v14, v168
	v_fma_f32 v169, v171, v15, v169
	v_fma_f32 v186, v168, v168, v186
	v_fma_f32 v186, v169, v169, v186
	v_cvt_pk_bf16_f32 v122, v168, v169
	v_lshlrev_b32_e32 v168, 16, v123
	v_and_b32_e32 v169, 0xffff0000, v123
	v_lshlrev_b32_e32 v170, 16, v155
	v_and_b32_e32 v171, 0xffff0000, v155
	v_mul_f32_e32 v170, s98, v170
	v_mul_f32_e32 v171, s98, v171
	v_fma_f32 v168, v170, v16, v168
	v_fma_f32 v169, v171, v17, v169
	v_fma_f32 v186, v168, v168, v186
	v_fma_f32 v186, v169, v169, v186
	v_cvt_pk_bf16_f32 v123, v168, v169
	global_store_dwordx4 v24, v[116:119], s[0:1]
	global_store_dwordx4 v24, v[120:123], s[0:1] offset:1024
	v_lshlrev_b32_e32 v168, 16, v124
	v_and_b32_e32 v169, 0xffff0000, v124
	v_lshlrev_b32_e32 v170, 16, v156
	v_and_b32_e32 v171, 0xffff0000, v156
	v_mul_f32_e32 v170, s101, v170
	v_mul_f32_e32 v171, s101, v171
	v_fma_f32 v168, v170, v2, v168
	v_fma_f32 v169, v171, v3, v169
	v_fma_f32 v187, v168, v168, v187
	v_fma_f32 v187, v169, v169, v187
	v_cvt_pk_bf16_f32 v124, v168, v169
	v_lshlrev_b32_e32 v168, 16, v125
	v_and_b32_e32 v169, 0xffff0000, v125
	v_lshlrev_b32_e32 v170, 16, v157
; __device__ __forceinline__ float bf_lo(unsigned w) { return __uint_as_float(w << 16); }
; __device__ __forceinline__ float bf_hi(unsigned w) { return __uint_as_float(w & 0xffff0000u); }
; __device__ __forceinline__ unsigned pk2(float lo, float hi) { bf16x2_t r = __builtin_convertvector((f32x2_t){lo, hi}, bf16x2_t); return __builtin_bit_cast(unsigned, r); }
; template <bool SRC_F32, bool FINAL, int R> __device__ __forceinline__ void ew_compute(const EwSet<SRC_F32, R>& S, int rb, const f32x4 (&g)[4], bf16* hb_out, float* out32, float scale, float* rs_out, int lane) {
;     ...
; #pragma unroll
;         for (int j = 0; j < 4; ++j) {
;             f32x4 h;
;             if constexpr (SRC_F32) h = S.h32[i][j];
;             else { const v2u hw = S.hb[i][j]; h.x = bf_lo(hw.x); h.y = bf_hi(hw.x); h.z = bf_lo(hw.y); h.w = bf_hi(hw.y); }
;             const v2u fw = S.fw[i][j];
;             f32x4 v; v.x = h.x + bf_lo(fw.x) * rs * g[j].x; v.y = h.y + bf_hi(fw.x) * rs * g[j].y; v.z = h.z + bf_lo(fw.y) * rs * g[j].z; v.w = h.w + bf_hi(fw.y) * rs * g[j].w;
;             if (FINAL) __builtin_nontemporal_store(v, (f32x4*)(out32 + (size_t)(rb + i) * D) + lane + 64 * j);
;             else { v2u o; o.x = pk2(v.x, v.y); o.y = pk2(v.z, v.w); ((v2u*)(hb_out + (size_t)(rb + i) * D) + lane)[64 * j] = o; s2 += (v.x * v.x + v.y * v.y) + (v.z * v.z + v.w * v.w); }
;         }
;         if (!FINAL) { const float tot = wave_sum(s2); if (lane == 0) rs_out[rb + i] = 1.0f / sqrtf(tot * (1.f / D) + EPS); }
	v_and_b32_e32 v171, 0xffff0000, v157
	v_mul_f32_e32 v170, s101, v170
	v_mul_f32_e32 v171, s101, v171
	v_fma_f32 v168, v170, v4, v168
	v_fma_f32 v169, v171, v5, v169
	v_fma_f32 v187, v168, v168, v187
	v_fma_f32 v187, v169, v169, v187
	v_cvt_pk_bf16_f32 v125, v168, v169
	v_lshlrev_b32_e32 v168, 16, v126
	v_and_b32_e32 v169, 0xffff0000, v126
	v_lshlrev_b32_e32 v170, 16, v158
	v_and_b32_e32 v171, 0xffff0000, v158
	v_mul_f32_e32 v170, s101, v170
	v_mul_f32_e32 v171, s101, v171
	v_fma_f32 v168, v170, v6, v168
	v_fma_f32 v169, v171, v7, v169
	v_fma_f32 v187, v168, v168, v187
	v_fma_f32 v187, v169, v169, v187
	v_cvt_pk_bf16_f32 v126, v168, v169
	v_lshlrev_b32_e32 v168, 16, v127
	v_and_b32_e32 v169, 0xffff0000, v127
	v_lshlrev_b32_e32 v170, 16, v159
	v_and_b32_e32 v171, 0xffff0000, v159
	v_mul_f32_e32 v170, s101, v170
	v_mul_f32_e32 v171, s101, v171
	v_fma_f32 v168, v170, v8, v168
	v_fma_f32 v169, v171, v9, v169
	v_fma_f32 v187, v168, v168, v187
	v_fma_f32 v187, v169, v169, v187
	v_cvt_pk_bf16_f32 v127, v168, v169
	v_lshlrev_b32_e32 v168, 16, v128
	v_and_b32_e32 v169, 0xffff0000, v128
	v_lshlrev_b32_e32 v170, 16, v160
	v_and_b32_e32 v171, 0xffff0000, v160
	v_mul_f32_e32 v170, s101, v170
	v_mul_f32_e32 v171, s101, v171
	v_fma_f32 v168, v170, v10, v168
	v_fma_f32 v169, v171, v11, v169
	v_fma_f32 v187, v168, v168, v187
	v_fma_f32 v187, v169, v169, v187
	v_cvt_pk_bf16_f32 v128, v168, v169
	v_lshlrev_b32_e32 v168, 16, v129
	v_and_b32_e32 v169, 0xffff0000, v129
	v_lshlrev_b32_e32 v170, 16, v161
	v_and_b32_e32 v171, 0xffff0000, v161
	v_mul_f32_e32 v170, s101, v170
	v_mul_f32_e32 v171, s101, v171
	v_fma_f32 v168, v170, v12, v168
	v_fma_f32 v169, v171, v13, v169
	v_fma_f32 v187, v168, v168, v187
	v_fma_f32 v187, v169, v169, v187
	v_cvt_pk_bf16_f32 v129, v168, v169
	v_lshlrev_b32_e32 v168, 16, v130
	v_and_b32_e32 v169, 0xffff0000, v130
	v_lshlrev_b32_e32 v170, 16, v162
	v_and_b32_e32 v171, 0xffff0000, v162
	v_mul_f32_e32 v170, s101, v170
	v_mul_f32_e32 v171, s101, v171
	v_fma_f32 v168, v170, v14, v168
	v_fma_f32 v169, v171, v15, v169
	v_fma_f32 v187, v168, v168, v187
	v_fma_f32 v187, v169, v169, v187
	v_cvt_pk_bf16_f32 v130, v168, v169
	v_lshlrev_b32_e32 v168, 16, v131
	v_and_b32_e32 v169, 0xffff0000, v131
	v_lshlrev_b32_e32 v170, 16, v163
	v_and_b32_e32 v171, 0xffff0000, v163
	v_mul_f32_e32 v170, s101, v170
	v_mul_f32_e32 v171, s101, v171
	v_fma_f32 v168, v170, v16, v168
	v_fma_f32 v169, v171, v17, v169
	v_fma_f32 v187, v168, v168, v187
	v_fma_f32 v187, v169, v169, v187
	v_cvt_pk_bf16_f32 v131, v168, v169
	global_store_dwordx4 v24, v[124:127], s[0:1] offset:2048
	global_store_dwordx4 v24, v[128:131], s[0:1] offset:3072
	s_nop 1
	v_add_f32_dpp v184, v184, v184 quad_perm:[1,0,3,2] row_mask:0xf bank_mask:0xf
	v_add_f32_dpp v185, v185, v185 quad_perm:[1,0,3,2] row_mask:0xf bank_mask:0xf
	v_add_f32_dpp v186, v186, v186 quad_perm:[1,0,3,2] row_mask:0xf bank_mask:0xf
	v_add_f32_dpp v187, v187, v187 quad_perm:[1,0,3,2] row_mask:0xf bank_mask:0xf
	v_add_f32_dpp v184, v184, v184 quad_perm:[2,3,0,1] row_mask:0xf bank_mask:0xf
	v_add_f32_dpp v185, v185, v185 quad_perm:[2,3,0,1] row_mask:0xf bank_mask:0xf
	v_add_f32_dpp v186, v186, v186 quad_perm:[2,3,0,1] row_mask:0xf bank_mask:0xf
	v_add_f32_dpp v187, v187, v187 quad_perm:[2,3,0,1] row_mask:0xf bank_mask:0xf
	v_add_f32_dpp v184, v184, v184 row_half_mirror row_mask:0xf bank_mask:0xf
	v_add_f32_dpp v185, v185, v185 row_half_mirror row_mask:0xf bank_mask:0xf
	v_add_f32_dpp v186, v186, v186 row_half_mirror row_mask:0xf bank_mask:0xf
	v_add_f32_dpp v187, v187, v187 row_half_mirror row_mask:0xf bank_mask:0xf
	v_add_f32_dpp v184, v184, v184 row_mirror row_mask:0xf bank_mask:0xf
	v_add_f32_dpp v185, v185, v185 row_mirror row_mask:0xf bank_mask:0xf
	v_add_f32_dpp v186, v186, v186 row_mirror row_mask:0xf bank_mask:0xf
	v_add_f32_dpp v187, v187, v187 row_mirror row_mask:0xf bank_mask:0xf
	v_add_f32_dpp v184, v184, v184 row_bcast:15 row_mask:0xa bank_mask:0xf
	v_add_f32_dpp v185, v185, v185 row_bcast:15 row_mask:0xa bank_mask:0xf
	v_add_f32_dpp v186, v186, v186 row_bcast:15 row_mask:0xa bank_mask:0xf
	v_add_f32_dpp v187, v187, v187 row_bcast:15 row_mask:0xa bank_mask:0xf
	v_add_f32_dpp v184, v184, v184 row_bcast:31 row_mask:0xc bank_mask:0xf
	v_add_f32_dpp v185, v185, v185 row_bcast:31 row_mask:0xc bank_mask:0xf
	v_add_f32_dpp v186, v186, v186 row_bcast:31 row_mask:0xc bank_mask:0xf
	v_add_f32_dpp v187, v187, v187 row_bcast:31 row_mask:0xc bank_mask:0xf
	s_nop 1
	v_readlane_b32 s3, v184, 63
	v_readlane_b32 s24, v185, 63
	v_readlane_b32 s98, v186, 63
	v_readlane_b32 s101, v187, 63
	s_nop 3
	v_writelane_b32 v188, s3, 0
	v_writelane_b32 v188, s24, 1
	v_writelane_b32 v188, s98, 2
	v_writelane_b32 v188, s101, 3
	s_nop 1
	v_mul_f32_e32 v188, 0x3a800000, v188
	v_add_f32_e32 v188, 0x358637bd, v188
	v_rsq_f32_e32 v188, v188
	s_mov_b64 exec, 15
	global_store_dword v26, v188, s[14:15]
	s_mov_b64 exec, -1

; __device__ __forceinline__ float bf_lo(unsigned w) { return __uint_as_float(w << 16); }
; __device__ __forceinline__ float bf_hi(unsigned w) { return __uint_as_float(w & 0xffff0000u); }
; template <bool SRC_F32, int R> __device__ __forceinline__ void ew_load(EwSet<SRC_F32, R>& S, int rb, const float* hsrc32, const bf16* hsrcb, const bf16* f, const float* part, int lane) {
; #pragma unroll
;     for (int i = 0; i < R; ++i) S.p[i] = (lane < 16) ? part[(size_t)(rb + i) * 16 + lane] : 0.f;
; #pragma unroll
;     for (int i = 0; i < R; ++i)
; #pragma unroll
;         for (int j = 0; j < 4; ++j) {
;             S.fw[i][j] = ((const v2u*)(f + (size_t)(rb + i) * D) + lane)[64 * j];
;             if constexpr (SRC_F32) S.h32[i][j] = __builtin_nontemporal_load((const f32x4*)(hsrc32 + (size_t)(rb + i) * D) + lane + 64 * j);
;             else S.hb[i][j] = ((const v2u*)(hsrcb + (size_t)(rb + i) * D) + lane)[64 * j];
;         }
; }
; template <bool SRC_F32, bool FINAL, int R> __device__ __forceinline__ void ew_compute(const EwSet<SRC_F32, R>& S, int rb, const f32x4 (&g)[4], bf16* hb_out, float* out32, float scale, float* rs_out, int lane) {
; #pragma unroll
;     for (int i = 0; i < R; ++i) {
;         float q = S.p[i];
;         q += __shfl_xor(q, 1); q += __shfl_xor(q, 2); q += __shfl_xor(q, 4); q += __shfl_xor(q, 8);
;         const float ss = __shfl(q, 0);
;         const float rs = scale / sqrtf(ss * (1.f / D) + EPS);
;         float s2 = 0.f;
; #pragma unroll
;         for (int j = 0; j < 4; ++j) {
;             f32x4 h;
;             if constexpr (SRC_F32) h = S.h32[i][j];
;             else { const v2u hw = S.hb[i][j]; h.x = bf_lo(hw.x); h.y = bf_hi(hw.x); h.z = bf_lo(hw.y); h.w = bf_hi(hw.y); }
;             const v2u fw = S.fw[i][j];
;             f32x4 v; v.x = h.x + bf_lo(fw.x) * rs * g[j].x; v.y = h.y + bf_hi(fw.x) * rs * g[j].y; v.z = h.z + bf_lo(fw.y) * rs * g[j].z; v.w = h.w + bf_hi(fw.y) * rs * g[j].w;
;             if (FINAL) __builtin_nontemporal_store(v, (f32x4*)(out32 + (size_t)(rb + i) * D) + lane + 64 * j);
;             else { v2u o; o.x = pk2(v.x, v.y); o.y = pk2(v.z, v.w); ((v2u*)(hb_out + (size_t)(rb + i) * D) + lane)[64 * j] = o; s2 += (v.x * v.x + v.y * v.y) + (v.z * v.z + v.w * v.w); }
;         }
;         if (!FINAL) { const float tot = wave_sum(s2); if (lane == 0) rs_out[rb + i] = 1.0f / sqrtf(tot * (1.f / D) + EPS); }
;     }
; }
.LBB0_1446:
	s_cmp_lt_i32 s30, 15
	s_cselect_b64 s[4:5], -1, 0
	s_and_b64 s[0:1], s[4:5], s[0:1]
	s_andn2_b64 vcc, exec, s[0:1]
	s_cbranch_vccnz .LBB0_1474
	s_waitcnt vmcnt(0) lgkmcnt(0)
	s_add_u32 s22, s84, 0xffffff10
	s_addc_u32 s23, s85, -1
	s_load_dwordx2 s[52:53], s[22:23], 0xd0
	s_load_dwordx2 s[14:15], s[22:23], 0xd8
	s_add_u32 s0, s28, 0x5000000
	s_addc_u32 s1, s29, 0
	s_add_u32 s4, s28, 0x15000000
	s_addc_u32 s5, s29, 0
	s_add_u32 s6, s28, 0x3700000
	s_addc_u32 s7, s29, 0
	v_and_b32_e32 v0, 63, v195
	v_lshlrev_b32_e32 v1, 5, v0
	s_and_b32 s26, s2, 7
	s_lshl_b32 s26, s26, 4
	s_bfe_u32 s27, s2, 0x30003
	s_add_u32 s26, s26, s27
	s_lshl_b32 s26, s26, 8
	s_lshr_b32 s27, s2, 6
	s_lshl_b32 s27, s27, 6
	s_add_u32 s26, s26, s27
	v_readfirstlane_b32 s27, v195
	s_lshr_b32 s27, s27, 6
	s_lshl_b32 s27, s27, 3
	s_add_u32 s26, s26, s27
	s_add_u32 s27, s26, 0
	s_lshl_b32 s22, s27, 11
	v_lshl_add_u32 v18, v0, 4, s22
	v_add_u32_e32 v19, 0x1000, v18
	s_lshl_b32 s22, s27, 6
	v_lshl_add_u32 v20, v0, 2, s22
	s_lshl_b32 s22, s27, 12
	v_lshl_add_u32 v22, v0, 5, s22
	global_load_dwordx4 v[32:35], v18, s[0:1]
	global_load_dwordx4 v[36:39], v18, s[0:1] offset:1024
	global_load_dwordx4 v[64:67], v18, s[4:5]
	global_load_dwordx4 v[68:71], v18, s[4:5] offset:1024
	global_load_dwordx4 v[40:43], v18, s[0:1] offset:2048
	global_load_dwordx4 v[44:47], v18, s[0:1] offset:3072
	global_load_dwordx4 v[72:75], v18, s[4:5] offset:2048
	global_load_dwordx4 v[76:79], v18, s[4:5] offset:3072
	global_load_dwordx4 v[48:51], v19, s[0:1]
	global_load_dwordx4 v[52:55], v19, s[0:1] offset:1024
	global_load_dwordx4 v[80:83], v19, s[4:5]
	global_load_dwordx4 v[84:87], v19, s[4:5] offset:1024
	global_load_dwordx4 v[56:59], v19, s[0:1] offset:2048
	global_load_dwordx4 v[60:63], v19, s[0:1] offset:3072
	global_load_dwordx4 v[88:91], v19, s[4:5] offset:2048
	global_load_dwordx4 v[92:95], v19, s[4:5] offset:3072
	global_load_dword v96, v20, s[6:7]
	s_waitcnt lgkmcnt(0)
	global_load_dwordx4 v[2:5], v1, s[52:53]
	global_load_dwordx4 v[6:9], v1, s[52:53] offset:16
	global_load_dwordx4 v[10:13], v1, s[52:53] offset:2048
	global_load_dwordx4 v[14:17], v1, s[52:53] offset:2064
	s_add_u32 s27, s26, 4
	s_lshl_b32 s22, s27, 11
	v_lshl_add_u32 v23, v0, 4, s22
	v_add_u32_e32 v24, 0x1000, v23
	s_lshl_b32 s22, s27, 6
	v_lshl_add_u32 v25, v0, 2, s22
	s_lshl_b32 s22, s27, 12
	v_lshl_add_u32 v27, v0, 5, s22
	global_load_dwordx4 v[100:103], v23, s[0:1]
	global_load_dwordx4 v[104:107], v23, s[0:1] offset:1024
	global_load_dwordx4 v[132:135], v23, s[4:5]
	global_load_dwordx4 v[136:139], v23, s[4:5] offset:1024
	global_load_dwordx4 v[108:111], v23, s[0:1] offset:2048
	global_load_dwordx4 v[112:115], v23, s[0:1] offset:3072
	global_load_dwordx4 v[140:143], v23, s[4:5] offset:2048
	global_load_dwordx4 v[144:147], v23, s[4:5] offset:3072
	global_load_dwordx4 v[116:119], v24, s[0:1]
	global_load_dwordx4 v[120:123], v24, s[0:1] offset:1024
	global_load_dwordx4 v[148:151], v24, s[4:5]
	global_load_dwordx4 v[152:155], v24, s[4:5] offset:1024
	global_load_dwordx4 v[124:127], v24, s[0:1] offset:2048
	global_load_dwordx4 v[128:131], v24, s[0:1] offset:3072
	global_load_dwordx4 v[156:159], v24, s[4:5] offset:2048
	global_load_dwordx4 v[160:163], v24, s[4:5] offset:3072
	global_load_dword v164, v25, s[6:7]
	s_waitcnt vmcnt(17)
	v_add_f32_dpp v96, v96, v96 quad_perm:[1,0,3,2] row_mask:0xf bank_mask:0xf
	s_nop 1
	v_add_f32_dpp v96, v96, v96 quad_perm:[2,3,0,1] row_mask:0xf bank_mask:0xf
	s_nop 1
	v_add_f32_dpp v96, v96, v96 row_half_mirror row_mask:0xf bank_mask:0xf
	s_nop 1
	v_add_f32_dpp v96, v96, v96 row_mirror row_mask:0xf bank_mask:0xf
	s_nop 1
	v_mul_f32_e32 v96, 0x3a800000, v96
	v_add_f32_e32 v96, 0x358637bd, v96
	v_rsq_f32_e32 v96, v96
	s_nop 0
	v_readlane_b32 s3, v96, 0
	v_readlane_b32 s24, v96, 16
	v_readlane_b32 s98, v96, 32
	v_readlane_b32 s101, v96, 48
	s_nop 1
	v_lshlrev_b32_e32 v168, 16, v32
	v_and_b32_e32 v169, 0xffff0000, v32
	v_lshlrev_b32_e32 v184, 16, v64
	v_and_b32_e32 v185, 0xffff0000, v64
	v_mul_f32_e32 v184, s3, v184
	v_mul_f32_e32 v185, s3, v185
	v_fma_f32 v168, v184, v2, v168
	v_fma_f32 v169, v185, v3, v169
	v_lshlrev_b32_e32 v170, 16, v33
	v_and_b32_e32 v171, 0xffff0000, v33
	v_lshlrev_b32_e32 v184, 16, v65
	v_and_b32_e32 v185, 0xffff0000, v65
	v_mul_f32_e32 v184, s3, v184
	v_mul_f32_e32 v185, s3, v185
	v_fma_f32 v170, v184, v4, v170
	v_fma_f32 v171, v185, v5, v171
	v_lshlrev_b32_e32 v172, 16, v34
	v_and_b32_e32 v173, 0xffff0000, v34
	v_lshlrev_b32_e32 v184, 16, v66
	v_and_b32_e32 v185, 0xffff0000, v66
	v_mul_f32_e32 v184, s3, v184
	v_mul_f32_e32 v185, s3, v185
	v_fma_f32 v172, v184, v6, v172
	v_fma_f32 v173, v185, v7, v173
	v_lshlrev_b32_e32 v174, 16, v35
	v_and_b32_e32 v175, 0xffff0000, v35
	v_lshlrev_b32_e32 v184, 16, v67
	v_and_b32_e32 v185, 0xffff0000, v67
	v_mul_f32_e32 v184, s3, v184
	v_mul_f32_e32 v185, s3, v185
	v_fma_f32 v174, v184, v8, v174
	v_fma_f32 v175, v185, v9, v175
	v_lshlrev_b32_e32 v176, 16, v36
	v_and_b32_e32 v177, 0xffff0000, v36
	v_lshlrev_b32_e32 v184, 16, v68
	v_and_b32_e32 v185, 0xffff0000, v68
	v_mul_f32_e32 v184, s3, v184
	v_mul_f32_e32 v185, s3, v185
	v_fma_f32 v176, v184, v10, v176
	v_fma_f32 v177, v185, v11, v177
	v_lshlrev_b32_e32 v178, 16, v37
	v_and_b32_e32 v179, 0xffff0000, v37
	v_lshlrev_b32_e32 v184, 16, v69
	v_and_b32_e32 v185, 0xffff0000, v69
	v_mul_f32_e32 v184, s3, v184
	v_mul_f32_e32 v185, s3, v185
	v_fma_f32 v178, v184, v12, v178
	v_fma_f32 v179, v185, v13, v179
	v_lshlrev_b32_e32 v180, 16, v38
	v_and_b32_e32 v181, 0xffff0000, v38
	v_lshlrev_b32_e32 v184, 16, v70
	v_and_b32_e32 v185, 0xffff0000, v70
	v_mul_f32_e32 v184, s3, v184
	v_mul_f32_e32 v185, s3, v185
; __device__ __forceinline__ float bf_lo(unsigned w) { return __uint_as_float(w << 16); }
; __device__ __forceinline__ float bf_hi(unsigned w) { return __uint_as_float(w & 0xffff0000u); }
; template <bool SRC_F32, bool FINAL, int R> __device__ __forceinline__ void ew_compute(const EwSet<SRC_F32, R>& S, int rb, const f32x4 (&g)[4], bf16* hb_out, float* out32, float scale, float* rs_out, int lane) {
;     ...
; #pragma unroll
;         for (int j = 0; j < 4; ++j) {
;             f32x4 h;
;             if constexpr (SRC_F32) h = S.h32[i][j];
;             else { const v2u hw = S.hb[i][j]; h.x = bf_lo(hw.x); h.y = bf_hi(hw.x); h.z = bf_lo(hw.y); h.w = bf_hi(hw.y); }
;             const v2u fw = S.fw[i][j];
;             f32x4 v; v.x = h.x + bf_lo(fw.x) * rs * g[j].x; v.y = h.y + bf_hi(fw.x) * rs * g[j].y; v.z = h.z + bf_lo(fw.y) * rs * g[j].z; v.w = h.w + bf_hi(fw.y) * rs * g[j].w;
;             if (FINAL) __builtin_nontemporal_store(v, (f32x4*)(out32 + (size_t)(rb + i) * D) + lane + 64 * j);
	v_fma_f32 v180, v184, v14, v180
	v_fma_f32 v181, v185, v15, v181
	v_lshlrev_b32_e32 v182, 16, v39
	v_and_b32_e32 v183, 0xffff0000, v39
	v_lshlrev_b32_e32 v184, 16, v71
	v_and_b32_e32 v185, 0xffff0000, v71
	v_mul_f32_e32 v184, s3, v184
	v_mul_f32_e32 v185, s3, v185
	v_fma_f32 v182, v184, v16, v182
	v_fma_f32 v183, v185, v17, v183
	global_store_dwordx4 v22, v[168:171], s[14:15] nt
	global_store_dwordx4 v22, v[172:175], s[14:15] offset:16 nt
	global_store_dwordx4 v22, v[176:179], s[14:15] offset:2048 nt
	global_store_dwordx4 v22, v[180:183], s[14:15] offset:2064 nt
	s_nop 1
	v_lshlrev_b32_e32 v168, 16, v40
	v_and_b32_e32 v169, 0xffff0000, v40
	v_lshlrev_b32_e32 v184, 16, v72
	v_and_b32_e32 v185, 0xffff0000, v72
	v_mul_f32_e32 v184, s24, v184
	v_mul_f32_e32 v185, s24, v185
	v_fma_f32 v168, v184, v2, v168
	v_fma_f32 v169, v185, v3, v169
	v_lshlrev_b32_e32 v170, 16, v41
	v_and_b32_e32 v171, 0xffff0000, v41
	v_lshlrev_b32_e32 v184, 16, v73
	v_and_b32_e32 v185, 0xffff0000, v73
	v_mul_f32_e32 v184, s24, v184
	v_mul_f32_e32 v185, s24, v185
	v_fma_f32 v170, v184, v4, v170
	v_fma_f32 v171, v185, v5, v171
	v_lshlrev_b32_e32 v172, 16, v42
	v_and_b32_e32 v173, 0xffff0000, v42
	v_lshlrev_b32_e32 v184, 16, v74
	v_and_b32_e32 v185, 0xffff0000, v74
	v_mul_f32_e32 v184, s24, v184
	v_mul_f32_e32 v185, s24, v185
	v_fma_f32 v172, v184, v6, v172
	v_fma_f32 v173, v185, v7, v173
	v_lshlrev_b32_e32 v174, 16, v43
	v_and_b32_e32 v175, 0xffff0000, v43
	v_lshlrev_b32_e32 v184, 16, v75
	v_and_b32_e32 v185, 0xffff0000, v75
	v_mul_f32_e32 v184, s24, v184
	v_mul_f32_e32 v185, s24, v185
	v_fma_f32 v174, v184, v8, v174
	v_fma_f32 v175, v185, v9, v175
	v_lshlrev_b32_e32 v176, 16, v44
	v_and_b32_e32 v177, 0xffff0000, v44
	v_lshlrev_b32_e32 v184, 16, v76
	v_and_b32_e32 v185, 0xffff0000, v76
	v_mul_f32_e32 v184, s24, v184
	v_mul_f32_e32 v185, s24, v185
	v_fma_f32 v176, v184, v10, v176
	v_fma_f32 v177, v185, v11, v177
	v_lshlrev_b32_e32 v178, 16, v45
	v_and_b32_e32 v179, 0xffff0000, v45
	v_lshlrev_b32_e32 v184, 16, v77
	v_and_b32_e32 v185, 0xffff0000, v77
	v_mul_f32_e32 v184, s24, v184
	v_mul_f32_e32 v185, s24, v185
	v_fma_f32 v178, v184, v12, v178
	v_fma_f32 v179, v185, v13, v179
	v_lshlrev_b32_e32 v180, 16, v46
	v_and_b32_e32 v181, 0xffff0000, v46
	v_lshlrev_b32_e32 v184, 16, v78
	v_and_b32_e32 v185, 0xffff0000, v78
	v_mul_f32_e32 v184, s24, v184
	v_mul_f32_e32 v185, s24, v185
	v_fma_f32 v180, v184, v14, v180
	v_fma_f32 v181, v185, v15, v181
	v_lshlrev_b32_e32 v182, 16, v47
	v_and_b32_e32 v183, 0xffff0000, v47
	v_lshlrev_b32_e32 v184, 16, v79
	v_and_b32_e32 v185, 0xffff0000, v79
	v_mul_f32_e32 v184, s24, v184
	v_mul_f32_e32 v185, s24, v185
	v_fma_f32 v182, v184, v16, v182
	v_fma_f32 v183, v185, v17, v183
	v_add_u32_e32 v1, 0x1000, v22
	global_store_dwordx4 v1, v[168:171], s[14:15] nt
	global_store_dwordx4 v1, v[172:175], s[14:15] offset:16 nt
	global_store_dwordx4 v1, v[176:179], s[14:15] offset:2048 nt
	global_store_dwordx4 v1, v[180:183], s[14:15] offset:2064 nt
	s_nop 1
	v_lshlrev_b32_e32 v168, 16, v48
	v_and_b32_e32 v169, 0xffff0000, v48
	v_lshlrev_b32_e32 v184, 16, v80
	v_and_b32_e32 v185, 0xffff0000, v80
	v_mul_f32_e32 v184, s98, v184
	v_mul_f32_e32 v185, s98, v185
	v_fma_f32 v168, v184, v2, v168
	v_fma_f32 v169, v185, v3, v169
	v_lshlrev_b32_e32 v170, 16, v49
	v_and_b32_e32 v171, 0xffff0000, v49
	v_lshlrev_b32_e32 v184, 16, v81
	v_and_b32_e32 v185, 0xffff0000, v81
	v_mul_f32_e32 v184, s98, v184
	v_mul_f32_e32 v185, s98, v185
	v_fma_f32 v170, v184, v4, v170
	v_fma_f32 v171, v185, v5, v171
	v_lshlrev_b32_e32 v172, 16, v50
	v_and_b32_e32 v173, 0xffff0000, v50
	v_lshlrev_b32_e32 v184, 16, v82
	v_and_b32_e32 v185, 0xffff0000, v82
	v_mul_f32_e32 v184, s98, v184
	v_mul_f32_e32 v185, s98, v185
	v_fma_f32 v172, v184, v6, v172
	v_fma_f32 v173, v185, v7, v173
	v_lshlrev_b32_e32 v174, 16, v51
	v_and_b32_e32 v175, 0xffff0000, v51
	v_lshlrev_b32_e32 v184, 16, v83
	v_and_b32_e32 v185, 0xffff0000, v83
	v_mul_f32_e32 v184, s98, v184
	v_mul_f32_e32 v185, s98, v185
	v_fma_f32 v174, v184, v8, v174
	v_fma_f32 v175, v185, v9, v175
	v_lshlrev_b32_e32 v176, 16, v52
	v_and_b32_e32 v177, 0xffff0000, v52
	v_lshlrev_b32_e32 v184, 16, v84
	v_and_b32_e32 v185, 0xffff0000, v84
	v_mul_f32_e32 v184, s98, v184
	v_mul_f32_e32 v185, s98, v185
	v_fma_f32 v176, v184, v10, v176
	v_fma_f32 v177, v185, v11, v177
	v_lshlrev_b32_e32 v178, 16, v53
	v_and_b32_e32 v179, 0xffff0000, v53
	v_lshlrev_b32_e32 v184, 16, v85
	v_and_b32_e32 v185, 0xffff0000, v85
	v_mul_f32_e32 v184, s98, v184
	v_mul_f32_e32 v185, s98, v185
	v_fma_f32 v178, v184, v12, v178
	v_fma_f32 v179, v185, v13, v179
	v_lshlrev_b32_e32 v180, 16, v54
	v_and_b32_e32 v181, 0xffff0000, v54
	v_lshlrev_b32_e32 v184, 16, v86
	v_and_b32_e32 v185, 0xffff0000, v86
	v_mul_f32_e32 v184, s98, v184
	v_mul_f32_e32 v185, s98, v185
	v_fma_f32 v180, v184, v14, v180
	v_fma_f32 v181, v185, v15, v181
	v_lshlrev_b32_e32 v182, 16, v55
	v_and_b32_e32 v183, 0xffff0000, v55
	v_lshlrev_b32_e32 v184, 16, v87
	v_and_b32_e32 v185, 0xffff0000, v87
	v_mul_f32_e32 v184, s98, v184
	v_mul_f32_e32 v185, s98, v185
	v_fma_f32 v182, v184, v16, v182
	v_fma_f32 v183, v185, v17, v183
	v_add_u32_e32 v1, 0x2000, v22
	global_store_dwordx4 v1, v[168:171], s[14:15] nt
	global_store_dwordx4 v1, v[172:175], s[14:15] offset:16 nt
	global_store_dwordx4 v1, v[176:179], s[14:15] offset:2048 nt
	global_store_dwordx4 v1, v[180:183], s[14:15] offset:2064 nt
	s_nop 1
	v_lshlrev_b32_e32 v168, 16, v56
	v_and_b32_e32 v169, 0xffff0000, v56
	v_lshlrev_b32_e32 v184, 16, v88
	v_and_b32_e32 v185, 0xffff0000, v88
	v_mul_f32_e32 v184, s101, v184
	v_mul_f32_e32 v185, s101, v185
	v_fma_f32 v168, v184, v2, v168
; __device__ __forceinline__ float bf_lo(unsigned w) { return __uint_as_float(w << 16); }
; __device__ __forceinline__ float bf_hi(unsigned w) { return __uint_as_float(w & 0xffff0000u); }
; template <bool SRC_F32, int R> __device__ __forceinline__ void ew_load(EwSet<SRC_F32, R>& S, int rb, const float* hsrc32, const bf16* hsrcb, const bf16* f, const float* part, int lane) {
; #pragma unroll
;     for (int i = 0; i < R; ++i) S.p[i] = (lane < 16) ? part[(size_t)(rb + i) * 16 + lane] : 0.f;
; #pragma unroll
;     for (int i = 0; i < R; ++i)
; #pragma unroll
;         for (int j = 0; j < 4; ++j) {
;             S.fw[i][j] = ((const v2u*)(f + (size_t)(rb + i) * D) + lane)[64 * j];
;             if constexpr (SRC_F32) S.h32[i][j] = __builtin_nontemporal_load((const f32x4*)(hsrc32 + (size_t)(rb + i) * D) + lane + 64 * j);
;             else S.hb[i][j] = ((const v2u*)(hsrcb + (size_t)(rb + i) * D) + lane)[64 * j];
;         }
; }
; template <bool SRC_F32, bool FINAL, int R> __device__ __forceinline__ void ew_compute(const EwSet<SRC_F32, R>& S, int rb, const f32x4 (&g)[4], bf16* hb_out, float* out32, float scale, float* rs_out, int lane) {
; #pragma unroll
;     for (int i = 0; i < R; ++i) {
;         float q = S.p[i];
;         q += __shfl_xor(q, 1); q += __shfl_xor(q, 2); q += __shfl_xor(q, 4); q += __shfl_xor(q, 8);
;         const float ss = __shfl(q, 0);
;         const float rs = scale / sqrtf(ss * (1.f / D) + EPS);
;         float s2 = 0.f;
; #pragma unroll
;         for (int j = 0; j < 4; ++j) {
;             f32x4 h;
;             if constexpr (SRC_F32) h = S.h32[i][j];
;             else { const v2u hw = S.hb[i][j]; h.x = bf_lo(hw.x); h.y = bf_hi(hw.x); h.z = bf_lo(hw.y); h.w = bf_hi(hw.y); }
;             const v2u fw = S.fw[i][j];
;             f32x4 v; v.x = h.x + bf_lo(fw.x) * rs * g[j].x; v.y = h.y + bf_hi(fw.x) * rs * g[j].y; v.z = h.z + bf_lo(fw.y) * rs * g[j].z; v.w = h.w + bf_hi(fw.y) * rs * g[j].w;
;             if (FINAL) __builtin_nontemporal_store(v, (f32x4*)(out32 + (size_t)(rb + i) * D) + lane + 64 * j);
	v_fma_f32 v169, v185, v3, v169
	v_lshlrev_b32_e32 v170, 16, v57
	v_and_b32_e32 v171, 0xffff0000, v57
	v_lshlrev_b32_e32 v184, 16, v89
	v_and_b32_e32 v185, 0xffff0000, v89
	v_mul_f32_e32 v184, s101, v184
	v_mul_f32_e32 v185, s101, v185
	v_fma_f32 v170, v184, v4, v170
	v_fma_f32 v171, v185, v5, v171
	v_lshlrev_b32_e32 v172, 16, v58
	v_and_b32_e32 v173, 0xffff0000, v58
	v_lshlrev_b32_e32 v184, 16, v90
	v_and_b32_e32 v185, 0xffff0000, v90
	v_mul_f32_e32 v184, s101, v184
	v_mul_f32_e32 v185, s101, v185
	v_fma_f32 v172, v184, v6, v172
	v_fma_f32 v173, v185, v7, v173
	v_lshlrev_b32_e32 v174, 16, v59
	v_and_b32_e32 v175, 0xffff0000, v59
	v_lshlrev_b32_e32 v184, 16, v91
	v_and_b32_e32 v185, 0xffff0000, v91
	v_mul_f32_e32 v184, s101, v184
	v_mul_f32_e32 v185, s101, v185
	v_fma_f32 v174, v184, v8, v174
	v_fma_f32 v175, v185, v9, v175
	v_lshlrev_b32_e32 v176, 16, v60
	v_and_b32_e32 v177, 0xffff0000, v60
	v_lshlrev_b32_e32 v184, 16, v92
	v_and_b32_e32 v185, 0xffff0000, v92
	v_mul_f32_e32 v184, s101, v184
	v_mul_f32_e32 v185, s101, v185
	v_fma_f32 v176, v184, v10, v176
	v_fma_f32 v177, v185, v11, v177
	v_lshlrev_b32_e32 v178, 16, v61
	v_and_b32_e32 v179, 0xffff0000, v61
	v_lshlrev_b32_e32 v184, 16, v93
	v_and_b32_e32 v185, 0xffff0000, v93
	v_mul_f32_e32 v184, s101, v184
	v_mul_f32_e32 v185, s101, v185
	v_fma_f32 v178, v184, v12, v178
	v_fma_f32 v179, v185, v13, v179
	v_lshlrev_b32_e32 v180, 16, v62
	v_and_b32_e32 v181, 0xffff0000, v62
	v_lshlrev_b32_e32 v184, 16, v94
	v_and_b32_e32 v185, 0xffff0000, v94
	v_mul_f32_e32 v184, s101, v184
	v_mul_f32_e32 v185, s101, v185
	v_fma_f32 v180, v184, v14, v180
	v_fma_f32 v181, v185, v15, v181
	v_lshlrev_b32_e32 v182, 16, v63
	v_and_b32_e32 v183, 0xffff0000, v63
	v_lshlrev_b32_e32 v184, 16, v95
	v_and_b32_e32 v185, 0xffff0000, v95
	v_mul_f32_e32 v184, s101, v184
	v_mul_f32_e32 v185, s101, v185
	v_fma_f32 v182, v184, v16, v182
	v_fma_f32 v183, v185, v17, v183
	v_add_u32_e32 v1, 0x3000, v22
	global_store_dwordx4 v1, v[168:171], s[14:15] nt
	global_store_dwordx4 v1, v[172:175], s[14:15] offset:16 nt
	global_store_dwordx4 v1, v[176:179], s[14:15] offset:2048 nt
	global_store_dwordx4 v1, v[180:183], s[14:15] offset:2064 nt
	s_nop 1
	s_add_u32 s27, s26, 2048
	s_lshl_b32 s22, s27, 11
	v_lshl_add_u32 v18, v0, 4, s22
	v_add_u32_e32 v19, 0x1000, v18
	s_lshl_b32 s22, s27, 6
	v_lshl_add_u32 v20, v0, 2, s22
	s_lshl_b32 s22, s27, 12
	v_lshl_add_u32 v22, v0, 5, s22
	global_load_dwordx4 v[32:35], v18, s[0:1]
	global_load_dwordx4 v[36:39], v18, s[0:1] offset:1024
	global_load_dwordx4 v[64:67], v18, s[4:5]
	global_load_dwordx4 v[68:71], v18, s[4:5] offset:1024
	global_load_dwordx4 v[40:43], v18, s[0:1] offset:2048
	global_load_dwordx4 v[44:47], v18, s[0:1] offset:3072
	global_load_dwordx4 v[72:75], v18, s[4:5] offset:2048
	global_load_dwordx4 v[76:79], v18, s[4:5] offset:3072
	global_load_dwordx4 v[48:51], v19, s[0:1]
	global_load_dwordx4 v[52:55], v19, s[0:1] offset:1024
	global_load_dwordx4 v[80:83], v19, s[4:5]
	global_load_dwordx4 v[84:87], v19, s[4:5] offset:1024
	global_load_dwordx4 v[56:59], v19, s[0:1] offset:2048
	global_load_dwordx4 v[60:63], v19, s[0:1] offset:3072
	global_load_dwordx4 v[88:91], v19, s[4:5] offset:2048
	global_load_dwordx4 v[92:95], v19, s[4:5] offset:3072
	global_load_dword v96, v20, s[6:7]
	s_waitcnt vmcnt(33)
	v_add_f32_dpp v164, v164, v164 quad_perm:[1,0,3,2] row_mask:0xf bank_mask:0xf
	s_nop 1
	v_add_f32_dpp v164, v164, v164 quad_perm:[2,3,0,1] row_mask:0xf bank_mask:0xf
	s_nop 1
	v_add_f32_dpp v164, v164, v164 row_half_mirror row_mask:0xf bank_mask:0xf
	s_nop 1
	v_add_f32_dpp v164, v164, v164 row_mirror row_mask:0xf bank_mask:0xf
	s_nop 1
	v_mul_f32_e32 v164, 0x3a800000, v164
	v_add_f32_e32 v164, 0x358637bd, v164
	v_rsq_f32_e32 v164, v164
	s_nop 0
	v_readlane_b32 s3, v164, 0
	v_readlane_b32 s24, v164, 16
	v_readlane_b32 s98, v164, 32
	v_readlane_b32 s101, v164, 48
	s_nop 1
	v_lshlrev_b32_e32 v168, 16, v100
	v_and_b32_e32 v169, 0xffff0000, v100
	v_lshlrev_b32_e32 v184, 16, v132
	v_and_b32_e32 v185, 0xffff0000, v132
	v_mul_f32_e32 v184, s3, v184
	v_mul_f32_e32 v185, s3, v185
	v_fma_f32 v168, v184, v2, v168
	v_fma_f32 v169, v185, v3, v169
	v_lshlrev_b32_e32 v170, 16, v101
	v_and_b32_e32 v171, 0xffff0000, v101
	v_lshlrev_b32_e32 v184, 16, v133
	v_and_b32_e32 v185, 0xffff0000, v133
	v_mul_f32_e32 v184, s3, v184
	v_mul_f32_e32 v185, s3, v185
	v_fma_f32 v170, v184, v4, v170
	v_fma_f32 v171, v185, v5, v171
	v_lshlrev_b32_e32 v172, 16, v102
	v_and_b32_e32 v173, 0xffff0000, v102
	v_lshlrev_b32_e32 v184, 16, v134
	v_and_b32_e32 v185, 0xffff0000, v134
	v_mul_f32_e32 v184, s3, v184
	v_mul_f32_e32 v185, s3, v185
	v_fma_f32 v172, v184, v6, v172
	v_fma_f32 v173, v185, v7, v173
	v_lshlrev_b32_e32 v174, 16, v103
	v_and_b32_e32 v175, 0xffff0000, v103
	v_lshlrev_b32_e32 v184, 16, v135
	v_and_b32_e32 v185, 0xffff0000, v135
	v_mul_f32_e32 v184, s3, v184
	v_mul_f32_e32 v185, s3, v185
	v_fma_f32 v174, v184, v8, v174
	v_fma_f32 v175, v185, v9, v175
	v_lshlrev_b32_e32 v176, 16, v104
	v_and_b32_e32 v177, 0xffff0000, v104
	v_lshlrev_b32_e32 v184, 16, v136
	v_and_b32_e32 v185, 0xffff0000, v136
	v_mul_f32_e32 v184, s3, v184
	v_mul_f32_e32 v185, s3, v185
	v_fma_f32 v176, v184, v10, v176
	v_fma_f32 v177, v185, v11, v177
	v_lshlrev_b32_e32 v178, 16, v105
	v_and_b32_e32 v179, 0xffff0000, v105
	v_lshlrev_b32_e32 v184, 16, v137
	v_and_b32_e32 v185, 0xffff0000, v137
	v_mul_f32_e32 v184, s3, v184
	v_mul_f32_e32 v185, s3, v185
	v_fma_f32 v178, v184, v12, v178
	v_fma_f32 v179, v185, v13, v179
	v_lshlrev_b32_e32 v180, 16, v106
	v_and_b32_e32 v181, 0xffff0000, v106
	v_lshlrev_b32_e32 v184, 16, v138
	v_and_b32_e32 v185, 0xffff0000, v138
; __device__ __forceinline__ float bf_lo(unsigned w) { return __uint_as_float(w << 16); }
; __device__ __forceinline__ float bf_hi(unsigned w) { return __uint_as_float(w & 0xffff0000u); }
; template <bool SRC_F32, bool FINAL, int R> __device__ __forceinline__ void ew_compute(const EwSet<SRC_F32, R>& S, int rb, const f32x4 (&g)[4], bf16* hb_out, float* out32, float scale, float* rs_out, int lane) {
;     ...
; #pragma unroll
;         for (int j = 0; j < 4; ++j) {
;             f32x4 h;
;             if constexpr (SRC_F32) h = S.h32[i][j];
;             else { const v2u hw = S.hb[i][j]; h.x = bf_lo(hw.x); h.y = bf_hi(hw.x); h.z = bf_lo(hw.y); h.w = bf_hi(hw.y); }
;             const v2u fw = S.fw[i][j];
;             f32x4 v; v.x = h.x + bf_lo(fw.x) * rs * g[j].x; v.y = h.y + bf_hi(fw.x) * rs * g[j].y; v.z = h.z + bf_lo(fw.y) * rs * g[j].z; v.w = h.w + bf_hi(fw.y) * rs * g[j].w;
;             if (FINAL) __builtin_nontemporal_store(v, (f32x4*)(out32 + (size_t)(rb + i) * D) + lane + 64 * j);
	v_mul_f32_e32 v184, s3, v184
	v_mul_f32_e32 v185, s3, v185
	v_fma_f32 v180, v184, v14, v180
	v_fma_f32 v181, v185, v15, v181
	v_lshlrev_b32_e32 v182, 16, v107
	v_and_b32_e32 v183, 0xffff0000, v107
	v_lshlrev_b32_e32 v184, 16, v139
	v_and_b32_e32 v185, 0xffff0000, v139
	v_mul_f32_e32 v184, s3, v184
	v_mul_f32_e32 v185, s3, v185
	v_fma_f32 v182, v184, v16, v182
	v_fma_f32 v183, v185, v17, v183
	global_store_dwordx4 v27, v[168:171], s[14:15] nt
	global_store_dwordx4 v27, v[172:175], s[14:15] offset:16 nt
	global_store_dwordx4 v27, v[176:179], s[14:15] offset:2048 nt
	global_store_dwordx4 v27, v[180:183], s[14:15] offset:2064 nt
	s_nop 1
	v_lshlrev_b32_e32 v168, 16, v108
	v_and_b32_e32 v169, 0xffff0000, v108
	v_lshlrev_b32_e32 v184, 16, v140
	v_and_b32_e32 v185, 0xffff0000, v140
	v_mul_f32_e32 v184, s24, v184
	v_mul_f32_e32 v185, s24, v185
	v_fma_f32 v168, v184, v2, v168
	v_fma_f32 v169, v185, v3, v169
	v_lshlrev_b32_e32 v170, 16, v109
	v_and_b32_e32 v171, 0xffff0000, v109
	v_lshlrev_b32_e32 v184, 16, v141
	v_and_b32_e32 v185, 0xffff0000, v141
	v_mul_f32_e32 v184, s24, v184
	v_mul_f32_e32 v185, s24, v185
	v_fma_f32 v170, v184, v4, v170
	v_fma_f32 v171, v185, v5, v171
	v_lshlrev_b32_e32 v172, 16, v110
	v_and_b32_e32 v173, 0xffff0000, v110
	v_lshlrev_b32_e32 v184, 16, v142
	v_and_b32_e32 v185, 0xffff0000, v142
	v_mul_f32_e32 v184, s24, v184
	v_mul_f32_e32 v185, s24, v185
	v_fma_f32 v172, v184, v6, v172
	v_fma_f32 v173, v185, v7, v173
	v_lshlrev_b32_e32 v174, 16, v111
	v_and_b32_e32 v175, 0xffff0000, v111
	v_lshlrev_b32_e32 v184, 16, v143
	v_and_b32_e32 v185, 0xffff0000, v143
	v_mul_f32_e32 v184, s24, v184
	v_mul_f32_e32 v185, s24, v185
	v_fma_f32 v174, v184, v8, v174
	v_fma_f32 v175, v185, v9, v175
	v_lshlrev_b32_e32 v176, 16, v112
	v_and_b32_e32 v177, 0xffff0000, v112
	v_lshlrev_b32_e32 v184, 16, v144
	v_and_b32_e32 v185, 0xffff0000, v144
	v_mul_f32_e32 v184, s24, v184
	v_mul_f32_e32 v185, s24, v185
	v_fma_f32 v176, v184, v10, v176
	v_fma_f32 v177, v185, v11, v177
	v_lshlrev_b32_e32 v178, 16, v113
	v_and_b32_e32 v179, 0xffff0000, v113
	v_lshlrev_b32_e32 v184, 16, v145
	v_and_b32_e32 v185, 0xffff0000, v145
	v_mul_f32_e32 v184, s24, v184
	v_mul_f32_e32 v185, s24, v185
	v_fma_f32 v178, v184, v12, v178
	v_fma_f32 v179, v185, v13, v179
	v_lshlrev_b32_e32 v180, 16, v114
	v_and_b32_e32 v181, 0xffff0000, v114
	v_lshlrev_b32_e32 v184, 16, v146
	v_and_b32_e32 v185, 0xffff0000, v146
	v_mul_f32_e32 v184, s24, v184
	v_mul_f32_e32 v185, s24, v185
	v_fma_f32 v180, v184, v14, v180
	v_fma_f32 v181, v185, v15, v181
	v_lshlrev_b32_e32 v182, 16, v115
	v_and_b32_e32 v183, 0xffff0000, v115
	v_lshlrev_b32_e32 v184, 16, v147
	v_and_b32_e32 v185, 0xffff0000, v147
	v_mul_f32_e32 v184, s24, v184
	v_mul_f32_e32 v185, s24, v185
	v_fma_f32 v182, v184, v16, v182
	v_fma_f32 v183, v185, v17, v183
	v_add_u32_e32 v1, 0x1000, v27
	global_store_dwordx4 v1, v[168:171], s[14:15] nt
	global_store_dwordx4 v1, v[172:175], s[14:15] offset:16 nt
	global_store_dwordx4 v1, v[176:179], s[14:15] offset:2048 nt
	global_store_dwordx4 v1, v[180:183], s[14:15] offset:2064 nt
	s_nop 1
	v_lshlrev_b32_e32 v168, 16, v116
	v_and_b32_e32 v169, 0xffff0000, v116
	v_lshlrev_b32_e32 v184, 16, v148
	v_and_b32_e32 v185, 0xffff0000, v148
	v_mul_f32_e32 v184, s98, v184
	v_mul_f32_e32 v185, s98, v185
	v_fma_f32 v168, v184, v2, v168
	v_fma_f32 v169, v185, v3, v169
	v_lshlrev_b32_e32 v170, 16, v117
	v_and_b32_e32 v171, 0xffff0000, v117
	v_lshlrev_b32_e32 v184, 16, v149
	v_and_b32_e32 v185, 0xffff0000, v149
	v_mul_f32_e32 v184, s98, v184
	v_mul_f32_e32 v185, s98, v185
	v_fma_f32 v170, v184, v4, v170
	v_fma_f32 v171, v185, v5, v171
	v_lshlrev_b32_e32 v172, 16, v118
	v_and_b32_e32 v173, 0xffff0000, v118
	v_lshlrev_b32_e32 v184, 16, v150
	v_and_b32_e32 v185, 0xffff0000, v150
	v_mul_f32_e32 v184, s98, v184
	v_mul_f32_e32 v185, s98, v185
	v_fma_f32 v172, v184, v6, v172
	v_fma_f32 v173, v185, v7, v173
	v_lshlrev_b32_e32 v174, 16, v119
	v_and_b32_e32 v175, 0xffff0000, v119
	v_lshlrev_b32_e32 v184, 16, v151
	v_and_b32_e32 v185, 0xffff0000, v151
	v_mul_f32_e32 v184, s98, v184
	v_mul_f32_e32 v185, s98, v185
	v_fma_f32 v174, v184, v8, v174
	v_fma_f32 v175, v185, v9, v175
	v_lshlrev_b32_e32 v176, 16, v120
	v_and_b32_e32 v177, 0xffff0000, v120
	v_lshlrev_b32_e32 v184, 16, v152
	v_and_b32_e32 v185, 0xffff0000, v152
	v_mul_f32_e32 v184, s98, v184
	v_mul_f32_e32 v185, s98, v185
	v_fma_f32 v176, v184, v10, v176
	v_fma_f32 v177, v185, v11, v177
	v_lshlrev_b32_e32 v178, 16, v121
	v_and_b32_e32 v179, 0xffff0000, v121
	v_lshlrev_b32_e32 v184, 16, v153
	v_and_b32_e32 v185, 0xffff0000, v153
	v_mul_f32_e32 v184, s98, v184
	v_mul_f32_e32 v185, s98, v185
	v_fma_f32 v178, v184, v12, v178
	v_fma_f32 v179, v185, v13, v179
	v_lshlrev_b32_e32 v180, 16, v122
	v_and_b32_e32 v181, 0xffff0000, v122
	v_lshlrev_b32_e32 v184, 16, v154
	v_and_b32_e32 v185, 0xffff0000, v154
	v_mul_f32_e32 v184, s98, v184
	v_mul_f32_e32 v185, s98, v185
	v_fma_f32 v180, v184, v14, v180
	v_fma_f32 v181, v185, v15, v181
	v_lshlrev_b32_e32 v182, 16, v123
	v_and_b32_e32 v183, 0xffff0000, v123
	v_lshlrev_b32_e32 v184, 16, v155
	v_and_b32_e32 v185, 0xffff0000, v155
	v_mul_f32_e32 v184, s98, v184
	v_mul_f32_e32 v185, s98, v185
	v_fma_f32 v182, v184, v16, v182
	v_fma_f32 v183, v185, v17, v183
	v_add_u32_e32 v1, 0x2000, v27
	global_store_dwordx4 v1, v[168:171], s[14:15] nt
	global_store_dwordx4 v1, v[172:175], s[14:15] offset:16 nt
	global_store_dwordx4 v1, v[176:179], s[14:15] offset:2048 nt
	global_store_dwordx4 v1, v[180:183], s[14:15] offset:2064 nt
	s_nop 1
	v_lshlrev_b32_e32 v168, 16, v124
	v_and_b32_e32 v169, 0xffff0000, v124
	v_lshlrev_b32_e32 v184, 16, v156
; __device__ __forceinline__ float bf_lo(unsigned w) { return __uint_as_float(w << 16); }
; __device__ __forceinline__ float bf_hi(unsigned w) { return __uint_as_float(w & 0xffff0000u); }
; template <bool SRC_F32, int R> __device__ __forceinline__ void ew_load(EwSet<SRC_F32, R>& S, int rb, const float* hsrc32, const bf16* hsrcb, const bf16* f, const float* part, int lane) {
; #pragma unroll
;     for (int i = 0; i < R; ++i) S.p[i] = (lane < 16) ? part[(size_t)(rb + i) * 16 + lane] : 0.f;
; #pragma unroll
;     for (int i = 0; i < R; ++i)
; #pragma unroll
;         for (int j = 0; j < 4; ++j) {
;             S.fw[i][j] = ((const v2u*)(f + (size_t)(rb + i) * D) + lane)[64 * j];
;             if constexpr (SRC_F32) S.h32[i][j] = __builtin_nontemporal_load((const f32x4*)(hsrc32 + (size_t)(rb + i) * D) + lane + 64 * j);
;             else S.hb[i][j] = ((const v2u*)(hsrcb + (size_t)(rb + i) * D) + lane)[64 * j];
;         }
; }
; template <bool SRC_F32, bool FINAL, int R> __device__ __forceinline__ void ew_compute(const EwSet<SRC_F32, R>& S, int rb, const f32x4 (&g)[4], bf16* hb_out, float* out32, float scale, float* rs_out, int lane) {
; #pragma unroll
;     for (int i = 0; i < R; ++i) {
;         float q = S.p[i];
;         q += __shfl_xor(q, 1); q += __shfl_xor(q, 2); q += __shfl_xor(q, 4); q += __shfl_xor(q, 8);
;         const float ss = __shfl(q, 0);
;         const float rs = scale / sqrtf(ss * (1.f / D) + EPS);
;         float s2 = 0.f;
; #pragma unroll
;         for (int j = 0; j < 4; ++j) {
;             f32x4 h;
;             if constexpr (SRC_F32) h = S.h32[i][j];
;             else { const v2u hw = S.hb[i][j]; h.x = bf_lo(hw.x); h.y = bf_hi(hw.x); h.z = bf_lo(hw.y); h.w = bf_hi(hw.y); }
;             const v2u fw = S.fw[i][j];
;             f32x4 v; v.x = h.x + bf_lo(fw.x) * rs * g[j].x; v.y = h.y + bf_hi(fw.x) * rs * g[j].y; v.z = h.z + bf_lo(fw.y) * rs * g[j].z; v.w = h.w + bf_hi(fw.y) * rs * g[j].w;
;             if (FINAL) __builtin_nontemporal_store(v, (f32x4*)(out32 + (size_t)(rb + i) * D) + lane + 64 * j);
	v_and_b32_e32 v185, 0xffff0000, v156
	v_mul_f32_e32 v184, s101, v184
	v_mul_f32_e32 v185, s101, v185
	v_fma_f32 v168, v184, v2, v168
	v_fma_f32 v169, v185, v3, v169
	v_lshlrev_b32_e32 v170, 16, v125
	v_and_b32_e32 v171, 0xffff0000, v125
	v_lshlrev_b32_e32 v184, 16, v157
	v_and_b32_e32 v185, 0xffff0000, v157
	v_mul_f32_e32 v184, s101, v184
	v_mul_f32_e32 v185, s101, v185
	v_fma_f32 v170, v184, v4, v170
	v_fma_f32 v171, v185, v5, v171
	v_lshlrev_b32_e32 v172, 16, v126
	v_and_b32_e32 v173, 0xffff0000, v126
	v_lshlrev_b32_e32 v184, 16, v158
	v_and_b32_e32 v185, 0xffff0000, v158
	v_mul_f32_e32 v184, s101, v184
	v_mul_f32_e32 v185, s101, v185
	v_fma_f32 v172, v184, v6, v172
	v_fma_f32 v173, v185, v7, v173
	v_lshlrev_b32_e32 v174, 16, v127
	v_and_b32_e32 v175, 0xffff0000, v127
	v_lshlrev_b32_e32 v184, 16, v159
	v_and_b32_e32 v185, 0xffff0000, v159
	v_mul_f32_e32 v184, s101, v184
	v_mul_f32_e32 v185, s101, v185
	v_fma_f32 v174, v184, v8, v174
	v_fma_f32 v175, v185, v9, v175
	v_lshlrev_b32_e32 v176, 16, v128
	v_and_b32_e32 v177, 0xffff0000, v128
	v_lshlrev_b32_e32 v184, 16, v160
	v_and_b32_e32 v185, 0xffff0000, v160
	v_mul_f32_e32 v184, s101, v184
	v_mul_f32_e32 v185, s101, v185
	v_fma_f32 v176, v184, v10, v176
	v_fma_f32 v177, v185, v11, v177
	v_lshlrev_b32_e32 v178, 16, v129
	v_and_b32_e32 v179, 0xffff0000, v129
	v_lshlrev_b32_e32 v184, 16, v161
	v_and_b32_e32 v185, 0xffff0000, v161
	v_mul_f32_e32 v184, s101, v184
	v_mul_f32_e32 v185, s101, v185
	v_fma_f32 v178, v184, v12, v178
	v_fma_f32 v179, v185, v13, v179
	v_lshlrev_b32_e32 v180, 16, v130
	v_and_b32_e32 v181, 0xffff0000, v130
	v_lshlrev_b32_e32 v184, 16, v162
	v_and_b32_e32 v185, 0xffff0000, v162
	v_mul_f32_e32 v184, s101, v184
	v_mul_f32_e32 v185, s101, v185
	v_fma_f32 v180, v184, v14, v180
	v_fma_f32 v181, v185, v15, v181
	v_lshlrev_b32_e32 v182, 16, v131
	v_and_b32_e32 v183, 0xffff0000, v131
	v_lshlrev_b32_e32 v184, 16, v163
	v_and_b32_e32 v185, 0xffff0000, v163
	v_mul_f32_e32 v184, s101, v184
	v_mul_f32_e32 v185, s101, v185
	v_fma_f32 v182, v184, v16, v182
	v_fma_f32 v183, v185, v17, v183
	v_add_u32_e32 v1, 0x3000, v27
	global_store_dwordx4 v1, v[168:171], s[14:15] nt
	global_store_dwordx4 v1, v[172:175], s[14:15] offset:16 nt
	global_store_dwordx4 v1, v[176:179], s[14:15] offset:2048 nt
	global_store_dwordx4 v1, v[180:183], s[14:15] offset:2064 nt
	s_nop 1
	s_add_u32 s27, s26, 2052
	s_lshl_b32 s22, s27, 11
	v_lshl_add_u32 v23, v0, 4, s22
	v_add_u32_e32 v24, 0x1000, v23
	s_lshl_b32 s22, s27, 6
	v_lshl_add_u32 v25, v0, 2, s22
	s_lshl_b32 s22, s27, 12
	v_lshl_add_u32 v27, v0, 5, s22
	global_load_dwordx4 v[100:103], v23, s[0:1]
	global_load_dwordx4 v[104:107], v23, s[0:1] offset:1024
	global_load_dwordx4 v[132:135], v23, s[4:5]
	global_load_dwordx4 v[136:139], v23, s[4:5] offset:1024
	global_load_dwordx4 v[108:111], v23, s[0:1] offset:2048
	global_load_dwordx4 v[112:115], v23, s[0:1] offset:3072
	global_load_dwordx4 v[140:143], v23, s[4:5] offset:2048
	global_load_dwordx4 v[144:147], v23, s[4:5] offset:3072
	global_load_dwordx4 v[116:119], v24, s[0:1]
	global_load_dwordx4 v[120:123], v24, s[0:1] offset:1024
	global_load_dwordx4 v[148:151], v24, s[4:5]
	global_load_dwordx4 v[152:155], v24, s[4:5] offset:1024
	global_load_dwordx4 v[124:127], v24, s[0:1] offset:2048
	global_load_dwordx4 v[128:131], v24, s[0:1] offset:3072
	global_load_dwordx4 v[156:159], v24, s[4:5] offset:2048
	global_load_dwordx4 v[160:163], v24, s[4:5] offset:3072
	global_load_dword v164, v25, s[6:7]
	s_waitcnt vmcnt(33)
	v_add_f32_dpp v96, v96, v96 quad_perm:[1,0,3,2] row_mask:0xf bank_mask:0xf
	s_nop 1
	v_add_f32_dpp v96, v96, v96 quad_perm:[2,3,0,1] row_mask:0xf bank_mask:0xf
	s_nop 1
	v_add_f32_dpp v96, v96, v96 row_half_mirror row_mask:0xf bank_mask:0xf
	s_nop 1
	v_add_f32_dpp v96, v96, v96 row_mirror row_mask:0xf bank_mask:0xf
	s_nop 1
	v_mul_f32_e32 v96, 0x3a800000, v96
	v_add_f32_e32 v96, 0x358637bd, v96
	v_rsq_f32_e32 v96, v96
	s_nop 0
	v_readlane_b32 s3, v96, 0
	v_readlane_b32 s24, v96, 16
	v_readlane_b32 s98, v96, 32
	v_readlane_b32 s101, v96, 48
	s_nop 1
	v_lshlrev_b32_e32 v168, 16, v32
	v_and_b32_e32 v169, 0xffff0000, v32
	v_lshlrev_b32_e32 v184, 16, v64
	v_and_b32_e32 v185, 0xffff0000, v64
	v_mul_f32_e32 v184, s3, v184
	v_mul_f32_e32 v185, s3, v185
	v_fma_f32 v168, v184, v2, v168
	v_fma_f32 v169, v185, v3, v169
	v_lshlrev_b32_e32 v170, 16, v33
	v_and_b32_e32 v171, 0xffff0000, v33
	v_lshlrev_b32_e32 v184, 16, v65
	v_and_b32_e32 v185, 0xffff0000, v65
	v_mul_f32_e32 v184, s3, v184
	v_mul_f32_e32 v185, s3, v185
	v_fma_f32 v170, v184, v4, v170
	v_fma_f32 v171, v185, v5, v171
	v_lshlrev_b32_e32 v172, 16, v34
	v_and_b32_e32 v173, 0xffff0000, v34
	v_lshlrev_b32_e32 v184, 16, v66
	v_and_b32_e32 v185, 0xffff0000, v66
	v_mul_f32_e32 v184, s3, v184
	v_mul_f32_e32 v185, s3, v185
	v_fma_f32 v172, v184, v6, v172
	v_fma_f32 v173, v185, v7, v173
	v_lshlrev_b32_e32 v174, 16, v35
	v_and_b32_e32 v175, 0xffff0000, v35
	v_lshlrev_b32_e32 v184, 16, v67
	v_and_b32_e32 v185, 0xffff0000, v67
	v_mul_f32_e32 v184, s3, v184
	v_mul_f32_e32 v185, s3, v185
	v_fma_f32 v174, v184, v8, v174
	v_fma_f32 v175, v185, v9, v175
	v_lshlrev_b32_e32 v176, 16, v36
	v_and_b32_e32 v177, 0xffff0000, v36
	v_lshlrev_b32_e32 v184, 16, v68
	v_and_b32_e32 v185, 0xffff0000, v68
	v_mul_f32_e32 v184, s3, v184
	v_mul_f32_e32 v185, s3, v185
	v_fma_f32 v176, v184, v10, v176
	v_fma_f32 v177, v185, v11, v177
	v_lshlrev_b32_e32 v178, 16, v37
	v_and_b32_e32 v179, 0xffff0000, v37
	v_lshlrev_b32_e32 v184, 16, v69
	v_and_b32_e32 v185, 0xffff0000, v69
	v_mul_f32_e32 v184, s3, v184
	v_mul_f32_e32 v185, s3, v185
	v_fma_f32 v178, v184, v12, v178
	v_fma_f32 v179, v185, v13, v179
; __device__ __forceinline__ float bf_lo(unsigned w) { return __uint_as_float(w << 16); }
; __device__ __forceinline__ float bf_hi(unsigned w) { return __uint_as_float(w & 0xffff0000u); }
; template <bool SRC_F32, bool FINAL, int R> __device__ __forceinline__ void ew_compute(const EwSet<SRC_F32, R>& S, int rb, const f32x4 (&g)[4], bf16* hb_out, float* out32, float scale, float* rs_out, int lane) {
;     ...
; #pragma unroll
;         for (int j = 0; j < 4; ++j) {
;             f32x4 h;
;             if constexpr (SRC_F32) h = S.h32[i][j];
;             else { const v2u hw = S.hb[i][j]; h.x = bf_lo(hw.x); h.y = bf_hi(hw.x); h.z = bf_lo(hw.y); h.w = bf_hi(hw.y); }
;             const v2u fw = S.fw[i][j];
;             f32x4 v; v.x = h.x + bf_lo(fw.x) * rs * g[j].x; v.y = h.y + bf_hi(fw.x) * rs * g[j].y; v.z = h.z + bf_lo(fw.y) * rs * g[j].z; v.w = h.w + bf_hi(fw.y) * rs * g[j].w;
;             if (FINAL) __builtin_nontemporal_store(v, (f32x4*)(out32 + (size_t)(rb + i) * D) + lane + 64 * j);
	v_lshlrev_b32_e32 v180, 16, v38
	v_and_b32_e32 v181, 0xffff0000, v38
	v_lshlrev_b32_e32 v184, 16, v70
	v_and_b32_e32 v185, 0xffff0000, v70
	v_mul_f32_e32 v184, s3, v184
	v_mul_f32_e32 v185, s3, v185
	v_fma_f32 v180, v184, v14, v180
	v_fma_f32 v181, v185, v15, v181
	v_lshlrev_b32_e32 v182, 16, v39
	v_and_b32_e32 v183, 0xffff0000, v39
	v_lshlrev_b32_e32 v184, 16, v71
	v_and_b32_e32 v185, 0xffff0000, v71
	v_mul_f32_e32 v184, s3, v184
	v_mul_f32_e32 v185, s3, v185
	v_fma_f32 v182, v184, v16, v182
	v_fma_f32 v183, v185, v17, v183
	global_store_dwordx4 v22, v[168:171], s[14:15] nt
	global_store_dwordx4 v22, v[172:175], s[14:15] offset:16 nt
	global_store_dwordx4 v22, v[176:179], s[14:15] offset:2048 nt
	global_store_dwordx4 v22, v[180:183], s[14:15] offset:2064 nt
	s_nop 1
	v_lshlrev_b32_e32 v168, 16, v40
	v_and_b32_e32 v169, 0xffff0000, v40
	v_lshlrev_b32_e32 v184, 16, v72
	v_and_b32_e32 v185, 0xffff0000, v72
	v_mul_f32_e32 v184, s24, v184
	v_mul_f32_e32 v185, s24, v185
	v_fma_f32 v168, v184, v2, v168
	v_fma_f32 v169, v185, v3, v169
	v_lshlrev_b32_e32 v170, 16, v41
	v_and_b32_e32 v171, 0xffff0000, v41
	v_lshlrev_b32_e32 v184, 16, v73
	v_and_b32_e32 v185, 0xffff0000, v73
	v_mul_f32_e32 v184, s24, v184
	v_mul_f32_e32 v185, s24, v185
	v_fma_f32 v170, v184, v4, v170
	v_fma_f32 v171, v185, v5, v171
	v_lshlrev_b32_e32 v172, 16, v42
	v_and_b32_e32 v173, 0xffff0000, v42
	v_lshlrev_b32_e32 v184, 16, v74
	v_and_b32_e32 v185, 0xffff0000, v74
	v_mul_f32_e32 v184, s24, v184
	v_mul_f32_e32 v185, s24, v185
	v_fma_f32 v172, v184, v6, v172
	v_fma_f32 v173, v185, v7, v173
	v_lshlrev_b32_e32 v174, 16, v43
	v_and_b32_e32 v175, 0xffff0000, v43
	v_lshlrev_b32_e32 v184, 16, v75
	v_and_b32_e32 v185, 0xffff0000, v75
	v_mul_f32_e32 v184, s24, v184
	v_mul_f32_e32 v185, s24, v185
	v_fma_f32 v174, v184, v8, v174
	v_fma_f32 v175, v185, v9, v175
	v_lshlrev_b32_e32 v176, 16, v44
	v_and_b32_e32 v177, 0xffff0000, v44
	v_lshlrev_b32_e32 v184, 16, v76
	v_and_b32_e32 v185, 0xffff0000, v76
	v_mul_f32_e32 v184, s24, v184
	v_mul_f32_e32 v185, s24, v185
	v_fma_f32 v176, v184, v10, v176
	v_fma_f32 v177, v185, v11, v177
	v_lshlrev_b32_e32 v178, 16, v45
	v_and_b32_e32 v179, 0xffff0000, v45
	v_lshlrev_b32_e32 v184, 16, v77
	v_and_b32_e32 v185, 0xffff0000, v77
	v_mul_f32_e32 v184, s24, v184
	v_mul_f32_e32 v185, s24, v185
	v_fma_f32 v178, v184, v12, v178
	v_fma_f32 v179, v185, v13, v179
	v_lshlrev_b32_e32 v180, 16, v46
	v_and_b32_e32 v181, 0xffff0000, v46
	v_lshlrev_b32_e32 v184, 16, v78
	v_and_b32_e32 v185, 0xffff0000, v78
	v_mul_f32_e32 v184, s24, v184
	v_mul_f32_e32 v185, s24, v185
	v_fma_f32 v180, v184, v14, v180
	v_fma_f32 v181, v185, v15, v181
	v_lshlrev_b32_e32 v182, 16, v47
	v_and_b32_e32 v183, 0xffff0000, v47
	v_lshlrev_b32_e32 v184, 16, v79
	v_and_b32_e32 v185, 0xffff0000, v79
	v_mul_f32_e32 v184, s24, v184
	v_mul_f32_e32 v185, s24, v185
	v_fma_f32 v182, v184, v16, v182
	v_fma_f32 v183, v185, v17, v183
	v_add_u32_e32 v1, 0x1000, v22
	global_store_dwordx4 v1, v[168:171], s[14:15] nt
	global_store_dwordx4 v1, v[172:175], s[14:15] offset:16 nt
	global_store_dwordx4 v1, v[176:179], s[14:15] offset:2048 nt
	global_store_dwordx4 v1, v[180:183], s[14:15] offset:2064 nt
	s_nop 1
	v_lshlrev_b32_e32 v168, 16, v48
	v_and_b32_e32 v169, 0xffff0000, v48
	v_lshlrev_b32_e32 v184, 16, v80
	v_and_b32_e32 v185, 0xffff0000, v80
	v_mul_f32_e32 v184, s98, v184
	v_mul_f32_e32 v185, s98, v185
	v_fma_f32 v168, v184, v2, v168
	v_fma_f32 v169, v185, v3, v169
	v_lshlrev_b32_e32 v170, 16, v49
	v_and_b32_e32 v171, 0xffff0000, v49
	v_lshlrev_b32_e32 v184, 16, v81
	v_and_b32_e32 v185, 0xffff0000, v81
	v_mul_f32_e32 v184, s98, v184
	v_mul_f32_e32 v185, s98, v185
	v_fma_f32 v170, v184, v4, v170
	v_fma_f32 v171, v185, v5, v171
	v_lshlrev_b32_e32 v172, 16, v50
	v_and_b32_e32 v173, 0xffff0000, v50
	v_lshlrev_b32_e32 v184, 16, v82
	v_and_b32_e32 v185, 0xffff0000, v82
	v_mul_f32_e32 v184, s98, v184
	v_mul_f32_e32 v185, s98, v185
	v_fma_f32 v172, v184, v6, v172
	v_fma_f32 v173, v185, v7, v173
	v_lshlrev_b32_e32 v174, 16, v51
	v_and_b32_e32 v175, 0xffff0000, v51
	v_lshlrev_b32_e32 v184, 16, v83
	v_and_b32_e32 v185, 0xffff0000, v83
	v_mul_f32_e32 v184, s98, v184
	v_mul_f32_e32 v185, s98, v185
	v_fma_f32 v174, v184, v8, v174
	v_fma_f32 v175, v185, v9, v175
	v_lshlrev_b32_e32 v176, 16, v52
	v_and_b32_e32 v177, 0xffff0000, v52
	v_lshlrev_b32_e32 v184, 16, v84
	v_and_b32_e32 v185, 0xffff0000, v84
	v_mul_f32_e32 v184, s98, v184
	v_mul_f32_e32 v185, s98, v185
	v_fma_f32 v176, v184, v10, v176
	v_fma_f32 v177, v185, v11, v177
	v_lshlrev_b32_e32 v178, 16, v53
	v_and_b32_e32 v179, 0xffff0000, v53
	v_lshlrev_b32_e32 v184, 16, v85
	v_and_b32_e32 v185, 0xffff0000, v85
	v_mul_f32_e32 v184, s98, v184
	v_mul_f32_e32 v185, s98, v185
	v_fma_f32 v178, v184, v12, v178
	v_fma_f32 v179, v185, v13, v179
	v_lshlrev_b32_e32 v180, 16, v54
	v_and_b32_e32 v181, 0xffff0000, v54
	v_lshlrev_b32_e32 v184, 16, v86
	v_and_b32_e32 v185, 0xffff0000, v86
	v_mul_f32_e32 v184, s98, v184
	v_mul_f32_e32 v185, s98, v185
	v_fma_f32 v180, v184, v14, v180
	v_fma_f32 v181, v185, v15, v181
	v_lshlrev_b32_e32 v182, 16, v55
	v_and_b32_e32 v183, 0xffff0000, v55
	v_lshlrev_b32_e32 v184, 16, v87
	v_and_b32_e32 v185, 0xffff0000, v87
	v_mul_f32_e32 v184, s98, v184
	v_mul_f32_e32 v185, s98, v185
	v_fma_f32 v182, v184, v16, v182
	v_fma_f32 v183, v185, v17, v183
	v_add_u32_e32 v1, 0x2000, v22
	global_store_dwordx4 v1, v[168:171], s[14:15] nt
	global_store_dwordx4 v1, v[172:175], s[14:15] offset:16 nt
	global_store_dwordx4 v1, v[176:179], s[14:15] offset:2048 nt
	global_store_dwordx4 v1, v[180:183], s[14:15] offset:2064 nt
	s_nop 1
	v_lshlrev_b32_e32 v168, 16, v56
; __device__ __forceinline__ float bf_lo(unsigned w) { return __uint_as_float(w << 16); }
; __device__ __forceinline__ float bf_hi(unsigned w) { return __uint_as_float(w & 0xffff0000u); }
; template <bool SRC_F32, bool FINAL, int R> __device__ __forceinline__ void ew_compute(const EwSet<SRC_F32, R>& S, int rb, const f32x4 (&g)[4], bf16* hb_out, float* out32, float scale, float* rs_out, int lane) {
;     ...
;         q += __shfl_xor(q, 1); q += __shfl_xor(q, 2); q += __shfl_xor(q, 4); q += __shfl_xor(q, 8);
;         const float ss = __shfl(q, 0);
;         const float rs = scale / sqrtf(ss * (1.f / D) + EPS);
;         float s2 = 0.f;
; #pragma unroll
;         for (int j = 0; j < 4; ++j) {
;             f32x4 h;
;             if constexpr (SRC_F32) h = S.h32[i][j];
;             else { const v2u hw = S.hb[i][j]; h.x = bf_lo(hw.x); h.y = bf_hi(hw.x); h.z = bf_lo(hw.y); h.w = bf_hi(hw.y); }
;             const v2u fw = S.fw[i][j];
;             f32x4 v; v.x = h.x + bf_lo(fw.x) * rs * g[j].x; v.y = h.y + bf_hi(fw.x) * rs * g[j].y; v.z = h.z + bf_lo(fw.y) * rs * g[j].z; v.w = h.w + bf_hi(fw.y) * rs * g[j].w;
;             if (FINAL) __builtin_nontemporal_store(v, (f32x4*)(out32 + (size_t)(rb + i) * D) + lane + 64 * j);
	v_and_b32_e32 v169, 0xffff0000, v56
	v_lshlrev_b32_e32 v184, 16, v88
	v_and_b32_e32 v185, 0xffff0000, v88
	v_mul_f32_e32 v184, s101, v184
	v_mul_f32_e32 v185, s101, v185
	v_fma_f32 v168, v184, v2, v168
	v_fma_f32 v169, v185, v3, v169
	v_lshlrev_b32_e32 v170, 16, v57
	v_and_b32_e32 v171, 0xffff0000, v57
	v_lshlrev_b32_e32 v184, 16, v89
	v_and_b32_e32 v185, 0xffff0000, v89
	v_mul_f32_e32 v184, s101, v184
	v_mul_f32_e32 v185, s101, v185
	v_fma_f32 v170, v184, v4, v170
	v_fma_f32 v171, v185, v5, v171
	v_lshlrev_b32_e32 v172, 16, v58
	v_and_b32_e32 v173, 0xffff0000, v58
	v_lshlrev_b32_e32 v184, 16, v90
	v_and_b32_e32 v185, 0xffff0000, v90
	v_mul_f32_e32 v184, s101, v184
	v_mul_f32_e32 v185, s101, v185
	v_fma_f32 v172, v184, v6, v172
	v_fma_f32 v173, v185, v7, v173
	v_lshlrev_b32_e32 v174, 16, v59
	v_and_b32_e32 v175, 0xffff0000, v59
	v_lshlrev_b32_e32 v184, 16, v91
	v_and_b32_e32 v185, 0xffff0000, v91
	v_mul_f32_e32 v184, s101, v184
	v_mul_f32_e32 v185, s101, v185
	v_fma_f32 v174, v184, v8, v174
	v_fma_f32 v175, v185, v9, v175
	v_lshlrev_b32_e32 v176, 16, v60
	v_and_b32_e32 v177, 0xffff0000, v60
	v_lshlrev_b32_e32 v184, 16, v92
	v_and_b32_e32 v185, 0xffff0000, v92
	v_mul_f32_e32 v184, s101, v184
	v_mul_f32_e32 v185, s101, v185
	v_fma_f32 v176, v184, v10, v176
	v_fma_f32 v177, v185, v11, v177
	v_lshlrev_b32_e32 v178, 16, v61
	v_and_b32_e32 v179, 0xffff0000, v61
	v_lshlrev_b32_e32 v184, 16, v93
	v_and_b32_e32 v185, 0xffff0000, v93
	v_mul_f32_e32 v184, s101, v184
	v_mul_f32_e32 v185, s101, v185
	v_fma_f32 v178, v184, v12, v178
	v_fma_f32 v179, v185, v13, v179
	v_lshlrev_b32_e32 v180, 16, v62
	v_and_b32_e32 v181, 0xffff0000, v62
	v_lshlrev_b32_e32 v184, 16, v94
	v_and_b32_e32 v185, 0xffff0000, v94
	v_mul_f32_e32 v184, s101, v184
	v_mul_f32_e32 v185, s101, v185
	v_fma_f32 v180, v184, v14, v180
	v_fma_f32 v181, v185, v15, v181
	v_lshlrev_b32_e32 v182, 16, v63
	v_and_b32_e32 v183, 0xffff0000, v63
	v_lshlrev_b32_e32 v184, 16, v95
	v_and_b32_e32 v185, 0xffff0000, v95
	v_mul_f32_e32 v184, s101, v184
	v_mul_f32_e32 v185, s101, v185
	v_fma_f32 v182, v184, v16, v182
	v_fma_f32 v183, v185, v17, v183
	v_add_u32_e32 v1, 0x3000, v22
	global_store_dwordx4 v1, v[168:171], s[14:15] nt
	global_store_dwordx4 v1, v[172:175], s[14:15] offset:16 nt
	global_store_dwordx4 v1, v[176:179], s[14:15] offset:2048 nt
	global_store_dwordx4 v1, v[180:183], s[14:15] offset:2064 nt
	s_nop 1
	s_waitcnt vmcnt(16)
	v_add_f32_dpp v164, v164, v164 quad_perm:[1,0,3,2] row_mask:0xf bank_mask:0xf
	s_nop 1
	v_add_f32_dpp v164, v164, v164 quad_perm:[2,3,0,1] row_mask:0xf bank_mask:0xf
	s_nop 1
	v_add_f32_dpp v164, v164, v164 row_half_mirror row_mask:0xf bank_mask:0xf
	s_nop 1
	v_add_f32_dpp v164, v164, v164 row_mirror row_mask:0xf bank_mask:0xf
	s_nop 1
	v_mul_f32_e32 v164, 0x3a800000, v164
	v_add_f32_e32 v164, 0x358637bd, v164
	v_rsq_f32_e32 v164, v164
	s_nop 0
	v_readlane_b32 s3, v164, 0
	v_readlane_b32 s24, v164, 16
	v_readlane_b32 s98, v164, 32
	v_readlane_b32 s101, v164, 48
	s_nop 1
	v_lshlrev_b32_e32 v168, 16, v100
	v_and_b32_e32 v169, 0xffff0000, v100
	v_lshlrev_b32_e32 v184, 16, v132
	v_and_b32_e32 v185, 0xffff0000, v132
	v_mul_f32_e32 v184, s3, v184
	v_mul_f32_e32 v185, s3, v185
	v_fma_f32 v168, v184, v2, v168
	v_fma_f32 v169, v185, v3, v169
	v_lshlrev_b32_e32 v170, 16, v101
	v_and_b32_e32 v171, 0xffff0000, v101
	v_lshlrev_b32_e32 v184, 16, v133
	v_and_b32_e32 v185, 0xffff0000, v133
	v_mul_f32_e32 v184, s3, v184
	v_mul_f32_e32 v185, s3, v185
	v_fma_f32 v170, v184, v4, v170
	v_fma_f32 v171, v185, v5, v171
	v_lshlrev_b32_e32 v172, 16, v102
	v_and_b32_e32 v173, 0xffff0000, v102
	v_lshlrev_b32_e32 v184, 16, v134
	v_and_b32_e32 v185, 0xffff0000, v134
	v_mul_f32_e32 v184, s3, v184
	v_mul_f32_e32 v185, s3, v185
	v_fma_f32 v172, v184, v6, v172
	v_fma_f32 v173, v185, v7, v173
	v_lshlrev_b32_e32 v174, 16, v103
	v_and_b32_e32 v175, 0xffff0000, v103
	v_lshlrev_b32_e32 v184, 16, v135
	v_and_b32_e32 v185, 0xffff0000, v135
	v_mul_f32_e32 v184, s3, v184
	v_mul_f32_e32 v185, s3, v185
	v_fma_f32 v174, v184, v8, v174
	v_fma_f32 v175, v185, v9, v175
	v_lshlrev_b32_e32 v176, 16, v104
	v_and_b32_e32 v177, 0xffff0000, v104
	v_lshlrev_b32_e32 v184, 16, v136
	v_and_b32_e32 v185, 0xffff0000, v136
	v_mul_f32_e32 v184, s3, v184
	v_mul_f32_e32 v185, s3, v185
	v_fma_f32 v176, v184, v10, v176
	v_fma_f32 v177, v185, v11, v177
	v_lshlrev_b32_e32 v178, 16, v105
	v_and_b32_e32 v179, 0xffff0000, v105
	v_lshlrev_b32_e32 v184, 16, v137
	v_and_b32_e32 v185, 0xffff0000, v137
	v_mul_f32_e32 v184, s3, v184
	v_mul_f32_e32 v185, s3, v185
	v_fma_f32 v178, v184, v12, v178
	v_fma_f32 v179, v185, v13, v179
	v_lshlrev_b32_e32 v180, 16, v106
	v_and_b32_e32 v181, 0xffff0000, v106
	v_lshlrev_b32_e32 v184, 16, v138
	v_and_b32_e32 v185, 0xffff0000, v138
	v_mul_f32_e32 v184, s3, v184
	v_mul_f32_e32 v185, s3, v185
	v_fma_f32 v180, v184, v14, v180
	v_fma_f32 v181, v185, v15, v181
	v_lshlrev_b32_e32 v182, 16, v107
	v_and_b32_e32 v183, 0xffff0000, v107
	v_lshlrev_b32_e32 v184, 16, v139
	v_and_b32_e32 v185, 0xffff0000, v139
	v_mul_f32_e32 v184, s3, v184
	v_mul_f32_e32 v185, s3, v185
	v_fma_f32 v182, v184, v16, v182
	v_fma_f32 v183, v185, v17, v183
	global_store_dwordx4 v27, v[168:171], s[14:15] nt
	global_store_dwordx4 v27, v[172:175], s[14:15] offset:16 nt
	global_store_dwordx4 v27, v[176:179], s[14:15] offset:2048 nt
	global_store_dwordx4 v27, v[180:183], s[14:15] offset:2064 nt
	s_nop 1
	v_lshlrev_b32_e32 v168, 16, v108
	v_and_b32_e32 v169, 0xffff0000, v108
	v_lshlrev_b32_e32 v184, 16, v140
	v_and_b32_e32 v185, 0xffff0000, v140
	v_mul_f32_e32 v184, s24, v184
	v_mul_f32_e32 v185, s24, v185
	v_fma_f32 v168, v184, v2, v168
; __device__ __forceinline__ float bf_lo(unsigned w) { return __uint_as_float(w << 16); }
; __device__ __forceinline__ float bf_hi(unsigned w) { return __uint_as_float(w & 0xffff0000u); }
; template <bool SRC_F32, bool FINAL, int R> __device__ __forceinline__ void ew_compute(const EwSet<SRC_F32, R>& S, int rb, const f32x4 (&g)[4], bf16* hb_out, float* out32, float scale, float* rs_out, int lane) {
;     ...
; #pragma unroll
;         for (int j = 0; j < 4; ++j) {
;             f32x4 h;
;             if constexpr (SRC_F32) h = S.h32[i][j];
;             else { const v2u hw = S.hb[i][j]; h.x = bf_lo(hw.x); h.y = bf_hi(hw.x); h.z = bf_lo(hw.y); h.w = bf_hi(hw.y); }
;             const v2u fw = S.fw[i][j];
;             f32x4 v; v.x = h.x + bf_lo(fw.x) * rs * g[j].x; v.y = h.y + bf_hi(fw.x) * rs * g[j].y; v.z = h.z + bf_lo(fw.y) * rs * g[j].z; v.w = h.w + bf_hi(fw.y) * rs * g[j].w;
;             if (FINAL) __builtin_nontemporal_store(v, (f32x4*)(out32 + (size_t)(rb + i) * D) + lane + 64 * j);
	v_fma_f32 v169, v185, v3, v169
	v_lshlrev_b32_e32 v170, 16, v109
	v_and_b32_e32 v171, 0xffff0000, v109
	v_lshlrev_b32_e32 v184, 16, v141
	v_and_b32_e32 v185, 0xffff0000, v141
	v_mul_f32_e32 v184, s24, v184
	v_mul_f32_e32 v185, s24, v185
	v_fma_f32 v170, v184, v4, v170
	v_fma_f32 v171, v185, v5, v171
	v_lshlrev_b32_e32 v172, 16, v110
	v_and_b32_e32 v173, 0xffff0000, v110
	v_lshlrev_b32_e32 v184, 16, v142
	v_and_b32_e32 v185, 0xffff0000, v142
	v_mul_f32_e32 v184, s24, v184
	v_mul_f32_e32 v185, s24, v185
	v_fma_f32 v172, v184, v6, v172
	v_fma_f32 v173, v185, v7, v173
	v_lshlrev_b32_e32 v174, 16, v111
	v_and_b32_e32 v175, 0xffff0000, v111
	v_lshlrev_b32_e32 v184, 16, v143
	v_and_b32_e32 v185, 0xffff0000, v143
	v_mul_f32_e32 v184, s24, v184
	v_mul_f32_e32 v185, s24, v185
	v_fma_f32 v174, v184, v8, v174
	v_fma_f32 v175, v185, v9, v175
	v_lshlrev_b32_e32 v176, 16, v112
	v_and_b32_e32 v177, 0xffff0000, v112
	v_lshlrev_b32_e32 v184, 16, v144
	v_and_b32_e32 v185, 0xffff0000, v144
	v_mul_f32_e32 v184, s24, v184
	v_mul_f32_e32 v185, s24, v185
	v_fma_f32 v176, v184, v10, v176
	v_fma_f32 v177, v185, v11, v177
	v_lshlrev_b32_e32 v178, 16, v113
	v_and_b32_e32 v179, 0xffff0000, v113
	v_lshlrev_b32_e32 v184, 16, v145
	v_and_b32_e32 v185, 0xffff0000, v145
	v_mul_f32_e32 v184, s24, v184
	v_mul_f32_e32 v185, s24, v185
	v_fma_f32 v178, v184, v12, v178
	v_fma_f32 v179, v185, v13, v179
	v_lshlrev_b32_e32 v180, 16, v114
	v_and_b32_e32 v181, 0xffff0000, v114
	v_lshlrev_b32_e32 v184, 16, v146
	v_and_b32_e32 v185, 0xffff0000, v146
	v_mul_f32_e32 v184, s24, v184
	v_mul_f32_e32 v185, s24, v185
	v_fma_f32 v180, v184, v14, v180
	v_fma_f32 v181, v185, v15, v181
	v_lshlrev_b32_e32 v182, 16, v115
	v_and_b32_e32 v183, 0xffff0000, v115
	v_lshlrev_b32_e32 v184, 16, v147
	v_and_b32_e32 v185, 0xffff0000, v147
	v_mul_f32_e32 v184, s24, v184
	v_mul_f32_e32 v185, s24, v185
	v_fma_f32 v182, v184, v16, v182
	v_fma_f32 v183, v185, v17, v183
	v_add_u32_e32 v1, 0x1000, v27
	global_store_dwordx4 v1, v[168:171], s[14:15] nt
	global_store_dwordx4 v1, v[172:175], s[14:15] offset:16 nt
	global_store_dwordx4 v1, v[176:179], s[14:15] offset:2048 nt
	global_store_dwordx4 v1, v[180:183], s[14:15] offset:2064 nt
	s_nop 1
	v_lshlrev_b32_e32 v168, 16, v116
	v_and_b32_e32 v169, 0xffff0000, v116
	v_lshlrev_b32_e32 v184, 16, v148
	v_and_b32_e32 v185, 0xffff0000, v148
	v_mul_f32_e32 v184, s98, v184
	v_mul_f32_e32 v185, s98, v185
	v_fma_f32 v168, v184, v2, v168
	v_fma_f32 v169, v185, v3, v169
	v_lshlrev_b32_e32 v170, 16, v117
	v_and_b32_e32 v171, 0xffff0000, v117
	v_lshlrev_b32_e32 v184, 16, v149
	v_and_b32_e32 v185, 0xffff0000, v149
	v_mul_f32_e32 v184, s98, v184
	v_mul_f32_e32 v185, s98, v185
	v_fma_f32 v170, v184, v4, v170
	v_fma_f32 v171, v185, v5, v171
	v_lshlrev_b32_e32 v172, 16, v118
	v_and_b32_e32 v173, 0xffff0000, v118
	v_lshlrev_b32_e32 v184, 16, v150
	v_and_b32_e32 v185, 0xffff0000, v150
	v_mul_f32_e32 v184, s98, v184
	v_mul_f32_e32 v185, s98, v185
	v_fma_f32 v172, v184, v6, v172
	v_fma_f32 v173, v185, v7, v173
	v_lshlrev_b32_e32 v174, 16, v119
	v_and_b32_e32 v175, 0xffff0000, v119
	v_lshlrev_b32_e32 v184, 16, v151
	v_and_b32_e32 v185, 0xffff0000, v151
	v_mul_f32_e32 v184, s98, v184
	v_mul_f32_e32 v185, s98, v185
	v_fma_f32 v174, v184, v8, v174
	v_fma_f32 v175, v185, v9, v175
	v_lshlrev_b32_e32 v176, 16, v120
	v_and_b32_e32 v177, 0xffff0000, v120
	v_lshlrev_b32_e32 v184, 16, v152
	v_and_b32_e32 v185, 0xffff0000, v152
	v_mul_f32_e32 v184, s98, v184
	v_mul_f32_e32 v185, s98, v185
	v_fma_f32 v176, v184, v10, v176
	v_fma_f32 v177, v185, v11, v177
; __device__ __forceinline__ float bf_lo(unsigned w) { return __uint_as_float(w << 16); }
; __device__ __forceinline__ float bf_hi(unsigned w) { return __uint_as_float(w & 0xffff0000u); }
; template <bool SRC_F32, bool FINAL, int R> __device__ __forceinline__ void ew_compute(const EwSet<SRC_F32, R>& S, int rb, const f32x4 (&g)[4], bf16* hb_out, float* out32, float scale, float* rs_out, int lane) {
;     ...
; #pragma unroll
;         for (int j = 0; j < 4; ++j) {
;             f32x4 h;
;             if constexpr (SRC_F32) h = S.h32[i][j];
;             else { const v2u hw = S.hb[i][j]; h.x = bf_lo(hw.x); h.y = bf_hi(hw.x); h.z = bf_lo(hw.y); h.w = bf_hi(hw.y); }
;             const v2u fw = S.fw[i][j];
;             f32x4 v; v.x = h.x + bf_lo(fw.x) * rs * g[j].x; v.y = h.y + bf_hi(fw.x) * rs * g[j].y; v.z = h.z + bf_lo(fw.y) * rs * g[j].z; v.w = h.w + bf_hi(fw.y) * rs * g[j].w;
;             if (FINAL) __builtin_nontemporal_store(v, (f32x4*)(out32 + (size_t)(rb + i) * D) + lane + 64 * j);
	v_lshlrev_b32_e32 v178, 16, v121
	v_and_b32_e32 v179, 0xffff0000, v121
	v_lshlrev_b32_e32 v184, 16, v153
	v_and_b32_e32 v185, 0xffff0000, v153
	v_mul_f32_e32 v184, s98, v184
	v_mul_f32_e32 v185, s98, v185
	v_fma_f32 v178, v184, v12, v178
	v_fma_f32 v179, v185, v13, v179
	v_lshlrev_b32_e32 v180, 16, v122
	v_and_b32_e32 v181, 0xffff0000, v122
	v_lshlrev_b32_e32 v184, 16, v154
	v_and_b32_e32 v185, 0xffff0000, v154
	v_mul_f32_e32 v184, s98, v184
	v_mul_f32_e32 v185, s98, v185
	v_fma_f32 v180, v184, v14, v180
	v_fma_f32 v181, v185, v15, v181
	v_lshlrev_b32_e32 v182, 16, v123
	v_and_b32_e32 v183, 0xffff0000, v123
	v_lshlrev_b32_e32 v184, 16, v155
	v_and_b32_e32 v185, 0xffff0000, v155
	v_mul_f32_e32 v184, s98, v184
	v_mul_f32_e32 v185, s98, v185
	v_fma_f32 v182, v184, v16, v182
	v_fma_f32 v183, v185, v17, v183
	v_add_u32_e32 v1, 0x2000, v27
	global_store_dwordx4 v1, v[168:171], s[14:15] nt
	global_store_dwordx4 v1, v[172:175], s[14:15] offset:16 nt
	global_store_dwordx4 v1, v[176:179], s[14:15] offset:2048 nt
	global_store_dwordx4 v1, v[180:183], s[14:15] offset:2064 nt
	s_nop 1
	v_lshlrev_b32_e32 v168, 16, v124
	v_and_b32_e32 v169, 0xffff0000, v124
	v_lshlrev_b32_e32 v184, 16, v156
	v_and_b32_e32 v185, 0xffff0000, v156
	v_mul_f32_e32 v184, s101, v184
	v_mul_f32_e32 v185, s101, v185
	v_fma_f32 v168, v184, v2, v168
	v_fma_f32 v169, v185, v3, v169
	v_lshlrev_b32_e32 v170, 16, v125
	v_and_b32_e32 v171, 0xffff0000, v125
	v_lshlrev_b32_e32 v184, 16, v157
	v_and_b32_e32 v185, 0xffff0000, v157
	v_mul_f32_e32 v184, s101, v184
	v_mul_f32_e32 v185, s101, v185
	v_fma_f32 v170, v184, v4, v170
	v_fma_f32 v171, v185, v5, v171
	v_lshlrev_b32_e32 v172, 16, v126
	v_and_b32_e32 v173, 0xffff0000, v126
	v_lshlrev_b32_e32 v184, 16, v158
	v_and_b32_e32 v185, 0xffff0000, v158
	v_mul_f32_e32 v184, s101, v184
	v_mul_f32_e32 v185, s101, v185
	v_fma_f32 v172, v184, v6, v172
	v_fma_f32 v173, v185, v7, v173
	v_lshlrev_b32_e32 v174, 16, v127
	v_and_b32_e32 v175, 0xffff0000, v127
	v_lshlrev_b32_e32 v184, 16, v159
	v_and_b32_e32 v185, 0xffff0000, v159
	v_mul_f32_e32 v184, s101, v184
	v_mul_f32_e32 v185, s101, v185
	v_fma_f32 v174, v184, v8, v174
	v_fma_f32 v175, v185, v9, v175
	v_lshlrev_b32_e32 v176, 16, v128
	v_and_b32_e32 v177, 0xffff0000, v128
	v_lshlrev_b32_e32 v184, 16, v160
	v_and_b32_e32 v185, 0xffff0000, v160
	v_mul_f32_e32 v184, s101, v184
	v_mul_f32_e32 v185, s101, v185
	v_fma_f32 v176, v184, v10, v176
	v_fma_f32 v177, v185, v11, v177
	v_lshlrev_b32_e32 v178, 16, v129
	v_and_b32_e32 v179, 0xffff0000, v129
	v_lshlrev_b32_e32 v184, 16, v161
	v_and_b32_e32 v185, 0xffff0000, v161
	v_mul_f32_e32 v184, s101, v184
	v_mul_f32_e32 v185, s101, v185
	v_fma_f32 v178, v184, v12, v178
	v_fma_f32 v179, v185, v13, v179
	v_lshlrev_b32_e32 v180, 16, v130
	v_and_b32_e32 v181, 0xffff0000, v130
	v_lshlrev_b32_e32 v184, 16, v162
	v_and_b32_e32 v185, 0xffff0000, v162
	v_mul_f32_e32 v184, s101, v184
	v_mul_f32_e32 v185, s101, v185
	v_fma_f32 v180, v184, v14, v180
	v_fma_f32 v181, v185, v15, v181
	v_lshlrev_b32_e32 v182, 16, v131
	v_and_b32_e32 v183, 0xffff0000, v131
	v_lshlrev_b32_e32 v184, 16, v163
	v_and_b32_e32 v185, 0xffff0000, v163
	v_mul_f32_e32 v184, s101, v184
	v_mul_f32_e32 v185, s101, v185
	v_fma_f32 v182, v184, v16, v182
	v_fma_f32 v183, v185, v17, v183
	v_add_u32_e32 v1, 0x3000, v27
	global_store_dwordx4 v1, v[168:171], s[14:15] nt
	global_store_dwordx4 v1, v[172:175], s[14:15] offset:16 nt
	global_store_dwordx4 v1, v[176:179], s[14:15] offset:2048 nt
	global_store_dwordx4 v1, v[180:183], s[14:15] offset:2064 nt
	s_nop 1
